# counted lgkmcnt waits in attention read/MFMA batches + all flat ops converted to global
# baseline (speedup 1.0000x reference)
; #define LAS __attribute__((address_space(3)))
; __device__ __forceinline__ unsigned cvt_pk_bf16(float lo, float hi) { unsigned r; asm("v_cvt_pk_bf16_f32 %0, %1, %2" : "=v"(r) : "v"(lo), "v"(hi)); return r; }
; template <int MAPK>
; __device__ __forceinline__ void transpose_item(const float* W, int K, int N, int ND, bf16_t* WT, const float* g, LAS float* scr, int item, int lane) {
;     ...
;     for (int i = 0; i < 16; ++i) { const int kk = 4 * i + kr; f32x4 v = vv[i];
;         if (g) v = v * g[k0 + kk];
;         scr[kk * 65 + c4] = v[0]; scr[kk * 65 + c4 + 1] = v[1]; scr[kk * 65 + c4 + 2] = v[2]; scr[kk * 65 + c4 + 3] = v[3]; }
;     asm volatile("s_waitcnt lgkmcnt(0)" ::: "memory");
;     const int c = lane & 7;
; #pragma unroll
;     for (int j = 0; j < 8; ++j) { const int n = (lane >> 3) + 8 * j; const LAS float* sp = scr + (8 * c) * 65 + n;
;         u32x4 o; o.x = cvt_pk_bf16(sp[0], sp[65]); o.y = cvt_pk_bf16(sp[2 * 65], sp[3 * 65]); o.z = cvt_pk_bf16(sp[4 * 65], sp[5 * 65]); o.w = cvt_pk_bf16(sp[6 * 65], sp[7 * 65]);
;         *(u32x4*)(WT + (size_t)(n0 + n) * K + k0 + 8 * c) = o; }
.LBB0_21:
	v_add_u32_e32 v4, 0x1040, v0
	ds_write2_b32 v4, v16, v17 offset1:1
	v_add_u32_e32 v4, 0x1048, v0
	ds_write2_b32 v4, v2, v3 offset1:1
	v_add_u32_e32 v2, 0x1450, v0
	v_add_u32_e32 v0, 0x1458, v0
	ds_write2_b32 v2, v12, v13 offset1:1
	ds_write2_b32 v0, v14, v15 offset1:1
	s_waitcnt lgkmcnt(0)
	ds_read_b32 v0, v85
	ds_read_b32 v2, v85 offset:260
	ds_read_b32 v3, v85 offset:520
	ds_read_b32 v4, v85 offset:780
	ds_read_b32 v5, v85 offset:1040
	ds_read_b32 v8, v85 offset:1300
	ds_read_b32 v9, v85 offset:1560
	ds_read_b32 v10, v85 offset:1820
	s_add_u32 s18, s7, s91
	s_addc_u32 s19, s9, s90
	s_lshl_b64 s[0:1], s[20:21], 1
	s_add_u32 s0, s18, s0
	s_waitcnt lgkmcnt(0)
	v_cvt_pk_bf16_f32 v3, v3, v4
	v_cvt_pk_bf16_f32 v4, v5, v8
	v_or_b32_e32 v8, s92, v84
	s_addc_u32 s1, s19, s1
	v_mov_b32_e32 v79, v1
	v_cvt_pk_bf16_f32 v5, v9, v10
	v_ashrrev_i32_e32 v9, 31, v8
	v_lshl_add_u64 v[6:7], s[0:1], 0, v[78:79]
	v_lshlrev_b64 v[8:9], 12, v[8:9]
	v_lshl_add_u64 v[8:9], v[6:7], 0, v[8:9]
	v_cvt_pk_bf16_f32 v2, v0, v2
	global_store_dwordx4 v[8:9], v[2:5], off
	ds_read_b32 v0, v85 offset:32
	ds_read_b32 v2, v85 offset:292
	ds_read_b32 v3, v85 offset:552
	ds_read_b32 v4, v85 offset:812
	ds_read_b32 v5, v85 offset:1072
	ds_read_b32 v8, v85 offset:1332
	ds_read_b32 v9, v85 offset:1592
	ds_read_b32 v10, v85 offset:1852
	s_waitcnt lgkmcnt(0)
	v_cvt_pk_bf16_f32 v3, v3, v4
	v_cvt_pk_bf16_f32 v4, v5, v8
	v_or_b32_e32 v8, s92, v86
	v_cvt_pk_bf16_f32 v5, v9, v10
	v_ashrrev_i32_e32 v9, 31, v8
	v_lshlrev_b64 v[8:9], 12, v[8:9]
	v_lshl_add_u64 v[8:9], v[6:7], 0, v[8:9]
	v_cvt_pk_bf16_f32 v2, v0, v2
	global_store_dwordx4 v[8:9], v[2:5], off
	ds_read_b32 v0, v85 offset:64
	ds_read_b32 v2, v85 offset:324
	ds_read_b32 v3, v85 offset:584
	ds_read_b32 v4, v85 offset:844
	ds_read_b32 v5, v85 offset:1104
	ds_read_b32 v8, v85 offset:1364
	ds_read_b32 v9, v85 offset:1624
	ds_read_b32 v10, v85 offset:1884
	s_waitcnt lgkmcnt(0)
	v_cvt_pk_bf16_f32 v3, v3, v4
	v_cvt_pk_bf16_f32 v4, v5, v8
	v_or_b32_e32 v8, s92, v87
	v_cvt_pk_bf16_f32 v5, v9, v10
	v_ashrrev_i32_e32 v9, 31, v8
	v_lshlrev_b64 v[8:9], 12, v[8:9]
	v_lshl_add_u64 v[8:9], v[6:7], 0, v[8:9]
	v_cvt_pk_bf16_f32 v2, v0, v2
	global_store_dwordx4 v[8:9], v[2:5], off
	ds_read_b32 v0, v85 offset:96
	ds_read_b32 v2, v85 offset:356
	ds_read_b32 v3, v85 offset:616
	ds_read_b32 v4, v85 offset:876
	ds_read_b32 v5, v85 offset:1136
	ds_read_b32 v8, v85 offset:1396
	ds_read_b32 v9, v85 offset:1656
	ds_read_b32 v10, v85 offset:1916
	s_waitcnt lgkmcnt(0)
	v_cvt_pk_bf16_f32 v3, v3, v4
	v_cvt_pk_bf16_f32 v4, v5, v8
	v_or_b32_e32 v8, s92, v88
	v_cvt_pk_bf16_f32 v5, v9, v10
	v_ashrrev_i32_e32 v9, 31, v8
	v_lshlrev_b64 v[8:9], 12, v[8:9]
	v_lshl_add_u64 v[8:9], v[6:7], 0, v[8:9]
	v_cvt_pk_bf16_f32 v2, v0, v2
	global_store_dwordx4 v[8:9], v[2:5], off
	ds_read_b32 v0, v85 offset:128
	ds_read_b32 v2, v85 offset:388
	ds_read_b32 v3, v85 offset:648
	ds_read_b32 v4, v85 offset:908
	ds_read_b32 v5, v85 offset:1168
	ds_read_b32 v8, v85 offset:1428
	ds_read_b32 v9, v85 offset:1688
	ds_read_b32 v10, v85 offset:1948
	s_waitcnt lgkmcnt(0)
	v_cvt_pk_bf16_f32 v3, v3, v4
	v_cvt_pk_bf16_f32 v4, v5, v8
	v_or_b32_e32 v8, s92, v89
	v_cvt_pk_bf16_f32 v5, v9, v10
	v_ashrrev_i32_e32 v9, 31, v8
	v_lshlrev_b64 v[8:9], 12, v[8:9]
	v_lshl_add_u64 v[8:9], v[6:7], 0, v[8:9]
	v_cvt_pk_bf16_f32 v2, v0, v2
	global_store_dwordx4 v[8:9], v[2:5], off
	ds_read_b32 v0, v85 offset:160
	ds_read_b32 v2, v85 offset:420
	ds_read_b32 v3, v85 offset:680
	ds_read_b32 v4, v85 offset:940
	ds_read_b32 v5, v85 offset:1200
	ds_read_b32 v8, v85 offset:1460
	ds_read_b32 v9, v85 offset:1720
	ds_read_b32 v10, v85 offset:1980
	s_waitcnt lgkmcnt(0)
	v_cvt_pk_bf16_f32 v3, v3, v4
	v_cvt_pk_bf16_f32 v4, v5, v8
	v_or_b32_e32 v8, s92, v90
	v_cvt_pk_bf16_f32 v5, v9, v10
	v_ashrrev_i32_e32 v9, 31, v8
	v_lshlrev_b64 v[8:9], 12, v[8:9]
	v_lshl_add_u64 v[8:9], v[6:7], 0, v[8:9]
	v_cvt_pk_bf16_f32 v2, v0, v2
	global_store_dwordx4 v[8:9], v[2:5], off
	ds_read_b32 v0, v85 offset:192
	ds_read_b32 v2, v85 offset:452
	ds_read_b32 v3, v85 offset:712
	ds_read_b32 v4, v85 offset:972
	ds_read_b32 v5, v85 offset:1232
	ds_read_b32 v8, v85 offset:1492
	ds_read_b32 v9, v85 offset:1752
	ds_read_b32 v10, v85 offset:2012
	s_waitcnt lgkmcnt(0)
	v_cvt_pk_bf16_f32 v3, v3, v4
	v_cvt_pk_bf16_f32 v4, v5, v8
	v_or_b32_e32 v8, s92, v91
	v_cvt_pk_bf16_f32 v5, v9, v10
	v_ashrrev_i32_e32 v9, 31, v8
	v_lshlrev_b64 v[8:9], 12, v[8:9]
	v_lshl_add_u64 v[8:9], v[6:7], 0, v[8:9]
	v_cvt_pk_bf16_f32 v2, v0, v2
	global_store_dwordx4 v[8:9], v[2:5], off
	ds_read_b32 v0, v85 offset:224
	ds_read_b32 v2, v85 offset:484
	ds_read_b32 v3, v85 offset:744
	ds_read_b32 v4, v85 offset:1004
	ds_read_b32 v5, v85 offset:1264
	ds_read_b32 v8, v85 offset:1524
	ds_read_b32 v9, v85 offset:1784
	ds_read_b32 v10, v85 offset:2044
	s_waitcnt lgkmcnt(0)
	v_cvt_pk_bf16_f32 v3, v3, v4
	v_cvt_pk_bf16_f32 v4, v5, v8
	v_or_b32_e32 v8, s92, v92
	v_cvt_pk_bf16_f32 v5, v9, v10
	v_ashrrev_i32_e32 v9, 31, v8
	v_lshlrev_b64 v[8:9], 12, v[8:9]
	v_lshl_add_u64 v[6:7], v[6:7], 0, v[8:9]
	v_cvt_pk_bf16_f32 v2, v0, v2
	global_store_dwordx4 v[6:7], v[2:5], off
	s_waitcnt lgkmcnt(0)

; #define LAS __attribute__((address_space(3)))
; template <int MAPK>
; __device__ __forceinline__ void transpose_item(const float* W, int K, int N, int ND, bf16_t* WT, const float* g, LAS float* scr, int item, int lane) {
;     const int nblk = ND / 64, kb = item / nblk, nb = item % nblk, k0 = 64 * kb, n0 = 64 * nb;
;     const int c4 = (lane & 15) * 4, kr = lane >> 4;
;     int src = n0 + c4; if (MAPK == 1) src = inmap(src); if (MAPK == 2) src = upmap(src);
;     f32x4 vv[16];
; #pragma unroll
;     for (int i = 0; i < 16; ++i) { const int kk = 4 * i + kr;
;         vv[i] = (f32x4){0.f, 0.f, 0.f, 0.f};
;         if (src >= 0) vv[i] = *(const f32x4*)(W + (size_t)(k0 + kk) * N + src); }
; #pragma unroll
;     for (int i = 0; i < 16; ++i) { const int kk = 4 * i + kr; f32x4 v = vv[i];
;         if (g) v = v * g[k0 + kk];
;         scr[kk * 65 + c4] = v[0]; scr[kk * 65 + c4 + 1] = v[1]; scr[kk * 65 + c4 + 2] = v[2]; scr[kk * 65 + c4 + 3] = v[3]; }
; __global__ void __launch_bounds__(512, 2) hybrid_fwd(Params p) {
;     ...
;         for (int it = gw; it < 4 * I_LAYER; it += NGW) {
;             const int l = it / I_LAYER; int r = it % I_LAYER; unsigned char* wl = ws + WS_W + (size_t)l * SZ_LAYER;
;             if (r < I_IN) { transpose_item<1>(p.w_in + (size_t)l * D_ * INC, D_, INC, NWIN, (bf16_t*)(WL + OF_WIN), p.norm_mix + l * D_, scr, r, lane); continue; } r -= I_IN;
;             if (r < I_OUT) { transpose_item<0>(p.w_mix_out + (size_t)l * D_ * D_, D_, D_, D_, (bf16_t*)(WL + OF_WOUT), nullptr, scr, r, lane); continue; } r -= I_OUT;
;             if (r < I_Q) { transpose_item<0>(p.wq_x + (size_t)l * D_ * 512, D_, 512, 512, (bf16_t*)(WL + OF_WQ), p.norm_xattn + l * D_, scr, r, lane); continue; } r -= I_Q;
;             if (r < I_KV) { transpose_item<0>(p.wkv_x + (size_t)l * D_ * 1024, D_, 1024, 1024, (bf16_t*)(WL + OF_WKV), p.norm_mem + l * D_, scr, r, lane); continue; } r -= I_KV;
;             if (r < I_O) { transpose_item<0>(p.wo_x + (size_t)l * 512 * D_, 512, D_, D_, (bf16_t*)(WL + OF_WO), nullptr, scr, r, lane); continue; } r -= I_O;
;             if (r < I_UP) { transpose_item<2>(p.w_up + (size_t)l * D_ * 2 * FF_, D_, 2 * FF_, 2 * FF_, (bf16_t*)(WL + OF_WUP), p.norm_ffn + l * D_, scr, r, lane); continue; } r -= I_UP;
;             transpose_item<0>(p.w_down + (size_t)l * FF_ * D_, FF_, D_, D_, (bf16_t*)(WL + OF_WDN), nullptr, scr, r, lane);
.LBB0_23:
	s_mul_hi_i32 s0, s89, 0x288df0cb
	s_lshr_b32 s1, s0, 31
	s_ashr_i32 s0, s0, 11
	s_add_i32 s18, s0, s1
	s_mul_i32 s0, s18, 0xffffcd80
	s_add_i32 s24, s89, s0
	s_ashr_i32 s19, s18, 31
	s_mul_hi_i32 s90, s18, 0x6500000
	s_mul_i32 s91, s18, 0x6500000
	s_cmpk_gt_i32 s24, 0x97f
	s_mov_b64 s[0:1], -1
	s_cbranch_scc0 .LBB0_117
	s_cmpk_gt_u32 s24, 0xd7f
	s_cbranch_scc0 .LBB0_114
	s_cmpk_gt_u32 s24, 0xe7f
	s_cbranch_scc0 .LBB0_87
	s_cmpk_gt_u32 s24, 0x107f
	s_cbranch_scc0 .LBB0_60
	s_cmpk_gt_u32 s24, 0x117f
	s_cbranch_scc0 .LBB0_57
	s_add_u32 s25, s7, s91
	s_addc_u32 s92, s9, s90
	s_cmpk_gt_u32 s24, 0x277f
	s_cbranch_scc0 .LBB0_30
	s_mul_i32 s1, s18, 0x2c00000
	s_mul_hi_i32 s0, s18, 0x2c00000
	s_add_u32 s20, s44, s1
	s_addc_u32 s21, s45, s0
	s_mul_i32 s0, s18, 0xffff9b00
	s_add_i32 s0, s30, s0
	s_add_i32 s0, s0, 0x1b100
	s_and_b32 s1, s0, 0x1ffc0
	s_and_b32 s0, s28, 0x7c0
	v_or_b32_e32 v0, s0, v75
	v_or_b32_e32 v4, s1, v76
	v_lshlrev_b32_e32 v0, 2, v0
	v_lshl_add_u64 v[2:3], s[20:21], 0, v[0:1]
	v_lshlrev_b32_e32 v0, 13, v4
	v_lshl_add_u64 v[62:63], v[2:3], 0, v[0:1]
	v_add_co_u32_e32 v6, vcc, s96, v62
	s_mov_b32 s20, 0x70000
	s_nop 0
	v_addc_co_u32_e32 v7, vcc, 0, v63, vcc
	v_add_co_u32_e32 v10, vcc, s97, v62
	global_load_dwordx4 v[2:5], v[62:63], off
	s_nop 0
	global_load_dwordx4 v[6:9], v[6:7], off
	v_addc_co_u32_e32 v11, vcc, 0, v63, vcc
	v_add_co_u32_e32 v14, vcc, s10, v62
	s_lshl_b32 s1, s1, 1
	s_nop 0
	v_addc_co_u32_e32 v15, vcc, 0, v63, vcc
	v_add_co_u32_e32 v18, vcc, s11, v62
	global_load_dwordx4 v[10:13], v[10:11], off
	s_nop 0
	global_load_dwordx4 v[14:17], v[14:15], off
	v_addc_co_u32_e32 v19, vcc, 0, v63, vcc
	v_add_co_u32_e32 v22, vcc, s85, v62
	v_mov_b32_e32 v79, v1
	s_nop 0
	v_addc_co_u32_e32 v23, vcc, 0, v63, vcc
	v_add_co_u32_e32 v26, vcc, s86, v62
	global_load_dwordx4 v[18:21], v[18:19], off
	s_nop 0
	global_load_dwordx4 v[22:25], v[22:23], off
	v_addc_co_u32_e32 v27, vcc, 0, v63, vcc
	v_add_co_u32_e32 v30, vcc, s87, v62
	s_nop 1
	v_addc_co_u32_e32 v31, vcc, 0, v63, vcc
	v_add_co_u32_e32 v34, vcc, s2, v62
	global_load_dwordx4 v[26:29], v[26:27], off
	s_nop 0
	global_load_dwordx4 v[30:33], v[30:31], off
	v_addc_co_u32_e32 v35, vcc, 0, v63, vcc
	v_add_co_u32_e32 v38, vcc, s3, v62
	s_nop 1
	v_addc_co_u32_e32 v39, vcc, 0, v63, vcc
	v_add_co_u32_e32 v42, vcc, s12, v62
	global_load_dwordx4 v[34:37], v[34:35], off
	s_nop 0
	global_load_dwordx4 v[38:41], v[38:39], off
	v_addc_co_u32_e32 v43, vcc, 0, v63, vcc
	v_add_co_u32_e32 v46, vcc, s13, v62
	s_nop 1
	v_addc_co_u32_e32 v47, vcc, 0, v63, vcc
	v_add_co_u32_e32 v50, vcc, s93, v62
	global_load_dwordx4 v[42:45], v[42:43], off
	s_nop 0
	global_load_dwordx4 v[46:49], v[46:47], off
	v_addc_co_u32_e32 v51, vcc, 0, v63, vcc
	v_add_co_u32_e32 v54, vcc, s94, v62
	s_nop 1
	v_addc_co_u32_e32 v55, vcc, 0, v63, vcc
	global_load_dwordx4 v[50:53], v[50:51], off
	s_nop 0
	global_load_dwordx4 v[54:57], v[54:55], off
	v_add_co_u32_e32 v58, vcc, s20, v62
	s_add_u32 s20, s25, s1
	s_nop 0
	v_addc_co_u32_e32 v59, vcc, 0, v63, vcc
	global_load_dwordx4 v[58:61], v[58:59], off
	v_add_co_u32_e32 v62, vcc, s84, v62
	s_addc_u32 s21, s92, 0
	s_nop 0
	v_addc_co_u32_e32 v63, vcc, 0, v63, vcc
	global_load_dwordx4 v[62:65], v[62:63], off
	s_waitcnt vmcnt(0)
	ds_write2_b32 v83, v2, v3 offset1:1
	ds_write2_b32 v83, v4, v5 offset0:2 offset1:3
	s_waitcnt vmcnt(14)
	ds_write2_b32 v99, v6, v7 offset1:1
	ds_write2_b32 v100, v8, v9 offset1:1
	s_waitcnt vmcnt(13)
	ds_write2_b32 v101, v10, v11 offset1:1
	ds_write2_b32 v102, v12, v13 offset1:1
	s_waitcnt vmcnt(12)
	ds_write2_b32 v103, v14, v15 offset1:1
	ds_write2_b32 v104, v16, v17 offset1:1
	s_waitcnt vmcnt(11)
	ds_write2_b32 v105, v18, v19 offset1:1
	ds_write2_b32 v106, v20, v21 offset1:1
	s_waitcnt vmcnt(10)
	ds_write2_b32 v107, v22, v23 offset1:1
	ds_write2_b32 v108, v24, v25 offset1:1
	s_waitcnt vmcnt(9)
	ds_write2_b32 v109, v26, v27 offset1:1
	ds_write2_b32 v110, v28, v29 offset1:1
	s_waitcnt vmcnt(8)
	ds_write2_b32 v111, v30, v31 offset1:1
	ds_write2_b32 v112, v32, v33 offset1:1
	s_waitcnt vmcnt(7)
	ds_write2_b32 v113, v34, v35 offset1:1
	ds_write2_b32 v114, v36, v37 offset1:1
	s_waitcnt vmcnt(6)
	ds_write2_b32 v115, v38, v39 offset1:1
	ds_write2_b32 v116, v40, v41 offset1:1
	s_waitcnt vmcnt(5)
	ds_write2_b32 v117, v42, v43 offset1:1
	ds_write2_b32 v118, v44, v45 offset1:1
	s_waitcnt vmcnt(4)
	ds_write2_b32 v119, v46, v47 offset1:1
	ds_write2_b32 v120, v48, v49 offset1:1
	s_waitcnt vmcnt(3)
	ds_write2_b32 v121, v50, v51 offset1:1
	ds_write2_b32 v122, v52, v53 offset1:1
	s_waitcnt vmcnt(2)
	ds_write2_b32 v123, v54, v55 offset1:1
	ds_write2_b32 v124, v56, v57 offset1:1
	s_waitcnt vmcnt(1)
	ds_write2_b32 v125, v58, v59 offset1:1
	ds_write2_b32 v126, v60, v61 offset1:1
	s_waitcnt vmcnt(0)
	ds_write2_b32 v127, v62, v63 offset1:1
	ds_write2_b32 v128, v64, v65 offset1:1
	s_waitcnt lgkmcnt(0)
; #define LAS __attribute__((address_space(3)))
; __device__ __forceinline__ unsigned cvt_pk_bf16(float lo, float hi) { unsigned r; asm("v_cvt_pk_bf16_f32 %0, %1, %2" : "=v"(r) : "v"(lo), "v"(hi)); return r; }
; template <int MAPK>
; __device__ __forceinline__ void transpose_item(const float* W, int K, int N, int ND, bf16_t* WT, const float* g, LAS float* scr, int item, int lane) {
;     ...
;     asm volatile("s_waitcnt lgkmcnt(0)" ::: "memory");
;     const int c = lane & 7;
; #pragma unroll
;     for (int j = 0; j < 8; ++j) { const int n = (lane >> 3) + 8 * j; const LAS float* sp = scr + (8 * c) * 65 + n;
;         u32x4 o; o.x = cvt_pk_bf16(sp[0], sp[65]); o.y = cvt_pk_bf16(sp[2 * 65], sp[3 * 65]); o.z = cvt_pk_bf16(sp[4 * 65], sp[5 * 65]); o.w = cvt_pk_bf16(sp[6 * 65], sp[7 * 65]);
;         *(u32x4*)(WT + (size_t)(n0 + n) * K + k0 + 8 * c) = o; }
	v_lshl_add_u64 v[2:3], s[20:21], 0, v[78:79]
	ds_read_b32 v0, v85
	ds_read_b32 v4, v85 offset:260
	ds_read_b32 v5, v85 offset:520
	ds_read_b32 v8, v85 offset:780
	ds_read_b32 v9, v85 offset:1040
	ds_read_b32 v10, v85 offset:1300
	ds_read_b32 v11, v85 offset:1560
	ds_read_b32 v12, v85 offset:1820
	s_mov_b64 s[20:21], 0x4f00000
	v_lshl_add_u64 v[6:7], v[2:3], 0, s[20:21]
	s_waitcnt lgkmcnt(6)
	v_cvt_pk_bf16_f32 v2, v0, v4
	v_or_b32_e32 v0, s0, v84
	v_mul_u32_u24_e32 v0, 0x1600, v0
	v_lshlrev_b32_e32 v0, 1, v0
	s_waitcnt lgkmcnt(4)
	v_cvt_pk_bf16_f32 v3, v5, v8
	s_waitcnt lgkmcnt(2)
	v_cvt_pk_bf16_f32 v4, v9, v10
	v_lshl_add_u64 v[8:9], v[6:7], 0, v[0:1]
	s_waitcnt lgkmcnt(0)
	v_cvt_pk_bf16_f32 v5, v11, v12
	global_store_dwordx4 v[8:9], v[2:5], off
	ds_read_b32 v0, v85 offset:32
	ds_read_b32 v2, v85 offset:292
	ds_read_b32 v3, v85 offset:552
	ds_read_b32 v4, v85 offset:812
	ds_read_b32 v5, v85 offset:1072
	ds_read_b32 v8, v85 offset:1332
	ds_read_b32 v9, v85 offset:1592
	ds_read_b32 v10, v85 offset:1852
	s_waitcnt lgkmcnt(0)
	v_cvt_pk_bf16_f32 v2, v0, v2
	v_or_b32_e32 v0, s0, v86
	v_mul_u32_u24_e32 v0, 0x1600, v0
	v_lshlrev_b32_e32 v0, 1, v0
	v_cvt_pk_bf16_f32 v3, v3, v4
	v_cvt_pk_bf16_f32 v4, v5, v8
	v_cvt_pk_bf16_f32 v5, v9, v10
	v_lshl_add_u64 v[8:9], v[6:7], 0, v[0:1]
	global_store_dwordx4 v[8:9], v[2:5], off
	ds_read_b32 v0, v85 offset:64
	ds_read_b32 v2, v85 offset:324
	ds_read_b32 v3, v85 offset:584
	ds_read_b32 v4, v85 offset:844
	ds_read_b32 v5, v85 offset:1104
	ds_read_b32 v8, v85 offset:1364
	ds_read_b32 v9, v85 offset:1624
	ds_read_b32 v10, v85 offset:1884
	s_waitcnt lgkmcnt(0)
	v_cvt_pk_bf16_f32 v2, v0, v2
	v_or_b32_e32 v0, s0, v87
	v_mul_u32_u24_e32 v0, 0x1600, v0
	v_lshlrev_b32_e32 v0, 1, v0
	v_cvt_pk_bf16_f32 v3, v3, v4
	v_cvt_pk_bf16_f32 v4, v5, v8
	v_cvt_pk_bf16_f32 v5, v9, v10
	v_lshl_add_u64 v[8:9], v[6:7], 0, v[0:1]
	global_store_dwordx4 v[8:9], v[2:5], off
	ds_read_b32 v0, v85 offset:96
	ds_read_b32 v2, v85 offset:356
	ds_read_b32 v3, v85 offset:616
	ds_read_b32 v4, v85 offset:876
	ds_read_b32 v5, v85 offset:1136
	ds_read_b32 v8, v85 offset:1396
	ds_read_b32 v9, v85 offset:1656
	ds_read_b32 v10, v85 offset:1916
	s_waitcnt lgkmcnt(0)
	v_cvt_pk_bf16_f32 v2, v0, v2
	v_or_b32_e32 v0, s0, v88
	v_mul_u32_u24_e32 v0, 0x1600, v0
	v_lshlrev_b32_e32 v0, 1, v0
	v_cvt_pk_bf16_f32 v3, v3, v4
	v_cvt_pk_bf16_f32 v4, v5, v8
	v_cvt_pk_bf16_f32 v5, v9, v10
	v_lshl_add_u64 v[8:9], v[6:7], 0, v[0:1]
	global_store_dwordx4 v[8:9], v[2:5], off
	ds_read_b32 v0, v85 offset:128
	ds_read_b32 v2, v85 offset:388
	ds_read_b32 v3, v85 offset:648
	ds_read_b32 v4, v85 offset:908
	ds_read_b32 v5, v85 offset:1168
	ds_read_b32 v8, v85 offset:1428
	ds_read_b32 v9, v85 offset:1688
	ds_read_b32 v10, v85 offset:1948
	s_waitcnt lgkmcnt(0)
	v_cvt_pk_bf16_f32 v2, v0, v2
	v_or_b32_e32 v0, s0, v89
	v_mul_u32_u24_e32 v0, 0x1600, v0
	v_lshlrev_b32_e32 v0, 1, v0
	v_cvt_pk_bf16_f32 v3, v3, v4
	v_cvt_pk_bf16_f32 v4, v5, v8
	v_cvt_pk_bf16_f32 v5, v9, v10
	v_lshl_add_u64 v[8:9], v[6:7], 0, v[0:1]
	global_store_dwordx4 v[8:9], v[2:5], off
	ds_read_b32 v0, v85 offset:160
	ds_read_b32 v2, v85 offset:420
	ds_read_b32 v3, v85 offset:680
	ds_read_b32 v4, v85 offset:940
	ds_read_b32 v5, v85 offset:1200
	ds_read_b32 v8, v85 offset:1460
	ds_read_b32 v9, v85 offset:1720
	ds_read_b32 v10, v85 offset:1980
	s_waitcnt lgkmcnt(0)
	v_cvt_pk_bf16_f32 v2, v0, v2
	v_or_b32_e32 v0, s0, v90
	v_mul_u32_u24_e32 v0, 0x1600, v0
	v_lshlrev_b32_e32 v0, 1, v0
	v_cvt_pk_bf16_f32 v3, v3, v4
	v_cvt_pk_bf16_f32 v4, v5, v8
	v_cvt_pk_bf16_f32 v5, v9, v10
	v_lshl_add_u64 v[8:9], v[6:7], 0, v[0:1]
	global_store_dwordx4 v[8:9], v[2:5], off
	ds_read_b32 v0, v85 offset:192
	ds_read_b32 v2, v85 offset:452
	ds_read_b32 v3, v85 offset:712
	ds_read_b32 v4, v85 offset:972
	ds_read_b32 v5, v85 offset:1232
	ds_read_b32 v8, v85 offset:1492
	ds_read_b32 v9, v85 offset:1752
	ds_read_b32 v10, v85 offset:2012
	s_waitcnt lgkmcnt(0)
	v_cvt_pk_bf16_f32 v2, v0, v2
	v_or_b32_e32 v0, s0, v91
	v_mul_u32_u24_e32 v0, 0x1600, v0
	v_lshlrev_b32_e32 v0, 1, v0
	v_cvt_pk_bf16_f32 v3, v3, v4
	v_cvt_pk_bf16_f32 v4, v5, v8
	v_cvt_pk_bf16_f32 v5, v9, v10
	v_lshl_add_u64 v[8:9], v[6:7], 0, v[0:1]
	global_store_dwordx4 v[8:9], v[2:5], off
	ds_read_b32 v0, v85 offset:224
	ds_read_b32 v2, v85 offset:484
	ds_read_b32 v3, v85 offset:744
	ds_read_b32 v4, v85 offset:1004
	ds_read_b32 v5, v85 offset:1264
	ds_read_b32 v8, v85 offset:1524
	ds_read_b32 v9, v85 offset:1784
	ds_read_b32 v10, v85 offset:2044
	s_waitcnt lgkmcnt(0)
	v_cvt_pk_bf16_f32 v2, v0, v2
	v_or_b32_e32 v0, s0, v92
	v_mul_u32_u24_e32 v0, 0x1600, v0
	v_lshlrev_b32_e32 v0, 1, v0
	v_lshl_add_u64 v[6:7], v[6:7], 0, v[0:1]
	v_cvt_pk_bf16_f32 v3, v3, v4
	v_cvt_pk_bf16_f32 v4, v5, v8
	v_cvt_pk_bf16_f32 v5, v9, v10
	global_store_dwordx4 v[6:7], v[2:5], off
	s_waitcnt lgkmcnt(0)
	s_mov_b64 s[0:1], 0

; #define LAS __attribute__((address_space(3)))
; __device__ __forceinline__ unsigned cvt_pk_bf16(float lo, float hi) { unsigned r; asm("v_cvt_pk_bf16_f32 %0, %1, %2" : "=v"(r) : "v"(lo), "v"(hi)); return r; }
; template <int MAPK>
; __device__ __forceinline__ void transpose_item(const float* W, int K, int N, int ND, bf16_t* WT, const float* g, LAS float* scr, int item, int lane) {
;     ...
;     for (int i = 0; i < 16; ++i) { const int kk = 4 * i + kr; f32x4 v = vv[i];
;         if (g) v = v * g[k0 + kk];
;         scr[kk * 65 + c4] = v[0]; scr[kk * 65 + c4 + 1] = v[1]; scr[kk * 65 + c4 + 2] = v[2]; scr[kk * 65 + c4 + 3] = v[3]; }
;     asm volatile("s_waitcnt lgkmcnt(0)" ::: "memory");
;     const int c = lane & 7;
; #pragma unroll
;     for (int j = 0; j < 8; ++j) { const int n = (lane >> 3) + 8 * j; const LAS float* sp = scr + (8 * c) * 65 + n;
;         u32x4 o; o.x = cvt_pk_bf16(sp[0], sp[65]); o.y = cvt_pk_bf16(sp[2 * 65], sp[3 * 65]); o.z = cvt_pk_bf16(sp[4 * 65], sp[5 * 65]); o.w = cvt_pk_bf16(sp[6 * 65], sp[7 * 65]);
;         *(u32x4*)(WT + (size_t)(n0 + n) * K + k0 + 8 * c) = o; }
.LBB0_55:
	v_add_u32_e32 v0, 0x1040, v34
	ds_write2_b32 v0, v16, v17 offset1:1
	v_add_u32_e32 v0, 0x1048, v34
	ds_write2_b32 v0, v14, v15 offset1:1
	v_add_u32_e32 v0, 0x1450, v34
	ds_write2_b32 v0, v10, v11 offset1:1
	v_add_u32_e32 v0, 0x1458, v34
	s_and_b32 s0, s94, 0xffc0
	ds_write2_b32 v0, v12, v13 offset1:1
	s_lshl_b32 s1, s93, 1
	s_waitcnt lgkmcnt(0)
	s_add_u32 s20, s25, s1
	s_addc_u32 s21, s92, 0
	v_mov_b32_e32 v79, v1
	ds_read_b32 v0, v85
	ds_read_b32 v4, v85 offset:260
	ds_read_b32 v5, v85 offset:520
	ds_read_b32 v8, v85 offset:780
	ds_read_b32 v9, v85 offset:1040
	ds_read_b32 v10, v85 offset:1300
	ds_read_b32 v11, v85 offset:1560
	ds_read_b32 v12, v85 offset:1820
	v_lshl_add_u64 v[2:3], s[20:21], 0, v[78:79]
	s_mov_b64 s[20:21], 0x2300000
	v_lshl_add_u64 v[6:7], v[2:3], 0, s[20:21]
	s_waitcnt lgkmcnt(0)
	v_cvt_pk_bf16_f32 v2, v0, v4
	v_or_b32_e32 v0, s0, v84
	v_lshlrev_b32_e32 v0, 12, v0
	v_cvt_pk_bf16_f32 v3, v5, v8
	v_cvt_pk_bf16_f32 v4, v9, v10
	v_lshl_add_u64 v[8:9], v[6:7], 0, v[0:1]
	v_cvt_pk_bf16_f32 v5, v11, v12
	global_store_dwordx4 v[8:9], v[2:5], off
	ds_read_b32 v0, v85 offset:32
	ds_read_b32 v2, v85 offset:292
	ds_read_b32 v3, v85 offset:552
	ds_read_b32 v4, v85 offset:812
	ds_read_b32 v5, v85 offset:1072
	ds_read_b32 v8, v85 offset:1332
	ds_read_b32 v9, v85 offset:1592
	ds_read_b32 v10, v85 offset:1852
	s_waitcnt lgkmcnt(0)
	v_cvt_pk_bf16_f32 v2, v0, v2
	v_or_b32_e32 v0, s0, v86
	v_lshlrev_b32_e32 v0, 12, v0
	v_cvt_pk_bf16_f32 v3, v3, v4
	v_cvt_pk_bf16_f32 v4, v5, v8
	v_cvt_pk_bf16_f32 v5, v9, v10
	v_lshl_add_u64 v[8:9], v[6:7], 0, v[0:1]
	global_store_dwordx4 v[8:9], v[2:5], off
	ds_read_b32 v0, v85 offset:64
	ds_read_b32 v2, v85 offset:324
	ds_read_b32 v3, v85 offset:584
	ds_read_b32 v4, v85 offset:844
	ds_read_b32 v5, v85 offset:1104
	ds_read_b32 v8, v85 offset:1364
	ds_read_b32 v9, v85 offset:1624
	ds_read_b32 v10, v85 offset:1884
	s_waitcnt lgkmcnt(0)
	v_cvt_pk_bf16_f32 v2, v0, v2
	v_or_b32_e32 v0, s0, v87
	v_lshlrev_b32_e32 v0, 12, v0
	v_cvt_pk_bf16_f32 v3, v3, v4
	v_cvt_pk_bf16_f32 v4, v5, v8
	v_cvt_pk_bf16_f32 v5, v9, v10
	v_lshl_add_u64 v[8:9], v[6:7], 0, v[0:1]
	global_store_dwordx4 v[8:9], v[2:5], off
	ds_read_b32 v0, v85 offset:96
	ds_read_b32 v2, v85 offset:356
	ds_read_b32 v3, v85 offset:616
	ds_read_b32 v4, v85 offset:876
	ds_read_b32 v5, v85 offset:1136
	ds_read_b32 v8, v85 offset:1396
	ds_read_b32 v9, v85 offset:1656
	ds_read_b32 v10, v85 offset:1916
	s_waitcnt lgkmcnt(0)
	v_cvt_pk_bf16_f32 v2, v0, v2
	v_or_b32_e32 v0, s0, v88
	v_lshlrev_b32_e32 v0, 12, v0
	v_cvt_pk_bf16_f32 v3, v3, v4
	v_cvt_pk_bf16_f32 v4, v5, v8
	v_cvt_pk_bf16_f32 v5, v9, v10
	v_lshl_add_u64 v[8:9], v[6:7], 0, v[0:1]
	global_store_dwordx4 v[8:9], v[2:5], off
	ds_read_b32 v0, v85 offset:128
	ds_read_b32 v2, v85 offset:388
	ds_read_b32 v3, v85 offset:648
	ds_read_b32 v4, v85 offset:908
	ds_read_b32 v5, v85 offset:1168
	ds_read_b32 v8, v85 offset:1428
	ds_read_b32 v9, v85 offset:1688
	ds_read_b32 v10, v85 offset:1948
	s_waitcnt lgkmcnt(0)
	v_cvt_pk_bf16_f32 v2, v0, v2
	v_or_b32_e32 v0, s0, v89
	v_lshlrev_b32_e32 v0, 12, v0
	v_cvt_pk_bf16_f32 v3, v3, v4
	v_cvt_pk_bf16_f32 v4, v5, v8
	v_cvt_pk_bf16_f32 v5, v9, v10
	v_lshl_add_u64 v[8:9], v[6:7], 0, v[0:1]
	global_store_dwordx4 v[8:9], v[2:5], off
	ds_read_b32 v0, v85 offset:160
	ds_read_b32 v2, v85 offset:420
	ds_read_b32 v3, v85 offset:680
	ds_read_b32 v4, v85 offset:940
	ds_read_b32 v5, v85 offset:1200
	ds_read_b32 v8, v85 offset:1460
	ds_read_b32 v9, v85 offset:1720
	ds_read_b32 v10, v85 offset:1980
	s_waitcnt lgkmcnt(0)
	v_cvt_pk_bf16_f32 v2, v0, v2
	v_or_b32_e32 v0, s0, v90
	v_lshlrev_b32_e32 v0, 12, v0
	v_cvt_pk_bf16_f32 v3, v3, v4
	v_cvt_pk_bf16_f32 v4, v5, v8
	v_cvt_pk_bf16_f32 v5, v9, v10
	v_lshl_add_u64 v[8:9], v[6:7], 0, v[0:1]
	global_store_dwordx4 v[8:9], v[2:5], off
	ds_read_b32 v0, v85 offset:192
	ds_read_b32 v2, v85 offset:452
	ds_read_b32 v3, v85 offset:712
	ds_read_b32 v4, v85 offset:972
	ds_read_b32 v5, v85 offset:1232
	ds_read_b32 v8, v85 offset:1492
	ds_read_b32 v9, v85 offset:1752
	ds_read_b32 v10, v85 offset:2012
	s_waitcnt lgkmcnt(0)
	v_cvt_pk_bf16_f32 v2, v0, v2
	v_or_b32_e32 v0, s0, v91
	v_lshlrev_b32_e32 v0, 12, v0
	v_cvt_pk_bf16_f32 v3, v3, v4
	v_cvt_pk_bf16_f32 v4, v5, v8
	v_cvt_pk_bf16_f32 v5, v9, v10
	v_lshl_add_u64 v[8:9], v[6:7], 0, v[0:1]
	global_store_dwordx4 v[8:9], v[2:5], off
	ds_read_b32 v0, v85 offset:224
	ds_read_b32 v2, v85 offset:484
	ds_read_b32 v3, v85 offset:744
	ds_read_b32 v4, v85 offset:1004
	ds_read_b32 v5, v85 offset:1264
	ds_read_b32 v8, v85 offset:1524
	ds_read_b32 v9, v85 offset:1784
	ds_read_b32 v10, v85 offset:2044
	s_waitcnt lgkmcnt(0)
	v_cvt_pk_bf16_f32 v2, v0, v2
	v_or_b32_e32 v0, s0, v92
	v_lshlrev_b32_e32 v0, 12, v0
	v_lshl_add_u64 v[6:7], v[6:7], 0, v[0:1]
	v_cvt_pk_bf16_f32 v3, v3, v4
	v_cvt_pk_bf16_f32 v4, v5, v8
	v_cvt_pk_bf16_f32 v5, v9, v10
	global_store_dwordx4 v[6:7], v[2:5], off
	s_waitcnt lgkmcnt(0)
	s_mov_b32 s93, 0x60000
	s_mov_b32 s94, 0x68000

; #define LAS __attribute__((address_space(3)))
; template <int MAPK>
; __device__ __forceinline__ void transpose_item(const float* W, int K, int N, int ND, bf16_t* WT, const float* g, LAS float* scr, int item, int lane) {
;     const int nblk = ND / 64, kb = item / nblk, nb = item % nblk, k0 = 64 * kb, n0 = 64 * nb;
;     const int c4 = (lane & 15) * 4, kr = lane >> 4;
;     int src = n0 + c4; if (MAPK == 1) src = inmap(src); if (MAPK == 2) src = upmap(src);
;     f32x4 vv[16];
; #pragma unroll
;     for (int i = 0; i < 16; ++i) { const int kk = 4 * i + kr;
;         vv[i] = (f32x4){0.f, 0.f, 0.f, 0.f};
;         if (src >= 0) vv[i] = *(const f32x4*)(W + (size_t)(k0 + kk) * N + src); }
; #pragma unroll
;     for (int i = 0; i < 16; ++i) { const int kk = 4 * i + kr; f32x4 v = vv[i];
;         if (g) v = v * g[k0 + kk];
;         scr[kk * 65 + c4] = v[0]; scr[kk * 65 + c4 + 1] = v[1]; scr[kk * 65 + c4 + 2] = v[2]; scr[kk * 65 + c4 + 3] = v[3]; }
.LBB0_57:
	s_andn2_b64 vcc, exec, s[0:1]
	s_cbranch_vccnz .LBB0_59
	v_readlane_b32 s68, v255, 4
	s_lshl_b64 s[0:1], s[18:19], 22
	v_readlane_b32 s82, v255, 18
	v_readlane_b32 s83, v255, 19
	s_add_u32 s20, s82, s0
	s_addc_u32 s21, s83, s1
	s_add_u32 s1, s7, s91
	s_addc_u32 s22, s9, s90
	s_lshl_b32 s0, s18, 8
	s_sub_i32 s0, s30, s0
	s_and_b32 s23, s0, 0x1c0
	s_and_b32 s0, s28, 0x7c0
	v_or_b32_e32 v0, s0, v75
	v_bitop3_b32 v4, s23, v76, v129 bitop3:0xde
	v_lshlrev_b32_e32 v0, 2, v0
	v_lshl_add_u64 v[2:3], s[20:21], 0, v[0:1]
	v_lshlrev_b32_e32 v0, 13, v4
	v_lshl_add_u64 v[62:63], v[2:3], 0, v[0:1]
	v_add_co_u32_e32 v6, vcc, s96, v62
	s_mov_b32 s20, 0x70000
	s_nop 0
	v_addc_co_u32_e32 v7, vcc, 0, v63, vcc
	v_add_co_u32_e32 v10, vcc, s97, v62
	global_load_dwordx4 v[2:5], v[62:63], off
	s_nop 0
	global_load_dwordx4 v[6:9], v[6:7], off
	v_addc_co_u32_e32 v11, vcc, 0, v63, vcc
	v_add_co_u32_e32 v14, vcc, s10, v62
	v_mov_b32_e32 v79, v1
	s_nop 0
	v_addc_co_u32_e32 v15, vcc, 0, v63, vcc
	v_add_co_u32_e32 v18, vcc, s11, v62
	global_load_dwordx4 v[10:13], v[10:11], off
	s_nop 0
	global_load_dwordx4 v[14:17], v[14:15], off
	v_addc_co_u32_e32 v19, vcc, 0, v63, vcc
	v_add_co_u32_e32 v22, vcc, s85, v62
	v_readlane_b32 s69, v255, 5
	s_nop 0
	v_addc_co_u32_e32 v23, vcc, 0, v63, vcc
	v_add_co_u32_e32 v26, vcc, s86, v62
	global_load_dwordx4 v[18:21], v[18:19], off
	s_nop 0
	global_load_dwordx4 v[22:25], v[22:23], off
	v_addc_co_u32_e32 v27, vcc, 0, v63, vcc
	v_add_co_u32_e32 v30, vcc, s87, v62
	v_readlane_b32 s70, v255, 6
	s_nop 0
	v_addc_co_u32_e32 v31, vcc, 0, v63, vcc
	v_add_co_u32_e32 v34, vcc, s2, v62
	global_load_dwordx4 v[26:29], v[26:27], off
	s_nop 0
	global_load_dwordx4 v[30:33], v[30:31], off
	v_addc_co_u32_e32 v35, vcc, 0, v63, vcc
	v_add_co_u32_e32 v38, vcc, s3, v62
	v_readlane_b32 s71, v255, 7
	s_nop 0
	v_addc_co_u32_e32 v39, vcc, 0, v63, vcc
	v_add_co_u32_e32 v42, vcc, s12, v62
	global_load_dwordx4 v[34:37], v[34:35], off
	s_nop 0
	global_load_dwordx4 v[38:41], v[38:39], off
	v_addc_co_u32_e32 v43, vcc, 0, v63, vcc
	v_add_co_u32_e32 v46, vcc, s13, v62
	v_readlane_b32 s72, v255, 8
	s_nop 0
	v_addc_co_u32_e32 v47, vcc, 0, v63, vcc
	v_add_co_u32_e32 v50, vcc, s93, v62
	global_load_dwordx4 v[42:45], v[42:43], off
	s_nop 0
	global_load_dwordx4 v[46:49], v[46:47], off
	v_addc_co_u32_e32 v51, vcc, 0, v63, vcc
	v_add_co_u32_e32 v54, vcc, s94, v62
	v_readlane_b32 s73, v255, 9
	s_nop 0
	v_addc_co_u32_e32 v55, vcc, 0, v63, vcc
	global_load_dwordx4 v[50:53], v[50:51], off
	s_nop 0
	global_load_dwordx4 v[54:57], v[54:55], off
	v_add_co_u32_e32 v58, vcc, s20, v62
	s_xor_b32 s20, s23, 0x100
	s_nop 0
	v_addc_co_u32_e32 v59, vcc, 0, v63, vcc
	global_load_dwordx4 v[58:61], v[58:59], off
	v_add_co_u32_e32 v62, vcc, s84, v62
	s_lshl_b32 s20, s20, 1
	s_nop 0
	v_addc_co_u32_e32 v63, vcc, 0, v63, vcc
	global_load_dwordx4 v[62:65], v[62:63], off
	s_add_u32 s20, s1, s20
	s_addc_u32 s21, s22, 0
	v_readlane_b32 s74, v255, 10
	v_readlane_b32 s75, v255, 11
	v_readlane_b32 s76, v255, 12
	v_readlane_b32 s77, v255, 13
	v_readlane_b32 s78, v255, 14
	v_readlane_b32 s79, v255, 15
	v_readlane_b32 s80, v255, 16
	v_readlane_b32 s81, v255, 17
	s_waitcnt vmcnt(0)
	ds_write2_b32 v83, v2, v3 offset1:1
	ds_write2_b32 v83, v4, v5 offset0:2 offset1:3
	ds_write2_b32 v99, v6, v7 offset1:1
	ds_write2_b32 v100, v8, v9 offset1:1
	ds_write2_b32 v101, v10, v11 offset1:1
	ds_write2_b32 v102, v12, v13 offset1:1
	ds_write2_b32 v103, v14, v15 offset1:1
	ds_write2_b32 v104, v16, v17 offset1:1
	ds_write2_b32 v105, v18, v19 offset1:1
	ds_write2_b32 v106, v20, v21 offset1:1
	ds_write2_b32 v107, v22, v23 offset1:1
	ds_write2_b32 v108, v24, v25 offset1:1
	ds_write2_b32 v109, v26, v27 offset1:1
	ds_write2_b32 v110, v28, v29 offset1:1
	ds_write2_b32 v111, v30, v31 offset1:1
	ds_write2_b32 v112, v32, v33 offset1:1
	ds_write2_b32 v113, v34, v35 offset1:1
	ds_write2_b32 v114, v36, v37 offset1:1
	ds_write2_b32 v115, v38, v39 offset1:1
	ds_write2_b32 v116, v40, v41 offset1:1
	ds_write2_b32 v117, v42, v43 offset1:1
	ds_write2_b32 v118, v44, v45 offset1:1
	ds_write2_b32 v119, v46, v47 offset1:1
	ds_write2_b32 v120, v48, v49 offset1:1
	ds_write2_b32 v121, v50, v51 offset1:1
	ds_write2_b32 v122, v52, v53 offset1:1
	ds_write2_b32 v123, v54, v55 offset1:1
	ds_write2_b32 v124, v56, v57 offset1:1
	ds_write2_b32 v125, v58, v59 offset1:1
	ds_write2_b32 v126, v60, v61 offset1:1
	ds_write2_b32 v127, v62, v63 offset1:1
	ds_write2_b32 v128, v64, v65 offset1:1
	s_waitcnt lgkmcnt(0)
; #define LAS __attribute__((address_space(3)))
; __device__ __forceinline__ unsigned cvt_pk_bf16(float lo, float hi) { unsigned r; asm("v_cvt_pk_bf16_f32 %0, %1, %2" : "=v"(r) : "v"(lo), "v"(hi)); return r; }
; template <int MAPK>
; __device__ __forceinline__ void transpose_item(const float* W, int K, int N, int ND, bf16_t* WT, const float* g, LAS float* scr, int item, int lane) {
;     ...
;     asm volatile("s_waitcnt lgkmcnt(0)" ::: "memory");
;     const int c = lane & 7;
; #pragma unroll
;     for (int j = 0; j < 8; ++j) { const int n = (lane >> 3) + 8 * j; const LAS float* sp = scr + (8 * c) * 65 + n;
;         u32x4 o; o.x = cvt_pk_bf16(sp[0], sp[65]); o.y = cvt_pk_bf16(sp[2 * 65], sp[3 * 65]); o.z = cvt_pk_bf16(sp[4 * 65], sp[5 * 65]); o.w = cvt_pk_bf16(sp[6 * 65], sp[7 * 65]);
;         *(u32x4*)(WT + (size_t)(n0 + n) * K + k0 + 8 * c) = o; }
	ds_read_b32 v0, v85
	ds_read_b32 v4, v85 offset:260
	ds_read_b32 v5, v85 offset:520
	ds_read_b32 v8, v85 offset:780
	ds_read_b32 v9, v85 offset:1040
	ds_read_b32 v10, v85 offset:1300
	ds_read_b32 v11, v85 offset:1560
	ds_read_b32 v12, v85 offset:1820
	v_lshl_add_u64 v[2:3], s[20:21], 0, v[78:79]
	s_mov_b64 s[20:21], 0x2100000
	v_lshl_add_u64 v[6:7], v[2:3], 0, s[20:21]
	s_waitcnt lgkmcnt(0)
	v_cvt_pk_bf16_f32 v2, v0, v4
	v_or_b32_e32 v0, s0, v84
	v_lshlrev_b32_e32 v0, 10, v0
	v_cvt_pk_bf16_f32 v3, v5, v8
	v_cvt_pk_bf16_f32 v4, v9, v10
	v_lshl_add_u64 v[8:9], v[6:7], 0, v[0:1]
	v_cvt_pk_bf16_f32 v5, v11, v12
	global_store_dwordx4 v[8:9], v[2:5], off
	ds_read_b32 v0, v85 offset:32
	ds_read_b32 v2, v85 offset:292
	ds_read_b32 v3, v85 offset:552
	ds_read_b32 v4, v85 offset:812
	ds_read_b32 v5, v85 offset:1072
	ds_read_b32 v8, v85 offset:1332
	ds_read_b32 v9, v85 offset:1592
	ds_read_b32 v10, v85 offset:1852
	s_waitcnt lgkmcnt(0)
	v_cvt_pk_bf16_f32 v2, v0, v2
	v_or_b32_e32 v0, s0, v86
	v_lshlrev_b32_e32 v0, 10, v0
	v_cvt_pk_bf16_f32 v3, v3, v4
	v_cvt_pk_bf16_f32 v4, v5, v8
	v_cvt_pk_bf16_f32 v5, v9, v10
	v_lshl_add_u64 v[8:9], v[6:7], 0, v[0:1]
	global_store_dwordx4 v[8:9], v[2:5], off
	ds_read_b32 v0, v85 offset:64
	ds_read_b32 v2, v85 offset:324
	ds_read_b32 v3, v85 offset:584
	ds_read_b32 v4, v85 offset:844
	ds_read_b32 v5, v85 offset:1104
	ds_read_b32 v8, v85 offset:1364
	ds_read_b32 v9, v85 offset:1624
	ds_read_b32 v10, v85 offset:1884
	s_waitcnt lgkmcnt(0)
	v_cvt_pk_bf16_f32 v2, v0, v2
	v_or_b32_e32 v0, s0, v87
	v_lshlrev_b32_e32 v0, 10, v0
	v_cvt_pk_bf16_f32 v3, v3, v4
	v_cvt_pk_bf16_f32 v4, v5, v8
	v_cvt_pk_bf16_f32 v5, v9, v10
	v_lshl_add_u64 v[8:9], v[6:7], 0, v[0:1]
	global_store_dwordx4 v[8:9], v[2:5], off
	ds_read_b32 v0, v85 offset:96
	ds_read_b32 v2, v85 offset:356
	ds_read_b32 v3, v85 offset:616
	ds_read_b32 v4, v85 offset:876
	ds_read_b32 v5, v85 offset:1136
	ds_read_b32 v8, v85 offset:1396
	ds_read_b32 v9, v85 offset:1656
	ds_read_b32 v10, v85 offset:1916
	s_waitcnt lgkmcnt(0)
	v_cvt_pk_bf16_f32 v2, v0, v2
	v_or_b32_e32 v0, s0, v88
	v_lshlrev_b32_e32 v0, 10, v0
	v_cvt_pk_bf16_f32 v3, v3, v4
	v_cvt_pk_bf16_f32 v4, v5, v8
	v_cvt_pk_bf16_f32 v5, v9, v10
	v_lshl_add_u64 v[8:9], v[6:7], 0, v[0:1]
	global_store_dwordx4 v[8:9], v[2:5], off
	ds_read_b32 v0, v85 offset:128
	ds_read_b32 v2, v85 offset:388
	ds_read_b32 v3, v85 offset:648
	ds_read_b32 v4, v85 offset:908
	ds_read_b32 v5, v85 offset:1168
	ds_read_b32 v8, v85 offset:1428
	ds_read_b32 v9, v85 offset:1688
	ds_read_b32 v10, v85 offset:1948
	s_waitcnt lgkmcnt(0)
	v_cvt_pk_bf16_f32 v2, v0, v2
	v_or_b32_e32 v0, s0, v89
	v_lshlrev_b32_e32 v0, 10, v0
	v_cvt_pk_bf16_f32 v3, v3, v4
	v_cvt_pk_bf16_f32 v4, v5, v8
	v_cvt_pk_bf16_f32 v5, v9, v10
	v_lshl_add_u64 v[8:9], v[6:7], 0, v[0:1]
	global_store_dwordx4 v[8:9], v[2:5], off
	ds_read_b32 v0, v85 offset:160
	ds_read_b32 v2, v85 offset:420
	ds_read_b32 v3, v85 offset:680
	ds_read_b32 v4, v85 offset:940
	ds_read_b32 v5, v85 offset:1200
	ds_read_b32 v8, v85 offset:1460
	ds_read_b32 v9, v85 offset:1720
	ds_read_b32 v10, v85 offset:1980
	s_waitcnt lgkmcnt(0)
	v_cvt_pk_bf16_f32 v2, v0, v2
	v_or_b32_e32 v0, s0, v90
	v_lshlrev_b32_e32 v0, 10, v0
	v_cvt_pk_bf16_f32 v3, v3, v4
	v_cvt_pk_bf16_f32 v4, v5, v8
	v_cvt_pk_bf16_f32 v5, v9, v10
	v_lshl_add_u64 v[8:9], v[6:7], 0, v[0:1]
	global_store_dwordx4 v[8:9], v[2:5], off
	ds_read_b32 v0, v85 offset:192
	ds_read_b32 v2, v85 offset:452
	ds_read_b32 v3, v85 offset:712
	ds_read_b32 v4, v85 offset:972
	ds_read_b32 v5, v85 offset:1232
	ds_read_b32 v8, v85 offset:1492
	ds_read_b32 v9, v85 offset:1752
	ds_read_b32 v10, v85 offset:2012
	s_waitcnt lgkmcnt(0)
	v_cvt_pk_bf16_f32 v2, v0, v2
	v_or_b32_e32 v0, s0, v91
	v_lshlrev_b32_e32 v0, 10, v0
	v_cvt_pk_bf16_f32 v3, v3, v4
	v_cvt_pk_bf16_f32 v4, v5, v8
	v_cvt_pk_bf16_f32 v5, v9, v10
	v_lshl_add_u64 v[8:9], v[6:7], 0, v[0:1]
	global_store_dwordx4 v[8:9], v[2:5], off
	ds_read_b32 v0, v85 offset:224
	ds_read_b32 v2, v85 offset:484
	ds_read_b32 v3, v85 offset:744
	ds_read_b32 v4, v85 offset:1004
	ds_read_b32 v5, v85 offset:1264
	ds_read_b32 v8, v85 offset:1524
	ds_read_b32 v9, v85 offset:1784
	ds_read_b32 v10, v85 offset:2044
	s_waitcnt lgkmcnt(0)
	v_cvt_pk_bf16_f32 v2, v0, v2
	v_or_b32_e32 v0, s0, v92
	v_lshlrev_b32_e32 v0, 10, v0
	v_lshl_add_u64 v[6:7], v[6:7], 0, v[0:1]
	v_cvt_pk_bf16_f32 v3, v3, v4
	v_cvt_pk_bf16_f32 v4, v5, v8
	v_cvt_pk_bf16_f32 v5, v9, v10
	global_store_dwordx4 v[6:7], v[2:5], off
	s_waitcnt lgkmcnt(0)

; #define LAS __attribute__((address_space(3)))
; __device__ __forceinline__ unsigned cvt_pk_bf16(float lo, float hi) { unsigned r; asm("v_cvt_pk_bf16_f32 %0, %1, %2" : "=v"(r) : "v"(lo), "v"(hi)); return r; }
; template <int MAPK>
; __device__ __forceinline__ void transpose_item(const float* W, int K, int N, int ND, bf16_t* WT, const float* g, LAS float* scr, int item, int lane) {
;     ...
;     for (int i = 0; i < 16; ++i) { const int kk = 4 * i + kr; f32x4 v = vv[i];
;         if (g) v = v * g[k0 + kk];
;         scr[kk * 65 + c4] = v[0]; scr[kk * 65 + c4 + 1] = v[1]; scr[kk * 65 + c4 + 2] = v[2]; scr[kk * 65 + c4 + 3] = v[3]; }
;     asm volatile("s_waitcnt lgkmcnt(0)" ::: "memory");
;     const int c = lane & 7;
; #pragma unroll
;     for (int j = 0; j < 8; ++j) { const int n = (lane >> 3) + 8 * j; const LAS float* sp = scr + (8 * c) * 65 + n;
;         u32x4 o; o.x = cvt_pk_bf16(sp[0], sp[65]); o.y = cvt_pk_bf16(sp[2 * 65], sp[3 * 65]); o.z = cvt_pk_bf16(sp[4 * 65], sp[5 * 65]); o.w = cvt_pk_bf16(sp[6 * 65], sp[7 * 65]);
;         *(u32x4*)(WT + (size_t)(n0 + n) * K + k0 + 8 * c) = o; }
.LBB0_85:
	v_add_u32_e32 v0, 0x1040, v34
	ds_write2_b32 v0, v16, v17 offset1:1
	v_add_u32_e32 v0, 0x1048, v34
	ds_write2_b32 v0, v14, v15 offset1:1
	v_add_u32_e32 v0, 0x1450, v34
	s_add_u32 s0, s7, s91
	ds_write2_b32 v0, v10, v11 offset1:1
	v_add_u32_e32 v0, 0x1458, v34
	s_addc_u32 s1, s9, s90
	ds_write2_b32 v0, v12, v13 offset1:1
	s_lshl_b32 s20, s92, 1
	s_waitcnt lgkmcnt(0)
	s_add_u32 s0, s0, s20
	s_addc_u32 s1, s1, 0
	v_mov_b32_e32 v79, v1
	ds_read_b32 v0, v85
	ds_read_b32 v4, v85 offset:260
	ds_read_b32 v5, v85 offset:520
	ds_read_b32 v8, v85 offset:780
	ds_read_b32 v9, v85 offset:1040
	ds_read_b32 v10, v85 offset:1300
	ds_read_b32 v11, v85 offset:1560
	ds_read_b32 v12, v85 offset:1820
	v_lshl_add_u64 v[2:3], s[0:1], 0, v[78:79]
	s_mov_b64 s[0:1], 0x1d00000
	v_lshl_add_u64 v[6:7], v[2:3], 0, s[0:1]
	s_waitcnt lgkmcnt(0)
	v_cvt_pk_bf16_f32 v2, v0, v4
	v_or_b32_e32 v0, s25, v84
	v_lshlrev_b32_e32 v0, 12, v0
	v_cvt_pk_bf16_f32 v3, v5, v8
	v_cvt_pk_bf16_f32 v4, v9, v10
	v_lshl_add_u64 v[8:9], v[6:7], 0, v[0:1]
	v_cvt_pk_bf16_f32 v5, v11, v12
	global_store_dwordx4 v[8:9], v[2:5], off
	ds_read_b32 v0, v85 offset:32
	ds_read_b32 v2, v85 offset:292
	ds_read_b32 v3, v85 offset:552
	ds_read_b32 v4, v85 offset:812
	ds_read_b32 v5, v85 offset:1072
	ds_read_b32 v8, v85 offset:1332
	ds_read_b32 v9, v85 offset:1592
	ds_read_b32 v10, v85 offset:1852
	s_waitcnt lgkmcnt(0)
	v_cvt_pk_bf16_f32 v2, v0, v2
	v_or_b32_e32 v0, s25, v86
	v_lshlrev_b32_e32 v0, 12, v0
	v_cvt_pk_bf16_f32 v3, v3, v4
	v_cvt_pk_bf16_f32 v4, v5, v8
	v_cvt_pk_bf16_f32 v5, v9, v10
	v_lshl_add_u64 v[8:9], v[6:7], 0, v[0:1]
	global_store_dwordx4 v[8:9], v[2:5], off
	ds_read_b32 v0, v85 offset:64
	ds_read_b32 v2, v85 offset:324
	ds_read_b32 v3, v85 offset:584
	ds_read_b32 v4, v85 offset:844
	ds_read_b32 v5, v85 offset:1104
	ds_read_b32 v8, v85 offset:1364
	ds_read_b32 v9, v85 offset:1624
	ds_read_b32 v10, v85 offset:1884
	s_waitcnt lgkmcnt(0)
	v_cvt_pk_bf16_f32 v2, v0, v2
	v_or_b32_e32 v0, s25, v87
	v_lshlrev_b32_e32 v0, 12, v0
	v_cvt_pk_bf16_f32 v3, v3, v4
	v_cvt_pk_bf16_f32 v4, v5, v8
	v_cvt_pk_bf16_f32 v5, v9, v10
	v_lshl_add_u64 v[8:9], v[6:7], 0, v[0:1]
	global_store_dwordx4 v[8:9], v[2:5], off
	ds_read_b32 v0, v85 offset:96
	ds_read_b32 v2, v85 offset:356
	ds_read_b32 v3, v85 offset:616
	ds_read_b32 v4, v85 offset:876
	ds_read_b32 v5, v85 offset:1136
	ds_read_b32 v8, v85 offset:1396
	ds_read_b32 v9, v85 offset:1656
	ds_read_b32 v10, v85 offset:1916
	s_waitcnt lgkmcnt(0)
	v_cvt_pk_bf16_f32 v2, v0, v2
	v_or_b32_e32 v0, s25, v88
	v_lshlrev_b32_e32 v0, 12, v0
	v_cvt_pk_bf16_f32 v3, v3, v4
	v_cvt_pk_bf16_f32 v4, v5, v8
	v_cvt_pk_bf16_f32 v5, v9, v10
	v_lshl_add_u64 v[8:9], v[6:7], 0, v[0:1]
	global_store_dwordx4 v[8:9], v[2:5], off
	ds_read_b32 v0, v85 offset:128
	ds_read_b32 v2, v85 offset:388
	ds_read_b32 v3, v85 offset:648
	ds_read_b32 v4, v85 offset:908
	ds_read_b32 v5, v85 offset:1168
	ds_read_b32 v8, v85 offset:1428
	ds_read_b32 v9, v85 offset:1688
	ds_read_b32 v10, v85 offset:1948
	s_waitcnt lgkmcnt(0)
	v_cvt_pk_bf16_f32 v2, v0, v2
	v_or_b32_e32 v0, s25, v89
	v_lshlrev_b32_e32 v0, 12, v0
	v_cvt_pk_bf16_f32 v3, v3, v4
	v_cvt_pk_bf16_f32 v4, v5, v8
	v_cvt_pk_bf16_f32 v5, v9, v10
	v_lshl_add_u64 v[8:9], v[6:7], 0, v[0:1]
	global_store_dwordx4 v[8:9], v[2:5], off
	ds_read_b32 v0, v85 offset:160
	ds_read_b32 v2, v85 offset:420
	ds_read_b32 v3, v85 offset:680
	ds_read_b32 v4, v85 offset:940
	ds_read_b32 v5, v85 offset:1200
	ds_read_b32 v8, v85 offset:1460
	ds_read_b32 v9, v85 offset:1720
	ds_read_b32 v10, v85 offset:1980
	s_waitcnt lgkmcnt(0)
	v_cvt_pk_bf16_f32 v2, v0, v2
	v_or_b32_e32 v0, s25, v90
	v_lshlrev_b32_e32 v0, 12, v0
	v_cvt_pk_bf16_f32 v3, v3, v4
	v_cvt_pk_bf16_f32 v4, v5, v8
	v_cvt_pk_bf16_f32 v5, v9, v10
	v_lshl_add_u64 v[8:9], v[6:7], 0, v[0:1]
	global_store_dwordx4 v[8:9], v[2:5], off
	ds_read_b32 v0, v85 offset:192
	ds_read_b32 v2, v85 offset:452
	ds_read_b32 v3, v85 offset:712
	ds_read_b32 v4, v85 offset:972
	ds_read_b32 v5, v85 offset:1232
	ds_read_b32 v8, v85 offset:1492
	ds_read_b32 v9, v85 offset:1752
	ds_read_b32 v10, v85 offset:2012
	s_waitcnt lgkmcnt(0)
	v_cvt_pk_bf16_f32 v2, v0, v2
	v_or_b32_e32 v0, s25, v91
	v_lshlrev_b32_e32 v0, 12, v0
	v_cvt_pk_bf16_f32 v3, v3, v4
	v_cvt_pk_bf16_f32 v4, v5, v8
	v_cvt_pk_bf16_f32 v5, v9, v10
	v_lshl_add_u64 v[8:9], v[6:7], 0, v[0:1]
	global_store_dwordx4 v[8:9], v[2:5], off
	ds_read_b32 v0, v85 offset:224
	ds_read_b32 v2, v85 offset:484
	ds_read_b32 v3, v85 offset:744
	ds_read_b32 v4, v85 offset:1004
	ds_read_b32 v5, v85 offset:1264
	ds_read_b32 v8, v85 offset:1524
	ds_read_b32 v9, v85 offset:1784
	ds_read_b32 v10, v85 offset:2044
	s_waitcnt lgkmcnt(0)
	v_cvt_pk_bf16_f32 v2, v0, v2
	v_or_b32_e32 v0, s25, v92
	v_lshlrev_b32_e32 v0, 12, v0
	v_lshl_add_u64 v[6:7], v[6:7], 0, v[0:1]
	v_cvt_pk_bf16_f32 v3, v3, v4
	v_cvt_pk_bf16_f32 v4, v5, v8
	v_cvt_pk_bf16_f32 v5, v9, v10
	global_store_dwordx4 v[6:7], v[2:5], off
	s_waitcnt lgkmcnt(0)

; #define LAS __attribute__((address_space(3)))
; __device__ __forceinline__ unsigned cvt_pk_bf16(float lo, float hi) { unsigned r; asm("v_cvt_pk_bf16_f32 %0, %1, %2" : "=v"(r) : "v"(lo), "v"(hi)); return r; }
; template <int MAPK>
; __device__ __forceinline__ void transpose_item(const float* W, int K, int N, int ND, bf16_t* WT, const float* g, LAS float* scr, int item, int lane) {
;     ...
;     for (int i = 0; i < 16; ++i) { const int kk = 4 * i + kr; f32x4 v = vv[i];
;         if (g) v = v * g[k0 + kk];
;         scr[kk * 65 + c4] = v[0]; scr[kk * 65 + c4 + 1] = v[1]; scr[kk * 65 + c4 + 2] = v[2]; scr[kk * 65 + c4 + 3] = v[3]; }
;     asm volatile("s_waitcnt lgkmcnt(0)" ::: "memory");
;     const int c = lane & 7;
; #pragma unroll
;     for (int j = 0; j < 8; ++j) { const int n = (lane >> 3) + 8 * j; const LAS float* sp = scr + (8 * c) * 65 + n;
;         u32x4 o; o.x = cvt_pk_bf16(sp[0], sp[65]); o.y = cvt_pk_bf16(sp[2 * 65], sp[3 * 65]); o.z = cvt_pk_bf16(sp[4 * 65], sp[5 * 65]); o.w = cvt_pk_bf16(sp[6 * 65], sp[7 * 65]);
;         *(u32x4*)(WT + (size_t)(n0 + n) * K + k0 + 8 * c) = o; }
.LBB0_112:
	v_add_u32_e32 v0, 0x1040, v34
	ds_write2_b32 v0, v16, v17 offset1:1
	v_add_u32_e32 v0, 0x1048, v34
	ds_write2_b32 v0, v14, v15 offset1:1
	v_add_u32_e32 v0, 0x1450, v34
	s_add_u32 s0, s7, s91
	ds_write2_b32 v0, v10, v11 offset1:1
	v_add_u32_e32 v0, 0x1458, v34
	s_addc_u32 s1, s9, s90
	ds_write2_b32 v0, v12, v13 offset1:1
	s_lshl_b32 s20, s92, 1
	s_waitcnt lgkmcnt(0)
	s_add_u32 s0, s0, s20
	s_addc_u32 s1, s1, 0
	v_mov_b32_e32 v79, v1
	ds_read_b32 v0, v85
	ds_read_b32 v4, v85 offset:260
	ds_read_b32 v5, v85 offset:520
	ds_read_b32 v8, v85 offset:780
	ds_read_b32 v9, v85 offset:1040
	ds_read_b32 v10, v85 offset:1300
	ds_read_b32 v11, v85 offset:1560
	ds_read_b32 v12, v85 offset:1820
	v_lshl_add_u64 v[2:3], s[0:1], 0, v[78:79]
	s_mov_b64 s[0:1], 0x1b00000
	v_lshl_add_u64 v[6:7], v[2:3], 0, s[0:1]
	s_waitcnt lgkmcnt(0)
	v_cvt_pk_bf16_f32 v2, v0, v4
	v_or_b32_e32 v0, s25, v84
	v_lshlrev_b32_e32 v0, 12, v0
	v_cvt_pk_bf16_f32 v3, v5, v8
	v_cvt_pk_bf16_f32 v4, v9, v10
	v_lshl_add_u64 v[8:9], v[6:7], 0, v[0:1]
	v_cvt_pk_bf16_f32 v5, v11, v12
	global_store_dwordx4 v[8:9], v[2:5], off
	ds_read_b32 v0, v85 offset:32
	ds_read_b32 v2, v85 offset:292
	ds_read_b32 v3, v85 offset:552
	ds_read_b32 v4, v85 offset:812
	ds_read_b32 v5, v85 offset:1072
	ds_read_b32 v8, v85 offset:1332
	ds_read_b32 v9, v85 offset:1592
	ds_read_b32 v10, v85 offset:1852
	s_waitcnt lgkmcnt(0)
	v_cvt_pk_bf16_f32 v2, v0, v2
	v_or_b32_e32 v0, s25, v86
	v_lshlrev_b32_e32 v0, 12, v0
	v_cvt_pk_bf16_f32 v3, v3, v4
	v_cvt_pk_bf16_f32 v4, v5, v8
	v_cvt_pk_bf16_f32 v5, v9, v10
	v_lshl_add_u64 v[8:9], v[6:7], 0, v[0:1]
	global_store_dwordx4 v[8:9], v[2:5], off
	ds_read_b32 v0, v85 offset:64
	ds_read_b32 v2, v85 offset:324
	ds_read_b32 v3, v85 offset:584
	ds_read_b32 v4, v85 offset:844
	ds_read_b32 v5, v85 offset:1104
	ds_read_b32 v8, v85 offset:1364
	ds_read_b32 v9, v85 offset:1624
	ds_read_b32 v10, v85 offset:1884
	s_waitcnt lgkmcnt(0)
	v_cvt_pk_bf16_f32 v2, v0, v2
	v_or_b32_e32 v0, s25, v87
	v_lshlrev_b32_e32 v0, 12, v0
	v_cvt_pk_bf16_f32 v3, v3, v4
	v_cvt_pk_bf16_f32 v4, v5, v8
	v_cvt_pk_bf16_f32 v5, v9, v10
	v_lshl_add_u64 v[8:9], v[6:7], 0, v[0:1]
	global_store_dwordx4 v[8:9], v[2:5], off
	ds_read_b32 v0, v85 offset:96
	ds_read_b32 v2, v85 offset:356
	ds_read_b32 v3, v85 offset:616
	ds_read_b32 v4, v85 offset:876
	ds_read_b32 v5, v85 offset:1136
	ds_read_b32 v8, v85 offset:1396
	ds_read_b32 v9, v85 offset:1656
	ds_read_b32 v10, v85 offset:1916
	s_waitcnt lgkmcnt(0)
	v_cvt_pk_bf16_f32 v2, v0, v2
	v_or_b32_e32 v0, s25, v88
	v_lshlrev_b32_e32 v0, 12, v0
	v_cvt_pk_bf16_f32 v3, v3, v4
	v_cvt_pk_bf16_f32 v4, v5, v8
	v_cvt_pk_bf16_f32 v5, v9, v10
	v_lshl_add_u64 v[8:9], v[6:7], 0, v[0:1]
	global_store_dwordx4 v[8:9], v[2:5], off
	ds_read_b32 v0, v85 offset:128
	ds_read_b32 v2, v85 offset:388
	ds_read_b32 v3, v85 offset:648
	ds_read_b32 v4, v85 offset:908
	ds_read_b32 v5, v85 offset:1168
	ds_read_b32 v8, v85 offset:1428
	ds_read_b32 v9, v85 offset:1688
	ds_read_b32 v10, v85 offset:1948
	s_waitcnt lgkmcnt(0)
	v_cvt_pk_bf16_f32 v2, v0, v2
	v_or_b32_e32 v0, s25, v89
	v_lshlrev_b32_e32 v0, 12, v0
	v_cvt_pk_bf16_f32 v3, v3, v4
	v_cvt_pk_bf16_f32 v4, v5, v8
	v_cvt_pk_bf16_f32 v5, v9, v10
	v_lshl_add_u64 v[8:9], v[6:7], 0, v[0:1]
	global_store_dwordx4 v[8:9], v[2:5], off
	ds_read_b32 v0, v85 offset:160
	ds_read_b32 v2, v85 offset:420
	ds_read_b32 v3, v85 offset:680
	ds_read_b32 v4, v85 offset:940
	ds_read_b32 v5, v85 offset:1200
	ds_read_b32 v8, v85 offset:1460
	ds_read_b32 v9, v85 offset:1720
	ds_read_b32 v10, v85 offset:1980
	s_waitcnt lgkmcnt(0)
	v_cvt_pk_bf16_f32 v2, v0, v2
	v_or_b32_e32 v0, s25, v90
	v_lshlrev_b32_e32 v0, 12, v0
	v_cvt_pk_bf16_f32 v3, v3, v4
	v_cvt_pk_bf16_f32 v4, v5, v8
	v_cvt_pk_bf16_f32 v5, v9, v10
	v_lshl_add_u64 v[8:9], v[6:7], 0, v[0:1]
	global_store_dwordx4 v[8:9], v[2:5], off
	ds_read_b32 v0, v85 offset:192
	ds_read_b32 v2, v85 offset:452
	ds_read_b32 v3, v85 offset:712
	ds_read_b32 v4, v85 offset:972
	ds_read_b32 v5, v85 offset:1232
	ds_read_b32 v8, v85 offset:1492
	ds_read_b32 v9, v85 offset:1752
	ds_read_b32 v10, v85 offset:2012
	s_waitcnt lgkmcnt(0)
	v_cvt_pk_bf16_f32 v2, v0, v2
	v_or_b32_e32 v0, s25, v91
	v_lshlrev_b32_e32 v0, 12, v0
	v_cvt_pk_bf16_f32 v3, v3, v4
	v_cvt_pk_bf16_f32 v4, v5, v8
	v_cvt_pk_bf16_f32 v5, v9, v10
	v_lshl_add_u64 v[8:9], v[6:7], 0, v[0:1]
	global_store_dwordx4 v[8:9], v[2:5], off
	ds_read_b32 v0, v85 offset:224
	ds_read_b32 v2, v85 offset:484
	ds_read_b32 v3, v85 offset:744
	ds_read_b32 v4, v85 offset:1004
	ds_read_b32 v5, v85 offset:1264
	ds_read_b32 v8, v85 offset:1524
	ds_read_b32 v9, v85 offset:1784
	ds_read_b32 v10, v85 offset:2044
	s_waitcnt lgkmcnt(0)
	v_cvt_pk_bf16_f32 v2, v0, v2
	v_or_b32_e32 v0, s25, v92
	v_lshlrev_b32_e32 v0, 12, v0
	v_lshl_add_u64 v[6:7], v[6:7], 0, v[0:1]
	v_cvt_pk_bf16_f32 v3, v3, v4
	v_cvt_pk_bf16_f32 v4, v5, v8
	v_cvt_pk_bf16_f32 v5, v9, v10
	global_store_dwordx4 v[6:7], v[2:5], off
	s_waitcnt lgkmcnt(0)

; #define LAS __attribute__((address_space(3)))
; template <int MAPK>
; __device__ __forceinline__ void transpose_item(const float* W, int K, int N, int ND, bf16_t* WT, const float* g, LAS float* scr, int item, int lane) {
;     const int nblk = ND / 64, kb = item / nblk, nb = item % nblk, k0 = 64 * kb, n0 = 64 * nb;
;     const int c4 = (lane & 15) * 4, kr = lane >> 4;
;     int src = n0 + c4; if (MAPK == 1) src = inmap(src); if (MAPK == 2) src = upmap(src);
;     f32x4 vv[16];
; #pragma unroll
;     for (int i = 0; i < 16; ++i) { const int kk = 4 * i + kr;
;         vv[i] = (f32x4){0.f, 0.f, 0.f, 0.f};
;         if (src >= 0) vv[i] = *(const f32x4*)(W + (size_t)(k0 + kk) * N + src); }
; #pragma unroll
;     for (int i = 0; i < 16; ++i) { const int kk = 4 * i + kr; f32x4 v = vv[i];
;         if (g) v = v * g[k0 + kk];
;         scr[kk * 65 + c4] = v[0]; scr[kk * 65 + c4 + 1] = v[1]; scr[kk * 65 + c4 + 2] = v[2]; scr[kk * 65 + c4 + 3] = v[3]; }
.LBB0_114:
	s_andn2_b64 vcc, exec, s[0:1]
	s_cbranch_vccnz .LBB0_116
	v_readlane_b32 s68, v255, 4
	s_lshl_b64 s[0:1], s[18:19], 24
	v_readlane_b32 s70, v255, 6
	v_readlane_b32 s71, v255, 7
	s_add_u32 s20, s70, s0
	s_addc_u32 s21, s71, s1
	s_add_u32 s1, s7, s91
	s_mul_i32 s0, s18, 0xffff9b00
	s_addc_u32 s19, s9, s90
	s_add_i32 s0, s30, s0
	s_add_i32 s0, s0, 0x1ed00
	s_and_b32 s22, s0, 0x1ffc0
	s_and_b32 s0, s28, 0x7c0
	v_or_b32_e32 v0, s0, v75
	v_or_b32_e32 v4, s22, v76
	v_lshlrev_b32_e32 v0, 2, v0
	v_lshl_add_u64 v[2:3], s[20:21], 0, v[0:1]
	v_lshlrev_b32_e32 v0, 13, v4
	v_lshl_add_u64 v[62:63], v[2:3], 0, v[0:1]
	v_add_co_u32_e32 v6, vcc, s96, v62
	s_mov_b32 s20, 0x70000
	s_nop 0
	v_addc_co_u32_e32 v7, vcc, 0, v63, vcc
	v_add_co_u32_e32 v10, vcc, s97, v62
	global_load_dwordx4 v[2:5], v[62:63], off
	s_nop 0
	global_load_dwordx4 v[6:9], v[6:7], off
	v_addc_co_u32_e32 v11, vcc, 0, v63, vcc
	v_add_co_u32_e32 v14, vcc, s10, v62
	v_mov_b32_e32 v79, v1
	s_nop 0
	v_addc_co_u32_e32 v15, vcc, 0, v63, vcc
	v_add_co_u32_e32 v18, vcc, s11, v62
	global_load_dwordx4 v[10:13], v[10:11], off
	s_nop 0
	global_load_dwordx4 v[14:17], v[14:15], off
	v_addc_co_u32_e32 v19, vcc, 0, v63, vcc
	v_add_co_u32_e32 v22, vcc, s85, v62
	v_readlane_b32 s69, v255, 5
	s_nop 0
	v_addc_co_u32_e32 v23, vcc, 0, v63, vcc
	v_add_co_u32_e32 v26, vcc, s86, v62
	global_load_dwordx4 v[18:21], v[18:19], off
	s_nop 0
	global_load_dwordx4 v[22:25], v[22:23], off
	v_addc_co_u32_e32 v27, vcc, 0, v63, vcc
	v_add_co_u32_e32 v30, vcc, s87, v62
	v_readlane_b32 s72, v255, 8
	s_nop 0
	v_addc_co_u32_e32 v31, vcc, 0, v63, vcc
	v_add_co_u32_e32 v34, vcc, s2, v62
	global_load_dwordx4 v[26:29], v[26:27], off
	s_nop 0
	global_load_dwordx4 v[30:33], v[30:31], off
	v_addc_co_u32_e32 v35, vcc, 0, v63, vcc
	v_add_co_u32_e32 v38, vcc, s3, v62
	v_readlane_b32 s73, v255, 9
	s_nop 0
	v_addc_co_u32_e32 v39, vcc, 0, v63, vcc
	v_add_co_u32_e32 v42, vcc, s12, v62
	global_load_dwordx4 v[34:37], v[34:35], off
	s_nop 0
	global_load_dwordx4 v[38:41], v[38:39], off
	v_addc_co_u32_e32 v43, vcc, 0, v63, vcc
	v_add_co_u32_e32 v46, vcc, s13, v62
	v_readlane_b32 s74, v255, 10
	s_nop 0
	v_addc_co_u32_e32 v47, vcc, 0, v63, vcc
	v_add_co_u32_e32 v50, vcc, s93, v62
	global_load_dwordx4 v[42:45], v[42:43], off
	s_nop 0
	global_load_dwordx4 v[46:49], v[46:47], off
	v_addc_co_u32_e32 v51, vcc, 0, v63, vcc
	v_add_co_u32_e32 v54, vcc, s94, v62
	v_readlane_b32 s75, v255, 11
	s_nop 0
	v_addc_co_u32_e32 v55, vcc, 0, v63, vcc
	global_load_dwordx4 v[50:53], v[50:51], off
	s_nop 0
	global_load_dwordx4 v[54:57], v[54:55], off
	v_add_co_u32_e32 v58, vcc, s20, v62
	s_lshl_b32 s20, s22, 1
	s_nop 0
	v_addc_co_u32_e32 v59, vcc, 0, v63, vcc
	global_load_dwordx4 v[58:61], v[58:59], off
	v_add_co_u32_e32 v62, vcc, s84, v62
	s_add_u32 s20, s1, s20
	s_nop 0
	v_addc_co_u32_e32 v63, vcc, 0, v63, vcc
	global_load_dwordx4 v[62:65], v[62:63], off
	s_addc_u32 s21, s19, 0
	v_readlane_b32 s76, v255, 12
	v_readlane_b32 s77, v255, 13
	v_readlane_b32 s78, v255, 14
	v_readlane_b32 s79, v255, 15
	v_readlane_b32 s80, v255, 16
	v_readlane_b32 s81, v255, 17
	v_readlane_b32 s82, v255, 18
	v_readlane_b32 s83, v255, 19
	s_waitcnt vmcnt(0)
	ds_write2_b32 v83, v2, v3 offset1:1
	ds_write2_b32 v83, v4, v5 offset0:2 offset1:3
	ds_write2_b32 v99, v6, v7 offset1:1
	ds_write2_b32 v100, v8, v9 offset1:1
	ds_write2_b32 v101, v10, v11 offset1:1
	ds_write2_b32 v102, v12, v13 offset1:1
	ds_write2_b32 v103, v14, v15 offset1:1
	ds_write2_b32 v104, v16, v17 offset1:1
	ds_write2_b32 v105, v18, v19 offset1:1
	ds_write2_b32 v106, v20, v21 offset1:1
	ds_write2_b32 v107, v22, v23 offset1:1
	ds_write2_b32 v108, v24, v25 offset1:1
	ds_write2_b32 v109, v26, v27 offset1:1
	ds_write2_b32 v110, v28, v29 offset1:1
	ds_write2_b32 v111, v30, v31 offset1:1
	ds_write2_b32 v112, v32, v33 offset1:1
	ds_write2_b32 v113, v34, v35 offset1:1
	ds_write2_b32 v114, v36, v37 offset1:1
	ds_write2_b32 v115, v38, v39 offset1:1
	ds_write2_b32 v116, v40, v41 offset1:1
	ds_write2_b32 v117, v42, v43 offset1:1
	ds_write2_b32 v118, v44, v45 offset1:1
	ds_write2_b32 v119, v46, v47 offset1:1
	ds_write2_b32 v120, v48, v49 offset1:1
	ds_write2_b32 v121, v50, v51 offset1:1
	ds_write2_b32 v122, v52, v53 offset1:1
	ds_write2_b32 v123, v54, v55 offset1:1
	ds_write2_b32 v124, v56, v57 offset1:1
	ds_write2_b32 v125, v58, v59 offset1:1
	ds_write2_b32 v126, v60, v61 offset1:1
	ds_write2_b32 v127, v62, v63 offset1:1
	ds_write2_b32 v128, v64, v65 offset1:1
	s_waitcnt lgkmcnt(0)
; #define LAS __attribute__((address_space(3)))
; __device__ __forceinline__ unsigned cvt_pk_bf16(float lo, float hi) { unsigned r; asm("v_cvt_pk_bf16_f32 %0, %1, %2" : "=v"(r) : "v"(lo), "v"(hi)); return r; }
; template <int MAPK>
; __device__ __forceinline__ void transpose_item(const float* W, int K, int N, int ND, bf16_t* WT, const float* g, LAS float* scr, int item, int lane) {
;     ...
;     asm volatile("s_waitcnt lgkmcnt(0)" ::: "memory");
;     const int c = lane & 7;
; #pragma unroll
;     for (int j = 0; j < 8; ++j) { const int n = (lane >> 3) + 8 * j; const LAS float* sp = scr + (8 * c) * 65 + n;
;         u32x4 o; o.x = cvt_pk_bf16(sp[0], sp[65]); o.y = cvt_pk_bf16(sp[2 * 65], sp[3 * 65]); o.z = cvt_pk_bf16(sp[4 * 65], sp[5 * 65]); o.w = cvt_pk_bf16(sp[6 * 65], sp[7 * 65]);
;         *(u32x4*)(WT + (size_t)(n0 + n) * K + k0 + 8 * c) = o; }
	ds_read_b32 v0, v85
	ds_read_b32 v4, v85 offset:260
	ds_read_b32 v5, v85 offset:520
	ds_read_b32 v8, v85 offset:780
	ds_read_b32 v9, v85 offset:1040
	ds_read_b32 v10, v85 offset:1300
	ds_read_b32 v11, v85 offset:1560
	ds_read_b32 v12, v85 offset:1820
	v_lshl_add_u64 v[2:3], s[20:21], 0, v[78:79]
	s_mov_b64 s[20:21], 0x1300000
	v_lshl_add_u64 v[6:7], v[2:3], 0, s[20:21]
	s_waitcnt lgkmcnt(0)
	v_cvt_pk_bf16_f32 v2, v0, v4
	v_or_b32_e32 v0, s0, v84
	v_lshlrev_b32_e32 v0, 12, v0
	v_cvt_pk_bf16_f32 v3, v5, v8
	v_cvt_pk_bf16_f32 v4, v9, v10
	v_lshl_add_u64 v[8:9], v[6:7], 0, v[0:1]
	v_cvt_pk_bf16_f32 v5, v11, v12
	global_store_dwordx4 v[8:9], v[2:5], off
	ds_read_b32 v0, v85 offset:32
	ds_read_b32 v2, v85 offset:292
	ds_read_b32 v3, v85 offset:552
	ds_read_b32 v4, v85 offset:812
	ds_read_b32 v5, v85 offset:1072
	ds_read_b32 v8, v85 offset:1332
	ds_read_b32 v9, v85 offset:1592
	ds_read_b32 v10, v85 offset:1852
	s_waitcnt lgkmcnt(0)
	v_cvt_pk_bf16_f32 v2, v0, v2
	v_or_b32_e32 v0, s0, v86
	v_lshlrev_b32_e32 v0, 12, v0
	v_cvt_pk_bf16_f32 v3, v3, v4
	v_cvt_pk_bf16_f32 v4, v5, v8
	v_cvt_pk_bf16_f32 v5, v9, v10
	v_lshl_add_u64 v[8:9], v[6:7], 0, v[0:1]
	global_store_dwordx4 v[8:9], v[2:5], off
	ds_read_b32 v0, v85 offset:64
	ds_read_b32 v2, v85 offset:324
	ds_read_b32 v3, v85 offset:584
	ds_read_b32 v4, v85 offset:844
	ds_read_b32 v5, v85 offset:1104
	ds_read_b32 v8, v85 offset:1364
	ds_read_b32 v9, v85 offset:1624
	ds_read_b32 v10, v85 offset:1884
	s_waitcnt lgkmcnt(0)
	v_cvt_pk_bf16_f32 v2, v0, v2
	v_or_b32_e32 v0, s0, v87
	v_lshlrev_b32_e32 v0, 12, v0
	v_cvt_pk_bf16_f32 v3, v3, v4
	v_cvt_pk_bf16_f32 v4, v5, v8
	v_cvt_pk_bf16_f32 v5, v9, v10
	v_lshl_add_u64 v[8:9], v[6:7], 0, v[0:1]
	global_store_dwordx4 v[8:9], v[2:5], off
	ds_read_b32 v0, v85 offset:96
	ds_read_b32 v2, v85 offset:356
	ds_read_b32 v3, v85 offset:616
	ds_read_b32 v4, v85 offset:876
	ds_read_b32 v5, v85 offset:1136
	ds_read_b32 v8, v85 offset:1396
	ds_read_b32 v9, v85 offset:1656
	ds_read_b32 v10, v85 offset:1916
	s_waitcnt lgkmcnt(0)
	v_cvt_pk_bf16_f32 v2, v0, v2
	v_or_b32_e32 v0, s0, v88
	v_lshlrev_b32_e32 v0, 12, v0
	v_cvt_pk_bf16_f32 v3, v3, v4
	v_cvt_pk_bf16_f32 v4, v5, v8
	v_cvt_pk_bf16_f32 v5, v9, v10
	v_lshl_add_u64 v[8:9], v[6:7], 0, v[0:1]
	global_store_dwordx4 v[8:9], v[2:5], off
	ds_read_b32 v0, v85 offset:128
	ds_read_b32 v2, v85 offset:388
	ds_read_b32 v3, v85 offset:648
	ds_read_b32 v4, v85 offset:908
	ds_read_b32 v5, v85 offset:1168
	ds_read_b32 v8, v85 offset:1428
	ds_read_b32 v9, v85 offset:1688
	ds_read_b32 v10, v85 offset:1948
	s_waitcnt lgkmcnt(0)
	v_cvt_pk_bf16_f32 v2, v0, v2
	v_or_b32_e32 v0, s0, v89
	v_lshlrev_b32_e32 v0, 12, v0
	v_cvt_pk_bf16_f32 v3, v3, v4
	v_cvt_pk_bf16_f32 v4, v5, v8
	v_cvt_pk_bf16_f32 v5, v9, v10
	v_lshl_add_u64 v[8:9], v[6:7], 0, v[0:1]
	global_store_dwordx4 v[8:9], v[2:5], off
	ds_read_b32 v0, v85 offset:160
	ds_read_b32 v2, v85 offset:420
	ds_read_b32 v3, v85 offset:680
	ds_read_b32 v4, v85 offset:940
	ds_read_b32 v5, v85 offset:1200
	ds_read_b32 v8, v85 offset:1460
	ds_read_b32 v9, v85 offset:1720
	ds_read_b32 v10, v85 offset:1980
	s_waitcnt lgkmcnt(0)
	v_cvt_pk_bf16_f32 v2, v0, v2
	v_or_b32_e32 v0, s0, v90
	v_lshlrev_b32_e32 v0, 12, v0
	v_cvt_pk_bf16_f32 v3, v3, v4
	v_cvt_pk_bf16_f32 v4, v5, v8
	v_cvt_pk_bf16_f32 v5, v9, v10
	v_lshl_add_u64 v[8:9], v[6:7], 0, v[0:1]
	global_store_dwordx4 v[8:9], v[2:5], off
	ds_read_b32 v0, v85 offset:192
	ds_read_b32 v2, v85 offset:452
	ds_read_b32 v3, v85 offset:712
	ds_read_b32 v4, v85 offset:972
	ds_read_b32 v5, v85 offset:1232
	ds_read_b32 v8, v85 offset:1492
	ds_read_b32 v9, v85 offset:1752
	ds_read_b32 v10, v85 offset:2012
	s_waitcnt lgkmcnt(0)
	v_cvt_pk_bf16_f32 v2, v0, v2
	v_or_b32_e32 v0, s0, v91
	v_lshlrev_b32_e32 v0, 12, v0
	v_cvt_pk_bf16_f32 v3, v3, v4
	v_cvt_pk_bf16_f32 v4, v5, v8
	v_cvt_pk_bf16_f32 v5, v9, v10
	v_lshl_add_u64 v[8:9], v[6:7], 0, v[0:1]
	global_store_dwordx4 v[8:9], v[2:5], off
	ds_read_b32 v0, v85 offset:224
	ds_read_b32 v2, v85 offset:484
	ds_read_b32 v3, v85 offset:744
	ds_read_b32 v4, v85 offset:1004
	ds_read_b32 v5, v85 offset:1264
	ds_read_b32 v8, v85 offset:1524
	ds_read_b32 v9, v85 offset:1784
	ds_read_b32 v10, v85 offset:2044
	s_waitcnt lgkmcnt(0)
	v_cvt_pk_bf16_f32 v2, v0, v2
	v_or_b32_e32 v0, s0, v92
	v_lshlrev_b32_e32 v0, 12, v0
	v_lshl_add_u64 v[6:7], v[6:7], 0, v[0:1]
	v_cvt_pk_bf16_f32 v3, v3, v4
	v_cvt_pk_bf16_f32 v4, v5, v8
	v_cvt_pk_bf16_f32 v5, v9, v10
	global_store_dwordx4 v[6:7], v[2:5], off
	s_waitcnt lgkmcnt(0)

; __device__ __forceinline__ unsigned cvt_pk_bf16(float lo, float hi) { unsigned r; asm("v_cvt_pk_bf16_f32 %0, %1, %2" : "=v"(r) : "v"(lo), "v"(hi)); return r; }
; __global__ void __launch_bounds__(512, 2) hybrid_fwd(Params p) {
;     ...
;         for (int mrow = gw; mrow < T_ + MEM_; mrow += NGW) {
;             const bool ism = mrow >= T_; const float* src = ism ? p.mem + (size_t)(mrow - T_) * D_ : p.x + (size_t)mrow * D_;
;             bf16_t* dst = ism ? MEMB + (size_t)(mrow - T_) * D_ : HB + (size_t)mrow * D_;
;             f32x4 v[8]; float s = 0.f;
; #pragma unroll
;             for (int j = 0; j < 8; ++j) { v[j] = *(const f32x4*)(src + 256 * j + 4 * lane); s += (v[j][0] * v[j][0] + v[j][1] * v[j][1]) + (v[j][2] * v[j][2] + v[j][3] * v[j][3]); }
;             s = wave_sum(s, lane);
;             float sc = 1.f; if (ism) sc = rsqrtf(s * (1.f / D_) + EPS); else if (lane == 0) ssq[mrow] = (u64)__float2ull_rn(s * SSQ_SCALE);
; #pragma unroll
;             for (int j = 0; j < 8; ++j) { u32x2 w2; w2.x = cvt_pk_bf16(v[j][0] * sc, v[j][1] * sc); w2.y = cvt_pk_bf16(v[j][2] * sc, v[j][3] * sc); *(u32x2*)(dst + 256 * j + 4 * lane) = w2; }
.LBB0_246:
	s_and_b64 s[16:17], s[16:17], exec
	s_cselect_b32 s16, s22, 0x1d600000
	s_add_u32 s16, s4, s16
	s_addc_u32 s17, s5, 0
	s_lshl_b64 s[14:15], s[14:15], 12
	s_add_u32 s14, s16, s14
	v_mul_f32_e32 v0, v43, v0
	v_mul_f32_e32 v1, v43, v1
	s_addc_u32 s15, s17, s15
	v_cvt_pk_bf16_f32 v0, v0, v1
	v_mul_f32_e32 v1, v43, v2
	v_lshl_add_u64 v[44:45], s[14:15], 0, v[34:35]
	v_mul_f32_e32 v2, v43, v3
	v_cvt_pk_bf16_f32 v1, v1, v2
	global_store_dwordx2 v[44:45], v[0:1], off offset:512
	v_mul_f32_e32 v0, v43, v4
	v_mul_f32_e32 v1, v43, v5
	v_cvt_pk_bf16_f32 v0, v0, v1
	v_mul_f32_e32 v1, v43, v6
	v_mul_f32_e32 v2, v43, v7
	v_cvt_pk_bf16_f32 v1, v1, v2
	global_store_dwordx2 v[44:45], v[0:1], off offset:1024
	v_mul_f32_e32 v0, v43, v8
	v_mul_f32_e32 v1, v43, v9
	v_cvt_pk_bf16_f32 v0, v0, v1
	v_mul_f32_e32 v1, v43, v10
	v_mul_f32_e32 v2, v43, v11
	v_cvt_pk_bf16_f32 v1, v1, v2
	global_store_dwordx2 v[44:45], v[0:1], off offset:1536
	v_mul_f32_e32 v0, v43, v16
	v_mul_f32_e32 v1, v43, v17
	v_cvt_pk_bf16_f32 v0, v0, v1
	v_mul_f32_e32 v1, v43, v18
	v_mul_f32_e32 v2, v43, v19
	v_cvt_pk_bf16_f32 v1, v1, v2
	global_store_dwordx2 v[44:45], v[0:1], off offset:2048
	v_mul_f32_e32 v0, v43, v20
	v_mul_f32_e32 v1, v43, v21
	v_cvt_pk_bf16_f32 v0, v0, v1
	v_mul_f32_e32 v1, v43, v22
	v_mul_f32_e32 v2, v43, v23
	v_cvt_pk_bf16_f32 v1, v1, v2
	global_store_dwordx2 v[44:45], v[0:1], off offset:2560
	v_mul_f32_e32 v0, v43, v24
	v_mul_f32_e32 v1, v43, v25
	s_add_u32 s6, s6, s8
	v_cvt_pk_bf16_f32 v0, v0, v1
	v_mul_f32_e32 v1, v43, v26
	s_addc_u32 s7, s7, s9
	v_mul_f32_e32 v2, v43, v27
	v_cvt_pk_bf16_f32 v1, v1, v2
	s_add_u32 s10, s10, s12
	v_mul_f32_e32 v12, v43, v12
	v_mul_f32_e32 v13, v43, v13
	global_store_dwordx2 v[44:45], v[0:1], off offset:3072
	v_mul_f32_e32 v0, v43, v28
	v_mul_f32_e32 v1, v43, v29
	s_addc_u32 s11, s11, s13
	v_cvt_pk_bf16_f32 v12, v12, v13
	v_mul_f32_e32 v13, v43, v14
	v_cvt_pk_bf16_f32 v0, v0, v1
	v_mul_f32_e32 v1, v43, v30
	s_cmpk_gt_i32 s6, 0x20ff
	v_mul_f32_e32 v14, v43, v15
	v_cvt_pk_bf16_f32 v13, v13, v14
	global_store_dwordx2 v[44:45], v[12:13], off
	v_mul_f32_e32 v2, v43, v31
	v_cvt_pk_bf16_f32 v1, v1, v2
	global_store_dwordx2 v[44:45], v[0:1], off offset:3584
	s_cbranch_scc1 .LBB0_253
.LBB0_247:
	s_add_i32 s18, s6, 0xffffe000
	s_cmpk_gt_i32 s6, 0x1fff
	s_cselect_b64 s[16:17], -1, 0
	s_and_b64 s[14:15], s[16:17], exec
	s_cselect_b32 s15, 0, s7
	s_cselect_b32 s14, s18, s6
	s_cselect_b32 s23, s55, s53
	s_cselect_b32 s24, s54, s52
	s_lshl_b64 s[18:19], s[14:15], 13
	s_add_u32 s18, s24, s18
	s_addc_u32 s19, s23, s19
	global_load_dwordx4 v[12:15], v32, s[18:19]
	global_load_dwordx4 v[0:3], v32, s[18:19] offset:1024
	global_load_dwordx4 v[4:7], v32, s[18:19] offset:2048
	global_load_dwordx4 v[8:11], v32, s[18:19] offset:3072
	v_lshl_add_u64 v[16:17], s[18:19], 0, v[32:33]
	v_add_co_u32_e32 v28, vcc, s20, v16
	s_cmpk_lt_i32 s6, 0x2000
	s_nop 0
	v_addc_co_u32_e32 v29, vcc, 0, v17, vcc
	global_load_dwordx4 v[16:19], v[28:29], off
	global_load_dwordx4 v[20:23], v[28:29], off offset:1024
	global_load_dwordx4 v[24:27], v[28:29], off offset:2048
	s_nop 0
	global_load_dwordx4 v[28:31], v[28:29], off offset:3072
	s_mov_b64 s[18:19], -1
	s_waitcnt vmcnt(0)
	v_mul_f32_e32 v43, v13, v13
	v_mul_f32_e32 v44, v15, v15
	v_mul_f32_e32 v45, v1, v1
	v_mul_f32_e32 v46, v3, v3
	v_mul_f32_e32 v47, v5, v5
	v_mul_f32_e32 v48, v7, v7
	v_fmac_f32_e32 v43, v12, v12
	v_fmac_f32_e32 v44, v14, v14
	v_fmac_f32_e32 v45, v0, v0
	v_fmac_f32_e32 v46, v2, v2
	v_mul_f32_e32 v49, v9, v9
	v_mul_f32_e32 v50, v11, v11
	v_fmac_f32_e32 v47, v4, v4
	v_fmac_f32_e32 v48, v6, v6
	v_add_f32_e32 v43, v43, v44
	v_add_f32_e32 v44, v45, v46
	v_fmac_f32_e32 v49, v8, v8
	v_fmac_f32_e32 v50, v10, v10
	v_add_f32_e32 v45, v47, v48
	v_mul_f32_e32 v47, v17, v17
	v_mul_f32_e32 v48, v19, v19
	v_add_f32_e32 v43, v43, v44
	v_add_f32_e32 v46, v49, v50
	v_mul_f32_e32 v49, v21, v21
	v_mul_f32_e32 v50, v23, v23
	v_fmac_f32_e32 v47, v16, v16
	v_fmac_f32_e32 v48, v18, v18
	v_add_f32_e32 v43, v43, v45
	v_mul_f32_e32 v51, v25, v25
	v_mul_f32_e32 v52, v27, v27
	v_fmac_f32_e32 v49, v20, v20
	v_fmac_f32_e32 v50, v22, v22
	v_add_f32_e32 v44, v47, v48
	v_add_f32_e32 v43, v43, v46
	v_mul_f32_e32 v53, v29, v29
	v_mul_f32_e32 v54, v31, v31
	v_fmac_f32_e32 v51, v24, v24
	v_fmac_f32_e32 v52, v26, v26
	v_add_f32_e32 v45, v49, v50
	v_add_f32_e32 v43, v43, v44
	v_fmac_f32_e32 v53, v28, v28
	v_fmac_f32_e32 v54, v30, v30
	v_add_f32_e32 v47, v51, v52
	v_add_f32_e32 v43, v43, v45
	v_add_f32_e32 v48, v53, v54
	v_add_f32_e32 v43, v43, v47
	v_add_f32_e32 v43, v43, v48
	ds_bpermute_b32 v44, v36, v43
	s_waitcnt lgkmcnt(0)
	v_add_f32_e32 v43, v43, v44
	ds_bpermute_b32 v44, v37, v43
	s_waitcnt lgkmcnt(0)
	v_add_f32_e32 v43, v43, v44
	ds_bpermute_b32 v44, v38, v43
	s_waitcnt lgkmcnt(0)
	v_add_f32_e32 v43, v43, v44
	ds_bpermute_b32 v44, v39, v43
	s_waitcnt lgkmcnt(0)
	v_add_f32_e32 v43, v43, v44
	ds_bpermute_b32 v44, v40, v43
	s_waitcnt lgkmcnt(0)
	v_add_f32_e32 v43, v43, v44
	ds_bpermute_b32 v44, v41, v43
	s_waitcnt lgkmcnt(0)
	v_add_f32_e32 v44, v43, v44
	s_cbranch_scc0 .LBB0_251
	s_and_saveexec_b64 s[18:19], s[0:1]
	s_cbranch_execz .LBB0_250
	v_mul_f32_e32 v43, 0x4b800000, v44
	v_rndne_f32_e32 v43, v43
	v_mul_f32_e32 v45, 0x2f800000, v43
	v_floor_f32_e32 v45, v45
	v_fmac_f32_e32 v43, 0xcf800000, v45
	v_cvt_u32_f32_e32 v46, v43
	v_cvt_u32_f32_e32 v47, v45
	v_mov_b64_e32 v[48:49], s[10:11]
	global_store_dwordx2 v[48:49], v[46:47], off

; __global__ void __launch_bounds__(512, 2) hybrid_fwd(Params p) {
;     ...
;         for (int i = c * 512 + tid; i < 12 * T_; i += G * 512) ssq[T_ + i] = 0ull;
;         if (c == 0 && tid < 16) KNB[tid] = 0u;
.LBB0_255:
	v_add_u32_e32 v0, s6, v0
	v_cmp_lt_i32_e32 vcc, s7, v0
	global_store_dwordx2 v[2:3], v[4:5], off
	s_or_b64 s[10:11], vcc, s[10:11]
	v_lshl_add_u64 v[2:3], v[2:3], 0, s[8:9]
	s_andn2_b64 exec, exec, s[10:11]
	s_cbranch_execnz .LBB0_255
.LBB0_256:
	s_or_b64 exec, exec, s[0:1]
	s_cmp_eq_u32 s26, 0
	s_cselect_b64 s[0:1], -1, 0
	v_cmp_gt_i32_e32 vcc, 16, v72
	s_and_b64 s[6:7], s[0:1], vcc
	s_and_saveexec_b64 s[0:1], s[6:7]
	s_cbranch_execz .LBB0_258
	v_ashrrev_i32_e32 v73, 31, v72
	v_lshl_add_u64 v[0:1], v[72:73], 2, s[4:5]
	v_add_co_u32_e32 v0, vcc, 0x38f80000, v0
	v_mov_b32_e32 v2, 0
	s_nop 0
	v_addc_co_u32_e32 v1, vcc, 0, v1, vcc
	global_store_dword v[0:1], v2, off

; __global__ void __launch_bounds__(512, 2) hybrid_fwd(Params p) {
;     ...
;         if (c == 1) for (int i = tid; i < 2 * D_ / 2; i += 512) ((unsigned*)HB)[i - 2 * D_ / 2] = 0u;
.LBB0_261:
	v_ashrrev_i32_e32 v9, 31, v0
	v_mov_b32_e32 v8, v0
	v_lshl_add_u64 v[8:9], v[8:9], 2, s[4:5]
	v_ashrrev_i32_e32 v7, 31, v1
	v_mov_b32_e32 v6, v1
	v_add_co_u32_e32 v8, vcc, 0x1d5fe000, v8
	v_add_u32_e32 v5, -2, v5
	v_lshl_add_u64 v[6:7], v[6:7], 2, s[4:5]
	v_addc_co_u32_e32 v9, vcc, 0, v9, vcc
	v_cmp_eq_u32_e64 s[0:1], 0, v5
	v_add_co_u32_e32 v6, vcc, 0x1d5fe000, v6
	v_add_u32_e32 v1, 0x400, v1
	v_add_u32_e32 v0, 0x400, v0
	s_or_b64 s[10:11], s[0:1], s[10:11]
	v_addc_co_u32_e32 v7, vcc, 0, v7, vcc
	global_store_dword v[8:9], v4, off
	global_store_dword v[6:7], v4, off
	s_andn2_b64 exec, exec, s[10:11]
	s_cbranch_execnz .LBB0_261
	s_or_b64 exec, exec, s[10:11]
	v_cmp_ne_u32_e32 vcc, v2, v3
	v_lshl_add_u32 v72, v3, 9, v72
	s_orn2_b64 s[0:1], vcc, exec

; __global__ void __launch_bounds__(512, 2) hybrid_fwd(Params p) {
;     ...
;         if (c == 1) for (int i = tid; i < 2 * D_ / 2; i += 512) ((unsigned*)HB)[i - 2 * D_ / 2] = 0u;
.LBB0_265:
	v_add_u32_e32 v2, 0x200, v2
	v_cmp_lt_i32_e32 vcc, s8, v2
	global_store_dword v[0:1], v3, off
	s_or_b64 s[0:1], vcc, s[0:1]
	v_lshl_add_u64 v[0:1], v[0:1], 0, s[4:5]
	s_andn2_b64 exec, exec, s[0:1]
	s_cbranch_execnz .LBB0_265

; __device__ __forceinline__ unsigned cvt_pk_bf16(float lo, float hi) { unsigned r; asm("v_cvt_pk_bf16_f32 %0, %1, %2" : "=v"(r) : "v"(lo), "v"(hi)); return r; }
;     __device__ __forceinline__ void operator()(const f32x4 (&acc)[2][2][4][2], const GU& u, int wr, int wc, int fr, int fq) const {
;     ...
; #pragma unroll
;         for (int ai = 0; ai < 2; ++ai)
; #pragma unroll
;             for (int m = 0; m < 4; ++m) {
;                 const int row = r0 + ai * 128 + m * 16;
;                 const float rs = rsv[ai][m];
;                 bf16_t* rowp = u.out + (size_t)row * u.ldc + c0;
; #pragma unroll
;                 for (int bj = 0; bj < 2; ++bj) {
;                     if (bj == 1 && (u.mode & 8)) continue;
;                     f32x4 v0 = acc[ai][bj][m][0] * cs[bj][0] * rs, v1 = acc[ai][bj][m][1] * cs[bj][1] * rs;
;                     u32x4 w; w.x = cvt_pk_bf16(v0[0], v0[1]); w.y = cvt_pk_bf16(v0[2], v0[3]); w.z = cvt_pk_bf16(v1[0], v1[1]); w.w = cvt_pk_bf16(v1[2], v1[3]);
;                     *(u32x4*)(rowp + bj * 128) = w;
;                     if (bj == 0 && u.gates != nullptr && wc == 0) { float* gp = u.gates + (size_t)row * 32 + 8 * fq; *(f32x4*)gp = v0; *(f32x4*)(gp + 4) = v1; }
;                 }
.LBB0_370:
	v_mul_lo_u32 v194, s19, v136
	v_mul_lo_u32 v195, s18, v137
	v_mad_u64_u32 v[192:193], s[0:1], s18, v136, 0
	s_cmp_lg_u64 s[20:21], 0
	v_add3_u32 v193, v193, v195, v194
	s_cselect_b64 s[0:1], -1, 0
	v_lshl_add_u64 v[192:193], v[192:193], 1, s[16:17]
	s_and_b64 s[4:5], s[8:9], s[0:1]
	v_lshl_add_u64 v[194:195], v[192:193], 0, v[200:201]
	v_pk_mul_f32 v[126:127], v[126:127], v[172:173]
	v_pk_mul_f32 v[124:125], v[124:125], v[170:171]
	v_pk_mul_f32 v[122:123], v[122:123], v[176:177]
	v_pk_mul_f32 v[120:121], v[120:121], v[168:169]
	v_cndmask_b32_e64 v192, 0, 1, s[4:5]
	v_pk_mul_f32 v[126:127], v[126:127], v[188:189] op_sel_hi:[1,0]
	v_pk_mul_f32 v[124:125], v[124:125], v[188:189] op_sel_hi:[1,0]
	v_pk_mul_f32 v[122:123], v[122:123], v[188:189] op_sel_hi:[1,0]
	v_pk_mul_f32 v[120:121], v[120:121], v[188:189] op_sel_hi:[1,0]
	v_cmp_ne_u32_e64 s[0:1], 1, v192
	s_andn2_b64 vcc, exec, s[4:5]
	v_lshlrev_b32_e32 v192, 2, v138
	v_cvt_pk_bf16_f32 v196, v124, v125
	v_cvt_pk_bf16_f32 v197, v126, v127
	v_cvt_pk_bf16_f32 v198, v120, v121
	v_cvt_pk_bf16_f32 v199, v122, v123
	global_store_dwordx4 v[194:195], v[196:199], off
	s_cbranch_vccnz .LBB0_372
	s_nop 0
	v_lshlrev_b64 v[196:197], 7, v[136:137]
	v_lshl_add_u64 v[196:197], s[20:21], 0, v[196:197]
	v_mov_b32_e32 v193, v201
	v_lshl_add_u64 v[196:197], v[196:197], 0, v[192:193]
	global_store_dwordx4 v[196:197], v[124:127], off
	global_store_dwordx4 v[196:197], v[120:123], off offset:16
.LBB0_372:
	s_nop 1
	v_mov_b32_e32 v120, v188
	v_mov_b32_e32 v121, v188
	v_pk_mul_f32 v[118:119], v[118:119], v[180:181]
	v_mov_b32_e32 v122, v188
	v_mov_b32_e32 v123, v188
	v_pk_mul_f32 v[114:115], v[114:115], v[182:183]
	v_pk_mul_f32 v[112:113], v[112:113], v[174:175]
	v_pk_mul_f32 v[116:117], v[116:117], v[178:179]
	v_pk_mul_f32 v[118:119], v[118:119], v[122:123]
	v_pk_mul_f32 v[122:123], v[114:115], v[122:123]
	v_pk_mul_f32 v[114:115], v[112:113], v[120:121]
	v_pk_mul_f32 v[116:117], v[116:117], v[120:121]
	v_cvt_pk_bf16_f32 v113, v118, v119
	v_cvt_pk_bf16_f32 v114, v114, v115
	v_cvt_pk_bf16_f32 v115, v122, v123
	v_pk_mul_f32 v[110:111], v[110:111], v[172:173]
	v_cvt_pk_bf16_f32 v112, v116, v117
	global_store_dwordx4 v[194:195], v[112:115], off offset:256
	v_pk_mul_f32 v[108:109], v[108:109], v[170:171]
	v_pk_mul_f32 v[106:107], v[106:107], v[176:177]
	v_mul_lo_u32 v114, s19, v142
	v_mul_lo_u32 v115, s18, v143
	v_mad_u64_u32 v[112:113], s[4:5], s18, v142, 0
	v_add3_u32 v113, v113, v115, v114
	v_lshl_add_u64 v[112:113], v[112:113], 1, s[16:17]
	v_pk_mul_f32 v[104:105], v[104:105], v[168:169]
	v_lshl_add_u64 v[112:113], v[112:113], 0, v[200:201]
	v_pk_mul_f32 v[110:111], v[110:111], v[188:189] op_sel:[0,1]
	v_pk_mul_f32 v[108:109], v[108:109], v[188:189] op_sel:[0,1]
	v_pk_mul_f32 v[106:107], v[106:107], v[188:189] op_sel:[0,1]
	v_pk_mul_f32 v[104:105], v[104:105], v[188:189] op_sel:[0,1]
	s_and_b64 vcc, exec, s[0:1]
	v_cvt_pk_bf16_f32 v114, v108, v109
	v_cvt_pk_bf16_f32 v115, v110, v111
	v_cvt_pk_bf16_f32 v116, v104, v105
	v_cvt_pk_bf16_f32 v117, v106, v107
	global_store_dwordx4 v[112:113], v[114:117], off
	s_cbranch_vccnz .LBB0_374
	s_nop 0
	v_lshlrev_b64 v[114:115], 7, v[142:143]
	v_lshl_add_u64 v[114:115], s[20:21], 0, v[114:115]
	v_mov_b32_e32 v193, v201
	v_lshl_add_u64 v[114:115], v[114:115], 0, v[192:193]
	global_store_dwordx4 v[114:115], v[108:111], off
	global_store_dwordx4 v[114:115], v[104:107], off offset:16
.LBB0_374:
	v_mov_b32_e32 v188, v189
	v_pk_mul_f32 v[102:103], v[102:103], v[180:181]
	v_mov_b32_e32 v104, v189
	v_mov_b32_e32 v105, v189
	v_pk_mul_f32 v[98:99], v[98:99], v[182:183]
	v_pk_mul_f32 v[96:97], v[96:97], v[174:175]
	v_pk_mul_f32 v[100:101], v[100:101], v[178:179]
	v_pk_mul_f32 v[102:103], v[102:103], v[104:105]
	v_pk_mul_f32 v[104:105], v[98:99], v[104:105]
	v_pk_mul_f32 v[98:99], v[96:97], v[188:189]
	v_pk_mul_f32 v[100:101], v[100:101], v[188:189]
	v_cvt_pk_bf16_f32 v97, v102, v103
	v_cvt_pk_bf16_f32 v98, v98, v99
	v_cvt_pk_bf16_f32 v99, v104, v105
	v_pk_mul_f32 v[94:95], v[94:95], v[172:173]
	v_cvt_pk_bf16_f32 v96, v100, v101
	global_store_dwordx4 v[112:113], v[96:99], off offset:256
	v_pk_mul_f32 v[92:93], v[92:93], v[170:171]
	v_pk_mul_f32 v[90:91], v[90:91], v[176:177]
	v_mul_lo_u32 v98, s19, v144
	v_mul_lo_u32 v99, s18, v145
	v_mad_u64_u32 v[96:97], s[4:5], s18, v144, 0
	v_add3_u32 v97, v97, v99, v98
	v_lshl_add_u64 v[96:97], v[96:97], 1, s[16:17]
	v_pk_mul_f32 v[88:89], v[88:89], v[168:169]
	v_lshl_add_u64 v[96:97], v[96:97], 0, v[200:201]
	v_pk_mul_f32 v[94:95], v[94:95], v[186:187] op_sel_hi:[1,0]
	v_pk_mul_f32 v[92:93], v[92:93], v[186:187] op_sel_hi:[1,0]
	v_pk_mul_f32 v[90:91], v[90:91], v[186:187] op_sel_hi:[1,0]
	v_pk_mul_f32 v[88:89], v[88:89], v[186:187] op_sel_hi:[1,0]
	s_and_b64 vcc, exec, s[0:1]
	v_cvt_pk_bf16_f32 v98, v92, v93
	v_cvt_pk_bf16_f32 v99, v94, v95
	v_cvt_pk_bf16_f32 v100, v88, v89
	v_cvt_pk_bf16_f32 v101, v90, v91
	global_store_dwordx4 v[96:97], v[98:101], off
	s_cbranch_vccnz .LBB0_376
	s_nop 0
	v_lshlrev_b64 v[98:99], 7, v[144:145]
	v_lshl_add_u64 v[98:99], s[20:21], 0, v[98:99]
	v_mov_b32_e32 v193, v201
	v_lshl_add_u64 v[98:99], v[98:99], 0, v[192:193]
	global_store_dwordx4 v[98:99], v[92:95], off
	global_store_dwordx4 v[98:99], v[88:91], off offset:16
; __device__ __forceinline__ unsigned cvt_pk_bf16(float lo, float hi) { unsigned r; asm("v_cvt_pk_bf16_f32 %0, %1, %2" : "=v"(r) : "v"(lo), "v"(hi)); return r; }
;     __device__ __forceinline__ void operator()(const f32x4 (&acc)[2][2][4][2], const GU& u, int wr, int wc, int fr, int fq) const {
;     ...
;         for (int ai = 0; ai < 2; ++ai)
; #pragma unroll
;             for (int m = 0; m < 4; ++m) {
;                 const int row = r0 + ai * 128 + m * 16;
;                 const float rs = rsv[ai][m];
;                 bf16_t* rowp = u.out + (size_t)row * u.ldc + c0;
; #pragma unroll
;                 for (int bj = 0; bj < 2; ++bj) {
;                     if (bj == 1 && (u.mode & 8)) continue;
;                     f32x4 v0 = acc[ai][bj][m][0] * cs[bj][0] * rs, v1 = acc[ai][bj][m][1] * cs[bj][1] * rs;
;                     u32x4 w; w.x = cvt_pk_bf16(v0[0], v0[1]); w.y = cvt_pk_bf16(v0[2], v0[3]); w.z = cvt_pk_bf16(v1[0], v1[1]); w.w = cvt_pk_bf16(v1[2], v1[3]);
;                     *(u32x4*)(rowp + bj * 128) = w;
;                     if (bj == 0 && u.gates != nullptr && wc == 0) { float* gp = u.gates + (size_t)row * 32 + 8 * fq; *(f32x4*)gp = v0; *(f32x4*)(gp + 4) = v1; }
;                 }
.LBB0_376:
	s_nop 1
	v_mov_b32_e32 v88, v186
	v_mov_b32_e32 v89, v186
	v_pk_mul_f32 v[86:87], v[86:87], v[180:181]
	v_mov_b32_e32 v90, v186
	v_mov_b32_e32 v91, v186
	v_pk_mul_f32 v[82:83], v[82:83], v[182:183]
	v_pk_mul_f32 v[80:81], v[80:81], v[174:175]
	v_pk_mul_f32 v[84:85], v[84:85], v[178:179]
	v_pk_mul_f32 v[86:87], v[86:87], v[90:91]
	v_pk_mul_f32 v[90:91], v[82:83], v[90:91]
	v_pk_mul_f32 v[82:83], v[80:81], v[88:89]
	v_pk_mul_f32 v[84:85], v[84:85], v[88:89]
	v_cvt_pk_bf16_f32 v81, v86, v87
	v_cvt_pk_bf16_f32 v82, v82, v83
	v_cvt_pk_bf16_f32 v83, v90, v91
	v_pk_mul_f32 v[78:79], v[78:79], v[172:173]
	v_cvt_pk_bf16_f32 v80, v84, v85
	global_store_dwordx4 v[96:97], v[80:83], off offset:256
	v_pk_mul_f32 v[76:77], v[76:77], v[170:171]
	v_pk_mul_f32 v[74:75], v[74:75], v[176:177]
	v_mul_lo_u32 v82, s19, v146
	v_mul_lo_u32 v83, s18, v147
	v_mad_u64_u32 v[80:81], s[4:5], s18, v146, 0
	v_add3_u32 v81, v81, v83, v82
	v_lshl_add_u64 v[80:81], v[80:81], 1, s[16:17]
	v_pk_mul_f32 v[72:73], v[72:73], v[168:169]
	v_lshl_add_u64 v[80:81], v[80:81], 0, v[200:201]
	v_pk_mul_f32 v[78:79], v[78:79], v[186:187] op_sel:[0,1]
	v_pk_mul_f32 v[76:77], v[76:77], v[186:187] op_sel:[0,1]
	v_pk_mul_f32 v[74:75], v[74:75], v[186:187] op_sel:[0,1]
	v_pk_mul_f32 v[72:73], v[72:73], v[186:187] op_sel:[0,1]
	s_and_b64 vcc, exec, s[0:1]
	v_cvt_pk_bf16_f32 v82, v76, v77
	v_cvt_pk_bf16_f32 v83, v78, v79
	v_cvt_pk_bf16_f32 v84, v72, v73
	v_cvt_pk_bf16_f32 v85, v74, v75
	global_store_dwordx4 v[80:81], v[82:85], off
	s_cbranch_vccnz .LBB0_378
	s_nop 0
	v_lshlrev_b64 v[82:83], 7, v[146:147]
	v_lshl_add_u64 v[82:83], s[20:21], 0, v[82:83]
	v_mov_b32_e32 v193, v201
	v_lshl_add_u64 v[82:83], v[82:83], 0, v[192:193]
	global_store_dwordx4 v[82:83], v[76:79], off
	global_store_dwordx4 v[82:83], v[72:75], off offset:16
.LBB0_378:
	v_mov_b32_e32 v186, v187
	v_pk_mul_f32 v[70:71], v[70:71], v[180:181]
	v_mov_b32_e32 v72, v187
	v_mov_b32_e32 v73, v187
	v_pk_mul_f32 v[66:67], v[66:67], v[182:183]
	v_pk_mul_f32 v[64:65], v[64:65], v[174:175]
	v_pk_mul_f32 v[68:69], v[68:69], v[178:179]
	v_pk_mul_f32 v[70:71], v[70:71], v[72:73]
	v_pk_mul_f32 v[72:73], v[66:67], v[72:73]
	v_pk_mul_f32 v[66:67], v[64:65], v[186:187]
	v_pk_mul_f32 v[68:69], v[68:69], v[186:187]
	v_cvt_pk_bf16_f32 v65, v70, v71
	v_cvt_pk_bf16_f32 v66, v66, v67
	v_cvt_pk_bf16_f32 v67, v72, v73
	v_pk_mul_f32 v[62:63], v[62:63], v[172:173]
	v_cvt_pk_bf16_f32 v64, v68, v69
	global_store_dwordx4 v[80:81], v[64:67], off offset:256
	v_pk_mul_f32 v[60:61], v[60:61], v[170:171]
	v_pk_mul_f32 v[58:59], v[58:59], v[176:177]
	v_mul_lo_u32 v66, s19, v148
	v_mul_lo_u32 v67, s18, v149
	v_mad_u64_u32 v[64:65], s[4:5], s18, v148, 0
	v_add3_u32 v65, v65, v67, v66
	v_lshl_add_u64 v[64:65], v[64:65], 1, s[16:17]
	v_pk_mul_f32 v[56:57], v[56:57], v[168:169]
	v_lshl_add_u64 v[64:65], v[64:65], 0, v[200:201]
	v_pk_mul_f32 v[62:63], v[62:63], v[184:185] op_sel_hi:[1,0]
	v_pk_mul_f32 v[60:61], v[60:61], v[184:185] op_sel_hi:[1,0]
	v_pk_mul_f32 v[58:59], v[58:59], v[184:185] op_sel_hi:[1,0]
	v_pk_mul_f32 v[56:57], v[56:57], v[184:185] op_sel_hi:[1,0]
	s_and_b64 vcc, exec, s[0:1]
	v_cvt_pk_bf16_f32 v66, v60, v61
	v_cvt_pk_bf16_f32 v67, v62, v63
	v_cvt_pk_bf16_f32 v68, v56, v57
	v_cvt_pk_bf16_f32 v69, v58, v59
	global_store_dwordx4 v[64:65], v[66:69], off
	s_cbranch_vccnz .LBB0_380
	s_nop 0
	v_lshl_add_u64 v[66:67], s[20:21], 0, v[150:151]
	v_mov_b32_e32 v193, v201
	v_lshl_add_u64 v[66:67], v[66:67], 0, v[192:193]
	global_store_dwordx4 v[66:67], v[60:63], off
	global_store_dwordx4 v[66:67], v[56:59], off offset:16
.LBB0_380:
	s_nop 1
	v_mov_b32_e32 v56, v184
	v_mov_b32_e32 v57, v184
	v_pk_mul_f32 v[54:55], v[54:55], v[180:181]
	v_mov_b32_e32 v58, v184
	v_mov_b32_e32 v59, v184
	v_pk_mul_f32 v[50:51], v[50:51], v[182:183]
	v_pk_mul_f32 v[48:49], v[48:49], v[174:175]
	v_pk_mul_f32 v[52:53], v[52:53], v[178:179]
	v_pk_mul_f32 v[54:55], v[54:55], v[58:59]
	v_pk_mul_f32 v[58:59], v[50:51], v[58:59]
	v_pk_mul_f32 v[50:51], v[48:49], v[56:57]
	v_pk_mul_f32 v[52:53], v[52:53], v[56:57]
	v_cvt_pk_bf16_f32 v49, v54, v55
	v_cvt_pk_bf16_f32 v50, v50, v51
	v_cvt_pk_bf16_f32 v51, v58, v59
	v_pk_mul_f32 v[46:47], v[46:47], v[172:173]
	v_cvt_pk_bf16_f32 v48, v52, v53
	global_store_dwordx4 v[64:65], v[48:51], off offset:256
	v_pk_mul_f32 v[44:45], v[44:45], v[170:171]
	v_pk_mul_f32 v[42:43], v[42:43], v[176:177]
	v_mul_lo_u32 v50, s19, v152
	v_mul_lo_u32 v51, s18, v153
	v_mad_u64_u32 v[48:49], s[4:5], s18, v152, 0
	v_add3_u32 v49, v49, v51, v50
	v_lshl_add_u64 v[48:49], v[48:49], 1, s[16:17]
	v_pk_mul_f32 v[40:41], v[40:41], v[168:169]
	v_lshl_add_u64 v[48:49], v[48:49], 0, v[200:201]
	v_pk_mul_f32 v[46:47], v[46:47], v[184:185] op_sel:[0,1]
	v_pk_mul_f32 v[44:45], v[44:45], v[184:185] op_sel:[0,1]
	v_pk_mul_f32 v[42:43], v[42:43], v[184:185] op_sel:[0,1]
	v_pk_mul_f32 v[40:41], v[40:41], v[184:185] op_sel:[0,1]
	s_and_b64 vcc, exec, s[0:1]
	v_cvt_pk_bf16_f32 v50, v44, v45
	v_cvt_pk_bf16_f32 v51, v46, v47
	v_cvt_pk_bf16_f32 v52, v40, v41
	v_cvt_pk_bf16_f32 v53, v42, v43
	global_store_dwordx4 v[48:49], v[50:53], off
	s_cbranch_vccnz .LBB0_382
	s_nop 0
	v_lshl_add_u64 v[50:51], s[20:21], 0, v[154:155]
	v_mov_b32_e32 v193, v201
	v_lshl_add_u64 v[50:51], v[50:51], 0, v[192:193]
	global_store_dwordx4 v[50:51], v[44:47], off
	global_store_dwordx4 v[50:51], v[40:43], off offset:16
; __device__ __forceinline__ unsigned cvt_pk_bf16(float lo, float hi) { unsigned r; asm("v_cvt_pk_bf16_f32 %0, %1, %2" : "=v"(r) : "v"(lo), "v"(hi)); return r; }
; #define PG8_BAR __builtin_amdgcn_s_barrier()
; template <class Epi, class Sched, bool APERM = false, bool HALFN = false>
; __device__ __forceinline__ void gemm_phase(LAS unsigned char* lds, const int tid_in, const int K, const Sched& S, const Epi& E) {
;     ...
;         if (!has_next) break;
; #pragma unroll
;         for (int a = 0; a < 2; ++a)
; #pragma unroll
;             for (int b = 0; b < 2; ++b)
; #pragma unroll
;                 for (int m = 0; m < 4; ++m)
; #pragma unroll
;                     for (int n = 0; n < 2; ++n) acc[a][b][m][n] = (f32x4){0.f, 0.f, 0.f, 0.f};
;         cur = nxt; cA = nA; cB = nB; ++ui;
;         if (wr == 1) PG8_BAR;
;     __device__ __forceinline__ void operator()(const f32x4 (&acc)[2][2][4][2], const GU& u, int wr, int wc, int fr, int fq) const {
;     ...
;         for (int ai = 0; ai < 2; ++ai)
; #pragma unroll
;             for (int m = 0; m < 4; ++m) {
;                 const int row = r0 + ai * 128 + m * 16;
;                 const float rs = rsv[ai][m];
;                 bf16_t* rowp = u.out + (size_t)row * u.ldc + c0;
; #pragma unroll
;                 for (int bj = 0; bj < 2; ++bj) {
;                     if (bj == 1 && (u.mode & 8)) continue;
;                     f32x4 v0 = acc[ai][bj][m][0] * cs[bj][0] * rs, v1 = acc[ai][bj][m][1] * cs[bj][1] * rs;
;                     u32x4 w; w.x = cvt_pk_bf16(v0[0], v0[1]); w.y = cvt_pk_bf16(v0[2], v0[3]); w.z = cvt_pk_bf16(v1[0], v1[1]); w.w = cvt_pk_bf16(v1[2], v1[3]);
;                     *(u32x4*)(rowp + bj * 128) = w;
;                     if (bj == 0 && u.gates != nullptr && wc == 0) { float* gp = u.gates + (size_t)row * 32 + 8 * fq; *(f32x4*)gp = v0; *(f32x4*)(gp + 4) = v1; }
;                 }
.LBB0_382:
	v_mov_b32_e32 v184, v185
	v_pk_mul_f32 v[38:39], v[38:39], v[180:181]
	v_mov_b32_e32 v40, v185
	v_mov_b32_e32 v41, v185
	v_pk_mul_f32 v[34:35], v[34:35], v[182:183]
	v_pk_mul_f32 v[32:33], v[32:33], v[174:175]
	v_pk_mul_f32 v[36:37], v[36:37], v[178:179]
	v_pk_mul_f32 v[38:39], v[38:39], v[40:41]
	v_pk_mul_f32 v[40:41], v[34:35], v[40:41]
	v_pk_mul_f32 v[34:35], v[32:33], v[184:185]
	v_pk_mul_f32 v[36:37], v[36:37], v[184:185]
	v_cvt_pk_bf16_f32 v33, v38, v39
	v_cvt_pk_bf16_f32 v34, v34, v35
	v_cvt_pk_bf16_f32 v35, v40, v41
	v_pk_mul_f32 v[30:31], v[30:31], v[172:173]
	v_cvt_pk_bf16_f32 v32, v36, v37
	global_store_dwordx4 v[48:49], v[32:35], off offset:256
	v_pk_mul_f32 v[28:29], v[28:29], v[170:171]
	v_pk_mul_f32 v[26:27], v[26:27], v[176:177]
	v_mul_lo_u32 v34, s19, v156
	v_mul_lo_u32 v35, s18, v157
	v_mad_u64_u32 v[32:33], s[4:5], s18, v156, 0
	v_add3_u32 v33, v33, v35, v34
	v_lshl_add_u64 v[32:33], v[32:33], 1, s[16:17]
	v_pk_mul_f32 v[24:25], v[24:25], v[168:169]
	v_lshl_add_u64 v[32:33], v[32:33], 0, v[200:201]
	v_pk_mul_f32 v[30:31], v[30:31], v[190:191] op_sel_hi:[1,0]
	v_pk_mul_f32 v[28:29], v[28:29], v[190:191] op_sel_hi:[1,0]
	v_pk_mul_f32 v[26:27], v[26:27], v[190:191] op_sel_hi:[1,0]
	v_pk_mul_f32 v[24:25], v[24:25], v[190:191] op_sel_hi:[1,0]
	s_and_b64 vcc, exec, s[0:1]
	v_cvt_pk_bf16_f32 v34, v28, v29
	v_cvt_pk_bf16_f32 v35, v30, v31
	v_cvt_pk_bf16_f32 v36, v24, v25
	v_cvt_pk_bf16_f32 v37, v26, v27
	global_store_dwordx4 v[32:33], v[34:37], off
	s_cbranch_vccnz .LBB0_384
	s_nop 0
	v_lshl_add_u64 v[34:35], s[20:21], 0, v[158:159]
	v_mov_b32_e32 v193, v201
	v_lshl_add_u64 v[34:35], v[34:35], 0, v[192:193]
	global_store_dwordx4 v[34:35], v[28:31], off
	global_store_dwordx4 v[34:35], v[24:27], off offset:16
.LBB0_384:
	s_nop 1
	v_mov_b32_e32 v24, v190
	v_mov_b32_e32 v25, v190
	v_pk_mul_f32 v[22:23], v[22:23], v[180:181]
	v_mov_b32_e32 v26, v190
	v_mov_b32_e32 v27, v190
	v_pk_mul_f32 v[18:19], v[18:19], v[182:183]
	v_pk_mul_f32 v[16:17], v[16:17], v[174:175]
	v_pk_mul_f32 v[20:21], v[20:21], v[178:179]
	v_pk_mul_f32 v[22:23], v[22:23], v[26:27]
	v_pk_mul_f32 v[26:27], v[18:19], v[26:27]
	v_pk_mul_f32 v[18:19], v[16:17], v[24:25]
	v_pk_mul_f32 v[20:21], v[20:21], v[24:25]
	v_cvt_pk_bf16_f32 v17, v22, v23
	v_cvt_pk_bf16_f32 v18, v18, v19
	v_cvt_pk_bf16_f32 v19, v26, v27
	v_pk_mul_f32 v[14:15], v[14:15], v[172:173]
	v_cvt_pk_bf16_f32 v16, v20, v21
	global_store_dwordx4 v[32:33], v[16:19], off offset:256
	v_pk_mul_f32 v[12:13], v[12:13], v[170:171]
	v_pk_mul_f32 v[10:11], v[10:11], v[176:177]
	v_mul_lo_u32 v18, s19, v160
	v_mul_lo_u32 v19, s18, v161
	v_mad_u64_u32 v[16:17], s[4:5], s18, v160, 0
	v_add3_u32 v17, v17, v19, v18
	v_lshl_add_u64 v[16:17], v[16:17], 1, s[16:17]
	v_pk_mul_f32 v[8:9], v[8:9], v[168:169]
	v_lshl_add_u64 v[16:17], v[16:17], 0, v[200:201]
	v_pk_mul_f32 v[14:15], v[14:15], v[190:191] op_sel:[0,1]
	v_pk_mul_f32 v[12:13], v[12:13], v[190:191] op_sel:[0,1]
	v_pk_mul_f32 v[10:11], v[10:11], v[190:191] op_sel:[0,1]
	v_pk_mul_f32 v[8:9], v[8:9], v[190:191] op_sel:[0,1]
	s_and_b64 vcc, exec, s[0:1]
	v_cvt_pk_bf16_f32 v18, v12, v13
	v_cvt_pk_bf16_f32 v19, v14, v15
	v_cvt_pk_bf16_f32 v20, v8, v9
	v_cvt_pk_bf16_f32 v21, v10, v11
	global_store_dwordx4 v[16:17], v[18:21], off
	s_cbranch_vccnz .LBB0_386
	s_nop 0
	v_lshl_add_u64 v[18:19], s[20:21], 0, v[162:163]
	v_mov_b32_e32 v193, v201
	v_lshl_add_u64 v[18:19], v[18:19], 0, v[192:193]
	global_store_dwordx4 v[18:19], v[12:15], off
	global_store_dwordx4 v[18:19], v[8:11], off offset:16
.LBB0_386:
	v_mov_b32_e32 v190, v191
	v_pk_mul_f32 v[6:7], v[6:7], v[180:181]
	v_mov_b32_e32 v8, v191
	v_mov_b32_e32 v9, v191
	v_pk_mul_f32 v[2:3], v[2:3], v[182:183]
	v_pk_mul_f32 v[0:1], v[0:1], v[174:175]
	v_pk_mul_f32 v[4:5], v[4:5], v[178:179]
	v_pk_mul_f32 v[6:7], v[6:7], v[8:9]
	v_pk_mul_f32 v[8:9], v[2:3], v[8:9]
	v_pk_mul_f32 v[2:3], v[0:1], v[190:191]
	s_andn2_b64 vcc, exec, s[14:15]
	s_mov_b64 s[0:1], -1
	v_readlane_b32 s19, v255, 1
	v_pk_mul_f32 v[4:5], v[4:5], v[190:191]
	v_cvt_pk_bf16_f32 v1, v6, v7
	v_cvt_pk_bf16_f32 v2, v2, v3
	v_cvt_pk_bf16_f32 v3, v8, v9
	s_nop 0
	v_cvt_pk_bf16_f32 v0, v4, v5
	global_store_dwordx4 v[16:17], v[0:3], off offset:256
	s_cbranch_vccnz .LBB0_335
	s_andn2_b64 vcc, exec, s[2:3]
	s_cbranch_vccnz .LBB0_334
	s_barrier
	s_branch .LBB0_334

; __global__ void __launch_bounds__(512, 2) hybrid_fwd(Params p) {
;     ...
;                     float base = 0.f;
; #pragma unroll
;                     for (int g = 0; g < 8; ++g) if (g < wave) base += wt[g];
;                     const float excl = base + xs - run;
; #pragma unroll
;                     for (int j = 0; j < 16; ++j) CC[(size_t)hd * T_ + tid * 16 + j] = excl + pre[j];
;                     __syncthreads();
.LBB0_444:
	v_cndmask_b32_e64 v69, v70, v69, s[14:15]
	v_add_f32_e32 v69, v69, v71
	v_sub_f32_e32 v70, v69, v15
	s_lshl_b64 s[18:19], s[2:3], 15
	v_lshl_add_u64 v[72:73], v[16:17], 0, s[18:19]
	v_pk_add_f32 v[0:1], v[70:71], v[0:1] op_sel_hi:[0,1]
	v_pk_add_f32 v[2:3], v[70:71], v[2:3] op_sel_hi:[0,1]
	global_store_dwordx4 v[72:73], v[0:3], off
	s_nop 1
	v_pk_add_f32 v[0:1], v[70:71], v[4:5] op_sel_hi:[0,1]
	v_pk_add_f32 v[2:3], v[70:71], v[6:7] op_sel_hi:[0,1]
	global_store_dwordx4 v[72:73], v[0:3], off offset:16
	s_nop 1
	v_pk_add_f32 v[0:1], v[70:71], v[8:9] op_sel_hi:[0,1]
	v_pk_add_f32 v[2:3], v[70:71], v[10:11] op_sel_hi:[0,1]
	global_store_dwordx4 v[72:73], v[0:3], off offset:32
	s_nop 1
	v_pk_add_f32 v[0:1], v[70:71], v[12:13] op_sel_hi:[0,1]
	v_pk_add_f32 v[2:3], v[70:71], v[14:15] op_sel_hi:[0,1]
	global_store_dwordx4 v[72:73], v[0:3], off offset:48
	s_waitcnt lgkmcnt(0)
	s_barrier

; __device__ __forceinline__ float bflo(unsigned w) { return __uint_as_float(w << 16); }
; __device__ __forceinline__ float bfhi(unsigned w) { return __uint_as_float(w & 0xffff0000u); }
; __device__ __forceinline__ float shx(float v, int off, int lane) { return __int_as_float(__builtin_amdgcn_ds_bpermute((lane ^ off) << 2, __float_as_int(v))); }
; __global__ void __launch_bounds__(512, 2) hybrid_fwd(Params p) {
;     ...
;                     const int v = u - 516, hd = v >> 4, sl = v & 15; float mxn = 0.f;
; #pragma unroll 4
;                     for (int ps = 0; ps < 16; ++ps) {
;                         const int key = sl * 512 + ps * 32 + (tid >> 4);
;                         const u32x4 kk = *(const u32x4*)(PROJ + (size_t)key * NP + PJ_FK + hd * 128 + (tid & 15) * 8);
;                         float q2 = bflo(kk.x) * bflo(kk.x) + bfhi(kk.x) * bfhi(kk.x) + bflo(kk.y) * bflo(kk.y) + bfhi(kk.y) * bfhi(kk.y) + bflo(kk.z) * bflo(kk.z) + bfhi(kk.z) * bfhi(kk.z) + bflo(kk.w) * bflo(kk.w) + bfhi(kk.w) * bfhi(kk.w);
;                         q2 += shx(q2, 1, lane); q2 += shx(q2, 2, lane); q2 += shx(q2, 4, lane); q2 += shx(q2, 8, lane);
;                         mxn = fmaxf(mxn, q2);
;                     }
;                     mxn = fmaxf(mxn, shx(mxn, 16, lane)); mxn = fmaxf(mxn, shx(mxn, 32, lane));
;                     if (lane == 0) atomicMax(KNB + l * 4 + hd, __float_as_uint(mxn));
.LBB0_449:
	v_lshl_add_u64 v[10:11], v[6:7], 0, s[18:19]
	global_load_dwordx4 v[10:13], v[10:11], off
	s_waitcnt vmcnt(0) lgkmcnt(0)
	v_lshlrev_b32_e32 v14, 16, v10
	v_and_b32_e32 v15, 0xffff0000, v10
	v_pk_mul_f32 v[14:15], v[14:15], v[14:15]
	v_and_b32_e32 v10, 0xffff0000, v11
	v_lshlrev_b32_e32 v11, 16, v11
	v_pk_mul_f32 v[10:11], v[10:11], v[10:11]
	v_add_f32_e32 v9, v14, v15
	v_and_b32_e32 v70, 0xffff0000, v12
	v_lshlrev_b32_e32 v71, 16, v12
	v_add_f32_e32 v9, v11, v9
	v_pk_mul_f32 v[70:71], v[70:71], v[70:71]
	v_add_f32_e32 v9, v10, v9
	v_and_b32_e32 v12, 0xffff0000, v13
	v_lshlrev_b32_e32 v13, 16, v13
	v_add_f32_e32 v9, v71, v9
	v_pk_mul_f32 v[12:13], v[12:13], v[12:13]
	v_add_f32_e32 v9, v70, v9
	v_add_f32_e32 v9, v13, v9
	v_add_f32_e32 v9, v12, v9
	ds_bpermute_b32 v10, v54, v9
	s_waitcnt lgkmcnt(0)
	v_add_f32_e32 v9, v9, v10
	ds_bpermute_b32 v10, v55, v9
	s_waitcnt lgkmcnt(0)
	v_add_f32_e32 v9, v9, v10
	ds_bpermute_b32 v10, v56, v9
	s_waitcnt lgkmcnt(0)
	v_add_f32_e32 v9, v9, v10
	ds_bpermute_b32 v10, v57, v9
	s_waitcnt lgkmcnt(0)
	v_add_f32_e32 v9, v9, v10
	v_lshl_add_u64 v[10:11], v[4:5], 0, s[18:19]
	global_load_dwordx4 v[10:13], v[10:11], off
	s_waitcnt vmcnt(0) lgkmcnt(0)
	v_lshlrev_b32_e32 v14, 16, v10
	v_and_b32_e32 v15, 0xffff0000, v10
	v_pk_mul_f32 v[14:15], v[14:15], v[14:15]
	v_and_b32_e32 v10, 0xffff0000, v11
	v_lshlrev_b32_e32 v11, 16, v11
	v_pk_mul_f32 v[10:11], v[10:11], v[10:11]
	v_add_f32_e32 v14, v14, v15
	v_and_b32_e32 v70, 0xffff0000, v12
	v_lshlrev_b32_e32 v71, 16, v12
	v_add_f32_e32 v11, v11, v14
	v_pk_mul_f32 v[70:71], v[70:71], v[70:71]
	v_add_f32_e32 v10, v10, v11
	v_and_b32_e32 v12, 0xffff0000, v13
	v_lshlrev_b32_e32 v13, 16, v13
	v_add_f32_e32 v10, v71, v10
	v_pk_mul_f32 v[12:13], v[12:13], v[12:13]
	v_add_f32_e32 v10, v70, v10
	v_add_f32_e32 v10, v13, v10
	v_add_f32_e32 v10, v12, v10
	ds_bpermute_b32 v11, v54, v10
	s_waitcnt lgkmcnt(0)
	v_add_f32_e32 v10, v10, v11
	ds_bpermute_b32 v11, v55, v10
	s_waitcnt lgkmcnt(0)
	v_add_f32_e32 v10, v10, v11
	ds_bpermute_b32 v11, v56, v10
	s_waitcnt lgkmcnt(0)
	v_add_f32_e32 v10, v10, v11
	ds_bpermute_b32 v11, v57, v10
	s_waitcnt lgkmcnt(0)
	v_add_f32_e32 v10, v10, v11
	v_max3_f32 v69, v8, v9, v10
	v_lshl_add_u64 v[8:9], v[2:3], 0, s[18:19]
	global_load_dwordx4 v[8:11], v[8:9], off
	s_waitcnt vmcnt(0) lgkmcnt(0)
	v_lshlrev_b32_e32 v12, 16, v8
	v_and_b32_e32 v13, 0xffff0000, v8
	v_pk_mul_f32 v[12:13], v[12:13], v[12:13]
	v_and_b32_e32 v8, 0xffff0000, v9
	v_lshlrev_b32_e32 v9, 16, v9
	v_pk_mul_f32 v[8:9], v[8:9], v[8:9]
	v_add_f32_e32 v12, v12, v13
	v_and_b32_e32 v14, 0xffff0000, v10
	v_lshlrev_b32_e32 v15, 16, v10
	v_add_f32_e32 v9, v9, v12
	v_pk_mul_f32 v[14:15], v[14:15], v[14:15]
	v_add_f32_e32 v8, v8, v9
	v_and_b32_e32 v10, 0xffff0000, v11
	v_lshlrev_b32_e32 v11, 16, v11
	v_add_f32_e32 v8, v15, v8
	v_pk_mul_f32 v[10:11], v[10:11], v[10:11]
	v_add_f32_e32 v8, v14, v8
	v_add_f32_e32 v8, v11, v8
	v_add_f32_e32 v8, v10, v8
	ds_bpermute_b32 v9, v54, v8
	s_waitcnt lgkmcnt(0)
	v_add_f32_e32 v8, v8, v9
	ds_bpermute_b32 v9, v55, v8
	s_waitcnt lgkmcnt(0)
	v_add_f32_e32 v8, v8, v9
	ds_bpermute_b32 v9, v56, v8
	s_waitcnt lgkmcnt(0)
	v_add_f32_e32 v8, v8, v9
	ds_bpermute_b32 v9, v57, v8
	s_waitcnt lgkmcnt(0)
	v_add_f32_e32 v70, v8, v9
	v_lshl_add_u64 v[8:9], v[0:1], 0, s[18:19]
	global_load_dwordx4 v[8:11], v[8:9], off
	s_add_u32 s18, s18, 0xe0000
	s_addc_u32 s19, s19, 0
	s_cmp_eq_u32 s18, 0x380000
	s_waitcnt vmcnt(0) lgkmcnt(0)
	v_lshlrev_b32_e32 v12, 16, v8
	v_and_b32_e32 v13, 0xffff0000, v8
	v_pk_mul_f32 v[12:13], v[12:13], v[12:13]
	v_and_b32_e32 v8, 0xffff0000, v9
	v_lshlrev_b32_e32 v9, 16, v9
	v_pk_mul_f32 v[8:9], v[8:9], v[8:9]
	v_add_f32_e32 v12, v12, v13
	v_and_b32_e32 v14, 0xffff0000, v10
	v_lshlrev_b32_e32 v15, 16, v10
	v_add_f32_e32 v9, v9, v12
	v_pk_mul_f32 v[14:15], v[14:15], v[14:15]
	v_add_f32_e32 v8, v8, v9
	v_and_b32_e32 v10, 0xffff0000, v11
	v_lshlrev_b32_e32 v11, 16, v11
	v_add_f32_e32 v8, v15, v8
	v_pk_mul_f32 v[10:11], v[10:11], v[10:11]
	v_add_f32_e32 v8, v14, v8
	v_add_f32_e32 v8, v11, v8
	v_add_f32_e32 v8, v10, v8
	ds_bpermute_b32 v9, v54, v8
	s_waitcnt lgkmcnt(0)
	v_add_f32_e32 v8, v8, v9
	ds_bpermute_b32 v9, v55, v8
	s_waitcnt lgkmcnt(0)
	v_add_f32_e32 v8, v8, v9
	ds_bpermute_b32 v9, v56, v8
	s_waitcnt lgkmcnt(0)
	v_add_f32_e32 v8, v8, v9
	ds_bpermute_b32 v9, v57, v8
	s_waitcnt lgkmcnt(0)
	v_add_f32_e32 v8, v8, v9
	v_max3_f32 v8, v69, v70, v8
	s_cbranch_scc0 .LBB0_449
	ds_bpermute_b32 v0, v58, v8
	v_max_f32_e32 v1, v8, v8
	s_waitcnt lgkmcnt(0)
	v_max_f32_e32 v0, v0, v0
	v_max_f32_e32 v0, v1, v0
	ds_bpermute_b32 v1, v59, v0
	s_and_saveexec_b64 s[18:19], s[0:1]
	s_cbranch_execz .LBB0_452
	s_add_i32 s3, s2, 0xfffffdfc
	s_lshr_b32 s3, s3, 2
	s_and_b32 s3, s3, 0x3ffffffc
	v_readlane_b32 s35, v255, 45
	s_add_u32 s44, s35, s3
	v_readlane_b32 s3, v255, 44
	s_waitcnt lgkmcnt(0)
	v_max_f32_e32 v1, v1, v1
	v_max_f32_e32 v0, v0, v0
	s_addc_u32 s45, s3, 0
	v_max_f32_e32 v2, v0, v1
	v_mov_b64_e32 v[0:1], s[44:45]
	global_atomic_umax v[0:1], v2, off

; #define LAS __attribute__((address_space(3)))
; template <int MODEC>
; __device__ __forceinline__ void gla_unit(LAS unsigned char* lds, const int tid_in, const Params& p, int l, int hh, int n) {
;     ...
;     const int t0 = 64 * n;
;     {
;         const int d = lane; const float* wg = p.w_gla_gate + (size_t)l * 16 * 256 + hh * 64 + d; const float bgv = p.b_gla_gate[l * 256 + hh * 64 + d];
;         float wgr[16];
; #pragma unroll
;         for (int q = 0; q < 16; ++q) wgr[q] = wg[q * 256];
;         LAS float* gl = (LAS float*)(lds + 38400);
;         if (tid < 256) *(LAS f32x4*)(gl + (tid >> 2) * 16 + (tid & 3) * 4) = *(const f32x4*)(gates + (size_t)(t0 + (tid >> 2)) * 32 + 4 + (tid & 3) * 4);
.LBB0_453:
	s_and_b64 vcc, exec, s[18:19]
	s_cbranch_vccz .LBB0_473
	s_add_i32 s45, s2, -4
	s_lshr_b32 s3, s45, 7
	s_lshl_b32 s72, s3, 6
	s_and_b32 s44, s45, 0x7f
	s_lshl_b64 s[18:19], s[72:73], 2
	v_mov_b32_e32 v4, v52
	s_add_u32 s18, s57, s18
	s_addc_u32 s19, s95, s19
	v_and_b32_e32 v10, 63, v4
	s_add_i32 s35, s72, s38
	v_or_b32_e32 v0, s35, v10
	s_waitcnt lgkmcnt(0)
	v_mov_b32_e32 v1, v201
	s_mov_b64 s[74:75], s[50:51]
	v_lshlrev_b32_e32 v200, 2, v10
	v_lshl_add_u64 v[0:1], v[0:1], 2, s[66:67]
	v_lshl_add_u64 v[70:71], s[18:19], 0, v[200:201]
	global_load_dword v0, v[0:1], off
	s_nop 0
	global_load_dword v1, v200, s[18:19]
	global_load_dword v2, v200, s[18:19] offset:1024
	global_load_dword v3, v200, s[18:19] offset:2048
	global_load_dword v5, v200, s[18:19] offset:3072
	s_movk_i32 s18, 0x1000
	v_add_co_u32_e32 v8, vcc, s18, v70
	s_movk_i32 s18, 0x100
	s_nop 0
	v_addc_co_u32_e32 v9, vcc, 0, v71, vcc
	v_add_co_u32_e32 v72, vcc, s89, v70
	v_readfirstlane_b32 s52, v4
	s_nop 0
	v_addc_co_u32_e32 v73, vcc, 0, v71, vcc
	global_load_dword v14, v[72:73], off offset:-4096
	global_load_dword v6, v[8:9], off offset:1024
	global_load_dword v7, v[8:9], off offset:2048
	s_nop 0
	global_load_dword v8, v[8:9], off offset:3072
	s_nop 0
	global_load_dword v9, v[72:73], off
	global_load_dword v11, v[72:73], off offset:1024
	global_load_dword v12, v[72:73], off offset:2048
	global_load_dword v13, v[72:73], off offset:3072
	v_add_co_u32_e32 v72, vcc, 0x3000, v70
	s_lshl_b32 s53, s44, 6
	s_nop 0
	v_addc_co_u32_e32 v73, vcc, 0, v71, vcc
	global_load_dword v71, v[72:73], off
	global_load_dword v70, v[72:73], off offset:1024
	global_load_dword v69, v[72:73], off offset:2048
	global_load_dword v15, v[72:73], off offset:3072
	v_cmp_gt_i32_e32 vcc, s18, v4
	s_and_saveexec_b64 s[18:19], vcc
	s_cbranch_execz .LBB0_456
	v_ashrrev_i32_e32 v78, 2, v4
	v_add_u32_e32 v72, s53, v78
	v_ashrrev_i32_e32 v73, 31, v72
	v_lshlrev_b64 v[72:73], 7, v[72:73]
	v_lshlrev_b32_e32 v74, 4, v4
	v_lshl_add_u64 v[72:73], s[74:75], 0, v[72:73]
	v_and_b32_e32 v76, 48, v74
	v_mov_b32_e32 v77, v201
	v_lshl_add_u64 v[72:73], v[72:73], 0, v[76:77]
	v_add_co_u32_e32 v72, vcc, 0x22e00000, v72
	v_lshlrev_b32_e32 v77, 6, v78
	s_nop 0
	v_addc_co_u32_e32 v73, vcc, 0, v73, vcc
	global_load_dwordx4 v[72:75], v[72:73], off offset:16
	v_add3_u32 v76, 0, v77, v76
	s_waitcnt vmcnt(0) lgkmcnt(0)
	ds_write_b128 v76, v[72:75] offset:38400

; #define LAS __attribute__((address_space(3)))
; __device__ __forceinline__ unsigned cvt_pk_bf16(float lo, float hi) { unsigned r; asm("v_cvt_pk_bf16_f32 %0, %1, %2" : "=v"(r) : "v"(lo), "v"(hi)); return r; }
; __device__ __forceinline__ float bflo(unsigned w) { return __uint_as_float(w << 16); }
; __device__ __forceinline__ float bfhi(unsigned w) { return __uint_as_float(w & 0xffff0000u); }
; #define MFMA32(a, b, c) __builtin_amdgcn_mfma_f32_32x32x16_bf16((a), (b), (c), 0, 0, 0)
; template <int MODEC>
; __device__ __forceinline__ void gla_unit(LAS unsigned char* lds, const int tid_in, const Params& p, int l, int hh, int n) {
;     ...
;     const int s = tid >> 3, dk8 = (tid & 7) * 8;
;     if (MODEC == 0) {
;         const u32x4 kk = *(const u32x4*)(proj + (size_t)(t0 + s) * NP + PJ_GK + hh * 64 + dk8);
;         const unsigned kw[4] = {kk.x, kk.y, kk.z, kk.w};
; #pragma unroll
;         for (int j = 0; j < 8; ++j) { const float kf = ((j & 1) ? bfhi(kw[j >> 1]) : bflo(kw[j >> 1])) * __expf(blast[dk8 + j] - bmat[s * 64 + dk8 + j]);
;             QT[(dk8 + j) * 72 + s] = (bf16_t)(cvt_pk_bf16(kf, 0.f) & 0xffffu); }
;         if (tid < 64) dec[(size_t)(hh * 128 + n) * 64 + tid] = __expf(blast[tid]);
;         __syncthreads();
;         const int dvb = w & 3, dkb = w >> 2;
;         f32x16 acc;
; #pragma unroll
;         for (int i = 0; i < 16; ++i) acc[i] = 0.f;
;         bf16x8 va[4];
; #pragma unroll
;         for (int ks = 0; ks < 4; ++ks) va[ks] = *(const bf16x8*)(vT + (size_t)(VT_G + hh * 128 + 32 * dvb + r) * T_ + t0 + 16 * ks + 8 * h2);
; #pragma unroll
;         for (int ks = 0; ks < 4; ++ks) {
;             const bf16x8 b = *(const LAS bf16x8*)(QT + (32 * dkb + r) * 72 + 16 * ks + 8 * h2);
;             acc = MFMA32(va[ks], b, acc);
;         }
;         float* kp = kvb + (size_t)(hh * 128 + n) * 128 * 64 + 32 * dkb + r;
; #pragma unroll
;         for (int i = 0; i < 16; ++i) { const int dv = 32 * dvb + (i & 3) + 8 * (i >> 2) + 4 * h2; kp[(size_t)dv * 64] = acc[i]; }
;         __syncthreads();
.LBB0_458:
	v_ashrrev_i32_e32 v5, 3, v4
	v_lshlrev_b32_e32 v0, 3, v4
	v_and_b32_e32 v11, 56, v0
	v_add_u32_e32 v2, s53, v5
	v_mov_b64_e32 v[0:1], s[74:75]
	v_mad_i64_i32 v[0:1], s[18:19], v2, s56, v[0:1]
	s_lshl_b32 s72, s72, 1
	v_lshl_add_u64 v[0:1], v[0:1], 0, s[72:73]
	v_lshlrev_b32_e32 v200, 1, v11
	v_lshl_add_u64 v[0:1], v[0:1], 0, v[200:201]
	s_mov_b32 s18, 0x1f601000
	v_add_co_u32_e32 v0, vcc, s18, v0
	s_waitcnt lgkmcnt(0)
	s_nop 0
	v_addc_co_u32_e32 v1, vcc, 0, v1, vcc
	s_barrier
	global_load_dwordx4 v[0:3], v[0:1], off offset:1024
	v_lshl_add_u32 v6, v11, 2, 0
	v_add_u32_e32 v75, 0x4800, v6
	v_lshl_add_u32 v69, v5, 8, v6
	ds_read2_b32 v[6:7], v75 offset1:1
	ds_read2_b32 v[8:9], v75 offset0:2 offset1:3
	ds_read2_b32 v[12:13], v75 offset0:4 offset1:5
	ds_read2_b32 v[14:15], v69 offset1:1
	ds_read2_b32 v[70:71], v69 offset0:2 offset1:3
	ds_read2_b32 v[72:73], v69 offset0:4 offset1:5
	v_lshlrev_b32_e32 v5, 1, v5
	v_mul_u32_u24_e32 v11, 0x90, v11
	s_waitcnt lgkmcnt(0)
	v_sub_f32_e32 v6, v6, v14
	v_mul_f32_e32 v6, 0x3fb8aa3b, v6
	v_exp_f32_e32 v6, v6
	v_add3_u32 v5, 0, v5, v11
	v_cmp_gt_i32_e32 vcc, 64, v4
	s_waitcnt vmcnt(0)
	v_lshlrev_b32_e32 v74, 16, v0
	v_mul_f32_e32 v6, v6, v74
	v_cvt_pk_bf16_f32 v6, v6, v201
	ds_write_b16 v5, v6 offset:18688
	v_sub_f32_e32 v6, v7, v15
	v_mul_f32_e32 v6, 0x3fb8aa3b, v6
	v_exp_f32_e32 v6, v6
	v_and_b32_e32 v0, 0xffff0000, v0
	v_mul_f32_e32 v0, v6, v0
	v_sub_f32_e32 v6, v8, v70
	v_mul_f32_e32 v6, 0x3fb8aa3b, v6
	v_exp_f32_e32 v6, v6
	v_cvt_pk_bf16_f32 v0, v0, v201
	ds_write_b16 v5, v0 offset:18832
	v_lshlrev_b32_e32 v0, 16, v1
	v_mul_f32_e32 v0, v6, v0
	v_cvt_pk_bf16_f32 v0, v0, v201
	ds_write_b16 v5, v0 offset:18976
	v_and_b32_e32 v0, 0xffff0000, v1
	v_sub_f32_e32 v1, v9, v71
	v_mul_f32_e32 v1, 0x3fb8aa3b, v1
	v_exp_f32_e32 v1, v1
	s_nop 0
	v_mul_f32_e32 v0, v1, v0
	v_sub_f32_e32 v1, v12, v72
	v_mul_f32_e32 v1, 0x3fb8aa3b, v1
	v_exp_f32_e32 v1, v1
	v_cvt_pk_bf16_f32 v0, v0, v201
	ds_write_b16 v5, v0 offset:19120
	v_lshlrev_b32_e32 v0, 16, v2
	v_mul_f32_e32 v0, v1, v0
	v_sub_f32_e32 v1, v13, v73
	v_mul_f32_e32 v1, 0x3fb8aa3b, v1
	v_exp_f32_e32 v1, v1
	v_cvt_pk_bf16_f32 v0, v0, v201
	ds_write_b16 v5, v0 offset:19264
	v_and_b32_e32 v0, 0xffff0000, v2
	v_mul_f32_e32 v0, v1, v0
	v_cvt_pk_bf16_f32 v0, v0, v201
	ds_write_b16 v5, v0 offset:19408
	ds_read2_b32 v[0:1], v75 offset0:6 offset1:7
	ds_read2_b32 v[6:7], v69 offset0:6 offset1:7
	v_lshlrev_b32_e32 v2, 16, v3
	s_waitcnt lgkmcnt(0)
	v_sub_f32_e32 v0, v0, v6
	v_mul_f32_e32 v0, 0x3fb8aa3b, v0
	v_exp_f32_e32 v0, v0
	v_sub_f32_e32 v1, v1, v7
	v_mul_f32_e32 v1, 0x3fb8aa3b, v1
	v_exp_f32_e32 v1, v1
	v_mul_f32_e32 v0, v0, v2
	v_cvt_pk_bf16_f32 v0, v0, v201
	ds_write_b16 v5, v0 offset:19552
	v_and_b32_e32 v0, 0xffff0000, v3
	v_mul_f32_e32 v0, v1, v0
	v_cvt_pk_bf16_f32 v0, v0, v201
	ds_write_b16 v5, v0 offset:19696
	s_and_saveexec_b64 s[18:19], vcc
	s_cbranch_execz .LBB0_460
	v_lshl_add_u32 v0, v4, 2, 0
	ds_read_b32 v2, v0 offset:18432
	s_lshl_b32 s72, s3, 13
	s_or_b32 s72, s53, s72
	s_lshl_b64 vcc, s[72:73], 2
	s_add_u32 vcc_lo, s74, vcc_lo
	s_waitcnt lgkmcnt(0)
	v_mul_f32_e32 v2, 0x3fb8aa3b, v2
	s_addc_u32 vcc_hi, s75, vcc_hi
	v_ashrrev_i32_e32 v5, 31, v4
	v_exp_f32_e32 v2, v2
	v_lshl_add_u64 v[0:1], v[4:5], 2, vcc
	v_add_co_u32_e32 v0, vcc, 0x38e00000, v0
	s_nop 1
	v_addc_co_u32_e32 v1, vcc, 0, v1, vcc
	global_store_dword v[0:1], v2, off
.LBB0_460:
	s_or_b64 exec, exec, s[18:19]
	s_lshl_b32 s19, s35, 5
	s_and_b32 s18, s45, 0x7ff80
	s_and_b32 s35, s19, 0x60
	s_or_b32 s18, s18, s35
	v_and_b32_e32 v69, 31, v4
	s_addk_i32 s18, 0x300
	v_or_b32_e32 v0, s18, v69
	v_lshlrev_b32_e32 v200, 13, v0
	v_lshrrev_b32_e32 v8, 5, v10
	v_lshl_add_u64 v[0:1], v[200:201], 1, s[74:75]
	s_lshl_b32 s72, s53, 1
	v_lshl_add_u64 v[0:1], v[0:1], 0, s[72:73]
	v_lshlrev_b32_e32 v200, 4, v8
	v_lshl_add_u64 v[6:7], v[0:1], 0, v[200:201]
	s_mov_b32 s18, 0x22f00000
	v_add_co_u32_e32 v0, vcc, s18, v6
	s_waitcnt lgkmcnt(0)
	s_nop 0
	v_addc_co_u32_e32 v1, vcc, 0, v7, vcc
	s_barrier
	global_load_dwordx4 v[0:3], v[0:1], off
	s_mov_b64 s[18:19], 0x22f00000
	v_lshl_add_u64 v[6:7], v[6:7], 0, s[18:19]
	global_load_dwordx4 v[70:73], v[6:7], off offset:32
	global_load_dwordx4 v[74:77], v[6:7], off offset:64
	global_load_dwordx4 v[78:81], v[6:7], off offset:96
	s_ashr_i32 s18, s52, 3
	s_lshl_b32 s19, s44, 13
	v_mov_b32_e32 v5, s18
	s_movk_i32 s44, 0xffe0
	v_bfi_b32 v4, s44, v5, v4
	v_mul_lo_u32 v4, v4, s83
	v_add3_u32 v90, 0, v4, v200
	ds_read_b128 v[4:7], v90 offset:18688
	ds_read_b128 v[82:85], v90 offset:18720
	v_lshlrev_b32_e32 v94, 10, v8
	ds_read_b128 v[86:89], v90 offset:18752
	ds_read_b128 v[90:93], v90 offset:18784
	s_lshl_b32 s3, s3, 20
	s_or_b32 s72, s19, s3
	s_andn2_b32 s18, s18, 31
	s_lshl_b64 s[44:45], s[72:73], 2
	s_add_u32 s3, s74, s44
	s_addc_u32 s44, s75, s45
	s_ashr_i32 s19, s18, 31
	s_lshl_b64 s[18:19], s[18:19], 2
	s_add_u32 s18, s3, s18
	v_lshlrev_b32_e32 v200, 2, v69
	s_addc_u32 s19, s44, s19
	s_mov_b32 s3, 0x37e00000
	s_waitcnt vmcnt(0) lgkmcnt(0)
	v_mfma_f32_32x32x16_bf16 v[0:15], v[0:3], v[4:7], 0
	v_mfma_f32_32x32x16_bf16 v[0:15], v[70:73], v[82:85], v[0:15]
	v_lshl_add_u64 v[70:71], s[18:19], 0, v[200:201]
	v_lshl_or_b32 v200, s35, 8, v94
	v_lshl_add_u64 v[70:71], v[70:71], 0, v[200:201]
	s_mov_b64 s[18:19], 0x37e00000
	v_lshl_add_u64 v[72:73], v[70:71], 0, s[18:19]
	s_mov_b64 s[18:19], 0
	v_mfma_f32_32x32x16_bf16 v[0:15], v[74:77], v[86:89], v[0:15]
	v_add_co_u32_e32 v74, vcc, s3, v70
	s_mov_b32 s3, 0x37e01000
	s_nop 0
	v_addc_co_u32_e32 v75, vcc, 0, v71, vcc
	v_add_co_u32_e32 v70, vcc, s3, v70
	v_mfma_f32_32x32x16_bf16 v[0:15], v[78:81], v[90:93], v[0:15]
	s_nop 0
	v_addc_co_u32_e32 v71, vcc, 0, v71, vcc
	s_nop 9
	global_store_dword v[74:75], v0, off
	global_store_dword v[72:73], v1, off offset:256
	global_store_dword v[72:73], v2, off offset:512
	global_store_dword v[72:73], v3, off offset:768
	global_store_dword v[72:73], v4, off offset:2048
	global_store_dword v[72:73], v5, off offset:2304
	global_store_dword v[72:73], v6, off offset:2560
	global_store_dword v[72:73], v7, off offset:2816
	global_store_dword v[70:71], v8, off
	global_store_dword v[70:71], v9, off offset:256
	global_store_dword v[70:71], v10, off offset:512
	global_store_dword v[70:71], v11, off offset:768
	global_store_dword v[70:71], v12, off offset:2048
	global_store_dword v[70:71], v13, off offset:2304
	global_store_dword v[70:71], v14, off offset:2560
	global_store_dword v[70:71], v15, off offset:2816
	s_waitcnt lgkmcnt(0)
	s_barrier

; __device__ __forceinline__ float logsig(float x) { return fminf(x, 0.f) - __logf(1.f + __expf(-fabsf(x))); }
; __global__ void __launch_bounds__(512, 2) hybrid_fwd(Params p) {
;     ...
; #pragma unroll
;                     for (int j = 0; j < 16; ++j) { run += logsig(GATES[(size_t)(tid * 16 + j) * 32 + hd] + bf); pre[j] = run; }
;                     float xs = run;
; #pragma unroll
.LBB0_462:
	s_add_i32 s18, s2, s20
	s_ashr_i32 s19, s18, 31
	s_lshl_b64 s[18:19], s[18:19], 2
	s_add_u32 s18, s58, s18
	s_addc_u32 s19, s59, s19
	s_ashr_i32 s3, s2, 31
	global_load_dword v14, v201, s[18:19]
	s_lshl_b64 s[18:19], s[2:3], 2
	s_add_u32 s74, s39, s18
	s_addc_u32 s75, s76, s19
	s_waitcnt lgkmcnt(0)
	v_lshl_add_u64 v[0:1], s[74:75], 0, v[18:19]
	global_load_dword v0, v[0:1], off
	v_lshl_add_u64 v[70:71], s[74:75], 0, v[46:47]
	s_waitcnt vmcnt(0) lgkmcnt(0)
	v_add_f32_e32 v0, v14, v0
	v_min_f32_e32 v1, 0, v0
	v_mul_f32_e64 v0, |v0|, s68
	v_exp_f32_e32 v0, v0
	s_nop 0
	v_add_f32_e32 v0, 1.0, v0
	v_cmp_gt_f32_e32 vcc, s85, v0
	s_nop 1
	v_cndmask_b32_e64 v2, 0, 32, vcc
	v_ldexp_f32 v0, v0, v2
	v_log_f32_e32 v0, v0
	s_nop 0
	v_mul_f32_e32 v2, 0x3f317217, v0
	v_fma_f32 v2, v0, s69, -v2
	v_fmac_f32_e32 v2, 0x3377d1cf, v0
	v_fmac_f32_e32 v2, 0x3f317217, v0
	v_cmp_lt_f32_e64 s[18:19], |v0|, s90
	s_nop 1
	v_cndmask_b32_e64 v0, v0, v2, s[18:19]
	v_cndmask_b32_e32 v2, 0, v241, vcc
	v_sub_f32_e32 v0, v0, v2
	v_sub_f32_e32 v2, v1, v0
	v_lshl_add_u64 v[0:1], s[74:75], 0, v[20:21]
	global_load_dword v0, v[0:1], off
	s_waitcnt vmcnt(0) lgkmcnt(0)
	v_add_f32_e32 v0, v14, v0
	v_min_f32_e32 v1, 0, v0
	v_mul_f32_e64 v0, |v0|, s68
	v_exp_f32_e32 v0, v0
	s_nop 0
	v_add_f32_e32 v0, 1.0, v0
	v_cmp_gt_f32_e32 vcc, s85, v0
	s_nop 1
	v_cndmask_b32_e64 v3, 0, 32, vcc
	v_ldexp_f32 v0, v0, v3
	v_log_f32_e32 v0, v0
	s_nop 0
	v_mul_f32_e32 v3, 0x3f317217, v0
	v_fma_f32 v3, v0, s69, -v3
	v_fmac_f32_e32 v3, 0x3377d1cf, v0
	v_fmac_f32_e32 v3, 0x3f317217, v0
	v_cmp_lt_f32_e64 s[18:19], |v0|, s90
	s_nop 1
	v_cndmask_b32_e64 v0, v0, v3, s[18:19]
	v_cndmask_b32_e32 v3, 0, v241, vcc
	v_sub_f32_e32 v0, v0, v3
	v_sub_f32_e32 v1, v1, v0
	v_add_f32_e32 v0, 0, v2
	v_lshl_add_u64 v[2:3], s[74:75], 0, v[22:23]
	global_load_dword v2, v[2:3], off
	v_add_f32_e32 v1, v0, v1
	s_waitcnt vmcnt(0) lgkmcnt(0)
	v_add_f32_e32 v2, v14, v2
	v_min_f32_e32 v3, 0, v2
	v_mul_f32_e64 v2, |v2|, s68
	v_exp_f32_e32 v2, v2
	s_nop 0
	v_add_f32_e32 v2, 1.0, v2
	v_cmp_gt_f32_e32 vcc, s85, v2
	s_nop 1
	v_cndmask_b32_e64 v4, 0, 32, vcc
	v_ldexp_f32 v2, v2, v4
	v_log_f32_e32 v2, v2
	s_nop 0
	v_mul_f32_e32 v4, 0x3f317217, v2
	v_fma_f32 v4, v2, s69, -v4
	v_fmac_f32_e32 v4, 0x3377d1cf, v2
	v_fmac_f32_e32 v4, 0x3f317217, v2
	v_cmp_lt_f32_e64 s[18:19], |v2|, s90
	s_nop 1
	v_cndmask_b32_e64 v2, v2, v4, s[18:19]
	v_cndmask_b32_e32 v4, 0, v241, vcc
	v_sub_f32_e32 v2, v2, v4
	v_sub_f32_e32 v4, v3, v2
	v_lshl_add_u64 v[2:3], s[74:75], 0, v[24:25]
	global_load_dword v2, v[2:3], off
	s_waitcnt vmcnt(0) lgkmcnt(0)
	v_add_f32_e32 v2, v14, v2
	v_min_f32_e32 v3, 0, v2
	v_mul_f32_e64 v2, |v2|, s68
	v_exp_f32_e32 v2, v2
	s_nop 0
	v_add_f32_e32 v2, 1.0, v2
	v_cmp_gt_f32_e32 vcc, s85, v2
	s_nop 1
	v_cndmask_b32_e64 v5, 0, 32, vcc
	v_ldexp_f32 v2, v2, v5
	v_log_f32_e32 v2, v2
	s_nop 0
	v_mul_f32_e32 v5, 0x3f317217, v2
	v_fma_f32 v5, v2, s69, -v5
	v_fmac_f32_e32 v5, 0x3377d1cf, v2
	v_fmac_f32_e32 v5, 0x3f317217, v2
	v_cmp_lt_f32_e64 s[18:19], |v2|, s90
	s_nop 1
	v_cndmask_b32_e64 v2, v2, v5, s[18:19]
	v_cndmask_b32_e32 v5, 0, v241, vcc
	v_sub_f32_e32 v2, v2, v5
	v_sub_f32_e32 v3, v3, v2
	v_add_f32_e32 v2, v1, v4
	v_lshl_add_u64 v[4:5], s[74:75], 0, v[26:27]
	global_load_dword v4, v[4:5], off
	v_add_f32_e32 v3, v2, v3
	s_waitcnt vmcnt(0) lgkmcnt(0)
	v_add_f32_e32 v4, v14, v4
	v_min_f32_e32 v5, 0, v4
	v_mul_f32_e64 v4, |v4|, s68
	v_exp_f32_e32 v4, v4
	s_nop 0
	v_add_f32_e32 v4, 1.0, v4
	v_cmp_gt_f32_e32 vcc, s85, v4
	s_nop 1
	v_cndmask_b32_e64 v6, 0, 32, vcc
	v_ldexp_f32 v4, v4, v6
	v_log_f32_e32 v4, v4
	s_nop 0
	v_mul_f32_e32 v6, 0x3f317217, v4
	v_fma_f32 v6, v4, s69, -v6
	v_fmac_f32_e32 v6, 0x3377d1cf, v4
	v_fmac_f32_e32 v6, 0x3f317217, v4
	v_cmp_lt_f32_e64 s[18:19], |v4|, s90
	s_nop 1
	v_cndmask_b32_e64 v4, v4, v6, s[18:19]
	v_cndmask_b32_e32 v6, 0, v241, vcc
	v_sub_f32_e32 v4, v4, v6
	v_sub_f32_e32 v6, v5, v4
	v_lshl_add_u64 v[4:5], s[74:75], 0, v[28:29]
	global_load_dword v4, v[4:5], off
	s_waitcnt vmcnt(0) lgkmcnt(0)
	v_add_f32_e32 v4, v14, v4
	v_min_f32_e32 v5, 0, v4
	v_mul_f32_e64 v4, |v4|, s68
	v_exp_f32_e32 v4, v4
	s_nop 0
	v_add_f32_e32 v4, 1.0, v4
	v_cmp_gt_f32_e32 vcc, s85, v4
	s_nop 1
	v_cndmask_b32_e64 v7, 0, 32, vcc
	v_ldexp_f32 v4, v4, v7
	v_log_f32_e32 v4, v4
	s_nop 0
	v_mul_f32_e32 v7, 0x3f317217, v4
	v_fma_f32 v7, v4, s69, -v7
	v_fmac_f32_e32 v7, 0x3377d1cf, v4
	v_fmac_f32_e32 v7, 0x3f317217, v4
	v_cmp_lt_f32_e64 s[18:19], |v4|, s90
	s_nop 1
	v_cndmask_b32_e64 v4, v4, v7, s[18:19]
	v_cndmask_b32_e32 v7, 0, v241, vcc
	v_sub_f32_e32 v4, v4, v7
	v_sub_f32_e32 v5, v5, v4
	v_add_f32_e32 v4, v3, v6
	v_lshl_add_u64 v[6:7], s[74:75], 0, v[30:31]
	global_load_dword v6, v[6:7], off
	v_add_f32_e32 v5, v4, v5
	s_waitcnt vmcnt(0) lgkmcnt(0)
	v_add_f32_e32 v6, v14, v6
	v_min_f32_e32 v7, 0, v6
	v_mul_f32_e64 v6, |v6|, s68
	v_exp_f32_e32 v6, v6
	s_nop 0
	v_add_f32_e32 v6, 1.0, v6
	v_cmp_gt_f32_e32 vcc, s85, v6
	s_nop 1
	v_cndmask_b32_e64 v8, 0, 32, vcc
	v_ldexp_f32 v6, v6, v8
	v_log_f32_e32 v6, v6
	s_nop 0
	v_mul_f32_e32 v8, 0x3f317217, v6
	v_fma_f32 v8, v6, s69, -v8
	v_fmac_f32_e32 v8, 0x3377d1cf, v6
	v_fmac_f32_e32 v8, 0x3f317217, v6
	v_cmp_lt_f32_e64 s[18:19], |v6|, s90
	s_nop 1
	v_cndmask_b32_e64 v6, v6, v8, s[18:19]
	v_cndmask_b32_e32 v8, 0, v241, vcc
	v_sub_f32_e32 v6, v6, v8
	v_sub_f32_e32 v8, v7, v6
	v_lshl_add_u64 v[6:7], s[74:75], 0, v[32:33]
	global_load_dword v6, v[6:7], off
	s_waitcnt vmcnt(0) lgkmcnt(0)
; __device__ __forceinline__ float logsig(float x) { return fminf(x, 0.f) - __logf(1.f + __expf(-fabsf(x))); }
; __global__ void __launch_bounds__(512, 2) hybrid_fwd(Params p) {
;     ...
; #pragma unroll
;                     for (int j = 0; j < 16; ++j) { run += logsig(GATES[(size_t)(tid * 16 + j) * 32 + hd] + bf); pre[j] = run; }
;                     float xs = run;
; #pragma unroll
	v_add_f32_e32 v6, v14, v6
	v_min_f32_e32 v7, 0, v6
	v_mul_f32_e64 v6, |v6|, s68
	v_exp_f32_e32 v6, v6
	s_nop 0
	v_add_f32_e32 v6, 1.0, v6
	v_cmp_gt_f32_e32 vcc, s85, v6
	s_nop 1
	v_cndmask_b32_e64 v9, 0, 32, vcc
	v_ldexp_f32 v6, v6, v9
	v_log_f32_e32 v6, v6
	s_nop 0
	v_mul_f32_e32 v9, 0x3f317217, v6
	v_fma_f32 v9, v6, s69, -v9
	v_fmac_f32_e32 v9, 0x3377d1cf, v6
	v_fmac_f32_e32 v9, 0x3f317217, v6
	v_cmp_lt_f32_e64 s[18:19], |v6|, s90
	s_nop 1
	v_cndmask_b32_e64 v6, v6, v9, s[18:19]
	v_cndmask_b32_e32 v9, 0, v241, vcc
	v_sub_f32_e32 v6, v6, v9
	v_sub_f32_e32 v7, v7, v6
	v_add_f32_e32 v6, v5, v8
	v_lshl_add_u64 v[8:9], s[74:75], 0, v[34:35]
	global_load_dword v8, v[8:9], off
	v_add_f32_e32 v7, v6, v7
	s_waitcnt vmcnt(0) lgkmcnt(0)
	v_add_f32_e32 v8, v14, v8
	v_min_f32_e32 v9, 0, v8
	v_mul_f32_e64 v8, |v8|, s68
	v_exp_f32_e32 v8, v8
	s_nop 0
	v_add_f32_e32 v8, 1.0, v8
	v_cmp_gt_f32_e32 vcc, s85, v8
	s_nop 1
	v_cndmask_b32_e64 v10, 0, 32, vcc
	v_ldexp_f32 v8, v8, v10
	v_log_f32_e32 v8, v8
	s_nop 0
	v_mul_f32_e32 v10, 0x3f317217, v8
	v_fma_f32 v10, v8, s69, -v10
	v_fmac_f32_e32 v10, 0x3377d1cf, v8
	v_fmac_f32_e32 v10, 0x3f317217, v8
	v_cmp_lt_f32_e64 s[18:19], |v8|, s90
	s_nop 1
	v_cndmask_b32_e64 v8, v8, v10, s[18:19]
	v_cndmask_b32_e32 v10, 0, v241, vcc
	v_sub_f32_e32 v8, v8, v10
	v_sub_f32_e32 v10, v9, v8
	v_lshl_add_u64 v[8:9], s[74:75], 0, v[36:37]
	global_load_dword v8, v[8:9], off
	s_waitcnt vmcnt(0) lgkmcnt(0)
	v_add_f32_e32 v8, v14, v8
	v_min_f32_e32 v9, 0, v8
	v_mul_f32_e64 v8, |v8|, s68
	v_exp_f32_e32 v8, v8
	s_nop 0
	v_add_f32_e32 v8, 1.0, v8
	v_cmp_gt_f32_e32 vcc, s85, v8
	s_nop 1
	v_cndmask_b32_e64 v11, 0, 32, vcc
	v_ldexp_f32 v8, v8, v11
	v_log_f32_e32 v8, v8
	s_nop 0
	v_mul_f32_e32 v11, 0x3f317217, v8
	v_fma_f32 v11, v8, s69, -v11
	v_fmac_f32_e32 v11, 0x3377d1cf, v8
	v_fmac_f32_e32 v11, 0x3f317217, v8
	v_cmp_lt_f32_e64 s[18:19], |v8|, s90
	s_nop 1
	v_cndmask_b32_e64 v8, v8, v11, s[18:19]
	v_cndmask_b32_e32 v11, 0, v241, vcc
	v_sub_f32_e32 v8, v8, v11
	v_sub_f32_e32 v9, v9, v8
	v_add_f32_e32 v8, v7, v10
	v_lshl_add_u64 v[10:11], s[74:75], 0, v[38:39]
	global_load_dword v10, v[10:11], off
	v_add_f32_e32 v9, v8, v9
	s_waitcnt vmcnt(0) lgkmcnt(0)
	v_add_f32_e32 v10, v14, v10
	v_min_f32_e32 v11, 0, v10
	v_mul_f32_e64 v10, |v10|, s68
	v_exp_f32_e32 v10, v10
	s_nop 0
	v_add_f32_e32 v10, 1.0, v10
	v_cmp_gt_f32_e32 vcc, s85, v10
	s_nop 1
	v_cndmask_b32_e64 v12, 0, 32, vcc
	v_ldexp_f32 v10, v10, v12
	v_log_f32_e32 v10, v10
	s_nop 0
	v_mul_f32_e32 v12, 0x3f317217, v10
	v_fma_f32 v12, v10, s69, -v12
	v_fmac_f32_e32 v12, 0x3377d1cf, v10
	v_fmac_f32_e32 v12, 0x3f317217, v10
	v_cmp_lt_f32_e64 s[18:19], |v10|, s90
	s_nop 1
	v_cndmask_b32_e64 v10, v10, v12, s[18:19]
	v_cndmask_b32_e32 v12, 0, v241, vcc
	v_sub_f32_e32 v10, v10, v12
	v_sub_f32_e32 v12, v11, v10
	v_lshl_add_u64 v[10:11], s[74:75], 0, v[40:41]
	global_load_dword v10, v[10:11], off
	s_waitcnt vmcnt(0) lgkmcnt(0)
	v_add_f32_e32 v10, v14, v10
	v_min_f32_e32 v11, 0, v10
	v_mul_f32_e64 v10, |v10|, s68
	v_exp_f32_e32 v10, v10
	s_nop 0
	v_add_f32_e32 v10, 1.0, v10
	v_cmp_gt_f32_e32 vcc, s85, v10
	s_nop 1
	v_cndmask_b32_e64 v13, 0, 32, vcc
	v_ldexp_f32 v10, v10, v13
	v_log_f32_e32 v10, v10
	s_nop 0
	v_mul_f32_e32 v13, 0x3f317217, v10
	v_fma_f32 v13, v10, s69, -v13
	v_fmac_f32_e32 v13, 0x3377d1cf, v10
	v_fmac_f32_e32 v13, 0x3f317217, v10
	v_cmp_lt_f32_e64 s[18:19], |v10|, s90
	s_nop 1
	v_cndmask_b32_e64 v10, v10, v13, s[18:19]
	v_cndmask_b32_e32 v13, 0, v241, vcc
	v_sub_f32_e32 v10, v10, v13
	v_sub_f32_e32 v11, v11, v10
	v_add_f32_e32 v10, v9, v12
	v_lshl_add_u64 v[12:13], s[74:75], 0, v[42:43]
	global_load_dword v12, v[12:13], off
	v_add_f32_e32 v11, v10, v11
	s_waitcnt vmcnt(0) lgkmcnt(0)
; __device__ __forceinline__ float logsig(float x) { return fminf(x, 0.f) - __logf(1.f + __expf(-fabsf(x))); }
; __global__ void __launch_bounds__(512, 2) hybrid_fwd(Params p) {
;     ...
; #pragma unroll
;                     for (int j = 0; j < 16; ++j) { run += logsig(GATES[(size_t)(tid * 16 + j) * 32 + hd] + bf); pre[j] = run; }
;                     float xs = run;
; #pragma unroll
;                     for (int off = 1; off < 64; off <<= 1) { const float y = __int_as_float(__builtin_amdgcn_ds_bpermute((lane >= off ? lane - off : lane) << 2, __float_as_int(xs))); if (lane >= off) xs += y; }
;                     if (lane == 63) wt[wave] = xs;
;                     __syncthreads();
;                     float base = 0.f;
; #pragma unroll
;                     for (int g = 0; g < 8; ++g) if (g < wave) base += wt[g];
	v_add_f32_e32 v12, v14, v12
	v_min_f32_e32 v13, 0, v12
	v_mul_f32_e64 v12, |v12|, s68
	v_exp_f32_e32 v12, v12
	s_nop 0
	v_add_f32_e32 v12, 1.0, v12
	v_cmp_gt_f32_e32 vcc, s85, v12
	s_nop 1
	v_cndmask_b32_e64 v15, 0, 32, vcc
	v_ldexp_f32 v12, v12, v15
	v_log_f32_e32 v12, v12
	s_nop 0
	v_mul_f32_e32 v15, 0x3f317217, v12
	v_fma_f32 v15, v12, s69, -v15
	v_fmac_f32_e32 v15, 0x3377d1cf, v12
	v_fmac_f32_e32 v15, 0x3f317217, v12
	v_cmp_lt_f32_e64 s[18:19], |v12|, s90
	s_nop 1
	v_cndmask_b32_e64 v12, v12, v15, s[18:19]
	v_cndmask_b32_e32 v15, 0, v241, vcc
	v_sub_f32_e32 v12, v12, v15
	v_sub_f32_e32 v15, v13, v12
	v_lshl_add_u64 v[12:13], s[74:75], 0, v[44:45]
	global_load_dword v12, v[12:13], off
	s_waitcnt vmcnt(0) lgkmcnt(0)
	v_add_f32_e32 v12, v14, v12
	v_min_f32_e32 v13, 0, v12
	v_mul_f32_e64 v12, |v12|, s68
	v_exp_f32_e32 v12, v12
	s_nop 0
	v_add_f32_e32 v12, 1.0, v12
	v_cmp_gt_f32_e32 vcc, s85, v12
	s_nop 1
	v_cndmask_b32_e64 v69, 0, 32, vcc
	v_ldexp_f32 v12, v12, v69
	v_log_f32_e32 v12, v12
	s_nop 0
	v_mul_f32_e32 v69, 0x3f317217, v12
	v_fma_f32 v69, v12, s69, -v69
	v_fmac_f32_e32 v69, 0x3377d1cf, v12
	v_fmac_f32_e32 v69, 0x3f317217, v12
	v_cmp_lt_f32_e64 s[18:19], |v12|, s90
	s_nop 1
	v_cndmask_b32_e64 v12, v12, v69, s[18:19]
	v_cndmask_b32_e32 v69, 0, v241, vcc
	v_sub_f32_e32 v12, v12, v69
	v_sub_f32_e32 v13, v13, v12
	v_add_f32_e32 v12, v11, v15
	global_load_dword v15, v[70:71], off
	v_add_f32_e32 v13, v12, v13
	s_waitcnt vmcnt(0) lgkmcnt(0)
	v_add_f32_e32 v15, v14, v15
	v_min_f32_e32 v69, 0, v15
	v_mul_f32_e64 v15, |v15|, s68
	v_exp_f32_e32 v15, v15
	s_nop 0
	v_add_f32_e32 v15, 1.0, v15
	v_cmp_gt_f32_e32 vcc, s85, v15
	s_nop 1
	v_cndmask_b32_e64 v70, 0, 32, vcc
	v_ldexp_f32 v15, v15, v70
	v_log_f32_e32 v15, v15
	s_nop 0
	v_mul_f32_e32 v70, 0x3f317217, v15
	v_fma_f32 v70, v15, s69, -v70
	v_fmac_f32_e32 v70, 0x3377d1cf, v15
	v_fmac_f32_e32 v70, 0x3f317217, v15
	v_cmp_lt_f32_e64 s[18:19], |v15|, s90
	s_nop 1
	v_cndmask_b32_e64 v15, v15, v70, s[18:19]
	v_cndmask_b32_e32 v70, 0, v241, vcc
	v_sub_f32_e32 v15, v15, v70
	v_lshl_add_u64 v[70:71], s[74:75], 0, v[48:49]
	v_sub_f32_e32 v15, v69, v15
	global_load_dword v69, v[70:71], off
	s_waitcnt vmcnt(0) lgkmcnt(0)
	v_add_f32_e32 v14, v14, v69
	v_min_f32_e32 v69, 0, v14
	v_mul_f32_e64 v14, |v14|, s68
	v_exp_f32_e32 v14, v14
	s_nop 0
	v_add_f32_e32 v14, 1.0, v14
	v_cmp_gt_f32_e32 vcc, s85, v14
	s_nop 1
	v_cndmask_b32_e64 v70, 0, 32, vcc
	v_ldexp_f32 v14, v14, v70
	v_log_f32_e32 v14, v14
	s_nop 0
	v_mul_f32_e32 v70, 0x3f317217, v14
	v_fma_f32 v70, v14, s69, -v70
	v_fmac_f32_e32 v70, 0x3377d1cf, v14
	v_fmac_f32_e32 v70, 0x3f317217, v14
	v_cmp_lt_f32_e64 s[18:19], |v14|, s90
	s_nop 1
	v_cndmask_b32_e64 v14, v14, v70, s[18:19]
	v_cndmask_b32_e32 v70, 0, v241, vcc
	v_sub_f32_e32 v14, v14, v70
	v_sub_f32_e32 v69, v69, v14
	v_add_f32_e32 v14, v13, v15
	v_add_f32_e32 v15, v14, v69
	ds_bpermute_b32 v69, v60, v15
	s_waitcnt lgkmcnt(0)
	v_add_f32_e32 v69, v15, v69
	v_cndmask_b32_e64 v69, v15, v69, s[4:5]
	ds_bpermute_b32 v70, v61, v69
	s_waitcnt lgkmcnt(0)
	v_add_f32_e32 v70, v69, v70
	v_cndmask_b32_e64 v69, v70, v69, s[6:7]
	ds_bpermute_b32 v70, v62, v69
	s_waitcnt lgkmcnt(0)
	v_add_f32_e32 v70, v69, v70
	v_cndmask_b32_e64 v69, v70, v69, s[8:9]
	ds_bpermute_b32 v70, v63, v69
	s_waitcnt lgkmcnt(0)
	v_add_f32_e32 v70, v69, v70
	v_cndmask_b32_e64 v69, v70, v69, s[10:11]
	ds_bpermute_b32 v70, v64, v69
	s_waitcnt lgkmcnt(0)
	v_add_f32_e32 v70, v69, v70
	v_cndmask_b32_e64 v69, v70, v69, s[12:13]
	ds_bpermute_b32 v70, v65, v69
	s_waitcnt lgkmcnt(0)
	v_add_f32_e32 v70, v69, v70
	s_and_saveexec_b64 s[18:19], s[16:17]
	v_mov_b32_e32 v71, s77
	ds_write_b32 v71, v70
	s_or_b64 exec, exec, s[18:19]
	s_andn2_b64 vcc, exec, s[22:23]
	s_waitcnt lgkmcnt(0)
	s_barrier
	s_cbranch_vccnz .LBB0_480
	ds_read_b32 v71, v201
	s_waitcnt lgkmcnt(0)
	v_add_f32_e32 v71, 0, v71
	s_andn2_b64 vcc, exec, s[24:25]
	s_cbranch_vccnz .LBB0_467

; __global__ void __launch_bounds__(512, 2) hybrid_fwd(Params p) {
;     ...
;                     for (int n0 = 0; n0 < 128; n0 += 32) {
;                         float kvv[32], dd[32];
; #pragma unroll
;                         for (int j = 0; j < 32; ++j) { kvv[j] = kp[(size_t)(n0 + j) * 8192]; dd[j] = dp[(n0 + j) * 64]; }
; #pragma unroll
;                         for (int j = 0; j < 32; ++j) { kp[(size_t)(n0 + j) * 8192] = S; S = dd[j] * S + kvv[j]; }
.LBB0_551:
	v_lshl_add_u64 v[10:11], s[8:9], 0, v[0:1]
	v_add_co_u32_e32 v4, vcc, 0x37e00000, v10
	v_lshl_add_u64 v[40:41], s[8:9], 0, v[2:3]
	s_nop 0
	v_addc_co_u32_e32 v5, vcc, 0, v11, vcc
	v_add_co_u32_e32 v26, vcc, 0x38e00000, v40
	global_load_dword v59, v[4:5], off
	s_nop 0
	v_addc_co_u32_e32 v27, vcc, 0, v41, vcc
	v_add_co_u32_e32 v6, vcc, 0x37e08000, v10
	global_load_dword v74, v[26:27], off
	global_load_dword v73, v[26:27], off offset:256
	global_load_dword v72, v[26:27], off offset:512
	global_load_dword v71, v[26:27], off offset:768
	global_load_dword v70, v[26:27], off offset:1024
	global_load_dword v69, v[26:27], off offset:1280
	global_load_dword v68, v[26:27], off offset:1536
	global_load_dword v67, v[26:27], off offset:1792
	global_load_dword v66, v[26:27], off offset:2048
	global_load_dword v65, v[26:27], off offset:2304
	global_load_dword v64, v[26:27], off offset:2560
	global_load_dword v63, v[26:27], off offset:2816
	global_load_dword v62, v[26:27], off offset:3072
	global_load_dword v61, v[26:27], off offset:3328
	global_load_dword v60, v[26:27], off offset:3584
	v_addc_co_u32_e32 v7, vcc, 0, v11, vcc
	v_add_co_u32_e32 v8, vcc, 0x37e10000, v10
	s_mov_b64 s[6:7], 0x100000
	s_nop 0
	v_addc_co_u32_e32 v9, vcc, 0, v11, vcc
	v_add_co_u32_e32 v12, vcc, 0x37e18000, v10
	global_load_dword v76, v[6:7], off
	global_load_dword v75, v[8:9], off
	v_addc_co_u32_e32 v13, vcc, 0, v11, vcc
	v_add_co_u32_e32 v14, vcc, 0x37e20000, v10
	v_lshl_add_u64 v[0:1], v[0:1], 0, s[6:7]
	s_nop 0
	v_addc_co_u32_e32 v15, vcc, 0, v11, vcc
	v_add_co_u32_e32 v16, vcc, 0x37e28000, v10
	global_load_dword v78, v[12:13], off
	global_load_dword v77, v[14:15], off
	v_addc_co_u32_e32 v17, vcc, 0, v11, vcc
	v_add_co_u32_e32 v18, vcc, 0x37e30000, v10
	s_mov_b64 s[6:7], 0x2000
	s_nop 0
	v_addc_co_u32_e32 v19, vcc, 0, v11, vcc
	v_add_co_u32_e32 v20, vcc, 0x37e38000, v10
	global_load_dword v80, v[16:17], off
	global_load_dword v79, v[18:19], off
	v_addc_co_u32_e32 v21, vcc, 0, v11, vcc
	v_add_co_u32_e32 v22, vcc, 0x37e40000, v10
	global_load_dword v81, v[20:21], off
	global_load_dword v82, v[26:27], off offset:3840
	v_addc_co_u32_e32 v23, vcc, 0, v11, vcc
	v_add_co_u32_e32 v24, vcc, 0x37e48000, v10
	s_add_i32 s4, s4, 32
	s_nop 0
	v_addc_co_u32_e32 v25, vcc, 0, v11, vcc
	v_add_co_u32_e32 v26, vcc, 0x37e50000, v10
	global_load_dword v83, v[22:23], off
	global_load_dword v94, v[24:25], off
	v_addc_co_u32_e32 v27, vcc, 0, v11, vcc
	v_add_co_u32_e32 v28, vcc, 0x37e58000, v10
	v_lshl_add_u64 v[2:3], v[2:3], 0, s[6:7]
	s_nop 0
	v_addc_co_u32_e32 v29, vcc, 0, v11, vcc
	v_add_co_u32_e32 v30, vcc, 0x37e60000, v10
	global_load_dword v95, v[26:27], off
	global_load_dword v96, v[28:29], off
	v_addc_co_u32_e32 v31, vcc, 0, v11, vcc
	v_add_co_u32_e32 v32, vcc, 0x37e68000, v10
	s_cmpk_gt_u32 s4, 0x5f
	s_nop 0
	v_addc_co_u32_e32 v33, vcc, 0, v11, vcc
	v_add_co_u32_e32 v34, vcc, 0x37e70000, v10
	global_load_dword v97, v[30:31], off
	global_load_dword v98, v[32:33], off
	v_addc_co_u32_e32 v35, vcc, 0, v11, vcc
	v_add_co_u32_e32 v36, vcc, 0x37e78000, v10
	s_waitcnt vmcnt(0) lgkmcnt(0)
; __global__ void __launch_bounds__(512, 2) hybrid_fwd(Params p) {
;     ...
;                     for (int n0 = 0; n0 < 128; n0 += 32) {
;                         float kvv[32], dd[32];
; #pragma unroll
;                         for (int j = 0; j < 32; ++j) { kvv[j] = kp[(size_t)(n0 + j) * 8192]; dd[j] = dp[(n0 + j) * 64]; }
; #pragma unroll
;                         for (int j = 0; j < 32; ++j) { kp[(size_t)(n0 + j) * 8192] = S; S = dd[j] * S + kvv[j]; }
;                     }
;                     asm volatile("s_waitcnt vmcnt(0)" ::: "memory"); __syncthreads();
;                     if (tid == 0) { __builtin_amdgcn_fence(__ATOMIC_RELEASE, "agent"); asm volatile("s_waitcnt vmcnt(0)" ::: "memory");
;                         (void)__hip_atomic_fetch_add((unsigned*)ws + 3584 + 64 * l, 1u, __ATOMIC_RELAXED, __HIP_MEMORY_SCOPE_AGENT); }
	v_fmac_f32_e32 v59, v58, v74
	v_addc_co_u32_e32 v37, vcc, 0, v11, vcc
	v_add_co_u32_e32 v38, vcc, 0x37e80000, v10
	global_load_dword v99, v[34:35], off
	global_load_dword v100, v[36:37], off
	v_addc_co_u32_e32 v39, vcc, 0, v11, vcc
	v_add_co_u32_e32 v84, vcc, 0x38e01000, v40
	global_load_dword v101, v[38:39], off
	s_nop 0
	v_addc_co_u32_e32 v85, vcc, 0, v41, vcc
	v_add_co_u32_e32 v40, vcc, 0x37e88000, v10
	global_load_dword v102, v[84:85], off
	global_load_dword v103, v[84:85], off offset:256
	global_load_dword v104, v[84:85], off offset:512
	global_load_dword v105, v[84:85], off offset:768
	global_load_dword v106, v[84:85], off offset:1024
	global_load_dword v107, v[84:85], off offset:1280
	global_load_dword v108, v[84:85], off offset:1536
	global_load_dword v109, v[84:85], off offset:1792
	global_load_dword v110, v[84:85], off offset:2048
	global_load_dword v111, v[84:85], off offset:2304
	global_load_dword v112, v[84:85], off offset:2560
	global_load_dword v113, v[84:85], off offset:2816
	global_load_dword v114, v[84:85], off offset:3072
	global_load_dword v115, v[84:85], off offset:3328
	global_load_dword v116, v[84:85], off offset:3584
	v_addc_co_u32_e32 v41, vcc, 0, v11, vcc
	v_add_co_u32_e32 v42, vcc, 0x37e90000, v10
	v_fmac_f32_e32 v76, v59, v73
	s_nop 0
	v_addc_co_u32_e32 v43, vcc, 0, v11, vcc
	v_add_co_u32_e32 v44, vcc, 0x37e98000, v10
	global_load_dword v117, v[40:41], off
	global_load_dword v118, v[42:43], off
	v_addc_co_u32_e32 v45, vcc, 0, v11, vcc
	v_add_co_u32_e32 v46, vcc, 0x37ea0000, v10
	v_fmac_f32_e32 v75, v76, v72
	s_nop 0
	v_addc_co_u32_e32 v47, vcc, 0, v11, vcc
	v_add_co_u32_e32 v48, vcc, 0x37ea8000, v10
	global_load_dword v119, v[44:45], off
	global_load_dword v120, v[46:47], off
	v_addc_co_u32_e32 v49, vcc, 0, v11, vcc
	v_add_co_u32_e32 v50, vcc, 0x37eb0000, v10
	v_fmac_f32_e32 v78, v75, v71
	s_nop 0
	v_addc_co_u32_e32 v51, vcc, 0, v11, vcc
	v_add_co_u32_e32 v52, vcc, 0x37eb8000, v10
	global_load_dword v121, v[48:49], off
	global_load_dword v122, v[50:51], off
	v_addc_co_u32_e32 v53, vcc, 0, v11, vcc
	v_add_co_u32_e32 v54, vcc, 0x37ec0000, v10
	v_fmac_f32_e32 v77, v78, v70
	s_nop 0
	v_addc_co_u32_e32 v55, vcc, 0, v11, vcc
	v_add_co_u32_e32 v56, vcc, 0x37ec8000, v10
	global_load_dword v123, v[52:53], off
	global_load_dword v124, v[84:85], off offset:3840
	global_load_dword v125, v[54:55], off
	v_addc_co_u32_e32 v57, vcc, 0, v11, vcc
	v_add_co_u32_e32 v84, vcc, 0x37ed0000, v10
	v_fmac_f32_e32 v80, v77, v69
	s_nop 0
	v_addc_co_u32_e32 v85, vcc, 0, v11, vcc
	v_add_co_u32_e32 v86, vcc, 0x37ed8000, v10
	global_load_dword v126, v[56:57], off
	global_load_dword v127, v[84:85], off
	v_addc_co_u32_e32 v87, vcc, 0, v11, vcc
	v_add_co_u32_e32 v88, vcc, 0x37ee0000, v10
	v_fmac_f32_e32 v79, v80, v68
	s_nop 0
	v_addc_co_u32_e32 v89, vcc, 0, v11, vcc
	v_add_co_u32_e32 v90, vcc, 0x37ee8000, v10
	global_load_dword v128, v[86:87], off
	global_load_dword v129, v[88:89], off
	v_addc_co_u32_e32 v91, vcc, 0, v11, vcc
	v_add_co_u32_e32 v92, vcc, 0x37ef0000, v10
	v_fmac_f32_e32 v81, v79, v67
	s_nop 0
	v_addc_co_u32_e32 v93, vcc, 0, v11, vcc
	v_add_co_u32_e32 v10, vcc, 0x37ef8000, v10
	global_load_dword v130, v[90:91], off
	global_load_dword v131, v[92:93], off
	v_addc_co_u32_e32 v11, vcc, 0, v11, vcc
	global_load_dword v132, v[10:11], off
	v_fmac_f32_e32 v83, v81, v66
	v_fmac_f32_e32 v94, v83, v65
	v_fmac_f32_e32 v95, v94, v64
	v_fmac_f32_e32 v96, v95, v63
	v_fmac_f32_e32 v97, v96, v62
	v_fmac_f32_e32 v98, v97, v61
	s_waitcnt vmcnt(0) lgkmcnt(0)
	v_fmac_f32_e32 v99, v98, v60
	v_fmac_f32_e32 v100, v99, v82
	v_fmac_f32_e32 v101, v100, v102
	global_store_dword v[4:5], v58, off
	global_store_dword v[6:7], v59, off
	global_store_dword v[8:9], v76, off
	global_store_dword v[12:13], v75, off
	global_store_dword v[14:15], v78, off
	global_store_dword v[16:17], v77, off
	v_fmac_f32_e32 v117, v101, v103
	v_fmac_f32_e32 v118, v117, v104
	global_store_dword v[18:19], v80, off
	global_store_dword v[20:21], v79, off
	global_store_dword v[22:23], v81, off
	global_store_dword v[24:25], v83, off
	global_store_dword v[26:27], v94, off
	global_store_dword v[28:29], v95, off
	global_store_dword v[30:31], v96, off
	global_store_dword v[32:33], v97, off
	v_fmac_f32_e32 v119, v118, v105
	v_fmac_f32_e32 v120, v119, v106
	global_store_dword v[34:35], v98, off
	global_store_dword v[36:37], v99, off
	global_store_dword v[38:39], v100, off
	global_store_dword v[40:41], v101, off
	global_store_dword v[42:43], v117, off
	global_store_dword v[44:45], v118, off
	global_store_dword v[46:47], v119, off
	global_store_dword v[48:49], v120, off
	v_fmac_f32_e32 v121, v120, v107
	v_fmac_f32_e32 v122, v121, v108
	global_store_dword v[50:51], v121, off
	global_store_dword v[52:53], v122, off
	v_fmac_f32_e32 v123, v122, v109
	global_store_dword v[54:55], v123, off
	v_fmac_f32_e32 v125, v123, v110
	global_store_dword v[56:57], v125, off
	v_fmac_f32_e32 v126, v125, v111
	v_fmac_f32_e32 v127, v126, v112
	global_store_dword v[84:85], v126, off
	global_store_dword v[86:87], v127, off
	v_fmac_f32_e32 v128, v127, v113
	v_fmac_f32_e32 v129, v128, v114
	global_store_dword v[88:89], v128, off
	global_store_dword v[90:91], v129, off
	v_fmac_f32_e32 v130, v129, v115
	v_fmac_f32_e32 v131, v130, v116
	global_store_dword v[92:93], v130, off
	global_store_dword v[10:11], v131, off
	v_fmac_f32_e32 v132, v131, v124
	v_mov_b32_e32 v58, v132
	s_cbranch_scc0 .LBB0_551
	s_waitcnt vmcnt(0)
	v_cmp_eq_u32_e32 vcc, 0, v144
	s_waitcnt lgkmcnt(0)
	s_barrier
	s_and_saveexec_b64 s[4:5], vcc
	s_cbranch_execz .LBB0_554
	v_readlane_b32 s6, v255, 42
	v_readlane_b32 s7, v255, 43
	s_lshl_b32 s72, s6, 6
	s_lshl_b64 s[6:7], s[72:73], 2
	s_add_u32 s6, s8, s6
	s_addc_u32 s7, s9, s7
	v_mov_b32_e32 v0, s6
	v_add_co_u32_e32 v0, vcc, 0x3000, v0
	v_mov_b32_e32 v1, s7
	buffer_wbl2 sc1
	s_waitcnt vmcnt(0)
	s_waitcnt vmcnt(0)
	v_addc_co_u32_e32 v1, vcc, 0, v1, vcc
	global_atomic_add v[0:1], v238, off offset:2048

; __device__ __forceinline__ unsigned cvt_pk_bf16(float lo, float hi) { unsigned r; asm("v_cvt_pk_bf16_f32 %0, %1, %2" : "=v"(r) : "v"(lo), "v"(hi)); return r; }
; __device__ __forceinline__ float xsum(float v) { const auto r = __builtin_amdgcn_permlane32_swap(__float_as_uint(v), __float_as_uint(v), false, false); return __uint_as_float(r[0]) + __uint_as_float(r[1]); }
; __device__ __forceinline__ void st16_wt(void* p, u32x4 v) { asm volatile("global_store_dwordx4 %0, %1, off sc1\n\ts_nop 1" :: "v"(p), "v"(v) : "memory"); }
;     ...
;     l = xsum(l);
;     const float inv = 1.f / l;
; #pragma unroll
;     for (int db = 0; db < 4; ++db)
; #pragma unroll
;         for (int g = 0; g < 4; g += 2) {
;             unsigned ax = cvt_pk_bf16(o[db][4 * g] * inv, o[db][4 * g + 1] * inv), ay = cvt_pk_bf16(o[db][4 * g + 2] * inv, o[db][4 * g + 3] * inv);
;             unsigned bx = cvt_pk_bf16(o[db][4 * g + 4] * inv, o[db][4 * g + 5] * inv), by = cvt_pk_bf16(o[db][4 * g + 6] * inv, o[db][4 * g + 7] * inv);
;             const auto rx = __builtin_amdgcn_permlane32_swap(ax, bx, false, false), ry = __builtin_amdgcn_permlane32_swap(ay, by, false, false);
;             u32x4 w; w.x = rx[0]; w.y = ry[0]; w.z = rx[1]; w.w = ry[1];
;             if (MODE == 2) st16_wt(Orow + 32 * db + 8 * g + 8 * hh, w); else *(u32x4*)(Orow + 32 * db + 8 * g + 8 * hh) = w;
;         }
.LBB0_557:
	v_mov_b32_e32 v67, v149
	v_mul_hi_i32_i24_e32 v65, 0xfffff400, v160
	v_mul_i32_i24_e32 v64, 0xfffff400, v160
	v_permlane32_swap_b32_e32 v149, v67
	v_lshl_add_u64 v[64:65], v[146:147], 0, v[64:65]
	v_add_f32_e32 v67, v149, v67
	v_lshl_add_u64 v[64:65], s[4:5], 1, v[64:65]
	v_div_scale_f32 v68, s[4:5], v67, v67, 1.0
	v_rcp_f32_e32 v69, v68
	v_lshlrev_b32_e32 v66, 3, v161
	v_lshlrev_b32_e32 v200, 1, v66
	v_lshl_add_u64 v[64:65], v[64:65], 0, v[200:201]
	v_fma_f32 v70, -v68, v69, 1.0
	v_fmac_f32_e32 v69, v70, v69
	v_div_scale_f32 v70, vcc, 1.0, v67, 1.0
	v_mul_f32_e32 v71, v70, v69
	v_fma_f32 v72, -v68, v71, v70
	v_fmac_f32_e32 v71, v72, v69
	v_fma_f32 v68, -v68, v71, v70
	v_div_fmas_f32 v68, v68, v69, v71
	v_div_fixup_f32 v68, v68, v67, 1.0
	v_mul_f32_e32 v48, v48, v68
	v_mul_f32_e32 v49, v49, v68
	v_mul_f32_e32 v32, v32, v68
	v_mul_f32_e32 v33, v33, v68
	v_mul_f32_e32 v16, v16, v68
	v_mul_f32_e32 v17, v17, v68
	v_mul_f32_e32 v0, v0, v68
	v_mul_f32_e32 v1, v1, v68
	v_cvt_pk_bf16_f32 v48, v48, v49
	v_mul_f32_e32 v49, v50, v68
	v_mul_f32_e32 v50, v51, v68
	v_cvt_pk_bf16_f32 v32, v32, v33
	v_mul_f32_e32 v33, v34, v68
	v_mul_f32_e32 v34, v35, v68
	v_cvt_pk_bf16_f32 v16, v16, v17
	v_mul_f32_e32 v17, v18, v68
	v_mul_f32_e32 v18, v19, v68
	v_cvt_pk_bf16_f32 v0, v0, v1
	v_mul_f32_e32 v1, v2, v68
	v_mul_f32_e32 v2, v3, v68
	s_mov_b64 s[4:5], 0x24300400
	v_cvt_pk_bf16_f32 v49, v49, v50
	v_mul_f32_e32 v50, v52, v68
	v_mul_f32_e32 v51, v53, v68
	v_cvt_pk_bf16_f32 v33, v33, v34
	v_mul_f32_e32 v34, v36, v68
	v_mul_f32_e32 v35, v37, v68
	v_cvt_pk_bf16_f32 v17, v17, v18
	v_mul_f32_e32 v18, v20, v68
	v_mul_f32_e32 v19, v21, v68
	v_cvt_pk_bf16_f32 v1, v1, v2
	v_mul_f32_e32 v2, v4, v68
	v_mul_f32_e32 v3, v5, v68
	v_lshl_add_u64 v[66:67], v[64:65], 0, s[4:5]
	v_cvt_pk_bf16_f32 v50, v50, v51
	v_mul_f32_e32 v51, v54, v68
	v_mul_f32_e32 v52, v55, v68
	s_mov_b32 s4, 0x24300000
	v_cvt_pk_bf16_f32 v34, v34, v35
	v_mul_f32_e32 v35, v38, v68
	v_cvt_pk_bf16_f32 v18, v18, v19
	v_mul_f32_e32 v19, v22, v68
	v_cvt_pk_bf16_f32 v2, v2, v3
	v_mul_f32_e32 v3, v6, v68
	v_cvt_pk_bf16_f32 v51, v51, v52
	v_add_co_u32_e32 v52, vcc, s4, v64
	v_mul_f32_e32 v36, v39, v68
	v_cvt_pk_bf16_f32 v35, v35, v36
	v_mul_f32_e32 v20, v23, v68
	v_cvt_pk_bf16_f32 v19, v19, v20
	v_mul_f32_e32 v4, v7, v68
	v_cvt_pk_bf16_f32 v3, v3, v4
	v_permlane32_swap_b32_e32 v48, v50
	v_permlane32_swap_b32_e32 v49, v51
	v_addc_co_u32_e32 v53, vcc, 0, v65, vcc
	v_permlane32_swap_b32_e32 v32, v34
	v_permlane32_swap_b32_e32 v33, v35
	v_permlane32_swap_b32_e32 v16, v18
	v_permlane32_swap_b32_e32 v17, v19
	v_permlane32_swap_b32_e32 v0, v2
	v_permlane32_swap_b32_e32 v1, v3
	global_store_dwordx4 v[52:53], v[48:51], off offset:1024
	global_store_dwordx4 v[66:67], v[32:35], off offset:64
	global_store_dwordx4 v[66:67], v[16:19], off offset:128
	v_mul_f32_e32 v48, v56, v68
	v_mul_f32_e32 v49, v57, v68
	v_mul_f32_e32 v32, v40, v68
	v_mul_f32_e32 v33, v41, v68
	v_mul_f32_e32 v16, v24, v68
	v_mul_f32_e32 v17, v25, v68
	global_store_dwordx4 v[66:67], v[0:3], off offset:192
	v_cvt_pk_bf16_f32 v48, v48, v49
	v_mul_f32_e32 v49, v58, v68
	v_mul_f32_e32 v50, v59, v68
	v_mul_f32_e32 v0, v8, v68
	v_mul_f32_e32 v1, v9, v68
	v_cvt_pk_bf16_f32 v32, v32, v33
	v_mul_f32_e32 v33, v42, v68
	v_mul_f32_e32 v34, v43, v68
	v_cvt_pk_bf16_f32 v16, v16, v17
	v_mul_f32_e32 v17, v26, v68
	v_mul_f32_e32 v18, v27, v68
	v_cvt_pk_bf16_f32 v0, v0, v1
	v_mul_f32_e32 v1, v10, v68
	v_mul_f32_e32 v2, v11, v68
	v_cvt_pk_bf16_f32 v49, v49, v50
	v_mul_f32_e32 v50, v60, v68
	v_mul_f32_e32 v51, v61, v68
	v_cvt_pk_bf16_f32 v33, v33, v34
	v_mul_f32_e32 v34, v44, v68
	v_mul_f32_e32 v35, v45, v68
	v_cvt_pk_bf16_f32 v17, v17, v18
	v_mul_f32_e32 v18, v28, v68
	v_mul_f32_e32 v19, v29, v68
	v_cvt_pk_bf16_f32 v1, v1, v2
	v_mul_f32_e32 v2, v12, v68
	v_mul_f32_e32 v3, v13, v68
	v_cvt_pk_bf16_f32 v50, v50, v51
	v_mul_f32_e32 v51, v62, v68
	v_cvt_pk_bf16_f32 v34, v34, v35
	v_mul_f32_e32 v35, v46, v68
	v_cvt_pk_bf16_f32 v18, v18, v19
	v_mul_f32_e32 v19, v30, v68
	v_cvt_pk_bf16_f32 v2, v2, v3
	v_mul_f32_e32 v3, v14, v68
	v_mul_f32_e32 v52, v63, v68
	v_cvt_pk_bf16_f32 v51, v51, v52
	v_mul_f32_e32 v36, v47, v68
	v_cvt_pk_bf16_f32 v35, v35, v36
	v_mul_f32_e32 v20, v31, v68
	v_cvt_pk_bf16_f32 v19, v19, v20
	v_mul_f32_e32 v4, v15, v68
	v_cvt_pk_bf16_f32 v3, v3, v4
	s_add_i32 s23, s23, 1
	v_permlane32_swap_b32_e32 v48, v50
	v_permlane32_swap_b32_e32 v49, v51
	v_permlane32_swap_b32_e32 v32, v34
	v_permlane32_swap_b32_e32 v33, v35
	v_permlane32_swap_b32_e32 v16, v18
	v_permlane32_swap_b32_e32 v17, v19
	v_permlane32_swap_b32_e32 v0, v2
	v_permlane32_swap_b32_e32 v1, v3
	s_cmp_lg_u32 s23, s13
	global_store_dwordx4 v[66:67], v[48:51], off offset:32
	global_store_dwordx4 v[66:67], v[32:35], off offset:96
	global_store_dwordx4 v[66:67], v[16:19], off offset:160
	global_store_dwordx4 v[66:67], v[0:3], off offset:224
	s_cbranch_scc0 .LBB0_567
; #define LAS __attribute__((address_space(3)))
; __device__ __forceinline__ float bflo(unsigned w) { return __uint_as_float(w << 16); }
; __device__ __forceinline__ float bfhi(unsigned w) { return __uint_as_float(w & 0xffff0000u); }
;     ...
;     bf16x8 qf[8];
; #pragma unroll
;     for (int ks = 0; ks < 8; ++ks) qf[ks] = *(const bf16x8*)(Qrow + 16 * ks + 8 * hh);
;     f32x16 o[4];
; #pragma unroll
;     for (int db = 0; db < 4; ++db)
; #pragma unroll
;         for (int i = 0; i < 16; ++i) o[db][i] = 0.f;
;     float m = m_init, l = (hh == 0) ? l_init : 0.f;
;     const int pr = (r & ~12) | ((r & 4) << 1) | ((r & 8) >> 1);
;     const unsigned koff = pr * AT_KROW + 16 * hh, voff = AT_KBUF + r * AT_VROW + 16 * hh;
;     const int kkey0 = tid >> 4, kc16 = tid & 15, vd0 = tid >> 3, vc8 = tid & 7;
;     u32x4 kreg[2], vreg[2]; float creg = 0.f;
;     ...
;     float qn = 0.f; bool wdone = false;
;     LAS unsigned* flg = (LAS unsigned*)(lds + 2 * AT_BUF);
;     if (MODE == 0) {
; #pragma unroll
;         for (int ks = 0; ks < 8; ++ks) { const u32x4 qq = __builtin_bit_cast(u32x4, qf[ks]);
;             qn += bflo(qq.x) * bflo(qq.x) + bfhi(qq.x) * bfhi(qq.x) + bflo(qq.y) * bflo(qq.y) + bfhi(qq.y) * bfhi(qq.y) + bflo(qq.z) * bflo(qq.z) + bfhi(qq.z) * bfhi(qq.z) + bflo(qq.w) * bflo(qq.w) + bfhi(qq.w) * bfhi(qq.w); }
;         qn = xsum(qn); qn = sqrtf(qn) * kn * SC * 1.0001f + 1e-3f;
;     }
;     AT_LOAD(kt1 - 1); AT_WRITE(0); __syncthreads();
; __global__ void __launch_bounds__(512, 2) hybrid_fwd(Params p) {
;     ...
;                 for (int si = 0; si < (cc < 64 ? 1 : 3); ++si) {
;                     const int su = cc < 64 ? cc : 64 + (cc - 64) * 3 + si;
;                     const int v = su, kvh = v >> 7, n = (v >> 1) & 63, pr = v & 1;
;                     const int hl = wave >> 2, qh = kvh * 4 + pr * 2 + hl, tq0 = 128 * n + 32 * (wave & 3), t_row = tq0 + (lane & 31);
;                     attn_unit<1>(lds, tid, PROJ + (size_t)t_row * NP + PJ_SQ + qh * 128, PROJ + PJ_SK + kvh * 128, NP, VT + (size_t)(VT_S + kvh * 128) * T_, T_,
;                                  (2 * n - 2) < 0 ? 0 : (2 * n - 2), 2 * n + 2, t_row, tq0, nullptr, p.swa_sinks[l * 8 + qh] * LOG2E, 1.f, t5 + qh * 128,
.LBB0_558:
	s_add_i32 s6, s14, s23
	s_and_b64 s[4:5], exec, s[0:1]
	s_cselect_b32 s6, s12, s6
	s_bfe_u32 s24, s6, 0x60001
	s_ashr_i32 s4, s6, 5
	s_lshl_b32 s5, s6, 1
	s_lshl_b32 s72, s24, 7
	s_and_b32 s4, s4, -4
	s_and_b32 s5, s5, 2
	s_or_b32 s28, s72, s16
	s_or_b32 s4, s4, s5
	v_or_b32_e32 v160, s28, v145
	v_mov_b64_e32 v[0:1], s[8:9]
	s_add_i32 s25, s4, s15
	v_mad_u64_u32 v[146:147], s[4:5], v160, s56, v[0:1]
	s_and_b32 s10, s6, 0xffffff80
	s_lshl_b32 s4, s25, 7
	s_ashr_i32 s11, s10, 31
	s_ashr_i32 s5, s4, 31
	s_lshl_b64 s[6:7], s[10:11], 1
	s_add_u32 s26, s17, s6
	s_addc_u32 s27, s18, s7
	s_lshl_b64 s[10:11], s[10:11], 14
	s_add_u32 s10, s19, s10
	s_addc_u32 s11, s21, s11
	s_lshl_b32 s29, s24, 1
	s_add_i32 s30, s29, -2
	s_cmp_lg_u32 s24, 0
	s_cselect_b32 s24, s30, 0
	s_add_i32 s30, s25, s22
	s_ashr_i32 s31, s30, 31
	s_lshl_b64 s[30:31], s[30:31], 2
	s_add_u32 s30, s60, s30
	s_addc_u32 s31, s61, s31
	v_mov_b32_e32 v5, v144
	global_load_dword v4, v201, s[30:31]
	v_lshl_add_u64 v[0:1], s[4:5], 1, v[146:147]
	v_bfe_u32 v161, v5, 5, 1
	v_lshlrev_b32_e32 v200, 4, v161
	v_lshl_add_u64 v[0:1], v[0:1], 0, v[200:201]
	s_mov_b32 s25, 0x1f600000
	s_mov_b64 s[30:31], 0x1f600800
	v_add_co_u32_e32 v10, vcc, s25, v0
	v_ashrrev_i32_e32 v6, 4, v5
	s_or_b32 s25, s29, 1
	v_lshl_add_u64 v[8:9], v[0:1], 0, s[30:31]
	v_addc_co_u32_e32 v11, vcc, 0, v1, vcc
	v_lshl_add_u32 v13, s25, 6, v6
	v_mov_b64_e32 v[0:1], s[26:27]
	v_mad_i64_i32 v[2:3], s[26:27], v13, s56, v[0:1]
	v_lshlrev_b32_e32 v14, 4, v5
	v_add_u32_e32 v13, 32, v13
	v_ashrrev_i32_e32 v12, 3, v5
	v_and_b32_e32 v148, 0xf0, v14
	v_mov_b32_e32 v149, v201
	v_mad_i64_i32 v[0:1], s[26:27], v13, s56, v[0:1]
	global_load_dwordx4 v[96:99], v[8:9], off offset:32
	global_load_dwordx4 v[100:103], v[8:9], off offset:64
	global_load_dwordx4 v[104:107], v[8:9], off offset:96
	global_load_dwordx4 v[108:111], v[8:9], off offset:128
	v_lshl_add_u64 v[2:3], v[2:3], 0, v[148:149]
	v_lshl_add_u64 v[0:1], v[0:1], 0, v[148:149]
	v_ashrrev_i32_e32 v13, 31, v12
	s_waitcnt vmcnt(0)
	global_load_dwordx4 v[112:115], v[2:3], off
	global_load_dwordx4 v[116:119], v[0:1], off
	v_lshlrev_b64 v[0:1], 14, v[12:13]
	v_lshl_add_u64 v[2:3], s[10:11], 0, v[0:1]
	s_mov_b64 s[10:11], 0x800000
	v_and_b32_e32 v7, 7, v5
	v_lshl_add_u64 v[0:1], v[2:3], 0, s[10:11]
	s_lshl_b32 s10, s25, 7
	s_mov_b32 s11, s73
	s_mov_b64 s[26:27], 0x900000
	v_lshl_add_u64 v[14:15], v[0:1], 0, s[10:11]
	v_lshlrev_b32_e32 v150, 4, v7
	v_mov_b32_e32 v151, v201
	v_lshl_add_u64 v[2:3], v[2:3], 0, s[26:27]
	v_lshl_add_u64 v[14:15], v[14:15], 0, v[150:151]
	v_lshl_add_u64 v[16:17], v[2:3], 0, s[10:11]
	v_lshl_add_u64 v[16:17], v[16:17], 0, v[150:151]
	global_load_dwordx4 v[136:139], v[14:15], off
	global_load_dwordx4 v[140:143], v[16:17], off
	global_load_dwordx4 v[120:123], v[8:9], off offset:160
	global_load_dwordx4 v[124:127], v[8:9], off offset:192
	global_load_dwordx4 v[128:131], v[10:11], off offset:2048
	global_load_dwordx4 v[132:135], v[8:9], off offset:224
	s_movk_i32 s10, 0x110
	v_cmp_eq_u32_e32 vcc, 0, v161
	v_mul_lo_u32 v151, v6, s10
	v_mov_b32_e32 v15, 0
	s_cmp_lt_u32 s29, s24
	v_cndmask_b32_e64 v149, 0, 1.0, vcc
	v_mul_lo_u32 v162, v12, s83
	v_add3_u32 v8, 0, v151, v148
	v_add3_u32 v9, 0, v162, v150
	s_waitcnt vmcnt(0) lgkmcnt(0)
	ds_write_b128 v8, v[112:115]
	ds_write_b128 v8, v[116:119] offset:8704
	ds_write_b128 v9, v[136:139] offset:17408
	ds_write_b128 v9, v[140:143] offset:26624
	s_waitcnt lgkmcnt(0)
	s_barrier
	s_cbranch_scc1 .LBB0_556
	v_and_b32_e32 v8, 31, v5
	v_and_b32_e32 v9, 19, v5
	v_lshlrev_b32_e32 v10, 1, v5
	v_lshrrev_b32_e32 v5, 1, v5
	v_and_b32_e32 v10, 8, v10
	v_and_b32_e32 v5, 4, v5
	v_lshlrev_b32_e32 v7, 3, v7
	v_or3_b32 v5, v9, v10, v5
	v_mul_u32_u24_e32 v163, 0x90, v8
	s_lshl_b32 s10, s4, 2
	v_lshlrev_b32_e32 v8, 1, v7
	v_mov_b32_e32 v9, v201
	s_add_i32 s26, s10, 0
	v_lshl_add_u64 v[152:153], v[0:1], 0, v[8:9]
	v_lshl_add_u64 v[154:155], v[2:3], 0, v[8:9]
	v_mov_b32_e32 v0, s16
	s_movk_i32 s10, 0x78
	v_add_u32_e32 v2, s72, v6
	s_add_i32 s26, s26, 0x12000
	s_or_b32 s27, s28, 31
	s_addk_i32 s28, 0xff80
	v_mad_u32_u24 v167, v161, s10, v0
	v_add_u32_e32 v0, 32, v2
	v_mad_i64_i32 v[0:1], s[10:11], v0, s56, 0
	s_add_u32 s6, s17, s6
	v_or_b32_e32 v0, v0, v148
	s_addc_u32 s7, s18, s7
	v_lshl_add_u64 v[156:157], s[6:7], 0, v[0:1]
	v_mad_i64_i32 v[0:1], s[10:11], v2, s56, 0
	v_mul_u32_u24_e32 v5, 0x110, v5
	v_or_b32_e32 v0, v0, v148
	v_mov_b32_e32 v48, 0
	v_add_u32_e32 v164, v5, v200
	v_add_u32_e32 v165, 0x2400, v162
	v_mul_f32_e32 v168, 0x3fb8aa3b, v4
	v_mad_i32_i24 v166, v161, -8, s16
	v_lshl_add_u64 v[158:159], s[6:7], 0, v[0:1]
	v_mov_b32_e32 v49, v48
	v_mov_b32_e32 v50, v48
	v_mov_b32_e32 v51, v48
	v_mov_b32_e32 v52, v48
	v_mov_b32_e32 v53, v48
	v_mov_b32_e32 v54, v48
	v_mov_b32_e32 v55, v48
	v_mov_b32_e32 v56, v48
	v_mov_b32_e32 v57, v48
	v_mov_b32_e32 v58, v48
	v_mov_b32_e32 v59, v48
	v_mov_b32_e32 v60, v48
	v_mov_b32_e32 v61, v48
	v_mov_b32_e32 v62, v48
	v_mov_b32_e32 v63, v48
	v_mov_b32_e32 v32, v48
	v_mov_b32_e32 v33, v48
	v_mov_b32_e32 v34, v48
	v_mov_b32_e32 v35, v48
	v_mov_b32_e32 v36, v48
	v_mov_b32_e32 v37, v48
	v_mov_b32_e32 v38, v48
	v_mov_b32_e32 v39, v48
	v_mov_b32_e32 v40, v48
	v_mov_b32_e32 v41, v48
	v_mov_b32_e32 v42, v48
	v_mov_b32_e32 v43, v48
	v_mov_b32_e32 v44, v48
	v_mov_b32_e32 v45, v48
	v_mov_b32_e32 v46, v48
	v_mov_b32_e32 v47, v48
	v_mov_b32_e32 v16, v48
	v_mov_b32_e32 v17, v48
	v_mov_b32_e32 v18, v48
	v_mov_b32_e32 v19, v48
	v_mov_b32_e32 v20, v48
	v_mov_b32_e32 v21, v48
	v_mov_b32_e32 v22, v48
	v_mov_b32_e32 v23, v48
	v_mov_b32_e32 v24, v48
	v_mov_b32_e32 v25, v48
	v_mov_b32_e32 v26, v48
	v_mov_b32_e32 v27, v48
	v_mov_b32_e32 v28, v48
	v_mov_b32_e32 v29, v48
	v_mov_b32_e32 v30, v48
	v_mov_b32_e32 v31, v48
	v_mov_b32_e32 v0, v48
	v_mov_b32_e32 v1, v48
	v_mov_b32_e32 v2, v48
	v_mov_b32_e32 v3, v48
	v_mov_b32_e32 v4, v48
	v_mov_b32_e32 v5, v48
	v_mov_b32_e32 v6, v48
	v_mov_b32_e32 v7, v48
	v_mov_b32_e32 v8, v48
	v_mov_b32_e32 v9, v48
	v_mov_b32_e32 v10, v48
	v_mov_b32_e32 v11, v48
	v_mov_b32_e32 v12, v48
	v_mov_b32_e32 v13, v48
	v_mov_b32_e32 v14, v48
	v_mov_b32_e32 v15, v48
	s_branch .LBB0_561

; #define LAS __attribute__((address_space(3)))
; #define MFMA32(a, b, c) __builtin_amdgcn_mfma_f32_32x32x16_bf16((a), (b), (c), 0, 0, 0)
;     ...
;         const int cur = (kt1 - 1 - kt) & 1, k0 = kt * 64;
;         if (kt > kt0) AT_LOAD(kt - 1);
;         bool active = true;
;         if (MODE == 0) active = (k0 <= tq0 + 31) && !wdone;
;         if (MODE == 1) active = (k0 <= tq0 + 31) && (k0 + 63 > tq0 - 128);
;         if (active) {
;             const LAS unsigned char* base = lds + cur * AT_BUF;
;             f32x16 s0, s1;
; #pragma unroll
;             for (int i = 0; i < 16; ++i) { s0[i] = 0.f; s1[i] = 0.f; }
;             {
;                 bf16x8 ka[8];
; #pragma unroll
;                 for (int ks = 0; ks < 8; ++ks) ka[ks] = *(const LAS bf16x8*)(base + koff + ks * 32);
;                 __builtin_amdgcn_sched_barrier(0);
; #pragma unroll
;                 for (int ks = 0; ks < 8; ++ks) s0 = MFMA32(ka[ks], qf[ks], s0);
;                 __builtin_amdgcn_sched_barrier(0);
; #pragma unroll
;                 for (int ks = 0; ks < 8; ++ks) ka[ks] = *(const LAS bf16x8*)(base + 32 * AT_KROW + koff + ks * 32);
;                 __builtin_amdgcn_sched_barrier(0);
; #pragma unroll
;                 for (int ks = 0; ks < 8; ++ks) s1 = MFMA32(ka[ks], qf[ks], s1);
;             }
;             float x[32];
;             const LAS float* cbl = (const LAS float*)(base + AT_KBUF + AT_VBUF);
;             const bool need_mask = (MODE == 0) ? (k0 + 63 > tq0) : true;
;             float mx = NEG;
;             if (MODE == 1) {
; #pragma unroll
;                 for (int i = 0; i < 32; ++i) { const int ii = i & 15, kl = 32 * (i >> 4) + (ii & 7) + 8 * hh + 16 * (ii >> 3); x[i] = t5[(t_row - (k0 + kl)) & 127]; }
.LBB0_561:
	s_cmp_gt_i32 s25, s24
	s_cselect_b64 s[10:11], -1, 0
	s_cmp_le_i32 s25, s24
	s_cselect_b64 s[6:7], -1, 0
	s_and_b64 vcc, exec, s[6:7]
	s_cbranch_vccnz .LBB0_563
	s_lshl_b64 s[30:31], s[72:73], 1
	v_lshl_add_u64 v[64:65], v[152:153], 0, s[30:31]
	s_waitcnt vmcnt(0)
	global_load_dwordx4 v[112:115], v[158:159], off
	global_load_dwordx4 v[116:119], v[156:157], off
	v_lshl_add_u64 v[66:67], v[154:155], 0, s[30:31]
	global_load_dwordx4 v[136:139], v[64:65], off
	global_load_dwordx4 v[140:143], v[66:67], off
.LBB0_563:
	s_and_b32 s29, s25, 1
	s_add_i32 s30, s72, 64
	s_cmp_le_u32 s30, s27
	s_cselect_b64 s[30:31], -1, 0
	s_add_i32 s34, s72, 0x7f
	s_cmp_gt_i32 s34, s28
	s_cselect_b64 s[34:35], -1, 0
	s_and_b64 s[30:31], s[30:31], s[34:35]
	s_andn2_b64 vcc, exec, s[30:31]
	s_cbranch_vccnz .LBB0_565
	s_xor_b32 s30, s29, 1
	s_mul_i32 s30, s30, 0x8d00
	s_add_i32 s30, s30, 0
	v_add_u32_e32 v169, s30, v164
	ds_read_b128 v[64:67], v169
	ds_read_b128 v[80:83], v169 offset:32
	ds_read_b128 v[84:87], v169 offset:64
	ds_read_b128 v[88:91], v169 offset:96
	ds_read_b128 v[92:95], v169 offset:128
	ds_read_b128 v[170:173], v169 offset:160
	ds_read_b128 v[174:177], v169 offset:192
	ds_read_b128 v[178:181], v169 offset:224
	s_waitcnt lgkmcnt(7)
	v_mfma_f32_32x32x16_bf16 v[64:79], v[64:67], v[128:131], 0
	s_waitcnt lgkmcnt(6)
	v_mfma_f32_32x32x16_bf16 v[64:79], v[80:83], v[96:99], v[64:79]
	s_waitcnt lgkmcnt(5)
	v_mfma_f32_32x32x16_bf16 v[64:79], v[84:87], v[100:103], v[64:79]
	s_waitcnt lgkmcnt(4)
	v_mfma_f32_32x32x16_bf16 v[64:79], v[88:91], v[104:107], v[64:79]
	s_waitcnt lgkmcnt(3)
	v_mfma_f32_32x32x16_bf16 v[64:79], v[92:95], v[108:111], v[64:79]
	s_waitcnt lgkmcnt(2)
	v_mfma_f32_32x32x16_bf16 v[64:79], v[170:173], v[120:123], v[64:79]
	s_waitcnt lgkmcnt(1)
	v_mfma_f32_32x32x16_bf16 v[64:79], v[174:177], v[124:127], v[64:79]
	s_waitcnt lgkmcnt(0)
	v_mfma_f32_32x32x16_bf16 v[64:79], v[178:181], v[132:135], v[64:79]
	ds_read_b128 v[80:83], v169 offset:8704
	ds_read_b128 v[170:173], v169 offset:8736
	ds_read_b128 v[174:177], v169 offset:8768
	ds_read_b128 v[178:181], v169 offset:8800
	ds_read_b128 v[182:185], v169 offset:8832
	ds_read_b128 v[186:189], v169 offset:8864
	ds_read_b128 v[190:193], v169 offset:8896
	ds_read_b128 v[194:197], v169 offset:8928
	v_add_u32_e32 v169, v145, v167
	v_subrev_u32_e32 v84, 64, v169
	v_and_b32_e32 v84, 0x7f, v84
	v_add_u32_e32 v85, 63, v169
	v_add_u32_e32 v86, 62, v169
	v_add_u32_e32 v87, 61, v169
	v_add_u32_e32 v88, 60, v169
	v_add_u32_e32 v89, 59, v169
	v_add_u32_e32 v90, 58, v169
	v_add_u32_e32 v91, 57, v169
	v_lshl_add_u32 v84, v84, 2, s26
	v_and_b32_e32 v85, 0x7f, v85
	v_and_b32_e32 v86, 0x7f, v86
	v_and_b32_e32 v87, 0x7f, v87
	v_and_b32_e32 v88, 0x7f, v88
	v_and_b32_e32 v89, 0x7f, v89
	v_and_b32_e32 v90, 0x7f, v90
	v_and_b32_e32 v91, 0x7f, v91
	v_lshl_add_u32 v85, v85, 2, s26
	v_lshl_add_u32 v86, v86, 2, s26
	v_lshl_add_u32 v87, v87, 2, s26
	v_lshl_add_u32 v88, v88, 2, s26
	v_lshl_add_u32 v89, v89, 2, s26
	v_lshl_add_u32 v90, v90, 2, s26
	v_lshl_add_u32 v91, v91, 2, s26
	ds_read_b32 v198, v84
	ds_read_b32 v199, v85
	ds_read_b32 v202, v86
	ds_read_b32 v204, v87
	ds_read_b32 v205, v88
	ds_read_b32 v206, v89
	ds_read_b32 v207, v90
	ds_read_b32 v208, v91
	v_add_u32_e32 v84, 48, v169
	v_and_b32_e32 v84, 0x7f, v84
	v_add_u32_e32 v85, 47, v169
	v_add_u32_e32 v86, 46, v169
	v_add_u32_e32 v87, 45, v169
	v_add_u32_e32 v88, 44, v169
	v_add_u32_e32 v89, 43, v169
	v_add_u32_e32 v90, 42, v169
	v_add_u32_e32 v91, 41, v169
	v_lshl_add_u32 v84, v84, 2, s26
	v_and_b32_e32 v85, 0x7f, v85
	v_and_b32_e32 v86, 0x7f, v86
	v_and_b32_e32 v87, 0x7f, v87
	v_and_b32_e32 v88, 0x7f, v88
	v_and_b32_e32 v89, 0x7f, v89
	v_and_b32_e32 v90, 0x7f, v90
	v_and_b32_e32 v91, 0x7f, v91
	v_lshl_add_u32 v85, v85, 2, s26
	v_lshl_add_u32 v86, v86, 2, s26
	v_lshl_add_u32 v87, v87, 2, s26
	v_lshl_add_u32 v88, v88, 2, s26
	v_lshl_add_u32 v89, v89, 2, s26
	v_lshl_add_u32 v90, v90, 2, s26
	v_lshl_add_u32 v91, v91, 2, s26
	ds_read_b32 v209, v84
	ds_read_b32 v210, v85
	ds_read_b32 v211, v86
	ds_read_b32 v212, v87
	ds_read_b32 v213, v88
	ds_read_b32 v214, v89
	ds_read_b32 v215, v90
	ds_read_b32 v216, v91
	v_add_u32_e32 v84, 32, v169
	v_and_b32_e32 v84, 0x7f, v84
	v_lshl_add_u32 v217, v84, 2, s26
	v_add_u32_e32 v84, 31, v169
	v_and_b32_e32 v84, 0x7f, v84
	v_lshl_add_u32 v218, v84, 2, s26
	v_add_u32_e32 v84, 30, v169
	v_and_b32_e32 v84, 0x7f, v84
	v_lshl_add_u32 v219, v84, 2, s26
	s_waitcnt lgkmcnt(0)
; #define LAS __attribute__((address_space(3)))
; #define MFMA32(a, b, c) __builtin_amdgcn_mfma_f32_32x32x16_bf16((a), (b), (c), 0, 0, 0)
;     ...
;                 for (int ks = 0; ks < 8; ++ks) s1 = MFMA32(ka[ks], qf[ks], s1);
;             }
;             float x[32];
;             const LAS float* cbl = (const LAS float*)(base + AT_KBUF + AT_VBUF);
;             const bool need_mask = (MODE == 0) ? (k0 + 63 > tq0) : true;
;             float mx = NEG;
;             if (MODE == 1) {
; #pragma unroll
;                 for (int i = 0; i < 32; ++i) { const int ii = i & 15, kl = 32 * (i >> 4) + (ii & 7) + 8 * hh + 16 * (ii >> 3); x[i] = t5[(t_row - (k0 + kl)) & 127]; }
;                 __builtin_amdgcn_sched_barrier(0);
;             }
; #pragma unroll
;             for (int i = 0; i < 32; ++i) {
;                 const int blk = i >> 4, ii = i & 15, kl = 32 * blk + (ii & 7) + 8 * hh + 16 * (ii >> 3);
;                 float v = (blk ? s1[ii] : s0[ii]) * SC;
;                 if (MODE == 0) v += cbl[kl];
;                 if (MODE == 1) { const int rel = t_row - (k0 + kl); v = ((unsigned)rel < 128u) ? v + x[i] : NEG; }
	v_mfma_f32_32x32x16_bf16 v[80:95], v[80:83], v[128:131], 0
	v_add_u32_e32 v222, 27, v169
	v_add_u32_e32 v220, 29, v169
	v_add_u32_e32 v221, 28, v169
	v_and_b32_e32 v222, 0x7f, v222
	v_and_b32_e32 v220, 0x7f, v220
	v_and_b32_e32 v221, 0x7f, v221
	v_lshl_add_u32 v220, v220, 2, s26
	v_mfma_f32_32x32x16_bf16 v[80:95], v[170:173], v[96:99], v[80:95]
	v_add_u32_e32 v171, 26, v169
	v_add_u32_e32 v172, 25, v169
	v_and_b32_e32 v171, 0x7f, v171
	v_and_b32_e32 v172, 0x7f, v172
	v_lshl_add_u32 v170, v222, 2, s26
	v_lshl_add_u32 v171, v171, 2, s26
	v_lshl_add_u32 v172, v172, 2, s26
	v_mfma_f32_32x32x16_bf16 v[80:95], v[174:177], v[100:103], v[80:95]
	v_lshl_add_u32 v221, v221, 2, s26
	ds_read_b32 v173, v217
	ds_read_b32 v174, v218
	ds_read_b32 v175, v219
	ds_read_b32 v176, v220
	ds_read_b32 v177, v221
	ds_read_b32 v170, v170
	ds_read_b32 v171, v171
	ds_read_b32 v172, v172
	v_add_u32_e32 v217, 16, v169
	v_and_b32_e32 v217, 0x7f, v217
	v_lshl_add_u32 v217, v217, 2, s26
	v_mfma_f32_32x32x16_bf16 v[80:95], v[178:181], v[104:107], v[80:95]
	v_add_u32_e32 v178, 15, v169
	v_add_u32_e32 v179, 14, v169
	v_add_u32_e32 v180, 13, v169
	v_add_u32_e32 v181, 12, v169
	v_and_b32_e32 v178, 0x7f, v178
	v_and_b32_e32 v179, 0x7f, v179
	v_and_b32_e32 v180, 0x7f, v180
	v_mfma_f32_32x32x16_bf16 v[80:95], v[182:185], v[108:111], v[80:95]
	v_add_u32_e32 v182, 11, v169
	v_add_u32_e32 v183, 10, v169
	v_add_u32_e32 v169, 9, v169
	v_and_b32_e32 v181, 0x7f, v181
	v_and_b32_e32 v182, 0x7f, v182
	v_and_b32_e32 v183, 0x7f, v183
	v_and_b32_e32 v169, 0x7f, v169
	v_mfma_f32_32x32x16_bf16 v[80:95], v[186:189], v[120:123], v[80:95]
	v_lshl_add_u32 v178, v178, 2, s26
	v_lshl_add_u32 v179, v179, 2, s26
	v_lshl_add_u32 v180, v180, 2, s26
	v_lshl_add_u32 v181, v181, 2, s26
	v_lshl_add_u32 v182, v182, 2, s26
	v_lshl_add_u32 v183, v183, 2, s26
	v_lshl_add_u32 v169, v169, 2, s26
	ds_read_b32 v184, v217
	ds_read_b32 v178, v178
	ds_read_b32 v179, v179
	ds_read_b32 v180, v180
	ds_read_b32 v181, v181
	ds_read_b32 v182, v182
	ds_read_b32 v183, v183
	ds_read_b32 v169, v169
	v_mfma_f32_32x32x16_bf16 v[80:95], v[190:193], v[124:127], v[80:95]
	v_mfma_f32_32x32x16_bf16 v[80:95], v[194:197], v[132:135], v[80:95]
	v_add_u32_e32 v185, v145, v166
	v_subrev_u32_e32 v186, 64, v185
	v_fmac_f32_e32 v198, 0x3e0293ee, v64
	v_cmp_gt_u32_e32 vcc, s33, v186
	v_add_u32_e32 v186, 0xffffffbf, v185
	v_fmac_f32_e32 v199, 0x3e0293ee, v65
	v_cndmask_b32_e32 v64, v242, v198, vcc
	v_cmp_gt_u32_e32 vcc, s33, v186
	v_add_u32_e32 v186, 0xffffffbe, v185
	v_fmac_f32_e32 v202, 0x3e0293ee, v66
	v_cndmask_b32_e32 v65, v242, v199, vcc
	v_cmp_gt_u32_e32 vcc, s33, v186
	v_add_u32_e32 v186, 0xffffffbd, v185
	v_fmac_f32_e32 v204, 0x3e0293ee, v67
	v_cndmask_b32_e32 v66, v242, v202, vcc
	v_cmp_gt_u32_e32 vcc, s33, v186
	v_add_u32_e32 v186, 0xffffffbc, v185
	v_fmac_f32_e32 v205, 0x3e0293ee, v68
	v_cndmask_b32_e32 v67, v242, v204, vcc
	v_cmp_gt_u32_e32 vcc, s33, v186
	v_add_u32_e32 v186, 0xffffffbb, v185
	v_fmac_f32_e32 v206, 0x3e0293ee, v69
	v_cndmask_b32_e32 v68, v242, v205, vcc
	v_cmp_gt_u32_e32 vcc, s33, v186
	v_add_u32_e32 v186, 0xffffffba, v185
	v_fmac_f32_e32 v207, 0x3e0293ee, v70
	v_cndmask_b32_e32 v69, v242, v206, vcc
	v_cmp_gt_u32_e32 vcc, s33, v186
	v_add_u32_e32 v186, 0xffffffb9, v185
	v_fmac_f32_e32 v208, 0x3e0293ee, v71
	v_cndmask_b32_e32 v70, v242, v207, vcc
	v_cmp_gt_u32_e32 vcc, s33, v186
	v_add_u32_e32 v186, 0xffffffb0, v185
	v_fmac_f32_e32 v209, 0x3e0293ee, v72
	v_cndmask_b32_e32 v71, v242, v208, vcc
	v_cmp_gt_u32_e32 vcc, s33, v186
	v_add_u32_e32 v186, 0xffffffaf, v185
	v_fmac_f32_e32 v210, 0x3e0293ee, v73
	v_cndmask_b32_e32 v72, v242, v209, vcc
	v_cmp_gt_u32_e32 vcc, s33, v186
	v_add_u32_e32 v186, 0xffffffae, v185
	v_fmac_f32_e32 v211, 0x3e0293ee, v74
	v_cndmask_b32_e32 v73, v242, v210, vcc
	v_cmp_gt_u32_e32 vcc, s33, v186
	v_add_u32_e32 v186, 0xffffffad, v185
	v_fmac_f32_e32 v212, 0x3e0293ee, v75
	v_cndmask_b32_e32 v74, v242, v211, vcc
	v_cmp_gt_u32_e32 vcc, s33, v186
	v_add_u32_e32 v186, 0xffffffac, v185
	v_fmac_f32_e32 v213, 0x3e0293ee, v76
	v_cndmask_b32_e32 v75, v242, v212, vcc
	v_cmp_gt_u32_e32 vcc, s33, v186
	v_add_u32_e32 v186, 0xffffffab, v185
	v_fmac_f32_e32 v214, 0x3e0293ee, v77
	v_cndmask_b32_e32 v76, v242, v213, vcc
	v_cmp_gt_u32_e32 vcc, s33, v186
	v_add_u32_e32 v186, 0xffffffaa, v185
	v_fmac_f32_e32 v215, 0x3e0293ee, v78
	v_cndmask_b32_e32 v77, v242, v214, vcc
	v_cmp_gt_u32_e32 vcc, s33, v186
	v_add_u32_e32 v186, 0xffffffa9, v185
	v_fmac_f32_e32 v216, 0x3e0293ee, v79
	v_cndmask_b32_e32 v78, v242, v215, vcc
	v_cmp_gt_u32_e32 vcc, s33, v186
	v_add_u32_e32 v186, 0xffffffa0, v185
	s_waitcnt lgkmcnt(0)
; __device__ __forceinline__ float ex2(float x) { return __builtin_amdgcn_exp2f(x); }
; __device__ __forceinline__ float xmax(float v) { const auto r = __builtin_amdgcn_permlane32_swap(__float_as_uint(v), __float_as_uint(v), false, false); return fmaxf(__uint_as_float(r[0]), __uint_as_float(r[1])); }
;     ...
;             for (int i = 0; i < 32; ++i) {
;                 const int blk = i >> 4, ii = i & 15, kl = 32 * blk + (ii & 7) + 8 * hh + 16 * (ii >> 3);
;                 float v = (blk ? s1[ii] : s0[ii]) * SC;
;                 if (MODE == 0) v += cbl[kl];
;                 if (MODE == 1) { const int rel = t_row - (k0 + kl); v = ((unsigned)rel < 128u) ? v + x[i] : NEG; }
;                 x[i] = v;
;             }
;             if (MODE == 0 && need_mask) {
; #pragma unroll
;                 for (int i = 0; i < 32; ++i) { const int ii = i & 15, kl = 32 * (i >> 4) + (ii & 7) + 8 * hh + 16 * (ii >> 3); if (k0 + kl > t_row) x[i] = NEG; }
;             }
; #pragma unroll
;             for (int i = 0; i < 32; ++i) mx = fmaxf(mx, x[i]);
;             mx = xmax(mx);
;             const float mn = fmaxf(m, mx), alpha = ex2(m - mn); m = mn;
;             float rs = 0.f;
; #pragma unroll
;             for (int i = 0; i < 32; ++i) { x[i] = ex2(x[i] - mn); rs += x[i]; }
	v_fmac_f32_e32 v173, 0x3e0293ee, v80
	v_cndmask_b32_e32 v79, v242, v216, vcc
	v_cmp_gt_u32_e32 vcc, s33, v186
	v_fmac_f32_e32 v174, 0x3e0293ee, v81
	v_fmac_f32_e32 v175, 0x3e0293ee, v82
	v_cndmask_b32_e32 v80, v242, v173, vcc
	v_add_u32_e32 v173, 0xffffff9f, v185
	v_cmp_gt_u32_e32 vcc, s33, v173
	v_add_u32_e32 v173, 0xffffff9e, v185
	v_fmac_f32_e32 v176, 0x3e0293ee, v83
	v_cndmask_b32_e32 v81, v242, v174, vcc
	v_cmp_gt_u32_e32 vcc, s33, v173
	v_add_u32_e32 v173, 0xffffff9d, v185
	v_fmac_f32_e32 v177, 0x3e0293ee, v84
	v_cndmask_b32_e32 v82, v242, v175, vcc
	v_cmp_gt_u32_e32 vcc, s33, v173
	v_add_u32_e32 v173, 0xffffff9c, v185
	v_fmac_f32_e32 v170, 0x3e0293ee, v85
	v_cndmask_b32_e32 v83, v242, v176, vcc
	v_cmp_gt_u32_e32 vcc, s33, v173
	v_add_u32_e32 v173, 0xffffff9b, v185
	v_fmac_f32_e32 v171, 0x3e0293ee, v86
	v_cndmask_b32_e32 v84, v242, v177, vcc
	v_cmp_gt_u32_e32 vcc, s33, v173
	v_fmac_f32_e32 v172, 0x3e0293ee, v87
	v_fmac_f32_e32 v184, 0x3e0293ee, v88
	v_cndmask_b32_e32 v85, v242, v170, vcc
	v_add_u32_e32 v170, 0xffffff9a, v185
	v_cmp_gt_u32_e32 vcc, s33, v170
	v_add_u32_e32 v170, 0xffffff99, v185
	v_fmac_f32_e32 v178, 0x3e0293ee, v89
	v_cndmask_b32_e32 v86, v242, v171, vcc
	v_cmp_gt_u32_e32 vcc, s33, v170
	v_add_u32_e32 v170, 0xffffff90, v185
	v_fmac_f32_e32 v179, 0x3e0293ee, v90
	v_cndmask_b32_e32 v87, v242, v172, vcc
	v_cmp_gt_u32_e32 vcc, s33, v170
	v_add_u32_e32 v170, 0xffffff8f, v185
	v_fmac_f32_e32 v180, 0x3e0293ee, v91
	v_cndmask_b32_e32 v88, v242, v184, vcc
	v_cmp_gt_u32_e32 vcc, s33, v170
	v_add_u32_e32 v170, 0xffffff8e, v185
	v_fmac_f32_e32 v181, 0x3e0293ee, v92
	v_cndmask_b32_e32 v89, v242, v178, vcc
	v_cmp_gt_u32_e32 vcc, s33, v170
	v_add_u32_e32 v170, 0xffffff8d, v185
	v_fmac_f32_e32 v182, 0x3e0293ee, v93
	v_cndmask_b32_e32 v90, v242, v179, vcc
	v_cmp_gt_u32_e32 vcc, s33, v170
	v_add_u32_e32 v170, 0xffffff8c, v185
	v_fmac_f32_e32 v183, 0x3e0293ee, v94
	v_cndmask_b32_e32 v91, v242, v180, vcc
	v_cmp_gt_u32_e32 vcc, s33, v170
	v_add_u32_e32 v170, 0xffffff8b, v185
	v_fmac_f32_e32 v169, 0x3e0293ee, v95
	v_cndmask_b32_e32 v92, v242, v181, vcc
	v_cmp_gt_u32_e32 vcc, s33, v170
	v_add_u32_e32 v170, 0xffffff8a, v185
	s_nop 0
	v_cndmask_b32_e32 v93, v242, v182, vcc
	v_cmp_gt_u32_e32 vcc, s33, v170
	v_add_u32_e32 v170, 0xffffff89, v185
	s_nop 0
	v_cndmask_b32_e32 v94, v242, v183, vcc
	v_cmp_gt_u32_e32 vcc, s33, v170
	s_nop 1
	v_cndmask_b32_e32 v95, v242, v169, vcc
	v_max3_f32 v169, v64, s36, v65
	v_max3_f32 v169, v169, v66, v67
	v_max3_f32 v169, v169, v68, v69
	v_max3_f32 v169, v169, v70, v71
	v_max3_f32 v169, v169, v72, v73
	v_max3_f32 v169, v169, v74, v75
	v_max3_f32 v169, v169, v76, v77
	v_max3_f32 v169, v169, v78, v79
	v_max3_f32 v169, v169, v80, v81
	v_max3_f32 v169, v169, v82, v83
	v_max3_f32 v169, v169, v84, v85
	v_max3_f32 v169, v169, v86, v87
	v_max3_f32 v169, v169, v88, v89
	v_max3_f32 v169, v169, v90, v91
	v_max3_f32 v169, v169, v92, v93
	v_max3_f32 v169, v169, v94, v95
	v_mov_b32_e32 v170, v169
	s_nop 1
	v_permlane32_swap_b32_e32 v169, v170
	v_max3_f32 v188, v168, v169, v170
	v_sub_f32_e32 v64, v64, v188
	v_exp_f32_e32 v169, v64
	v_sub_f32_e32 v64, v65, v188
	v_exp_f32_e32 v65, v64
	v_sub_f32_e32 v64, v66, v188
	v_exp_f32_e32 v170, v64
	v_sub_f32_e32 v64, v67, v188
	v_sub_f32_e32 v66, v94, v188
	v_exp_f32_e32 v67, v64
	v_sub_f32_e32 v64, v68, v188
	v_exp_f32_e32 v94, v66
	v_sub_f32_e32 v66, v95, v188
	v_exp_f32_e32 v68, v64
	v_sub_f32_e32 v64, v69, v188
	v_exp_f32_e32 v95, v66
	v_add_f32_e32 v66, 0, v169
	v_exp_f32_e32 v69, v64
	v_sub_f32_e32 v64, v70, v188
	v_add_f32_e32 v66, v65, v66
	v_exp_f32_e32 v70, v64
	v_sub_f32_e32 v64, v71, v188
	v_add_f32_e32 v66, v170, v66
	v_exp_f32_e32 v71, v64
	v_sub_f32_e32 v64, v72, v188
	v_add_f32_e32 v66, v67, v66
	v_exp_f32_e32 v72, v64
	v_sub_f32_e32 v64, v73, v188
	v_add_f32_e32 v66, v68, v66
	v_exp_f32_e32 v73, v64
	v_sub_f32_e32 v64, v74, v188
	v_add_f32_e32 v66, v69, v66
	v_exp_f32_e32 v74, v64
	v_sub_f32_e32 v64, v75, v188
	v_add_f32_e32 v66, v70, v66
	v_exp_f32_e32 v75, v64
	v_sub_f32_e32 v64, v76, v188
	v_add_f32_e32 v66, v71, v66
	v_exp_f32_e32 v76, v64
	v_sub_f32_e32 v64, v77, v188
	v_add_f32_e32 v66, v72, v66
	v_exp_f32_e32 v77, v64
	v_sub_f32_e32 v64, v78, v188
	v_add_f32_e32 v66, v73, v66
	v_exp_f32_e32 v78, v64
	v_sub_f32_e32 v64, v79, v188
	v_add_f32_e32 v66, v74, v66
	v_exp_f32_e32 v79, v64
	v_sub_f32_e32 v64, v80, v188
	v_add_f32_e32 v66, v75, v66
	v_exp_f32_e32 v80, v64
	v_sub_f32_e32 v64, v81, v188
	v_add_f32_e32 v66, v76, v66
	v_exp_f32_e32 v81, v64
	v_sub_f32_e32 v64, v82, v188
	v_add_f32_e32 v66, v77, v66
	v_exp_f32_e32 v82, v64
	v_sub_f32_e32 v64, v83, v188
	v_add_f32_e32 v66, v78, v66
	v_exp_f32_e32 v83, v64
	v_sub_f32_e32 v64, v84, v188
	v_add_f32_e32 v66, v79, v66
	v_exp_f32_e32 v84, v64
	v_sub_f32_e32 v64, v85, v188
	v_add_f32_e32 v66, v80, v66
	v_exp_f32_e32 v85, v64
	v_sub_f32_e32 v64, v86, v188
	v_add_f32_e32 v66, v81, v66
	v_exp_f32_e32 v86, v64
	v_sub_f32_e32 v64, v87, v188
	v_add_f32_e32 v66, v82, v66
	v_exp_f32_e32 v87, v64
	v_sub_f32_e32 v64, v88, v188
	v_add_f32_e32 v66, v83, v66
; #define LAS __attribute__((address_space(3)))
; __device__ __forceinline__ float ex2(float x) { return __builtin_amdgcn_exp2f(x); }
; #define MFMA32(a, b, c) __builtin_amdgcn_mfma_f32_32x32x16_bf16((a), (b), (c), 0, 0, 0)
;     ...
;             const float mn = fmaxf(m, mx), alpha = ex2(m - mn); m = mn;
;             float rs = 0.f;
; #pragma unroll
;             for (int i = 0; i < 32; ++i) { x[i] = ex2(x[i] - mn); rs += x[i]; }
;             l = l * alpha + rs;
; #pragma unroll
;             for (int db = 0; db < 4; ++db)
; #pragma unroll
;                 for (int i = 0; i < 16; ++i) o[db][i] *= alpha;
;             bf16x8 pf[4];
; #pragma unroll
;             for (int j = 0; j < 4; ++j) pf[j] = pack8(x[8 * j], x[8 * j + 1], x[8 * j + 2], x[8 * j + 3], x[8 * j + 4], x[8 * j + 5], x[8 * j + 6], x[8 * j + 7]);
; #pragma unroll
;             for (int jh = 0; jh < 2; ++jh) {
;                 bf16x8 va[2][4];
; #pragma unroll
;                 for (int j = 0; j < 2; ++j)
; #pragma unroll
;                     for (int db = 0; db < 4; ++db) va[j][db] = *(const LAS bf16x8*)(base + voff + db * 32 * AT_VROW + (2 * jh + j) * 32);
;                 __builtin_amdgcn_sched_barrier(0);
; #pragma unroll
;                 for (int j = 0; j < 2; ++j)
; #pragma unroll
;                     for (int db = 0; db < 4; ++db) o[db] = MFMA32(va[j][db], pf[2 * jh + j], o[db]);
;                 __builtin_amdgcn_sched_barrier(0);
;             }
	v_exp_f32_e32 v184, v64
	v_sub_f32_e32 v64, v89, v188
	v_add_f32_e32 v66, v84, v66
	v_exp_f32_e32 v185, v64
	v_sub_f32_e32 v64, v90, v188
	v_add_f32_e32 v66, v85, v66
	v_exp_f32_e32 v186, v64
	v_sub_f32_e32 v64, v91, v188
	v_add_f32_e32 v66, v86, v66
	v_exp_f32_e32 v187, v64
	v_sub_f32_e32 v64, v92, v188
	v_add_f32_e32 v66, v87, v66
	v_exp_f32_e32 v189, v64
	v_sub_f32_e32 v64, v93, v188
	v_add_f32_e32 v66, v184, v66
	v_exp_f32_e32 v190, v64
	v_add_f32_e32 v66, v185, v66
	v_sub_f32_e32 v168, v168, v188
	v_add_f32_e32 v66, v186, v66
	v_exp_f32_e32 v64, v168
	v_add_f32_e32 v66, v187, v66
	v_add_f32_e32 v66, v189, v66
	v_add_f32_e32 v66, v190, v66
	v_add_f32_e32 v66, v94, v66
	v_pk_mul_f32 v[62:63], v[62:63], v[64:65] op_sel_hi:[1,0]
	v_pk_mul_f32 v[60:61], v[60:61], v[64:65] op_sel_hi:[1,0]
	v_pk_mul_f32 v[58:59], v[58:59], v[64:65] op_sel_hi:[1,0]
	v_pk_mul_f32 v[56:57], v[56:57], v[64:65] op_sel_hi:[1,0]
	v_pk_mul_f32 v[54:55], v[54:55], v[64:65] op_sel_hi:[1,0]
	v_pk_mul_f32 v[52:53], v[52:53], v[64:65] op_sel_hi:[1,0]
	v_pk_mul_f32 v[50:51], v[50:51], v[64:65] op_sel_hi:[1,0]
	v_pk_mul_f32 v[48:49], v[48:49], v[64:65] op_sel_hi:[1,0]
	v_pk_mul_f32 v[46:47], v[46:47], v[64:65] op_sel_hi:[1,0]
	v_pk_mul_f32 v[44:45], v[44:45], v[64:65] op_sel_hi:[1,0]
	v_pk_mul_f32 v[42:43], v[42:43], v[64:65] op_sel_hi:[1,0]
	v_pk_mul_f32 v[40:41], v[40:41], v[64:65] op_sel_hi:[1,0]
	v_pk_mul_f32 v[38:39], v[38:39], v[64:65] op_sel_hi:[1,0]
	v_pk_mul_f32 v[36:37], v[36:37], v[64:65] op_sel_hi:[1,0]
	v_pk_mul_f32 v[34:35], v[34:35], v[64:65] op_sel_hi:[1,0]
	v_pk_mul_f32 v[32:33], v[32:33], v[64:65] op_sel_hi:[1,0]
	v_pk_mul_f32 v[30:31], v[30:31], v[64:65] op_sel_hi:[1,0]
	v_pk_mul_f32 v[28:29], v[28:29], v[64:65] op_sel_hi:[1,0]
	v_pk_mul_f32 v[26:27], v[26:27], v[64:65] op_sel_hi:[1,0]
	v_pk_mul_f32 v[24:25], v[24:25], v[64:65] op_sel_hi:[1,0]
	v_pk_mul_f32 v[22:23], v[22:23], v[64:65] op_sel_hi:[1,0]
	v_pk_mul_f32 v[20:21], v[20:21], v[64:65] op_sel_hi:[1,0]
	v_pk_mul_f32 v[18:19], v[18:19], v[64:65] op_sel_hi:[1,0]
	v_pk_mul_f32 v[16:17], v[16:17], v[64:65] op_sel_hi:[1,0]
	v_pk_mul_f32 v[14:15], v[14:15], v[64:65] op_sel_hi:[1,0]
	v_pk_mul_f32 v[12:13], v[12:13], v[64:65] op_sel_hi:[1,0]
	v_pk_mul_f32 v[10:11], v[10:11], v[64:65] op_sel_hi:[1,0]
	v_pk_mul_f32 v[8:9], v[8:9], v[64:65] op_sel_hi:[1,0]
	v_pk_mul_f32 v[6:7], v[6:7], v[64:65] op_sel_hi:[1,0]
	v_pk_mul_f32 v[4:5], v[4:5], v[64:65] op_sel_hi:[1,0]
	v_pk_mul_f32 v[2:3], v[2:3], v[64:65] op_sel_hi:[1,0]
	v_pk_mul_f32 v[0:1], v[0:1], v[64:65] op_sel_hi:[1,0]
	v_add_f32_e32 v191, v95, v66
	v_cvt_pk_bf16_f32 v66, v169, v65
	v_add3_u32 v65, s30, v163, v200
	v_cvt_pk_bf16_f32 v67, v170, v67
	v_cvt_pk_bf16_f32 v68, v68, v69
	v_cvt_pk_bf16_f32 v69, v70, v71
	v_cvt_pk_bf16_f32 v70, v72, v73
	v_cvt_pk_bf16_f32 v71, v74, v75
	v_cvt_pk_bf16_f32 v72, v76, v77
	v_cvt_pk_bf16_f32 v73, v78, v79
	v_cvt_pk_bf16_f32 v74, v80, v81
	v_cvt_pk_bf16_f32 v75, v82, v83
	v_cvt_pk_bf16_f32 v76, v84, v85
	v_cvt_pk_bf16_f32 v77, v86, v87
	ds_read_b128 v[78:81], v65 offset:17408
	ds_read_b128 v[82:85], v65 offset:17440
	ds_read_b128 v[86:89], v65 offset:22016
	ds_read_b128 v[90:93], v65 offset:22048
	ds_read_b128 v[168:171], v65 offset:26624
	ds_read_b128 v[172:175], v65 offset:26656
	ds_read_b128 v[176:179], v65 offset:31232
	ds_read_b128 v[180:183], v65 offset:31264
	v_cvt_pk_bf16_f32 v184, v184, v185
	v_cvt_pk_bf16_f32 v185, v186, v187
	v_cvt_pk_bf16_f32 v186, v189, v190
	v_cvt_pk_bf16_f32 v187, v94, v95
	s_waitcnt lgkmcnt(0)
	v_mfma_f32_32x32x16_bf16 v[48:63], v[78:81], v[66:69], v[48:63]
	v_mfma_f32_32x32x16_bf16 v[32:47], v[86:89], v[66:69], v[32:47]
	v_mfma_f32_32x32x16_bf16 v[16:31], v[168:171], v[66:69], v[16:31]
	v_mfma_f32_32x32x16_bf16 v[0:15], v[176:179], v[66:69], v[0:15]
	v_mfma_f32_32x32x16_bf16 v[48:63], v[82:85], v[70:73], v[48:63]
	v_mfma_f32_32x32x16_bf16 v[32:47], v[90:93], v[70:73], v[32:47]
	v_mfma_f32_32x32x16_bf16 v[16:31], v[172:175], v[70:73], v[16:31]
	v_mfma_f32_32x32x16_bf16 v[0:15], v[180:183], v[70:73], v[0:15]
	ds_read_b128 v[66:69], v65 offset:17472
	ds_read_b128 v[70:73], v65 offset:17504
	ds_read_b128 v[78:81], v65 offset:22080
	ds_read_b128 v[82:85], v65 offset:22112
	ds_read_b128 v[86:89], v65 offset:26688
	ds_read_b128 v[90:93], v65 offset:26720
	ds_read_b128 v[168:171], v65 offset:31296
	ds_read_b128 v[172:175], v65 offset:31328
	s_waitcnt lgkmcnt(7)
	v_mfma_f32_32x32x16_bf16 v[48:63], v[66:69], v[74:77], v[48:63]
	s_waitcnt lgkmcnt(5)
	v_mfma_f32_32x32x16_bf16 v[32:47], v[78:81], v[74:77], v[32:47]
	s_waitcnt lgkmcnt(3)
	v_mfma_f32_32x32x16_bf16 v[16:31], v[86:89], v[74:77], v[16:31]
	s_waitcnt lgkmcnt(1)
	v_mfma_f32_32x32x16_bf16 v[0:15], v[168:171], v[74:77], v[0:15]
	v_mfma_f32_32x32x16_bf16 v[48:63], v[70:73], v[184:187], v[48:63]
	v_mfma_f32_32x32x16_bf16 v[32:47], v[82:85], v[184:187], v[32:47]
	v_mfma_f32_32x32x16_bf16 v[16:31], v[90:93], v[184:187], v[16:31]
	s_waitcnt lgkmcnt(0)
	v_mfma_f32_32x32x16_bf16 v[0:15], v[172:175], v[184:187], v[0:15]
	v_fmac_f32_e32 v191, v149, v64
	v_mov_b32_e32 v149, v191
	v_mov_b32_e32 v168, v188

; #define LAS __attribute__((address_space(3)))
; __device__ __forceinline__ float bflo(unsigned w) { return __uint_as_float(w << 16); }
; __device__ __forceinline__ float bfhi(unsigned w) { return __uint_as_float(w & 0xffff0000u); }
; __device__ __forceinline__ float xsum(float v) { const auto r = __builtin_amdgcn_permlane32_swap(__float_as_uint(v), __float_as_uint(v), false, false); return __uint_as_float(r[0]) + __uint_as_float(r[1]); }
;     ...
; #pragma unroll
;     for (int ks = 0; ks < 8; ++ks) qf[ks] = *(const bf16x8*)(Qrow + 16 * ks + 8 * hh);
;     f32x16 o[4];
; #pragma unroll
;     for (int db = 0; db < 4; ++db)
; #pragma unroll
;         for (int i = 0; i < 16; ++i) o[db][i] = 0.f;
;     float m = m_init, l = (hh == 0) ? l_init : 0.f;
;     const int pr = (r & ~12) | ((r & 4) << 1) | ((r & 8) >> 1);
;     const unsigned koff = pr * AT_KROW + 16 * hh, voff = AT_KBUF + r * AT_VROW + 16 * hh;
;     const int kkey0 = tid >> 4, kc16 = tid & 15, vd0 = tid >> 3, vc8 = tid & 7;
;     u32x4 kreg[2], vreg[2]; float creg = 0.f;
;     ...
;     float qn = 0.f; bool wdone = false;
;     LAS unsigned* flg = (LAS unsigned*)(lds + 2 * AT_BUF);
;     if (MODE == 0) {
; #pragma unroll
;         for (int ks = 0; ks < 8; ++ks) { const u32x4 qq = __builtin_bit_cast(u32x4, qf[ks]);
;             qn += bflo(qq.x) * bflo(qq.x) + bfhi(qq.x) * bfhi(qq.x) + bflo(qq.y) * bflo(qq.y) + bfhi(qq.y) * bfhi(qq.y) + bflo(qq.z) * bflo(qq.z) + bfhi(qq.z) * bfhi(qq.z) + bflo(qq.w) * bflo(qq.w) + bfhi(qq.w) * bfhi(qq.w); }
;         qn = xsum(qn); qn = sqrtf(qn) * kn * SC * 1.0001f + 1e-3f;
; __global__ void __launch_bounds__(512, 2) hybrid_fwd(Params p) {
;     ...
;                     const int qb = 31 - (u >> 2), hd = u & 3, tq0 = 256 * qb + 32 * wave, t_row = tq0 + (lane & 31);
;                     attn_unit<0>(lds, tid, PROJ + (size_t)t_row * NP + PJ_FQ + hd * 128, PROJ + PJ_FK + hd * 128, NP, VT + (size_t)(VT_F + hd * 128) * T_, T_,
;                                  0, 4 * (qb + 1), t_row, tq0, CC + (size_t)hd * T_, NEG, 0.f, nullptr, O + (size_t)t_row * D_ + hd * 128, sqrtf(__uint_as_float(KNB[l * 4 + hd])));
.LBB0_568:
	s_lshl_b32 s0, s2, 6
	s_and_b32 s12, s0, 0xffffff00
	s_lshl_b32 s0, s3, 5
	s_sub_i32 s13, s0, s12
	s_add_i32 s3, s13, 0x1f00
	s_and_b32 s14, s2, 3
	v_and_or_b32 v146, v144, 31, s3
	v_mov_b64_e32 v[0:1], s[8:9]
	v_mad_i64_i32 v[0:1], s[0:1], v146, s56, v[0:1]
	s_lshl_b32 s72, s14, 8
	s_add_u32 s0, s8, s72
	s_addc_u32 s1, s9, 0
	s_add_u32 s6, s0, 0x1f600400
	s_addc_u32 s7, s1, 0
	s_lshl_b32 s0, s14, 21
	s_add_u32 s0, s8, s0
	s_addc_u32 s1, s9, 0
	s_and_b32 s4, s2, -4
	s_lshl_b32 s5, s14, 15
	s_add_u32 s5, s8, s5
	s_addc_u32 s11, s9, 0
	s_add_u32 s10, s5, 0x38f00000
	v_lshl_add_u64 v[0:1], v[0:1], 0, s[72:73]
	s_addc_u32 s11, s11, 0
	s_or_b32 s72, s14, s20
	s_lshl_b64 s[16:17], s[72:73], 2
	s_add_u32 s5, s8, s16
	s_addc_u32 s15, s9, s17
	v_mov_b32_e32 v2, s5
	s_mov_b32 s5, 0x38f80000
	v_add_co_u32_e32 v2, vcc, s5, v2
	v_mov_b32_e32 v3, s15
	s_nop 0
	v_addc_co_u32_e32 v3, vcc, 0, v3, vcc
	v_mov_b32_e32 v145, v144
	global_load_dword v6, v[2:3], off
	s_mov_b64 s[16:17], 0x1f600000
	v_bfe_u32 v7, v145, 5, 1
	v_lshlrev_b32_e32 v200, 4, v7
	v_lshl_add_u64 v[0:1], v[0:1], 0, v[200:201]
	s_mov_b32 s5, 0x1f600000
	v_lshl_add_u64 v[2:3], v[0:1], 0, s[16:17]
	v_add_co_u32_e32 v0, vcc, s5, v0
	s_sub_i32 s15, 0x7f, s4
	s_nop 0
	v_addc_co_u32_e32 v1, vcc, 0, v1, vcc
	global_load_dwordx4 v[96:99], v[0:1], off
	global_load_dwordx4 v[100:103], v[2:3], off offset:32
	global_load_dwordx4 v[104:107], v[2:3], off offset:64
	global_load_dwordx4 v[108:111], v[2:3], off offset:96
	s_waitcnt vmcnt(0)
	global_load_dwordx4 v[112:115], v[2:3], off offset:128
	global_load_dwordx4 v[116:119], v[2:3], off offset:160
	global_load_dwordx4 v[120:123], v[2:3], off offset:192
	global_load_dwordx4 v[124:127], v[2:3], off offset:224
	v_ashrrev_i32_e32 v168, 4, v145
	s_lshl_b32 s72, s15, 6
	v_and_b32_e32 v10, 15, v145
	v_ashrrev_i32_e32 v0, 3, v145
	v_lshlrev_b32_e32 v148, 4, v10
	v_mov_b32_e32 v149, v201
	v_and_b32_e32 v11, 7, v145
	v_lshlrev_b32_e32 v150, 4, v11
	v_mov_b32_e32 v151, v201
	s_waitcnt lgkmcnt(0)
	v_and_b32_e32 v2, 0xffff0000, v96
	v_lshlrev_b32_e32 v1, 16, v96
	v_mul_f32_e32 v2, v2, v2
	v_fmac_f32_e32 v2, v1, v1
	v_lshlrev_b32_e32 v1, 16, v97
	v_fmac_f32_e32 v2, v1, v1
	v_and_b32_e32 v1, 0xffff0000, v97
	v_fmac_f32_e32 v2, v1, v1
	v_lshlrev_b32_e32 v1, 16, v98
	v_fmac_f32_e32 v2, v1, v1
	v_and_b32_e32 v1, 0xffff0000, v98
	v_fmac_f32_e32 v2, v1, v1
	v_lshlrev_b32_e32 v1, 16, v99
	v_fmac_f32_e32 v2, v1, v1
	v_and_b32_e32 v1, 0xffff0000, v99
	v_and_b32_e32 v3, 0xffff0000, v100
	v_fmac_f32_e32 v2, v1, v1
	v_lshlrev_b32_e32 v1, 16, v100
	v_mul_f32_e32 v3, v3, v3
	v_fmac_f32_e32 v3, v1, v1
	v_lshlrev_b32_e32 v1, 16, v101
	v_fmac_f32_e32 v3, v1, v1
	v_and_b32_e32 v1, 0xffff0000, v101
	v_fmac_f32_e32 v3, v1, v1
	v_lshlrev_b32_e32 v1, 16, v102
	v_fmac_f32_e32 v3, v1, v1
	v_and_b32_e32 v1, 0xffff0000, v102
	v_fmac_f32_e32 v3, v1, v1
	v_lshlrev_b32_e32 v1, 16, v103
	v_fmac_f32_e32 v3, v1, v1
	v_and_b32_e32 v1, 0xffff0000, v103
	v_fmac_f32_e32 v3, v1, v1
	v_add_f32_e32 v1, v2, v3
	v_and_b32_e32 v3, 0xffff0000, v104
	v_lshlrev_b32_e32 v2, 16, v104
	v_mul_f32_e32 v3, v3, v3
	v_fmac_f32_e32 v3, v2, v2
	v_lshlrev_b32_e32 v2, 16, v105
	v_fmac_f32_e32 v3, v2, v2
	v_and_b32_e32 v2, 0xffff0000, v105
	v_fmac_f32_e32 v3, v2, v2
	v_lshlrev_b32_e32 v2, 16, v106
	v_fmac_f32_e32 v3, v2, v2
	v_and_b32_e32 v2, 0xffff0000, v106
	v_fmac_f32_e32 v3, v2, v2
	v_lshlrev_b32_e32 v2, 16, v107
	v_fmac_f32_e32 v3, v2, v2
	v_and_b32_e32 v2, 0xffff0000, v107
	v_fmac_f32_e32 v3, v2, v2
	v_add_f32_e32 v1, v1, v3
	v_and_b32_e32 v3, 0xffff0000, v108
	v_lshlrev_b32_e32 v2, 16, v108
	v_mul_f32_e32 v3, v3, v3
	v_fmac_f32_e32 v3, v2, v2
	v_lshlrev_b32_e32 v2, 16, v109
	v_fmac_f32_e32 v3, v2, v2
	v_and_b32_e32 v2, 0xffff0000, v109
	v_fmac_f32_e32 v3, v2, v2
	v_lshlrev_b32_e32 v2, 16, v110
	v_fmac_f32_e32 v3, v2, v2
	v_and_b32_e32 v2, 0xffff0000, v110
	v_fmac_f32_e32 v3, v2, v2
	v_lshlrev_b32_e32 v2, 16, v111
	v_fmac_f32_e32 v3, v2, v2
	v_and_b32_e32 v2, 0xffff0000, v111
	v_fmac_f32_e32 v3, v2, v2
	v_add_f32_e32 v1, v1, v3
	s_waitcnt vmcnt(0)
; #define LAS __attribute__((address_space(3)))
; __device__ __forceinline__ float bflo(unsigned w) { return __uint_as_float(w << 16); }
; __device__ __forceinline__ float bfhi(unsigned w) { return __uint_as_float(w & 0xffff0000u); }
; __device__ __forceinline__ float xsum(float v) { const auto r = __builtin_amdgcn_permlane32_swap(__float_as_uint(v), __float_as_uint(v), false, false); return __uint_as_float(r[0]) + __uint_as_float(r[1]); }
;     ...
;     float qn = 0.f; bool wdone = false;
;     LAS unsigned* flg = (LAS unsigned*)(lds + 2 * AT_BUF);
;     if (MODE == 0) {
; #pragma unroll
;         for (int ks = 0; ks < 8; ++ks) { const u32x4 qq = __builtin_bit_cast(u32x4, qf[ks]);
;             qn += bflo(qq.x) * bflo(qq.x) + bfhi(qq.x) * bfhi(qq.x) + bflo(qq.y) * bflo(qq.y) + bfhi(qq.y) * bfhi(qq.y) + bflo(qq.z) * bflo(qq.z) + bfhi(qq.z) * bfhi(qq.z) + bflo(qq.w) * bflo(qq.w) + bfhi(qq.w) * bfhi(qq.w); }
;         qn = xsum(qn); qn = sqrtf(qn) * kn * SC * 1.0001f + 1e-3f;
;     }
;     AT_LOAD(kt1 - 1); AT_WRITE(0); __syncthreads();
	v_and_b32_e32 v3, 0xffff0000, v112
	v_lshlrev_b32_e32 v2, 16, v112
	v_mul_f32_e32 v3, v3, v3
	v_fmac_f32_e32 v3, v2, v2
	v_lshlrev_b32_e32 v2, 16, v113
	v_fmac_f32_e32 v3, v2, v2
	v_and_b32_e32 v2, 0xffff0000, v113
	v_fmac_f32_e32 v3, v2, v2
	v_lshlrev_b32_e32 v2, 16, v114
	v_fmac_f32_e32 v3, v2, v2
	v_and_b32_e32 v2, 0xffff0000, v114
	v_fmac_f32_e32 v3, v2, v2
	v_lshlrev_b32_e32 v2, 16, v115
	v_fmac_f32_e32 v3, v2, v2
	v_and_b32_e32 v2, 0xffff0000, v115
	v_fmac_f32_e32 v3, v2, v2
	v_add_f32_e32 v1, v1, v3
	v_and_b32_e32 v3, 0xffff0000, v116
	v_lshlrev_b32_e32 v2, 16, v116
	v_mul_f32_e32 v3, v3, v3
	v_fmac_f32_e32 v3, v2, v2
	v_lshlrev_b32_e32 v2, 16, v117
	v_fmac_f32_e32 v3, v2, v2
	v_and_b32_e32 v2, 0xffff0000, v117
	v_fmac_f32_e32 v3, v2, v2
	v_lshlrev_b32_e32 v2, 16, v118
	v_fmac_f32_e32 v3, v2, v2
	v_and_b32_e32 v2, 0xffff0000, v118
	v_fmac_f32_e32 v3, v2, v2
	v_lshlrev_b32_e32 v2, 16, v119
	v_fmac_f32_e32 v3, v2, v2
	v_and_b32_e32 v2, 0xffff0000, v119
	v_fmac_f32_e32 v3, v2, v2
	v_add_f32_e32 v1, v1, v3
	v_and_b32_e32 v3, 0xffff0000, v120
	v_lshlrev_b32_e32 v2, 16, v120
	v_mul_f32_e32 v3, v3, v3
	v_fmac_f32_e32 v3, v2, v2
	v_lshlrev_b32_e32 v2, 16, v121
	v_fmac_f32_e32 v3, v2, v2
	v_and_b32_e32 v2, 0xffff0000, v121
	v_fmac_f32_e32 v3, v2, v2
	v_lshlrev_b32_e32 v2, 16, v122
	v_fmac_f32_e32 v3, v2, v2
	v_and_b32_e32 v2, 0xffff0000, v122
	v_fmac_f32_e32 v3, v2, v2
	v_lshlrev_b32_e32 v2, 16, v123
	v_fmac_f32_e32 v3, v2, v2
	v_and_b32_e32 v2, 0xffff0000, v123
	v_fmac_f32_e32 v3, v2, v2
	v_add_f32_e32 v1, v1, v3
	v_and_b32_e32 v3, 0xffff0000, v124
	v_lshlrev_b32_e32 v2, 16, v124
	v_mul_f32_e32 v3, v3, v3
	v_fmac_f32_e32 v3, v2, v2
	v_lshlrev_b32_e32 v2, 16, v125
	v_fmac_f32_e32 v3, v2, v2
	v_and_b32_e32 v2, 0xffff0000, v125
	v_fmac_f32_e32 v3, v2, v2
	v_lshlrev_b32_e32 v2, 16, v126
	v_fmac_f32_e32 v3, v2, v2
	v_and_b32_e32 v2, 0xffff0000, v126
	v_fmac_f32_e32 v3, v2, v2
	v_lshlrev_b32_e32 v2, 16, v127
	v_fmac_f32_e32 v3, v2, v2
	v_and_b32_e32 v2, 0xffff0000, v127
	v_fmac_f32_e32 v3, v2, v2
	v_add_f32_e32 v8, v1, v3
	v_add_u32_e32 v1, s72, v168
	v_mov_b64_e32 v[2:3], s[6:7]
	v_mad_i64_i32 v[4:5], s[4:5], v1, s56, v[2:3]
	v_add_u32_e32 v1, 32, v1
	v_mad_i64_i32 v[2:3], s[4:5], v1, s56, v[2:3]
	v_lshl_add_u64 v[4:5], v[4:5], 0, v[148:149]
	v_lshl_add_u64 v[2:3], v[2:3], 0, v[148:149]
	v_ashrrev_i32_e32 v1, 31, v0
	global_load_dwordx4 v[128:131], v[4:5], off
	global_load_dwordx4 v[132:135], v[2:3], off
	v_lshlrev_b64 v[2:3], 14, v[0:1]
	v_lshl_add_u64 v[4:5], s[0:1], 0, v[2:3]
	s_mov_b64 s[0:1], 0x22f00000
	v_lshl_add_u64 v[2:3], v[4:5], 0, s[0:1]
	s_lshl_b64 s[0:1], s[72:73], 1
	v_lshl_add_u64 v[12:13], v[2:3], 0, s[0:1]
	s_mov_b64 s[4:5], 0x23000000
	v_lshl_add_u64 v[12:13], v[12:13], 0, v[150:151]
	v_lshl_add_u64 v[4:5], v[4:5], 0, s[4:5]
	global_load_dwordx4 v[136:139], v[12:13], off
	v_lshl_add_u64 v[12:13], v[4:5], 0, s[0:1]
	v_lshl_add_u64 v[12:13], v[12:13], 0, v[150:151]
	global_load_dwordx4 v[140:143], v[12:13], off
	v_mov_b32_e32 v9, v8
	s_nop 1
	v_permlane32_swap_b32_e32 v8, v9
	v_cmp_gt_i32_e64 s[0:1], 64, v145
	v_mov_b32_e32 v149, 0
	s_and_saveexec_b64 s[4:5], s[0:1]
	s_cbranch_execz .LBB0_570
	v_add_u32_e32 v12, s72, v145
	v_ashrrev_i32_e32 v13, 31, v12
	v_lshl_add_u64 v[12:13], v[12:13], 2, s[10:11]
	global_load_dword v149, v[12:13], off

;     ...
;         const int cur = (kt1 - 1 - kt) & 1, k0 = kt * 64;
;         if (kt > kt0) AT_LOAD(kt - 1);
.LBB0_573:
	v_add_u32_e32 v66, s18, v168
	v_add_u32_e32 v64, 0xffffff81, v66
	v_add_u32_e32 v66, 0xffffffa1, v66
	s_add_i32 s72, s18, 0xffffff81
	v_mad_i64_i32 v[64:65], s[14:15], v64, s56, v[152:153]
	v_mad_i64_i32 v[66:67], s[14:15], v66, s56, v[152:153]
	s_lshl_b64 s[14:15], s[72:73], 1
	s_waitcnt vmcnt(0)
	global_load_dwordx4 v[128:131], v[64:65], off
	global_load_dwordx4 v[132:135], v[66:67], off
	v_lshl_add_u64 v[64:65], v[154:155], 0, s[14:15]
	v_lshl_add_u64 v[66:67], v[156:157], 0, s[14:15]
	global_load_dwordx4 v[136:139], v[64:65], off
	global_load_dwordx4 v[140:143], v[66:67], off
	s_and_saveexec_b64 s[14:15], s[0:1]
	s_cbranch_execz .LBB0_575
	v_add_u32_e32 v64, s18, v145
	v_add_u32_e32 v64, 0xffffff81, v64
	v_ashrrev_i32_e32 v65, 31, v64
	v_lshl_add_u64 v[64:65], v[64:65], 2, s[10:11]
	global_load_dword v149, v[64:65], off

; #define LAS __attribute__((address_space(3)))
; #define MFMA32(a, b, c) __builtin_amdgcn_mfma_f32_32x32x16_bf16((a), (b), (c), 0, 0, 0)
;     ...
;         if (MODE == 0) active = (k0 <= tq0 + 31) && !wdone;
;         if (MODE == 1) active = (k0 <= tq0 + 31) && (k0 + 63 > tq0 - 128);
;         if (active) {
;             const LAS unsigned char* base = lds + cur * AT_BUF;
;             f32x16 s0, s1;
; #pragma unroll
;             for (int i = 0; i < 16; ++i) { s0[i] = 0.f; s1[i] = 0.f; }
;             {
;                 bf16x8 ka[8];
; #pragma unroll
;                 for (int ks = 0; ks < 8; ++ks) ka[ks] = *(const LAS bf16x8*)(base + koff + ks * 32);
;                 __builtin_amdgcn_sched_barrier(0);
; #pragma unroll
;                 for (int ks = 0; ks < 8; ++ks) s0 = MFMA32(ka[ks], qf[ks], s0);
;                 __builtin_amdgcn_sched_barrier(0);
; #pragma unroll
;                 for (int ks = 0; ks < 8; ++ks) ka[ks] = *(const LAS bf16x8*)(base + 32 * AT_KROW + koff + ks * 32);
;                 __builtin_amdgcn_sched_barrier(0);
; #pragma unroll
;                 for (int ks = 0; ks < 8; ++ks) s1 = MFMA32(ka[ks], qf[ks], s1);
;             }
;             float x[32];
;             const LAS float* cbl = (const LAS float*)(base + AT_KBUF + AT_VBUF);
;             const bool need_mask = (MODE == 0) ? (k0 + 63 > tq0) : true;
;             float mx = NEG;
;             if (MODE == 1) {
; #pragma unroll
;                 for (int i = 0; i < 32; ++i) { const int ii = i & 15, kl = 32 * (i >> 4) + (ii & 7) + 8 * hh + 16 * (ii >> 3); x[i] = t5[(t_row - (k0 + kl)) & 127]; }
;                 __builtin_amdgcn_sched_barrier(0);
;             }
; #pragma unroll
;             for (int i = 0; i < 32; ++i) {
;                 const int blk = i >> 4, ii = i & 15, kl = 32 * blk + (ii & 7) + 8 * hh + 16 * (ii >> 3);
;                 float v = (blk ? s1[ii] : s0[ii]) * SC;
;                 if (MODE == 0) v += cbl[kl];
;                 if (MODE == 1) { const int rel = t_row - (k0 + kl); v = ((unsigned)rel < 128u) ? v + x[i] : NEG; }
;                 x[i] = v;
;             }
;             if (MODE == 0 && need_mask) {
; #pragma unroll
;                 for (int i = 0; i < 32; ++i) { const int ii = i & 15, kl = 32 * (i >> 4) + (ii & 7) + 8 * hh + 16 * (ii >> 3); if (k0 + kl > t_row) x[i] = NEG; }
.LBB0_576:
	s_sub_i32 s14, s18, 63
	s_cmp_gt_i32 s14, s17
	s_cselect_b64 s[20:21], -1, 0
	v_and_b32_e32 v181, 1, v178
	s_or_b64 s[20:21], s[20:21], s[12:13]
	v_xor_b32_e32 v180, 1, v181
	s_and_b64 vcc, exec, s[20:21]
	s_cbranch_vccnz .LBB0_582
	s_mov_b32 s12, 0x8d00
	v_mul_lo_u32 v64, v180, s12
	v_add_u32_e32 v182, 0, v64
	v_add_u32_e32 v166, v182, v173
	ds_read_b128 v[64:67], v166
	ds_read_b128 v[80:83], v166 offset:32
	ds_read_b128 v[84:87], v166 offset:64
	ds_read_b128 v[88:91], v166 offset:96
	ds_read_b128 v[92:95], v166 offset:128
	ds_read_b128 v[158:161], v166 offset:160
	ds_read_b128 v[162:165], v166 offset:192
	ds_read_b128 v[184:187], v166 offset:224
	s_waitcnt lgkmcnt(7)
	v_mfma_f32_32x32x16_bf16 v[64:79], v[64:67], v[96:99], 0
	s_waitcnt lgkmcnt(6)
	v_mfma_f32_32x32x16_bf16 v[64:79], v[80:83], v[100:103], v[64:79]
	s_waitcnt lgkmcnt(5)
	v_mfma_f32_32x32x16_bf16 v[64:79], v[84:87], v[104:107], v[64:79]
	s_waitcnt lgkmcnt(4)
	v_mfma_f32_32x32x16_bf16 v[64:79], v[88:91], v[108:111], v[64:79]
	s_waitcnt lgkmcnt(3)
	v_mfma_f32_32x32x16_bf16 v[64:79], v[92:95], v[112:115], v[64:79]
	s_waitcnt lgkmcnt(2)
	v_mfma_f32_32x32x16_bf16 v[64:79], v[158:161], v[116:119], v[64:79]
	s_waitcnt lgkmcnt(1)
	v_mfma_f32_32x32x16_bf16 v[64:79], v[162:165], v[120:123], v[64:79]
	s_waitcnt lgkmcnt(0)
	v_mfma_f32_32x32x16_bf16 v[64:79], v[184:187], v[124:127], v[64:79]
	ds_read_b128 v[80:83], v166 offset:8704
	ds_read_b128 v[158:161], v166 offset:8736
	ds_read_b128 v[162:165], v166 offset:8768
	ds_read_b128 v[184:187], v166 offset:8800
	ds_read_b128 v[188:191], v166 offset:8832
	ds_read_b128 v[192:195], v166 offset:8864
	ds_read_b128 v[196:199], v166 offset:8896
	ds_read_b128 v[204:207], v166 offset:8928
	s_waitcnt lgkmcnt(7)
	v_mfma_f32_32x32x16_bf16 v[80:95], v[80:83], v[96:99], 0
	s_cmp_le_i32 s18, s3
	s_waitcnt lgkmcnt(6)
	v_mfma_f32_32x32x16_bf16 v[80:95], v[158:161], v[100:103], v[80:95]
	v_add_u32_e32 v158, v182, v176
	s_waitcnt lgkmcnt(5)
	v_mfma_f32_32x32x16_bf16 v[80:95], v[162:165], v[104:107], v[80:95]
	s_waitcnt lgkmcnt(4)
	v_mfma_f32_32x32x16_bf16 v[80:95], v[184:187], v[108:111], v[80:95]
	s_waitcnt lgkmcnt(3)
	v_mfma_f32_32x32x16_bf16 v[80:95], v[188:191], v[112:115], v[80:95]
	s_waitcnt lgkmcnt(2)
	v_mfma_f32_32x32x16_bf16 v[80:95], v[192:195], v[116:119], v[80:95]
	s_waitcnt lgkmcnt(1)
	v_mfma_f32_32x32x16_bf16 v[80:95], v[196:199], v[120:123], v[80:95]
	s_waitcnt lgkmcnt(0)
	v_mfma_f32_32x32x16_bf16 v[80:95], v[204:207], v[124:127], v[80:95]
	ds_read_b128 v[184:187], v158 offset:35840
	ds_read_b128 v[164:167], v158 offset:35856
	ds_read_b128 v[160:163], v158 offset:35904
	ds_read_b128 v[188:191], v158 offset:35920
	ds_read_b128 v[192:195], v158 offset:35968
	ds_read_b128 v[196:199], v158 offset:35984
	ds_read_b128 v[204:207], v158 offset:36032
	ds_read_b128 v[208:211], v158 offset:36048
	s_waitcnt lgkmcnt(0)
	v_pk_fma_f32 v[78:79], v[78:79], s[94:95], v[190:191] op_sel_hi:[1,0,1]
	v_pk_fma_f32 v[76:77], v[76:77], s[94:95], v[188:189] op_sel_hi:[1,0,1]
	v_pk_fma_f32 v[158:159], v[74:75], s[94:95], v[162:163] op_sel_hi:[1,0,1]
	v_pk_fma_f32 v[160:161], v[72:73], s[94:95], v[160:161] op_sel_hi:[1,0,1]
	v_pk_fma_f32 v[162:163], v[70:71], s[94:95], v[166:167] op_sel_hi:[1,0,1]
	v_pk_fma_f32 v[164:165], v[68:69], s[94:95], v[164:165] op_sel_hi:[1,0,1]
	v_pk_fma_f32 v[166:167], v[66:67], s[94:95], v[186:187] op_sel_hi:[1,0,1]
	v_pk_fma_f32 v[66:67], v[94:95], s[94:95], v[210:211] op_sel_hi:[1,0,1]
	v_pk_fma_f32 v[68:69], v[92:93], s[94:95], v[208:209] op_sel_hi:[1,0,1]
	v_pk_fma_f32 v[70:71], v[90:91], s[94:95], v[206:207] op_sel_hi:[1,0,1]
	v_pk_fma_f32 v[72:73], v[88:89], s[94:95], v[204:205] op_sel_hi:[1,0,1]
	v_pk_fma_f32 v[74:75], v[86:87], s[94:95], v[198:199] op_sel_hi:[1,0,1]
	v_pk_fma_f32 v[84:85], v[84:85], s[94:95], v[196:197] op_sel_hi:[1,0,1]
	v_pk_fma_f32 v[82:83], v[82:83], s[94:95], v[194:195] op_sel_hi:[1,0,1]
	v_pk_fma_f32 v[86:87], v[64:65], s[94:95], v[184:185] op_sel_hi:[1,0,1]
	v_pk_fma_f32 v[80:81], v[80:81], s[94:95], v[192:193] op_sel_hi:[1,0,1]
	s_cbranch_scc1 .LBB0_579
	v_add_u32_e32 v64, s18, v151
	v_subrev_u32_e32 v65, 63, v64
	v_cmp_lt_i32_e32 vcc, v65, v146
	s_nop 1
	v_cndmask_b32_e32 v87, v242, v87, vcc
	v_cmp_le_i32_e32 vcc, v65, v146
	v_subrev_u32_e32 v65, 61, v64
	s_nop 0
	v_cndmask_b32_e32 v86, v242, v86, vcc
	v_cmp_le_i32_e32 vcc, v65, v146
	v_subrev_u32_e32 v65, 60, v64
	s_nop 0
	v_cndmask_b32_e32 v166, v242, v166, vcc
	v_cmp_le_i32_e32 vcc, v65, v146
	v_subrev_u32_e32 v65, 59, v64
	s_nop 0
	v_cndmask_b32_e32 v167, v242, v167, vcc
	v_cmp_le_i32_e32 vcc, v65, v146
	v_subrev_u32_e32 v65, 58, v64
	s_nop 0
	v_cndmask_b32_e32 v164, v242, v164, vcc
	v_cmp_le_i32_e32 vcc, v65, v146
	v_subrev_u32_e32 v65, 57, v64
	s_nop 0
	v_cndmask_b32_e32 v165, v242, v165, vcc
	v_cmp_le_i32_e32 vcc, v65, v146
	v_subrev_u32_e32 v65, 56, v64
	s_nop 0
	v_cndmask_b32_e32 v162, v242, v162, vcc
	v_cmp_le_i32_e32 vcc, v65, v146
	v_subrev_u32_e32 v65, 47, v64
	s_nop 0
	v_cndmask_b32_e32 v163, v242, v163, vcc
	v_cmp_le_i32_e32 vcc, v65, v146
	v_subrev_u32_e32 v65, 46, v64
	s_nop 0
	v_cndmask_b32_e32 v160, v242, v160, vcc
	v_cmp_le_i32_e32 vcc, v65, v146
	v_subrev_u32_e32 v65, 45, v64
	s_nop 0
	v_cndmask_b32_e32 v161, v242, v161, vcc
	v_cmp_le_i32_e32 vcc, v65, v146
	v_subrev_u32_e32 v65, 44, v64
	s_nop 0
	v_cndmask_b32_e32 v158, v242, v158, vcc
	v_cmp_le_i32_e32 vcc, v65, v146
	v_subrev_u32_e32 v65, 43, v64
	s_nop 0
	v_cndmask_b32_e32 v159, v242, v159, vcc
	v_cmp_le_i32_e32 vcc, v65, v146
	v_subrev_u32_e32 v65, 42, v64
	s_nop 0
	v_cndmask_b32_e32 v76, v242, v76, vcc
	v_cmp_le_i32_e32 vcc, v65, v146
	v_subrev_u32_e32 v65, 41, v64
; #define LAS __attribute__((address_space(3)))
; __device__ __forceinline__ float ex2(float x) { return __builtin_amdgcn_exp2f(x); }
; __device__ __forceinline__ float xmax(float v) { const auto r = __builtin_amdgcn_permlane32_swap(__float_as_uint(v), __float_as_uint(v), false, false); return fmaxf(__uint_as_float(r[0]), __uint_as_float(r[1])); }
;     ...
;                 for (int i = 0; i < 32; ++i) { const int ii = i & 15, kl = 32 * (i >> 4) + (ii & 7) + 8 * hh + 16 * (ii >> 3); if (k0 + kl > t_row) x[i] = NEG; }
;             }
; #pragma unroll
;             for (int i = 0; i < 32; ++i) mx = fmaxf(mx, x[i]);
;             mx = xmax(mx);
;             const float mn = fmaxf(m, mx), alpha = ex2(m - mn); m = mn;
;             float rs = 0.f;
; #pragma unroll
;             for (int i = 0; i < 32; ++i) { x[i] = ex2(x[i] - mn); rs += x[i]; }
;             l = l * alpha + rs;
; #pragma unroll
;             for (int db = 0; db < 4; ++db)
; #pragma unroll
;                 for (int i = 0; i < 16; ++i) o[db][i] *= alpha;
;             bf16x8 pf[4];
; #pragma unroll
;             for (int j = 0; j < 4; ++j) pf[j] = pack8(x[8 * j], x[8 * j + 1], x[8 * j + 2], x[8 * j + 3], x[8 * j + 4], x[8 * j + 5], x[8 * j + 6], x[8 * j + 7]);
; #pragma unroll
;             for (int jh = 0; jh < 2; ++jh) {
;                 bf16x8 va[2][4];
; #pragma unroll
;                 for (int j = 0; j < 2; ++j)
; #pragma unroll
;                     for (int db = 0; db < 4; ++db) va[j][db] = *(const LAS bf16x8*)(base + voff + db * 32 * AT_VROW + (2 * jh + j) * 32);
	s_nop 0
	v_cndmask_b32_e32 v77, v242, v77, vcc
	v_cmp_le_i32_e32 vcc, v65, v146
	v_subrev_u32_e32 v65, 40, v64
	s_nop 0
	v_cndmask_b32_e32 v78, v242, v78, vcc
	v_cmp_le_i32_e32 vcc, v65, v146
	v_subrev_u32_e32 v65, 31, v64
	s_nop 0
	v_cndmask_b32_e32 v79, v242, v79, vcc
	v_cmp_le_i32_e32 vcc, v65, v146
	v_subrev_u32_e32 v65, 30, v64
	s_nop 0
	v_cndmask_b32_e32 v80, v242, v80, vcc
	v_cmp_le_i32_e32 vcc, v65, v146
	v_subrev_u32_e32 v65, 29, v64
	s_nop 0
	v_cndmask_b32_e32 v81, v242, v81, vcc
	v_cmp_le_i32_e32 vcc, v65, v146
	v_subrev_u32_e32 v65, 28, v64
	s_nop 0
	v_cndmask_b32_e32 v82, v242, v82, vcc
	v_cmp_le_i32_e32 vcc, v65, v146
	v_subrev_u32_e32 v65, 27, v64
	s_nop 0
	v_cndmask_b32_e32 v83, v242, v83, vcc
	v_cmp_le_i32_e32 vcc, v65, v146
	v_subrev_u32_e32 v65, 26, v64
	s_nop 0
	v_cndmask_b32_e32 v84, v242, v84, vcc
	v_cmp_le_i32_e32 vcc, v65, v146
	v_subrev_u32_e32 v65, 25, v64
	s_nop 0
	v_cndmask_b32_e32 v85, v242, v85, vcc
	v_cmp_le_i32_e32 vcc, v65, v146
	v_subrev_u32_e32 v65, 24, v64
	s_nop 0
	v_cndmask_b32_e32 v74, v242, v74, vcc
	v_cmp_le_i32_e32 vcc, v65, v146
	v_add_u32_e32 v65, -15, v64
	s_nop 0
	v_cndmask_b32_e32 v75, v242, v75, vcc
	v_cmp_le_i32_e32 vcc, v65, v146
	v_add_u32_e32 v65, -14, v64
	s_nop 0
	v_cndmask_b32_e32 v72, v242, v72, vcc
	v_cmp_le_i32_e32 vcc, v65, v146
	v_add_u32_e32 v65, -13, v64
	s_nop 0
	v_cndmask_b32_e32 v73, v242, v73, vcc
	v_cmp_le_i32_e32 vcc, v65, v146
	v_add_u32_e32 v65, -12, v64
	s_nop 0
	v_cndmask_b32_e32 v70, v242, v70, vcc
	v_cmp_le_i32_e32 vcc, v65, v146
	v_add_u32_e32 v65, -11, v64
	s_nop 0
	v_cndmask_b32_e32 v71, v242, v71, vcc
	v_cmp_le_i32_e32 vcc, v65, v146
	v_add_u32_e32 v65, -10, v64
	s_nop 0
	v_cndmask_b32_e32 v68, v242, v68, vcc
	v_cmp_le_i32_e32 vcc, v65, v146
	v_add_u32_e32 v65, -9, v64
	v_add_u32_e32 v64, -8, v64
	v_cndmask_b32_e32 v69, v242, v69, vcc
	v_cmp_le_i32_e32 vcc, v65, v146
	s_nop 1
	v_cndmask_b32_e32 v66, v242, v66, vcc
	v_cmp_le_i32_e32 vcc, v64, v146
	s_nop 1
	v_cndmask_b32_e32 v67, v242, v67, vcc
.LBB0_579:
	v_max3_f32 v64, v86, s36, v87
	v_max3_f32 v64, v64, v166, v167
	v_max3_f32 v64, v64, v164, v165
	v_max3_f32 v64, v64, v162, v163
	v_max3_f32 v64, v64, v160, v161
	v_max3_f32 v64, v64, v158, v159
	v_max3_f32 v64, v64, v76, v77
	v_max3_f32 v64, v64, v78, v79
	v_max3_f32 v64, v64, v80, v81
	v_max3_f32 v64, v64, v82, v83
	v_max3_f32 v64, v64, v84, v85
	v_max3_f32 v64, v64, v74, v75
	v_max3_f32 v64, v64, v72, v73
	v_max3_f32 v64, v64, v70, v71
	v_max3_f32 v64, v64, v68, v69
	v_max3_f32 v64, v64, v66, v67
	v_mov_b32_e32 v65, v64
	s_nop 1
	v_permlane32_swap_b32_e32 v64, v65
	v_max3_f32 v65, v183, v64, v65
	v_sub_f32_e32 v64, v183, v65
	v_sub_f32_e32 v94, v160, v65
	v_sub_f32_e32 v160, v66, v65
	v_exp_f32_e32 v66, v64
	v_sub_f32_e32 v64, v67, v65
	v_exp_f32_e32 v67, v64
	v_add3_u32 v64, v182, v174, v200
	ds_read_b128 v[192:195], v64 offset:17408
	ds_read_b128 v[196:199], v64 offset:17440
	ds_read_b128 v[204:207], v64 offset:22016
	ds_read_b128 v[208:211], v64 offset:22048
	ds_read_b128 v[212:215], v64 offset:26624
	ds_read_b128 v[216:219], v64 offset:26656
	ds_read_b128 v[220:223], v64 offset:31232
	ds_read_b128 v[224:227], v64 offset:31264
	v_sub_f32_e32 v86, v86, v65
	v_sub_f32_e32 v87, v87, v65
	v_sub_f32_e32 v88, v166, v65
	v_sub_f32_e32 v89, v167, v65
	v_sub_f32_e32 v90, v164, v65
	v_sub_f32_e32 v91, v165, v65
	v_sub_f32_e32 v92, v162, v65
	v_sub_f32_e32 v93, v163, v65
	v_sub_f32_e32 v95, v161, v65
	v_sub_f32_e32 v158, v158, v65
	v_sub_f32_e32 v159, v159, v65
	v_sub_f32_e32 v76, v76, v65
	v_sub_f32_e32 v77, v77, v65
	v_sub_f32_e32 v78, v78, v65
	v_sub_f32_e32 v79, v79, v65
	v_sub_f32_e32 v80, v80, v65
	v_sub_f32_e32 v81, v81, v65
	v_sub_f32_e32 v82, v82, v65
	v_sub_f32_e32 v83, v83, v65
	v_sub_f32_e32 v84, v84, v65
	v_sub_f32_e32 v85, v85, v65
	v_sub_f32_e32 v74, v74, v65
	v_sub_f32_e32 v75, v75, v65
	v_sub_f32_e32 v72, v72, v65
	v_sub_f32_e32 v73, v73, v65
	v_sub_f32_e32 v70, v70, v65
	v_sub_f32_e32 v71, v71, v65
	v_sub_f32_e32 v68, v68, v65
	v_sub_f32_e32 v69, v69, v65
	v_exp_f32_e32 v86, v86
	v_exp_f32_e32 v87, v87
	v_exp_f32_e32 v88, v88
	v_exp_f32_e32 v89, v89
	v_exp_f32_e32 v90, v90
	v_exp_f32_e32 v91, v91
	v_exp_f32_e32 v92, v92
	v_exp_f32_e32 v93, v93
	v_exp_f32_e32 v94, v94
	v_exp_f32_e32 v95, v95
	v_exp_f32_e32 v158, v158
	v_exp_f32_e32 v159, v159
	v_exp_f32_e32 v76, v76
	v_exp_f32_e32 v77, v77
	v_exp_f32_e32 v78, v78
	v_exp_f32_e32 v79, v79
	v_exp_f32_e32 v80, v80
	v_exp_f32_e32 v81, v81
	v_exp_f32_e32 v82, v82
	v_exp_f32_e32 v83, v83
	v_exp_f32_e32 v84, v84
	v_exp_f32_e32 v85, v85
	v_exp_f32_e32 v74, v74
; #define LAS __attribute__((address_space(3)))
; __device__ __forceinline__ float ex2(float x) { return __builtin_amdgcn_exp2f(x); }
; #define MFMA32(a, b, c) __builtin_amdgcn_mfma_f32_32x32x16_bf16((a), (b), (c), 0, 0, 0)
;     ...
;             for (int i = 0; i < 32; ++i) { x[i] = ex2(x[i] - mn); rs += x[i]; }
;             l = l * alpha + rs;
; #pragma unroll
;             for (int db = 0; db < 4; ++db)
; #pragma unroll
;                 for (int i = 0; i < 16; ++i) o[db][i] *= alpha;
;             bf16x8 pf[4];
; #pragma unroll
;             for (int j = 0; j < 4; ++j) pf[j] = pack8(x[8 * j], x[8 * j + 1], x[8 * j + 2], x[8 * j + 3], x[8 * j + 4], x[8 * j + 5], x[8 * j + 6], x[8 * j + 7]);
; #pragma unroll
;             for (int jh = 0; jh < 2; ++jh) {
;                 bf16x8 va[2][4];
; #pragma unroll
;                 for (int j = 0; j < 2; ++j)
; #pragma unroll
;                     for (int db = 0; db < 4; ++db) va[j][db] = *(const LAS bf16x8*)(base + voff + db * 32 * AT_VROW + (2 * jh + j) * 32);
;                 __builtin_amdgcn_sched_barrier(0);
; #pragma unroll
;                 for (int j = 0; j < 2; ++j)
; #pragma unroll
;                     for (int db = 0; db < 4; ++db) o[db] = MFMA32(va[j][db], pf[2 * jh + j], o[db]);
;                 __builtin_amdgcn_sched_barrier(0);
;             }
;             if (MODE == 0 && kt > kt0 && k0 <= tq0) {
;                 const float ub = qn + cbl[0];
;                 wdone = __all(ub < m - 30.f);
;             }
	v_exp_f32_e32 v75, v75
	v_exp_f32_e32 v72, v72
	v_exp_f32_e32 v73, v73
	v_exp_f32_e32 v70, v70
	v_exp_f32_e32 v71, v71
	v_exp_f32_e32 v68, v68
	v_exp_f32_e32 v69, v69
	v_exp_f32_e32 v160, v160
	v_pk_mul_f32 v[62:63], v[62:63], v[66:67] op_sel_hi:[1,0]
	v_pk_mul_f32 v[60:61], v[60:61], v[66:67] op_sel_hi:[1,0]
	v_pk_mul_f32 v[58:59], v[58:59], v[66:67] op_sel_hi:[1,0]
	v_pk_mul_f32 v[56:57], v[56:57], v[66:67] op_sel_hi:[1,0]
	v_pk_mul_f32 v[54:55], v[54:55], v[66:67] op_sel_hi:[1,0]
	v_pk_mul_f32 v[52:53], v[52:53], v[66:67] op_sel_hi:[1,0]
	v_pk_mul_f32 v[50:51], v[50:51], v[66:67] op_sel_hi:[1,0]
	v_pk_mul_f32 v[48:49], v[48:49], v[66:67] op_sel_hi:[1,0]
	v_pk_mul_f32 v[46:47], v[46:47], v[66:67] op_sel_hi:[1,0]
	v_pk_mul_f32 v[44:45], v[44:45], v[66:67] op_sel_hi:[1,0]
	v_pk_mul_f32 v[42:43], v[42:43], v[66:67] op_sel_hi:[1,0]
	v_pk_mul_f32 v[40:41], v[40:41], v[66:67] op_sel_hi:[1,0]
	v_pk_mul_f32 v[38:39], v[38:39], v[66:67] op_sel_hi:[1,0]
	v_pk_mul_f32 v[36:37], v[36:37], v[66:67] op_sel_hi:[1,0]
	v_pk_mul_f32 v[34:35], v[34:35], v[66:67] op_sel_hi:[1,0]
	v_pk_mul_f32 v[32:33], v[32:33], v[66:67] op_sel_hi:[1,0]
	v_pk_mul_f32 v[30:31], v[30:31], v[66:67] op_sel_hi:[1,0]
	v_pk_mul_f32 v[28:29], v[28:29], v[66:67] op_sel_hi:[1,0]
	v_pk_mul_f32 v[26:27], v[26:27], v[66:67] op_sel_hi:[1,0]
	v_pk_mul_f32 v[24:25], v[24:25], v[66:67] op_sel_hi:[1,0]
	v_pk_mul_f32 v[22:23], v[22:23], v[66:67] op_sel_hi:[1,0]
	v_pk_mul_f32 v[20:21], v[20:21], v[66:67] op_sel_hi:[1,0]
	v_pk_mul_f32 v[18:19], v[18:19], v[66:67] op_sel_hi:[1,0]
	v_pk_mul_f32 v[16:17], v[16:17], v[66:67] op_sel_hi:[1,0]
	v_pk_mul_f32 v[14:15], v[14:15], v[66:67] op_sel_hi:[1,0]
	v_pk_mul_f32 v[12:13], v[12:13], v[66:67] op_sel_hi:[1,0]
	v_pk_mul_f32 v[10:11], v[10:11], v[66:67] op_sel_hi:[1,0]
	v_pk_mul_f32 v[8:9], v[8:9], v[66:67] op_sel_hi:[1,0]
	v_pk_mul_f32 v[6:7], v[6:7], v[66:67] op_sel_hi:[1,0]
	v_pk_mul_f32 v[4:5], v[4:5], v[66:67] op_sel_hi:[1,0]
	v_pk_mul_f32 v[2:3], v[2:3], v[66:67] op_sel_hi:[1,0]
	v_pk_mul_f32 v[0:1], v[0:1], v[66:67] op_sel_hi:[1,0]
	v_cvt_pk_bf16_f32 v162, v86, v87
	v_cvt_pk_bf16_f32 v163, v88, v89
	v_cvt_pk_bf16_f32 v164, v90, v91
	v_cvt_pk_bf16_f32 v165, v92, v93
	v_cvt_pk_bf16_f32 v184, v94, v95
	v_cvt_pk_bf16_f32 v185, v158, v159
	v_cvt_pk_bf16_f32 v186, v76, v77
	v_cvt_pk_bf16_f32 v187, v78, v79
	v_cvt_pk_bf16_f32 v188, v80, v81
	v_cvt_pk_bf16_f32 v189, v82, v83
	v_cvt_pk_bf16_f32 v190, v84, v85
	v_cvt_pk_bf16_f32 v191, v74, v75
	v_cvt_pk_bf16_f32 v228, v72, v73
	v_cvt_pk_bf16_f32 v229, v70, v71
	v_cvt_pk_bf16_f32 v230, v68, v69
	v_cvt_pk_bf16_f32 v231, v160, v67
	s_waitcnt lgkmcnt(0)
	v_mfma_f32_32x32x16_bf16 v[48:63], v[192:195], v[162:165], v[48:63]
	v_mfma_f32_32x32x16_bf16 v[32:47], v[204:207], v[162:165], v[32:47]
	v_mfma_f32_32x32x16_bf16 v[16:31], v[212:215], v[162:165], v[16:31]
	v_mfma_f32_32x32x16_bf16 v[0:15], v[220:223], v[162:165], v[0:15]
	v_mfma_f32_32x32x16_bf16 v[48:63], v[196:199], v[184:187], v[48:63]
	v_mfma_f32_32x32x16_bf16 v[32:47], v[208:211], v[184:187], v[32:47]
	v_mfma_f32_32x32x16_bf16 v[16:31], v[216:219], v[184:187], v[16:31]
	v_mfma_f32_32x32x16_bf16 v[0:15], v[224:227], v[184:187], v[0:15]
	ds_read_b128 v[162:165], v64 offset:17472
	ds_read_b128 v[184:187], v64 offset:17504
	ds_read_b128 v[192:195], v64 offset:22080
	ds_read_b128 v[196:199], v64 offset:22112
	ds_read_b128 v[204:207], v64 offset:26688
	ds_read_b128 v[208:211], v64 offset:26720
	ds_read_b128 v[212:215], v64 offset:31296
	ds_read_b128 v[216:219], v64 offset:31328
	s_waitcnt lgkmcnt(7)
	v_mfma_f32_32x32x16_bf16 v[48:63], v[162:165], v[188:191], v[48:63]
	s_waitcnt lgkmcnt(5)
	v_mfma_f32_32x32x16_bf16 v[32:47], v[192:195], v[188:191], v[32:47]
	s_waitcnt lgkmcnt(3)
	v_mfma_f32_32x32x16_bf16 v[16:31], v[204:207], v[188:191], v[16:31]
	s_waitcnt lgkmcnt(1)
	v_mfma_f32_32x32x16_bf16 v[0:15], v[212:215], v[188:191], v[0:15]
	v_mfma_f32_32x32x16_bf16 v[48:63], v[184:187], v[228:231], v[48:63]
	v_mfma_f32_32x32x16_bf16 v[32:47], v[196:199], v[228:231], v[32:47]
	v_mfma_f32_32x32x16_bf16 v[16:31], v[208:211], v[228:231], v[16:31]
	s_waitcnt lgkmcnt(0)
	v_mfma_f32_32x32x16_bf16 v[0:15], v[216:219], v[228:231], v[0:15]
	s_cmp_gt_i32 s14, s3
	s_cselect_b64 s[12:13], -1, 0
	s_or_b64 s[14:15], s[4:5], s[12:13]
	s_mov_b64 s[12:13], 0
	s_and_b64 vcc, exec, s[14:15]
	s_cbranch_vccnz .LBB0_581
	ds_read_b32 v64, v182 offset:35840
	s_waitcnt lgkmcnt(0)
	v_pk_add_f32 v[162:163], v[202:203], v[64:65]
	s_nop 0
	v_cmp_lt_f32_e32 vcc, v162, v163
	s_cmp_eq_u64 vcc, exec
	s_cselect_b64 s[12:13], -1, 0

; __device__ __forceinline__ unsigned cvt_pk_bf16(float lo, float hi) { unsigned r; asm("v_cvt_pk_bf16_f32 %0, %1, %2" : "=v"(r) : "v"(lo), "v"(hi)); return r; }
; __device__ __forceinline__ float xsum(float v) { const auto r = __builtin_amdgcn_permlane32_swap(__float_as_uint(v), __float_as_uint(v), false, false); return __uint_as_float(r[0]) + __uint_as_float(r[1]); }
; __device__ __forceinline__ void st16_wt(void* p, u32x4 v) { asm volatile("global_store_dwordx4 %0, %1, off sc1\n\ts_nop 1" :: "v"(p), "v"(v) : "memory"); }
;     ...
;     if (MODE == 0) __syncthreads();
;     ...
;     l = xsum(l);
;     const float inv = 1.f / l;
; #pragma unroll
;     for (int db = 0; db < 4; ++db)
; #pragma unroll
;         for (int g = 0; g < 4; g += 2) {
;             unsigned ax = cvt_pk_bf16(o[db][4 * g] * inv, o[db][4 * g + 1] * inv), ay = cvt_pk_bf16(o[db][4 * g + 2] * inv, o[db][4 * g + 3] * inv);
;             unsigned bx = cvt_pk_bf16(o[db][4 * g + 4] * inv, o[db][4 * g + 5] * inv), by = cvt_pk_bf16(o[db][4 * g + 6] * inv, o[db][4 * g + 7] * inv);
;             const auto rx = __builtin_amdgcn_permlane32_swap(ax, bx, false, false), ry = __builtin_amdgcn_permlane32_swap(ay, by, false, false);
;             u32x4 w; w.x = rx[0]; w.y = ry[0]; w.z = rx[1]; w.w = ry[1];
;             if (MODE == 2) st16_wt(Orow + 32 * db + 8 * g + 8 * hh, w); else *(u32x4*)(Orow + 32 * db + 8 * g + 8 * hh) = w;
;         }
.LBB0_590:
	v_mov_b32_e32 v66, v177
	s_nop 1
	v_permlane32_swap_b32_e32 v177, v66
	v_add_f32_e32 v66, v177, v66
	v_div_scale_f32 v67, s[0:1], v66, v66, 1.0
	v_rcp_f32_e32 v68, v67
	v_lshlrev_b64 v[64:65], 12, v[146:147]
	v_lshl_add_u64 v[64:65], s[8:9], 0, v[64:65]
	s_lshl_b32 s72, s16, 1
	v_fma_f32 v69, -v67, v68, 1.0
	v_fmac_f32_e32 v68, v69, v68
	v_div_scale_f32 v69, vcc, 1.0, v66, 1.0
	v_mul_f32_e32 v70, v69, v68
	v_fma_f32 v71, -v67, v70, v69
	v_fmac_f32_e32 v70, v71, v68
	v_fma_f32 v67, -v67, v70, v69
	v_div_fmas_f32 v67, v67, v68, v70
	v_div_fixup_f32 v68, v67, v66, 1.0
	v_mul_f32_e32 v48, v48, v68
	v_mul_f32_e32 v49, v49, v68
	v_mul_f32_e32 v32, v32, v68
	v_mul_f32_e32 v33, v33, v68
	v_mul_f32_e32 v16, v16, v68
	v_mul_f32_e32 v17, v17, v68
	v_mul_f32_e32 v0, v0, v68
	v_mul_f32_e32 v1, v1, v68
	v_lshl_add_u64 v[64:65], v[64:65], 0, s[72:73]
	v_lshlrev_b32_e32 v200, 1, v151
	v_cvt_pk_bf16_f32 v48, v48, v49
	v_mul_f32_e32 v49, v50, v68
	v_mul_f32_e32 v50, v51, v68
	v_cvt_pk_bf16_f32 v32, v32, v33
	v_mul_f32_e32 v33, v34, v68
	v_mul_f32_e32 v34, v35, v68
	v_cvt_pk_bf16_f32 v16, v16, v17
	v_mul_f32_e32 v17, v18, v68
	v_mul_f32_e32 v18, v19, v68
	v_cvt_pk_bf16_f32 v0, v0, v1
	v_mul_f32_e32 v1, v2, v68
	v_mul_f32_e32 v2, v3, v68
	v_lshl_add_u64 v[64:65], v[64:65], 0, v[200:201]
	s_mov_b64 s[0:1], 0x24300000
	v_cvt_pk_bf16_f32 v49, v49, v50
	v_mul_f32_e32 v50, v52, v68
	v_mul_f32_e32 v51, v53, v68
	v_cvt_pk_bf16_f32 v33, v33, v34
	v_mul_f32_e32 v34, v36, v68
	v_mul_f32_e32 v35, v37, v68
	v_cvt_pk_bf16_f32 v17, v17, v18
	v_mul_f32_e32 v18, v20, v68
	v_mul_f32_e32 v19, v21, v68
	v_cvt_pk_bf16_f32 v1, v1, v2
	v_mul_f32_e32 v2, v4, v68
	v_mul_f32_e32 v3, v5, v68
	v_lshl_add_u64 v[66:67], v[64:65], 0, s[0:1]
	v_cvt_pk_bf16_f32 v50, v50, v51
	v_mul_f32_e32 v51, v54, v68
	v_mul_f32_e32 v52, v55, v68
	s_mov_b32 s0, 0x24300000
	v_cvt_pk_bf16_f32 v34, v34, v35
	v_mul_f32_e32 v35, v38, v68
	v_cvt_pk_bf16_f32 v18, v18, v19
	v_mul_f32_e32 v19, v22, v68
	v_cvt_pk_bf16_f32 v2, v2, v3
	v_mul_f32_e32 v3, v6, v68
	v_cvt_pk_bf16_f32 v51, v51, v52
	v_add_co_u32_e32 v52, vcc, s0, v64
	v_mul_f32_e32 v36, v39, v68
	v_cvt_pk_bf16_f32 v35, v35, v36
	v_mul_f32_e32 v20, v23, v68
	v_cvt_pk_bf16_f32 v19, v19, v20
	v_mul_f32_e32 v4, v7, v68
	v_cvt_pk_bf16_f32 v3, v3, v4
	v_permlane32_swap_b32_e32 v48, v50
	v_permlane32_swap_b32_e32 v49, v51
	v_addc_co_u32_e32 v53, vcc, 0, v65, vcc
	v_permlane32_swap_b32_e32 v32, v34
	v_permlane32_swap_b32_e32 v33, v35
	v_permlane32_swap_b32_e32 v16, v18
	v_permlane32_swap_b32_e32 v17, v19
	v_permlane32_swap_b32_e32 v0, v2
	v_permlane32_swap_b32_e32 v1, v3
	s_barrier
	global_store_dwordx4 v[52:53], v[48:51], off
	global_store_dwordx4 v[66:67], v[32:35], off offset:64
	global_store_dwordx4 v[66:67], v[16:19], off offset:128
	v_mul_f32_e32 v48, v56, v68
	v_mul_f32_e32 v49, v57, v68
	v_mul_f32_e32 v32, v40, v68
	v_mul_f32_e32 v33, v41, v68
	v_mul_f32_e32 v16, v24, v68
	v_mul_f32_e32 v17, v25, v68
	global_store_dwordx4 v[66:67], v[0:3], off offset:192
	v_cvt_pk_bf16_f32 v48, v48, v49
	v_mul_f32_e32 v49, v58, v68
	v_mul_f32_e32 v50, v59, v68
	v_mul_f32_e32 v0, v8, v68
	v_mul_f32_e32 v1, v9, v68
	v_cvt_pk_bf16_f32 v32, v32, v33
	v_mul_f32_e32 v33, v42, v68
	v_mul_f32_e32 v34, v43, v68
	v_cvt_pk_bf16_f32 v16, v16, v17
	v_mul_f32_e32 v17, v26, v68
	v_mul_f32_e32 v18, v27, v68
	v_cvt_pk_bf16_f32 v0, v0, v1
	v_mul_f32_e32 v1, v10, v68
	v_mul_f32_e32 v2, v11, v68
	v_cvt_pk_bf16_f32 v49, v49, v50
	v_mul_f32_e32 v50, v60, v68
	v_mul_f32_e32 v51, v61, v68
	v_cvt_pk_bf16_f32 v33, v33, v34
	v_mul_f32_e32 v34, v44, v68
	v_mul_f32_e32 v35, v45, v68
	v_cvt_pk_bf16_f32 v17, v17, v18
	v_mul_f32_e32 v18, v28, v68
	v_mul_f32_e32 v19, v29, v68
	v_cvt_pk_bf16_f32 v1, v1, v2
	v_mul_f32_e32 v2, v12, v68
	v_mul_f32_e32 v3, v13, v68
	v_cvt_pk_bf16_f32 v50, v50, v51
	v_mul_f32_e32 v51, v62, v68
	v_cvt_pk_bf16_f32 v34, v34, v35
	v_mul_f32_e32 v35, v46, v68
	v_cvt_pk_bf16_f32 v18, v18, v19
	v_mul_f32_e32 v19, v30, v68
	v_cvt_pk_bf16_f32 v2, v2, v3
	v_mul_f32_e32 v3, v14, v68
	v_mul_f32_e32 v52, v63, v68
	v_cvt_pk_bf16_f32 v51, v51, v52
	v_mul_f32_e32 v36, v47, v68
	v_cvt_pk_bf16_f32 v35, v35, v36
	v_mul_f32_e32 v20, v31, v68
	v_cvt_pk_bf16_f32 v19, v19, v20
	v_mul_f32_e32 v4, v15, v68
	v_cvt_pk_bf16_f32 v3, v3, v4
	v_permlane32_swap_b32_e32 v48, v50
	v_permlane32_swap_b32_e32 v49, v51
	v_permlane32_swap_b32_e32 v32, v34
	v_permlane32_swap_b32_e32 v33, v35
	v_permlane32_swap_b32_e32 v16, v18
	v_permlane32_swap_b32_e32 v17, v19
	v_permlane32_swap_b32_e32 v0, v2
	v_permlane32_swap_b32_e32 v1, v3
	global_store_dwordx4 v[66:67], v[48:51], off offset:32
	global_store_dwordx4 v[66:67], v[32:35], off offset:96
	global_store_dwordx4 v[66:67], v[16:19], off offset:160
	global_store_dwordx4 v[66:67], v[0:3], off offset:224
	v_cmp_eq_u32_e32 vcc, 0, v144
	s_and_saveexec_b64 s[0:1], vcc
	s_cbranch_execz .LBB0_604

; __global__ void __launch_bounds__(512, 2) hybrid_fwd(Params p) {
;     ...
;             if (tid == 0) { unsigned* cw_ = (unsigned*)ws + 3584 + 64 * l; unsigned sp_ = 0;
;                 while (__hip_atomic_load(cw_, __ATOMIC_RELAXED, __HIP_MEMORY_SCOPE_AGENT) < 64u) { __builtin_amdgcn_s_sleep(2); if (++sp_ > (1u << 22)) break; }
;                 __builtin_amdgcn_fence(__ATOMIC_ACQUIRE, "agent"); asm volatile("s_waitcnt vmcnt(0)" ::: "memory"); }
.LBB0_597:
	v_mov_b64_e32 v[0:1], s[4:5]
	global_load_dword v0, v[0:1], off sc1
	s_or_b64 s[8:9], s[8:9], exec
	s_waitcnt vmcnt(0) lgkmcnt(0)
	v_cmp_gt_u32_e32 vcc, 64, v0
	s_and_saveexec_b64 s[10:11], vcc
	s_cbranch_execz .LBB0_596
	v_mov_b64_e32 v[0:1], s[4:5]
	s_sleep 2
	global_load_dword v0, v[0:1], off sc1
	s_mov_b64 s[14:15], -1
	s_waitcnt vmcnt(0) lgkmcnt(0)
	v_cmp_gt_u32_e32 vcc, 64, v0
	s_and_saveexec_b64 s[12:13], vcc
	s_cbranch_execz .LBB0_595
	v_mov_b64_e32 v[0:1], s[4:5]
	s_sleep 2
	global_load_dword v0, v[0:1], off sc1
	s_mov_b64 s[16:17], -1
	s_waitcnt vmcnt(0) lgkmcnt(0)
	v_cmp_gt_u32_e32 vcc, 64, v0
	s_and_saveexec_b64 s[14:15], vcc
	s_cbranch_execz .LBB0_594
	v_mov_b64_e32 v[0:1], s[4:5]
	s_sleep 2
	global_load_dword v0, v[0:1], off sc1
	s_mov_b64 s[18:19], -1
	s_waitcnt vmcnt(0) lgkmcnt(0)
	v_cmp_gt_u32_e32 vcc, 64, v0
	s_and_saveexec_b64 s[16:17], vcc
	s_cbranch_execz .LBB0_593
	v_mov_b64_e32 v[0:1], s[4:5]
	s_sleep 2
	global_load_dword v0, v[0:1], off sc1
	s_waitcnt vmcnt(0) lgkmcnt(0)
	v_cmp_gt_u32_e32 vcc, 64, v0
	s_and_saveexec_b64 s[20:21], vcc
	s_cbranch_execz .LBB0_592
	s_add_i32 s3, s3, -5
	s_cmp_eq_u32 s3, 0
	s_cselect_b64 s[18:19], -1, 0
	s_orn2_b64 s[18:19], s[18:19], exec
	s_sleep 2
	s_branch .LBB0_592

; __device__ __forceinline__ unsigned cvt_pk_bf16(float lo, float hi) { unsigned r; asm("v_cvt_pk_bf16_f32 %0, %1, %2" : "=v"(r) : "v"(lo), "v"(hi)); return r; }
; __device__ __forceinline__ float bflo(unsigned w) { return __uint_as_float(w << 16); }
; __device__ __forceinline__ float bfhi(unsigned w) { return __uint_as_float(w & 0xffff0000u); }
; template <int MODEC>
; __device__ __forceinline__ void gla_unit(LAS unsigned char* lds, const int tid_in, const Params& p, int l, int hh, int n) {
;     ...
;         __syncthreads();
;         const float tot = (ss[tt * 4] + ss[tt * 4 + 1]) + (ss[tt * 4 + 2] + ss[tt * 4 + 3]);
;         const float rstd = rsqrtf(tot * (1.f / 128.f) + EPS);
;         bf16_t* op = (bf16_t*)(ws + WS_O) + (size_t)(t0 + tt) * D_ + 1536 + hh * 128;
;         const bf16_t* grp = proj + (size_t)(t0 + tt) * NP + PJ_GR + hh * 128;
;         const float* gn = p.gla_norm + l * 128;
; #pragma unroll
;         for (int g = 0; g < 4; ++g) {
;             const int dv = 32 * dvb + 8 * g + 4 * h2;
;             const u32x2 gw = *(const u32x2*)(grp + dv); const f32x4 gnv = *(const f32x4*)(gn + dv);
;             const float g0 = bflo(gw.x), g1 = bfhi(gw.x), g2 = bflo(gw.y), g3 = bfhi(gw.y);
;             const float v0 = acc[4 * g] * rstd * gnv[0] * (g0 * __builtin_amdgcn_rcpf(1.f + __expf(-g0))), v1 = acc[4 * g + 1] * rstd * gnv[1] * (g1 * __builtin_amdgcn_rcpf(1.f + __expf(-g1)));
;             const float v2 = acc[4 * g + 2] * rstd * gnv[2] * (g2 * __builtin_amdgcn_rcpf(1.f + __expf(-g2))), v3 = acc[4 * g + 3] * rstd * gnv[3] * (g3 * __builtin_amdgcn_rcpf(1.f + __expf(-g3)));
;             u32x2 wv; wv.x = cvt_pk_bf16(v0, v1); wv.y = cvt_pk_bf16(v2, v3); *(u32x2*)(op + dv) = wv;
;         }
;         __syncthreads();
.LBB0_606:
	s_or_b64 exec, exec, s[0:1]
	v_add_u32_e32 v16, 0, v17
	s_waitcnt lgkmcnt(0)
	s_barrier
	ds_read_b128 v[16:19], v16 offset:37120
	s_ashr_i32 s77, s76, 31
	v_mov_b64_e32 v[22:23], s[34:35]
	s_lshl_b64 s[0:1], s[76:77], 1
	s_add_i32 s2, s2, s70
	s_waitcnt lgkmcnt(0)
	v_mov_b32_e32 v20, v17
	v_mov_b32_e32 v21, v18
	v_mov_b32_e32 v17, v19
	v_pk_add_f32 v[16:17], v[20:21], v[16:17]
	v_lshl_or_b32 v21, v89, 2, s45
	v_add_f32_e32 v16, v16, v17
	v_fmamk_f32 v16, v16, 0x3c000000, v240
	v_cmp_gt_f32_e32 vcc, s85, v16
	v_mul_f32_e32 v17, 0x4b800000, v16
	v_lshlrev_b32_e32 v200, 1, v21
	v_cndmask_b32_e32 v16, v16, v17, vcc
	v_rsq_f32_e32 v16, v16
	s_movk_i32 s45, 0x1000
	v_lshlrev_b32_e32 v21, 2, v21
	s_add_u32 s92, s92, s74
	v_mul_f32_e32 v17, 0x45800000, v16
	v_cndmask_b32_e32 v20, v16, v17, vcc
	v_add_u32_e32 v16, s44, v90
	v_ashrrev_i32_e32 v17, 31, v16
	v_lshlrev_b64 v[18:19], 12, v[16:17]
	v_mad_i64_i32 v[16:17], s[4:5], v16, s56, v[22:23]
	v_lshl_add_u64 v[18:19], s[86:87], 0, v[18:19]
	v_lshl_add_u64 v[16:17], v[16:17], 0, s[0:1]
	v_lshl_add_u64 v[18:19], v[18:19], 0, s[0:1]
	v_lshl_add_u64 v[22:23], v[16:17], 0, v[200:201]
	s_mov_b64 s[0:1], 0x1600
	v_lshl_add_u64 v[16:17], v[22:23], 0, s[0:1]
	v_add_co_u32_e32 v22, vcc, s45, v22
	v_mul_f32_e32 v29, v0, v20
	s_nop 0
	v_addc_co_u32_e32 v23, vcc, 0, v23, vcc
	global_load_dwordx2 v[26:27], v[22:23], off offset:1536
	v_mul_f32_e32 v31, v2, v20
	global_load_dwordx4 v[22:25], v21, s[80:81]
	v_mul_f32_e32 v33, v3, v20
	v_lshl_add_u64 v[18:19], v[18:19], 0, v[200:201]
	s_mov_b64 s[0:1], 0x24300c00
	s_addc_u32 s93, s93, s75
	s_add_i32 s3, s3, s39
	s_cmpk_gt_i32 s2, 0x1ff
	s_waitcnt vmcnt(0) lgkmcnt(0)
	v_lshlrev_b32_e32 v28, 16, v26
	v_mul_f32_e32 v0, 0xbfb8aa3b, v28
	v_exp_f32_e32 v0, v0
	v_and_b32_e32 v26, 0xffff0000, v26
	v_mov_b32_e32 v35, v22
	v_lshlrev_b32_e32 v30, 16, v27
	v_add_f32_e32 v0, 1.0, v0
	v_rcp_f32_e32 v34, v0
	v_mul_f32_e32 v0, 0xbfb8aa3b, v26
	v_exp_f32_e32 v0, v0
	v_and_b32_e32 v32, 0xffff0000, v27
	v_mul_f32_e32 v27, v1, v20
	v_pk_mul_f32 v[28:29], v[34:35], v[28:29]
	v_add_f32_e32 v0, 1.0, v0
	v_rcp_f32_e32 v22, v0
	v_mul_f32_e32 v28, v28, v29
	v_pk_mul_f32 v[0:1], v[22:23], v[26:27]
	s_nop 0
	v_mul_f32_e32 v22, v0, v1
	v_mul_f32_e32 v0, 0xbfb8aa3b, v30
	v_exp_f32_e32 v0, v0
	v_mov_b32_e32 v1, v24
	v_cvt_pk_bf16_f32 v2, v28, v22
	v_mul_f32_e32 v26, v5, v20
	v_add_f32_e32 v0, 1.0, v0
	v_rcp_f32_e32 v0, v0
	v_mul_f32_e32 v28, v6, v20
	v_pk_mul_f32 v[0:1], v[0:1], v[30:31]
	s_nop 0
	v_mul_f32_e32 v23, v0, v1
	v_mul_f32_e32 v0, 0xbfb8aa3b, v32
	v_exp_f32_e32 v0, v0
	s_nop 0
	v_add_f32_e32 v0, 1.0, v0
	v_rcp_f32_e32 v24, v0
	s_nop 0
	v_pk_mul_f32 v[0:1], v[24:25], v[32:33]
	s_nop 0
	v_mul_f32_e32 v0, v0, v1
	v_cvt_pk_bf16_f32 v3, v23, v0
	v_lshl_add_u64 v[0:1], v[18:19], 0, s[0:1]
	s_mov_b32 s0, 0x24300000
	v_add_co_u32_e32 v18, vcc, s0, v18
	s_nop 1
	v_addc_co_u32_e32 v19, vcc, 0, v19, vcc
	global_store_dwordx2 v[18:19], v[2:3], off offset:3072
	global_load_dwordx2 v[2:3], v[16:17], off offset:16
	s_nop 0
	global_load_dwordx4 v[22:25], v21, s[80:81] offset:32
	v_mul_f32_e32 v18, v4, v20
	s_waitcnt vmcnt(0) lgkmcnt(0)
	v_lshlrev_b32_e32 v19, 16, v2
	v_and_b32_e32 v27, 0xffff0000, v2
	v_mul_f32_e32 v2, 0xbfb8aa3b, v19
	v_exp_f32_e32 v2, v2
	v_lshlrev_b32_e32 v29, 16, v3
	v_mov_b32_e32 v30, v22
	v_mov_b32_e32 v4, v23
	v_add_f32_e32 v2, 1.0, v2
	v_rcp_f32_e32 v31, v2
	v_mul_f32_e32 v2, 0xbfb8aa3b, v27
	v_exp_f32_e32 v2, v2
	v_and_b32_e32 v3, 0xffff0000, v3
	v_pk_mul_f32 v[18:19], v[30:31], v[18:19]
	v_add_f32_e32 v2, 1.0, v2
	v_rcp_f32_e32 v5, v2
	v_mul_f32_e32 v2, 0xbfb8aa3b, v29
	v_exp_f32_e32 v2, v2
	v_mul_f32_e32 v18, v18, v19
	v_pk_mul_f32 v[4:5], v[4:5], v[26:27]
	v_mul_f32_e32 v26, v8, v20
	v_add_f32_e32 v2, 1.0, v2
	v_mul_f32_e32 v19, v4, v5
	v_rcp_f32_e32 v5, v2
	v_mov_b32_e32 v4, v24
	v_mul_f32_e32 v2, v7, v20
	v_mul_f32_e32 v8, v9, v20
	v_pk_mul_f32 v[4:5], v[4:5], v[28:29]
	s_nop 0
	v_mul_f32_e32 v6, v4, v5
	v_mul_f32_e32 v4, 0xbfb8aa3b, v3
	v_exp_f32_e32 v4, v4
	s_nop 0
	v_add_f32_e32 v4, 1.0, v4
	v_rcp_f32_e32 v5, v4
	v_mov_b32_e32 v4, v25
	v_pk_mul_f32 v[2:3], v[4:5], v[2:3]
	s_nop 0
	v_mul_f32_e32 v3, v2, v3
	v_cvt_pk_bf16_f32 v2, v18, v19
	v_cvt_pk_bf16_f32 v3, v6, v3
	global_store_dwordx2 v[0:1], v[2:3], off offset:16
	global_load_dwordx2 v[6:7], v[16:17], off offset:32
	s_nop 0
	global_load_dwordx4 v[2:5], v21, s[80:81] offset:64
	s_waitcnt vmcnt(0) lgkmcnt(0)
	v_and_b32_e32 v23, 0xffff0000, v6
	v_mov_b32_e32 v18, v2
	v_mul_f32_e32 v2, 0xbfb8aa3b, v23
	v_exp_f32_e32 v2, v2
	v_mov_b32_e32 v22, v3
	v_lshlrev_b32_e32 v25, 16, v7
	v_mov_b32_e32 v24, v4
	v_add_f32_e32 v2, 1.0, v2
	v_rcp_f32_e32 v9, v2
	v_and_b32_e32 v7, 0xffff0000, v7
	v_lshlrev_b32_e32 v19, 16, v6
	v_mul_f32_e32 v6, 0xbfb8aa3b, v19
	v_pk_mul_f32 v[2:3], v[8:9], v[22:23]
	v_exp_f32_e32 v6, v6
	v_mul_f32_e32 v8, v2, v3
	v_mul_f32_e32 v3, 0xbfb8aa3b, v25
	v_exp_f32_e32 v3, v3
	v_mul_f32_e32 v2, v10, v20
	v_add_f32_e32 v6, 1.0, v6
	v_rcp_f32_e32 v27, v6
	v_add_f32_e32 v3, 1.0, v3
	v_rcp_f32_e32 v3, v3
	v_mov_b32_e32 v6, v5
	v_pk_mul_f32 v[18:19], v[26:27], v[18:19]
	v_pk_mul_f32 v[2:3], v[2:3], v[24:25]
	s_nop 0
	v_mul_f32_e32 v4, v2, v3
	v_mul_f32_e32 v3, 0xbfb8aa3b, v7
	v_exp_f32_e32 v3, v3
	v_mul_f32_e32 v2, v11, v20
	v_mul_f32_e32 v18, v18, v19
	v_add_f32_e32 v3, 1.0, v3
	v_rcp_f32_e32 v3, v3
	s_nop 0
	v_pk_mul_f32 v[2:3], v[2:3], v[6:7]
	s_nop 0
	v_mul_f32_e32 v3, v2, v3
	v_cvt_pk_bf16_f32 v2, v18, v8
	v_cvt_pk_bf16_f32 v3, v4, v3
	global_store_dwordx2 v[0:1], v[2:3], off offset:32
	global_load_dwordx2 v[2:3], v[16:17], off offset:48
	s_nop 0
	global_load_dwordx4 v[4:7], v21, s[80:81] offset:96
	v_mul_f32_e32 v18, v12, v20
	s_waitcnt vmcnt(0) lgkmcnt(0)
	v_lshlrev_b32_e32 v9, 16, v2
	v_and_b32_e32 v11, 0xffff0000, v2
	v_mul_f32_e32 v2, 0xbfb8aa3b, v9
	v_exp_f32_e32 v2, v2
	v_mov_b32_e32 v8, v4
	v_lshlrev_b32_e32 v17, 16, v3
	v_mov_b32_e32 v10, v5
	v_add_f32_e32 v2, 1.0, v2
	v_rcp_f32_e32 v19, v2
	v_mul_f32_e32 v2, 0xbfb8aa3b, v11
	v_exp_f32_e32 v2, v2
	v_and_b32_e32 v3, 0xffff0000, v3
	v_pk_mul_f32 v[8:9], v[18:19], v[8:9]
	v_mov_b32_e32 v16, v6
	v_add_f32_e32 v2, 1.0, v2
	v_mul_f32_e32 v12, v8, v9
	v_rcp_f32_e32 v9, v2
	v_mul_f32_e32 v2, 0xbfb8aa3b, v17
	v_exp_f32_e32 v2, v2
	v_mul_f32_e32 v8, v13, v20
	v_pk_mul_f32 v[4:5], v[8:9], v[10:11]
	v_add_f32_e32 v2, 1.0, v2
	v_mul_f32_e32 v8, v4, v5
	v_rcp_f32_e32 v5, v2
	v_mul_f32_e32 v2, 0xbfb8aa3b, v3
	v_exp_f32_e32 v2, v2
	v_mul_f32_e32 v4, v14, v20
	v_pk_mul_f32 v[4:5], v[4:5], v[16:17]
	v_add_f32_e32 v2, 1.0, v2
	v_mul_f32_e32 v6, v4, v5
	v_rcp_f32_e32 v5, v2
	v_mul_f32_e32 v4, v15, v20
	v_mov_b32_e32 v2, v7
	v_pk_mul_f32 v[2:3], v[4:5], v[2:3]
	s_nop 0
	v_mul_f32_e32 v3, v2, v3
	v_cvt_pk_bf16_f32 v2, v12, v8
	v_cvt_pk_bf16_f32 v3, v6, v3
	global_store_dwordx2 v[0:1], v[2:3], off offset:48
	s_waitcnt lgkmcnt(0)
	s_barrier
	s_cbranch_scc1 .LBB0_619
; #define LAS __attribute__((address_space(3)))
; template <int MODEC>
; __device__ __forceinline__ void gla_unit(LAS unsigned char* lds, const int tid_in, const Params& p, int l, int hh, int n) {
;     ...
;         const int d = lane; const float* wg = p.w_gla_gate + (size_t)l * 16 * 256 + hh * 64 + d; const float bgv = p.b_gla_gate[l * 256 + hh * 64 + d];
;         float wgr[16];
; #pragma unroll
;         for (int q = 0; q < 16; ++q) wgr[q] = wg[q * 256];
;         LAS float* gl = (LAS float*)(lds + 38400);
;         if (tid < 256) *(LAS f32x4*)(gl + (tid >> 2) * 16 + (tid & 3) * 4) = *(const f32x4*)(gates + (size_t)(t0 + (tid >> 2)) * 32 + 4 + (tid & 3) * 4);
.LBB0_607:
	s_ashr_i32 s0, s2, 1
	s_and_b32 s4, s0, 0xffffffc0
	s_ashr_i32 s5, s4, 31
	v_mov_b32_e32 v8, v144
	s_lshl_b64 s[0:1], s[4:5], 2
	s_add_u32 s0, s57, s0
	v_and_b32_e32 v88, 63, v8
	s_addc_u32 s1, s95, s1
	v_lshlrev_b32_e32 v200, 2, v88
	v_lshl_add_u64 v[14:15], s[0:1], 0, v[200:201]
	s_add_i32 s6, s4, s38
	v_add_co_u32_e32 v10, vcc, s45, v14
	v_or_b32_e32 v0, s6, v88
	s_nop 0
	v_addc_co_u32_e32 v11, vcc, 0, v15, vcc
	v_ashrrev_i32_e32 v1, 31, v0
	v_add_co_u32_e32 v16, vcc, s89, v14
	s_mov_b64 s[86:87], s[50:51]
	v_lshl_add_u64 v[0:1], v[0:1], 2, s[66:67]
	v_addc_co_u32_e32 v17, vcc, 0, v15, vcc
	global_load_dword v0, v[0:1], off
	s_nop 0
	global_load_dword v1, v200, s[0:1]
	global_load_dword v2, v200, s[0:1] offset:1024
	global_load_dword v3, v200, s[0:1] offset:2048
	global_load_dword v4, v200, s[0:1] offset:3072
	global_load_dword v13, v[16:17], off offset:-4096
	global_load_dword v5, v[10:11], off offset:1024
	global_load_dword v6, v[10:11], off offset:2048
	global_load_dword v7, v[10:11], off offset:3072
	global_load_dword v9, v[16:17], off
	s_nop 0
	global_load_dword v10, v[16:17], off offset:1024
	global_load_dword v11, v[16:17], off offset:2048
	global_load_dword v12, v[16:17], off offset:3072
	v_add_co_u32_e32 v18, vcc, 0x3000, v14
	s_movk_i32 s0, 0x100
	s_nop 0
	v_addc_co_u32_e32 v19, vcc, 0, v15, vcc
	global_load_dword v17, v[18:19], off
	global_load_dword v16, v[18:19], off offset:1024
	global_load_dword v15, v[18:19], off offset:2048
	global_load_dword v14, v[18:19], off offset:3072
	v_readfirstlane_b32 s6, v8
	s_and_b32 s44, s3, 0x1fc0
	v_cmp_gt_i32_e32 vcc, s0, v8
	s_and_saveexec_b64 s[0:1], vcc
	s_cbranch_execz .LBB0_609
	v_ashrrev_i32_e32 v24, 2, v8
	v_add_u32_e32 v18, s44, v24
	v_ashrrev_i32_e32 v19, 31, v18
	v_lshlrev_b64 v[18:19], 7, v[18:19]
	v_lshlrev_b32_e32 v20, 4, v8
	v_lshl_add_u64 v[18:19], s[86:87], 0, v[18:19]
	v_and_b32_e32 v22, 48, v20
	v_mov_b32_e32 v23, v201
	v_lshl_add_u64 v[18:19], v[18:19], 0, v[22:23]
	v_add_co_u32_e32 v18, vcc, 0x22e00000, v18
	v_lshlrev_b32_e32 v23, 6, v24
	s_nop 0
	v_addc_co_u32_e32 v19, vcc, 0, v19, vcc
	global_load_dwordx4 v[18:21], v[18:19], off offset:16
	v_add3_u32 v22, 0, v23, v22
	s_waitcnt vmcnt(0) lgkmcnt(0)
	ds_write_b128 v22, v[18:21] offset:38400

; #define LAS __attribute__((address_space(3)))
; __device__ __forceinline__ float bflo(unsigned w) { return __uint_as_float(w << 16); }
; __device__ __forceinline__ float bfhi(unsigned w) { return __uint_as_float(w & 0xffff0000u); }
; template <int MODEC>
; __device__ __forceinline__ void gla_unit(LAS unsigned char* lds, const int tid_in, const Params& p, int l, int hh, int n) {
;     ...
;         const u32x4 qq = *(const u32x4*)(proj + (size_t)(t0 + s) * NP + PJ_GQ + hh * 64 + dk8);
;         const u32x4 kk = *(const u32x4*)(proj + (size_t)(t0 + s) * NP + PJ_GK + hh * 64 + dk8);
;         const unsigned qw[4] = {qq.x, qq.y, qq.z, qq.w}, kw[4] = {kk.x, kk.y, kk.z, kk.w};
;         float qv[8], kv[8];
; #pragma unroll
;         for (int j = 0; j < 8; ++j) { const float b = bmat[s * 64 + dk8 + j];
;             qv[j] = ((j & 1) ? bfhi(qw[j >> 1]) : bflo(qw[j >> 1])) * 0.125f * __expf(b);
;             kv[j] = ((j & 1) ? bfhi(kw[j >> 1]) : bflo(kw[j >> 1])) * __expf(-b); }
;         *(LAS bf16x8*)(QT + s * 72 + dk8) = pack8(qv[0], qv[1], qv[2], qv[3], qv[4], qv[5], qv[6], qv[7]);
;         *(LAS bf16x8*)(KT + s * 72 + dk8) = pack8(kv[0], kv[1], kv[2], kv[3], kv[4], kv[5], kv[6], kv[7]);
;         __syncthreads();
;         const int dvb = w & 3, tb = w >> 2, tt = 32 * tb + r;
.LBB0_611:
	s_add_u32 s34, s86, 0x1f600000
	s_addc_u32 s35, s87, 0
	v_ashrrev_i32_e32 v9, 3, v8
	v_lshlrev_b32_e32 v0, 3, v8
	v_and_b32_e32 v14, 56, v0
	v_add_u32_e32 v2, s44, v9
	v_mov_b64_e32 v[0:1], s[34:35]
	v_mad_i64_i32 v[0:1], s[0:1], v2, s56, v[0:1]
	v_lshlrev_b32_e32 v6, 1, v14
	v_mov_b32_e32 v7, v201
	v_lshl_add_u64 v[0:1], s[4:5], 1, v[0:1]
	v_lshl_add_u64 v[0:1], v[0:1], 0, v[6:7]
	v_add_co_u32_e32 v0, vcc, s45, v0
	s_waitcnt lgkmcnt(0)
	s_nop 0
	v_addc_co_u32_e32 v1, vcc, 0, v1, vcc
	s_barrier
	global_load_dwordx4 v[2:5], v[0:1], off offset:512
	global_load_dwordx4 v[10:13], v[0:1], off offset:1024
	v_lshlrev_b32_e32 v0, 8, v9
	v_lshlrev_b32_e32 v1, 2, v14
	v_add3_u32 v1, 0, v0, v1
	ds_read_b128 v[14:17], v1
	ds_read_b128 v[18:21], v1 offset:16
	s_movk_i32 s4, 0x90
	s_bfe_u32 s52, s6, 0x20006
	s_and_b32 s76, s2, 0xffffff80
	s_waitcnt lgkmcnt(0)
	v_mul_f32_e32 v1, 0x3fb8aa3b, v14
	v_mul_f32_e32 v7, 0xbfb8aa3b, v14
	v_mul_f32_e32 v14, 0x3fb8aa3b, v15
	v_mul_f32_e32 v15, 0xbfb8aa3b, v15
	v_mul_f32_e32 v23, 0x3fb8aa3b, v17
	v_mul_f32_e32 v17, 0xbfb8aa3b, v17
	v_mul_f32_e32 v25, 0x3fb8aa3b, v19
	v_mul_f32_e32 v19, 0xbfb8aa3b, v19
	v_mul_f32_e32 v22, 0x3fb8aa3b, v16
	v_mul_f32_e32 v24, 0x3fb8aa3b, v18
	v_mul_f32_e32 v26, 0x3fb8aa3b, v20
	v_exp_f32_e32 v15, v15
	v_exp_f32_e32 v17, v17
	v_exp_f32_e32 v19, v19
	v_mul_f32_e32 v20, 0xbfb8aa3b, v20
	v_exp_f32_e32 v14, v14
	v_exp_f32_e32 v22, v22
	v_exp_f32_e32 v24, v24
	v_exp_f32_e32 v26, v26
	v_exp_f32_e32 v20, v20
	v_exp_f32_e32 v1, v1
	v_exp_f32_e32 v23, v23
	v_exp_f32_e32 v25, v25
	v_mul_f32_e32 v16, 0xbfb8aa3b, v16
	v_mul_f32_e32 v18, 0xbfb8aa3b, v18
	v_exp_f32_e32 v7, v7
	v_exp_f32_e32 v16, v16
	v_exp_f32_e32 v18, v18
	s_lshl_b32 s45, s52, 5
	s_or_b32 s0, s76, s45
	v_and_b32_e32 v0, 31, v8
	s_addk_i32 s0, 0x300
	v_lshrrev_b32_e32 v89, 5, v88
	s_lshl_b32 s72, s44, 1
	s_ashr_i32 s53, s6, 8
	v_lshl_or_b32 v90, s53, 5, v0
	s_movk_i32 s83, 0x90
	s_waitcnt vmcnt(0)
	v_lshlrev_b32_e32 v27, 16, v2
	v_lshlrev_b32_e32 v28, 16, v10
	v_and_b32_e32 v2, 0xffff0000, v2
	v_and_b32_e32 v10, 0xffff0000, v10
	v_lshlrev_b32_e32 v29, 16, v3
	v_lshlrev_b32_e32 v30, 16, v11
	v_and_b32_e32 v11, 0xffff0000, v11
	v_lshlrev_b32_e32 v31, 16, v4
	v_lshlrev_b32_e32 v32, 16, v12
	v_and_b32_e32 v12, 0xffff0000, v12
	v_lshlrev_b32_e32 v33, 16, v5
	v_mul_f32_e32 v2, 0x3e000000, v2
	v_mul_f32_e32 v10, v15, v10
	v_mul_f32_e32 v15, 0x3e000000, v29
	v_mul_f32_e32 v11, v17, v11
	v_mul_f32_e32 v17, 0x3e000000, v31
	v_mul_f32_e32 v12, v19, v12
	v_mul_f32_e32 v19, 0x3e000000, v33
	v_mul_f32_e32 v2, v2, v14
	v_mul_f32_e32 v14, v15, v22
	v_mul_f32_e32 v15, v17, v24
	v_mul_f32_e32 v17, v19, v26
	v_lshlrev_b32_e32 v19, 16, v13
	v_mul_f32_e32 v19, v20, v19
	v_mul_f32_e32 v20, 0x3fb8aa3b, v21
	v_exp_f32_e32 v20, v20
	v_mul_f32_e32 v27, 0x3e000000, v27
	v_mul_f32_e32 v21, 0xbfb8aa3b, v21
	v_and_b32_e32 v3, 0xffff0000, v3
	v_and_b32_e32 v4, 0xffff0000, v4
	v_mul_f32_e32 v1, v1, v27
	v_and_b32_e32 v5, 0xffff0000, v5
	v_exp_f32_e32 v21, v21
	v_mul_f32_e32 v3, 0x3e000000, v3
	v_mul_f32_e32 v4, 0x3e000000, v4
	v_mul_f32_e32 v5, 0x3e000000, v5
	v_cvt_pk_bf16_f32 v2, v1, v2
	v_mul_lo_u32 v1, v9, s4
	v_mul_f32_e32 v3, v3, v23
	v_mul_f32_e32 v4, v4, v25
	v_mul_f32_e32 v5, v5, v20
	v_add3_u32 v1, 0, v1, v6
	v_mul_f32_e32 v7, v7, v28
	v_and_b32_e32 v13, 0xffff0000, v13
	v_cvt_pk_bf16_f32 v3, v14, v3
	v_cvt_pk_bf16_f32 v4, v15, v4
	v_cvt_pk_bf16_f32 v5, v17, v5
	ds_write_b128 v1, v[2:5] offset:18688
	v_cvt_pk_bf16_f32 v2, v7, v10
	v_mul_f32_e32 v16, v16, v30
	v_mul_f32_e32 v18, v18, v32
	v_mul_f32_e32 v13, v21, v13
	v_cvt_pk_bf16_f32 v3, v16, v11
	v_cvt_pk_bf16_f32 v4, v18, v12
	v_cvt_pk_bf16_f32 v5, v19, v13
	ds_write_b128 v1, v[2:5] offset:27904
	v_or_b32_e32 v2, s0, v0
	v_ashrrev_i32_e32 v3, 31, v2
	v_lshlrev_b64 v[2:3], 14, v[2:3]
	v_lshl_add_u64 v[2:3], s[86:87], 0, v[2:3]
	v_lshlrev_b32_e32 v4, 4, v89
	v_lshl_add_u64 v[2:3], v[2:3], 0, s[72:73]
	v_mov_b32_e32 v5, v201
	v_lshl_add_u64 v[2:3], v[2:3], 0, v[4:5]
	s_mov_b64 s[0:1], 0x22f00000
	v_lshl_add_u64 v[2:3], v[2:3], 0, s[0:1]
	s_add_u32 s0, s92, s45
	v_mov_b32_e32 v1, v201
	s_addc_u32 s1, s93, 0
	v_lshl_add_u64 v[6:7], s[0:1], 0, v[0:1]
	v_lshlrev_b64 v[6:7], 8, v[6:7]
	v_lshl_add_u64 v[6:7], s[86:87], 0, v[6:7]
	v_and_b32_e32 v10, 32, v88
	v_mov_b32_e32 v11, v201
	v_lshl_add_u64 v[6:7], v[6:7], 0, v[10:11]
	s_mov_b64 s[0:1], 0x37e00000
	v_lshl_add_u64 v[10:11], v[6:7], 0, s[0:1]
	s_mov_b32 s0, 0x37e00000
	v_add_co_u32_e32 v6, vcc, s0, v6
	s_waitcnt lgkmcnt(0)
	s_barrier
; #define LAS __attribute__((address_space(3)))
; #define MFMA32(a, b, c) __builtin_amdgcn_mfma_f32_32x32x16_bf16((a), (b), (c), 0, 0, 0)
; template <int MODEC>
; __device__ __forceinline__ void gla_unit(LAS unsigned char* lds, const int tid_in, const Params& p, int l, int hh, int n) {
;     ...
;         bf16x8 qfr[4];
; #pragma unroll
;         for (int ks = 0; ks < 4; ++ks) qfr[ks] = *(const LAS bf16x8*)(QT + tt * 72 + 16 * ks + 8 * h2);
;         f32x16 acc;
; #pragma unroll
;         for (int i = 0; i < 16; ++i) acc[i] = 0.f;
;         bf16x8 vfr[2][2]; f32x4 sfr[4][2];
; #pragma unroll
;         for (int sb = 0; sb < 2; ++sb)
; #pragma unroll
;             for (int kk2 = 0; kk2 < 2; ++kk2) vfr[sb][kk2] = *(const bf16x8*)(vT + (size_t)(VT_G + hh * 128 + 32 * dvb + r) * T_ + t0 + 32 * sb + 16 * kk2 + 8 * h2);
;         { const float* sp_ = kvb + ((size_t)(hh * 128 + n) * 128 + 32 * dvb + r) * 64 + 8 * h2;
; #pragma unroll
;           for (int ks = 0; ks < 4; ++ks) { sfr[ks][0] = *(const f32x4*)(sp_ + 16 * ks); sfr[ks][1] = *(const f32x4*)(sp_ + 16 * ks + 4); } }
; #pragma unroll
;         for (int sb = 0; sb < 2; ++sb) {
;             if (sb <= tb) {
;                 f32x16 sa;
; #pragma unroll
;                 for (int i = 0; i < 16; ++i) sa[i] = 0.f;
; #pragma unroll
;                 for (int ks = 0; ks < 4; ++ks) { const bf16x8 a = *(const LAS bf16x8*)(KT + (32 * sb + pr) * 72 + 16 * ks + 8 * h2); sa = MFMA32(a, qfr[ks], sa); }
; #pragma unroll
;                 for (int i = 0; i < 16; ++i) { const int sl = 32 * sb + (i & 7) + 8 * h2 + 16 * (i >> 3); if (sl > tt) sa[i] = 0.f; }
; #pragma unroll
;                 for (int kk2 = 0; kk2 < 2; ++kk2) {
;                     const bf16x8 pfr = pack8(sa[8 * kk2], sa[8 * kk2 + 1], sa[8 * kk2 + 2], sa[8 * kk2 + 3], sa[8 * kk2 + 4], sa[8 * kk2 + 5], sa[8 * kk2 + 6], sa[8 * kk2 + 7]);
;                     acc = MFMA32(vfr[sb][kk2], pfr, acc);
;                 }
	global_load_dwordx4 v[84:87], v[2:3], off offset:64
	global_load_dwordx4 v[80:83], v[2:3], off offset:96
	v_addc_co_u32_e32 v7, vcc, 0, v7, vcc
	global_load_dwordx4 v[68:71], v[10:11], off offset:16
	global_load_dwordx4 v[60:63], v[10:11], off offset:64
	global_load_dwordx4 v[56:59], v[10:11], off offset:80
	global_load_dwordx4 v[48:51], v[10:11], off offset:128
	global_load_dwordx4 v[44:47], v[10:11], off offset:144
	global_load_dwordx4 v[32:35], v[10:11], off offset:192
	global_load_dwordx4 v[76:79], v[6:7], off
	global_load_dwordx4 v[36:39], v[10:11], off offset:208
	v_lshlrev_b32_e32 v0, 1, v8
	v_and_b32_e32 v1, 8, v0
	v_lshrrev_b32_e32 v0, 1, v8
	v_and_b32_e32 v6, 4, v0
	v_add_u32_e32 v0, 0, v4
	v_mad_u64_u32 v[4:5], s[0:1], v90, s4, v[0:1]
	ds_read_b128 v[72:75], v4 offset:18688
	ds_read_b128 v[64:67], v4 offset:18720
	ds_read_b128 v[52:55], v4 offset:18752
	ds_read_b128 v[40:43], v4 offset:18784
	v_and_b32_e32 v4, 19, v8
	v_lshlrev_b32_e32 v5, 3, v89
	v_or3_b32 v1, v1, v4, v6
	v_sub_u32_e32 v91, v90, v5
	s_cmp_lt_i32 s53, 0
	v_mad_u32_u24 v92, v1, s4, v0
	s_cbranch_scc1 .LBB0_613
	global_load_dwordx4 v[94:97], v[2:3], off offset:32
	global_load_dwordx4 v[16:19], v[2:3], off
	ds_read_b128 v[0:3], v92 offset:27904
	ds_read_b128 v[20:23], v92 offset:27936
	v_cmp_gt_i32_e64 s[28:29], 22, v91
	v_cmp_gt_i32_e64 s[30:31], 23, v91
	s_waitcnt lgkmcnt(0)
	v_mfma_f32_32x32x16_bf16 v[0:15], v[0:3], v[72:75], 0
	v_cmp_gt_i32_e64 s[26:27], 21, v91
	s_and_b64 s[28:29], s[30:31], s[28:29]
	v_cmp_gt_i32_e64 s[24:25], 20, v91
	s_and_b64 s[26:27], s[28:29], s[26:27]
	v_cmp_gt_i32_e64 s[22:23], 19, v91
	s_and_b64 s[24:25], s[26:27], s[24:25]
	v_cmp_gt_i32_e64 s[20:21], 18, v91
	v_mfma_f32_32x32x16_bf16 v[0:15], v[20:23], v[64:67], v[0:15]
	ds_read_b128 v[20:23], v92 offset:27968
	s_and_b64 s[22:23], s[24:25], s[22:23]
	v_cmp_gt_i32_e64 s[18:19], 17, v91
	s_and_b64 s[20:21], s[22:23], s[20:21]
	v_cmp_gt_i32_e64 s[16:17], 16, v91
	s_and_b64 s[18:19], s[20:21], s[18:19]
	v_cmp_gt_i32_e64 s[14:15], 7, v91
	s_waitcnt lgkmcnt(0)
	v_mfma_f32_32x32x16_bf16 v[0:15], v[20:23], v[52:55], v[0:15]
	ds_read_b128 v[20:23], v92 offset:28000
	s_and_b64 s[16:17], s[18:19], s[16:17]
	v_cmp_gt_i32_e64 s[12:13], 6, v91
	s_and_b64 s[14:15], s[16:17], s[14:15]
	v_cmp_gt_i32_e64 s[10:11], 5, v91
	s_and_b64 s[12:13], s[14:15], s[12:13]
	v_cmp_gt_i32_e64 s[8:9], 4, v91
	s_waitcnt lgkmcnt(0)
	v_mfma_f32_32x32x16_bf16 v[0:15], v[20:23], v[40:43], v[0:15]
	s_and_b64 s[10:11], s[12:13], s[10:11]
	v_cmp_gt_i32_e64 s[6:7], 3, v91
	s_and_b64 s[8:9], s[10:11], s[8:9]
	v_cmp_gt_i32_e64 s[4:5], 2, v91
	s_and_b64 s[6:7], s[8:9], s[6:7]
	v_cmp_gt_i32_e64 s[0:1], 1, v91
	s_and_b64 s[4:5], s[6:7], s[4:5]
	v_cmp_gt_i32_e32 vcc, 0, v91
	s_and_b64 s[0:1], s[4:5], s[0:1]
	s_nop 2
	v_cndmask_b32_e64 v1, v1, 0, s[0:1]
	s_and_b64 s[0:1], s[0:1], vcc
	v_cndmask_b32_e64 v3, v3, 0, s[6:7]
	v_cndmask_b32_e64 v2, v2, 0, s[4:5]
	v_cndmask_b32_e64 v0, v0, 0, s[0:1]
	v_cndmask_b32_e64 v7, v7, 0, s[14:15]
	v_cndmask_b32_e64 v6, v6, 0, s[12:13]
	v_cndmask_b32_e64 v5, v5, 0, s[10:11]
	v_cndmask_b32_e64 v4, v4, 0, s[8:9]
	v_cvt_pk_bf16_f32 v0, v0, v1
	v_cvt_pk_bf16_f32 v1, v2, v3
	v_cvt_pk_bf16_f32 v2, v4, v5
	v_cvt_pk_bf16_f32 v3, v6, v7
	v_cndmask_b32_e64 v14, v14, 0, s[28:29]
	v_cndmask_b32_e64 v15, v15, 0, s[30:31]
	v_cndmask_b32_e64 v12, v12, 0, s[24:25]
	v_cndmask_b32_e64 v13, v13, 0, s[26:27]
	v_cndmask_b32_e64 v10, v10, 0, s[20:21]
	v_cndmask_b32_e64 v11, v11, 0, s[22:23]
	v_cndmask_b32_e64 v9, v9, 0, s[18:19]
	v_cndmask_b32_e64 v8, v8, 0, s[16:17]
	s_waitcnt vmcnt(0)
	v_mfma_f32_32x32x16_bf16 v[16:31], v[16:19], v[0:3], 0
	v_cvt_pk_bf16_f32 v0, v8, v9
	v_cvt_pk_bf16_f32 v1, v10, v11
	v_cvt_pk_bf16_f32 v2, v12, v13
	v_cvt_pk_bf16_f32 v3, v14, v15
	s_nop 0
	v_mfma_f32_32x32x16_bf16 v[16:31], v[94:97], v[0:3], v[16:31]
	s_cmp_gt_i32 s53, 0
	s_mov_b64 s[0:1], -1
	s_cbranch_scc1 .LBB0_614
	s_branch .LBB0_615

; __device__ __forceinline__ unsigned cvt_pk_bf16(float lo, float hi) { unsigned r; asm("v_cvt_pk_bf16_f32 %0, %1, %2" : "=v"(r) : "v"(lo), "v"(hi)); return r; }
; __device__ __forceinline__ float bflo(unsigned w) { return __uint_as_float(w << 16); }
; __device__ __forceinline__ float bfhi(unsigned w) { return __uint_as_float(w & 0xffff0000u); }
; __device__ __forceinline__ float shx(float v, int off, int lane) { return __int_as_float(__builtin_amdgcn_ds_bpermute((lane ^ off) << 2, __float_as_int(v))); }
;     __device__ __forceinline__ void operator()(const f32x4 (&acc)[2][2][4][2], const RU& u, int wr, int wc, int fr, int fq) const {
;         const int col0 = u.pn * 256 + wc * 32 + 8 * fq, ln_ = fq * 16 + fr;
;         u32x4 bb[2][4][2];
; #pragma unroll
;         for (int ai = 0; ai < 2; ++ai)
; #pragma unroll
;             for (int m = 0; m < 4; ++m) { const bf16_t* rp = hb + (size_t)(u.pm * 256 + ai * 128 + wr * 64 + m * 16 + fr) * D_ + col0; bb[ai][m][0] = *(const u32x4*)rp; bb[ai][m][1] = *(const u32x4*)(rp + 128); }
; #pragma unroll
;         for (int ai = 0; ai < 2; ++ai)
; #pragma unroll
;             for (int m = 0; m < 4; ++m) {
;                 const int row = u.pm * 256 + ai * 128 + wr * 64 + m * 16 + fr; float sq = 0.f;
;                 bf16_t* rp = hb + (size_t)row * D_ + col0;
; #pragma unroll
;                 for (int bj = 0; bj < 2; ++bj) {
;                     const u32x4 b = bb[ai][m][bj];
;                     const f32x4 v0 = acc[ai][bj][m][0] + (f32x4){bflo(b.x), bfhi(b.x), bflo(b.y), bfhi(b.y)};
;                     const f32x4 v1 = acc[ai][bj][m][1] + (f32x4){bflo(b.z), bfhi(b.z), bflo(b.w), bfhi(b.w)};
;                     u32x4 w; w.x = cvt_pk_bf16(v0[0], v0[1]); w.y = cvt_pk_bf16(v0[2], v0[3]); w.z = cvt_pk_bf16(v1[0], v1[1]); w.w = cvt_pk_bf16(v1[2], v1[3]);
;                     *(u32x4*)(rp + bj * 128) = w;
;                     sq += ((v0[0] * v0[0] + v0[1] * v0[1]) + (v0[2] * v0[2] + v0[3] * v0[3])) + ((v1[0] * v1[0] + v1[1] * v1[1]) + (v1[2] * v1[2] + v1[3] * v1[3]));
;                 }
;                 sq += shx(sq, 16, ln_); sq += shx(sq, 32, ln_);
;                 if (fq == 0) red[wc * 256 + ai * 128 + wr * 64 + m * 16 + fr] = sq;
.LBB0_685:
	s_mul_i32 s16, s44, s23
	s_add_i32 s16, s16, s22
	s_lshl_b32 s17, s16, 3
	s_and_b32 s17, s17, 0xffffff00
	s_lshl_b32 s16, s16, 8
	v_or_b32_e32 v204, s17, v221
	s_and_b32 s18, s16, 0x1f00
	v_add_u32_e32 v112, s18, v202
	v_ashrrev_i32_e32 v205, 31, v204
	v_lshlrev_b64 v[232:233], 1, v[204:205]
	v_ashrrev_i32_e32 v113, 31, v112
	v_lshl_add_u64 v[114:115], s[6:7], 0, v[232:233]
	v_lshlrev_b64 v[236:237], 12, v[112:113]
	v_lshl_add_u64 v[116:117], v[114:115], 0, v[236:237]
	global_load_dwordx4 v[228:231], v[116:117], off
	global_load_dwordx4 v[184:187], v[116:117], off offset:256
	v_or_b32_e32 v116, 16, v112
	v_ashrrev_i32_e32 v117, 31, v116
	v_lshlrev_b64 v[218:219], 12, v[116:117]
	v_lshl_add_u64 v[116:117], v[114:115], 0, v[218:219]
	global_load_dwordx4 v[180:183], v[116:117], off
	global_load_dwordx4 v[176:179], v[116:117], off offset:256
	v_or_b32_e32 v116, 32, v112
	v_or_b32_e32 v112, 48, v112
	v_ashrrev_i32_e32 v117, 31, v116
	v_ashrrev_i32_e32 v113, 31, v112
	v_lshlrev_b64 v[216:217], 12, v[116:117]
	v_lshlrev_b64 v[214:215], 12, v[112:113]
	s_mov_b64 s[16:17], 0x80000
	v_lshl_add_u64 v[116:117], v[114:115], 0, v[216:217]
	v_lshl_add_u64 v[112:113], v[114:115], 0, v[214:215]
	v_lshl_add_u64 v[212:213], v[236:237], 0, s[16:17]
	s_mov_b64 s[16:17], 0x90000
	global_load_dwordx4 v[172:175], v[116:117], off
	global_load_dwordx4 v[168:171], v[116:117], off offset:256
	global_load_dwordx4 v[164:167], v[112:113], off
	global_load_dwordx4 v[160:163], v[112:113], off offset:256
	v_lshl_add_u64 v[112:113], v[114:115], 0, v[212:213]
	v_lshl_add_u64 v[210:211], v[236:237], 0, s[16:17]
	s_mov_b64 s[16:17], 0xa0000
	global_load_dwordx4 v[156:159], v[112:113], off
	global_load_dwordx4 v[144:147], v[112:113], off offset:256
	v_lshl_add_u64 v[112:113], v[114:115], 0, v[210:211]
	v_lshl_add_u64 v[208:209], v[236:237], 0, s[16:17]
	s_mov_b64 s[16:17], 0xb0000
	global_load_dwordx4 v[140:143], v[112:113], off
	global_load_dwordx4 v[136:139], v[112:113], off offset:256
	v_lshl_add_u64 v[112:113], v[114:115], 0, v[208:209]
	v_lshl_add_u64 v[206:207], v[236:237], 0, s[16:17]
	global_load_dwordx4 v[128:131], v[112:113], off
	global_load_dwordx4 v[116:119], v[112:113], off offset:256
	v_lshl_add_u64 v[112:113], v[114:115], 0, v[206:207]
	global_load_dwordx4 v[120:123], v[112:113], off
	s_nop 0
	global_load_dwordx4 v[112:115], v[112:113], off offset:256
	v_lshl_add_u64 v[236:237], s[6:7], 0, v[236:237]
	v_lshl_add_u64 v[232:233], v[236:237], 0, v[232:233]
	s_waitcnt vmcnt(0) lgkmcnt(0)
	v_lshlrev_b32_e32 v236, 16, v228
	v_and_b32_e32 v237, 0xffff0000, v228
	v_lshlrev_b32_e32 v228, 16, v229
	v_and_b32_e32 v229, 0xffff0000, v229
	v_pk_add_f32 v[154:155], v[154:155], v[228:229]
	v_lshlrev_b32_e32 v228, 16, v230
	v_and_b32_e32 v229, 0xffff0000, v230
	v_pk_add_f32 v[152:153], v[152:153], v[236:237]
	v_lshlrev_b32_e32 v230, 16, v231
	v_and_b32_e32 v231, 0xffff0000, v231
	v_pk_add_f32 v[228:229], v[148:149], v[228:229]
	v_cvt_pk_bf16_f32 v148, v152, v153
	v_cvt_pk_bf16_f32 v149, v154, v155
	v_pk_add_f32 v[230:231], v[150:151], v[230:231]
	v_cvt_pk_bf16_f32 v150, v228, v229
	s_nop 0
	v_cvt_pk_bf16_f32 v151, v230, v231
	global_store_dwordx4 v[232:233], v[148:151], off
	s_nop 1
	v_mul_f32_e32 v148, v153, v153
	v_mul_f32_e32 v149, v155, v155
	v_fmac_f32_e32 v148, v152, v152
	v_fmac_f32_e32 v149, v154, v154
	v_add_f32_e32 v148, v148, v149
	v_mul_f32_e32 v149, v229, v229
	v_mul_f32_e32 v150, v231, v231
	v_fmac_f32_e32 v149, v228, v228
	v_fmac_f32_e32 v150, v230, v230
	v_add_f32_e32 v149, v149, v150
	v_add_f32_e32 v152, v148, v149
	v_lshlrev_b32_e32 v148, 16, v184
	v_and_b32_e32 v149, 0xffff0000, v184
	v_lshlrev_b32_e32 v150, 16, v185
	v_and_b32_e32 v151, 0xffff0000, v185
	v_pk_add_f32 v[132:133], v[132:133], v[148:149]
	v_lshlrev_b32_e32 v148, 16, v186
	v_and_b32_e32 v149, 0xffff0000, v186
	v_pk_add_f32 v[134:135], v[134:135], v[150:151]
	v_lshlrev_b32_e32 v150, 16, v187
	v_and_b32_e32 v151, 0xffff0000, v187
	v_pk_add_f32 v[148:149], v[124:125], v[148:149]
	v_cvt_pk_bf16_f32 v124, v132, v133
	v_cvt_pk_bf16_f32 v125, v134, v135
	v_pk_add_f32 v[150:151], v[126:127], v[150:151]
	v_cvt_pk_bf16_f32 v126, v148, v149
	s_nop 0
	v_cvt_pk_bf16_f32 v127, v150, v151
	global_store_dwordx4 v[232:233], v[124:127], off offset:256
	s_nop 1
	v_mul_f32_e32 v124, v133, v133
	v_mul_f32_e32 v125, v135, v135
	v_fmac_f32_e32 v124, v132, v132
	v_fmac_f32_e32 v125, v134, v134
	v_add_f32_e32 v124, v124, v125
	v_mul_f32_e32 v125, v149, v149
	v_mul_f32_e32 v126, v151, v151
	v_fmac_f32_e32 v125, v148, v148
	v_fmac_f32_e32 v126, v150, v150
	v_add_f32_e32 v125, v125, v126
	v_add_f32_e32 v124, v124, v125
	v_add_f32_e32 v124, v152, v124
	ds_bpermute_b32 v125, v222, v124
	s_waitcnt lgkmcnt(0)
	v_add_f32_e32 v124, v124, v125
	ds_bpermute_b32 v125, v223, v124
	s_and_saveexec_b64 s[16:17], s[0:1]
	s_cbranch_execz .LBB0_687
	s_waitcnt lgkmcnt(0)
	v_add_f32_e32 v124, v124, v125
	ds_write_b32 v224, v124
; __device__ __forceinline__ unsigned cvt_pk_bf16(float lo, float hi) { unsigned r; asm("v_cvt_pk_bf16_f32 %0, %1, %2" : "=v"(r) : "v"(lo), "v"(hi)); return r; }
; __device__ __forceinline__ float bflo(unsigned w) { return __uint_as_float(w << 16); }
; __device__ __forceinline__ float bfhi(unsigned w) { return __uint_as_float(w & 0xffff0000u); }
; __device__ __forceinline__ float shx(float v, int off, int lane) { return __int_as_float(__builtin_amdgcn_ds_bpermute((lane ^ off) << 2, __float_as_int(v))); }
;     __device__ __forceinline__ void operator()(const f32x4 (&acc)[2][2][4][2], const RU& u, int wr, int wc, int fr, int fq) const {
;     ...
;         for (int ai = 0; ai < 2; ++ai)
; #pragma unroll
;             for (int m = 0; m < 4; ++m) {
;                 const int row = u.pm * 256 + ai * 128 + wr * 64 + m * 16 + fr; float sq = 0.f;
;                 bf16_t* rp = hb + (size_t)row * D_ + col0;
; #pragma unroll
;                 for (int bj = 0; bj < 2; ++bj) {
;                     const u32x4 b = bb[ai][m][bj];
;                     const f32x4 v0 = acc[ai][bj][m][0] + (f32x4){bflo(b.x), bfhi(b.x), bflo(b.y), bfhi(b.y)};
;                     const f32x4 v1 = acc[ai][bj][m][1] + (f32x4){bflo(b.z), bfhi(b.z), bflo(b.w), bfhi(b.w)};
;                     u32x4 w; w.x = cvt_pk_bf16(v0[0], v0[1]); w.y = cvt_pk_bf16(v0[2], v0[3]); w.z = cvt_pk_bf16(v1[0], v1[1]); w.w = cvt_pk_bf16(v1[2], v1[3]);
;                     *(u32x4*)(rp + bj * 128) = w;
;                     sq += ((v0[0] * v0[0] + v0[1] * v0[1]) + (v0[2] * v0[2] + v0[3] * v0[3])) + ((v1[0] * v1[0] + v1[1] * v1[1]) + (v1[2] * v1[2] + v1[3] * v1[3]));
;                 }
;                 sq += shx(sq, 16, ln_); sq += shx(sq, 32, ln_);
;                 if (fq == 0) red[wc * 256 + ai * 128 + wr * 64 + m * 16 + fr] = sq;
.LBB0_687:
	s_or_b64 exec, exec, s[16:17]
	v_lshlrev_b32_e32 v126, 16, v180
	v_and_b32_e32 v127, 0xffff0000, v180
	v_lshlrev_b32_e32 v132, 16, v181
	v_and_b32_e32 v133, 0xffff0000, v181
	v_pk_add_f32 v[110:111], v[110:111], v[132:133]
	v_pk_add_f32 v[108:109], v[108:109], v[126:127]
	v_lshlrev_b32_e32 v126, 16, v182
	v_and_b32_e32 v127, 0xffff0000, v182
	v_lshlrev_b32_e32 v132, 16, v183
	v_and_b32_e32 v133, 0xffff0000, v183
	v_pk_add_f32 v[132:133], v[106:107], v[132:133]
	v_pk_add_f32 v[106:107], v[104:105], v[126:127]
	v_cvt_pk_bf16_f32 v104, v108, v109
	v_mul_f32_e32 v109, v109, v109
	v_fmac_f32_e32 v109, v108, v108
	v_mul_f32_e32 v108, v111, v111
	v_fmac_f32_e32 v108, v110, v110
	v_cvt_pk_bf16_f32 v105, v110, v111
	v_add_f32_e32 v108, v109, v108
	v_mul_f32_e32 v109, v107, v107
	v_mul_f32_e32 v110, v133, v133
	v_fmac_f32_e32 v109, v106, v106
	v_fmac_f32_e32 v110, v132, v132
	v_add_f32_e32 v109, v109, v110
	v_add_f32_e32 v126, v108, v109
	v_lshlrev_b32_e32 v108, 16, v176
	v_and_b32_e32 v109, 0xffff0000, v176
	v_lshlrev_b32_e32 v110, 16, v177
	v_and_b32_e32 v111, 0xffff0000, v177
	v_pk_add_f32 v[102:103], v[102:103], v[110:111]
	v_pk_add_f32 v[100:101], v[100:101], v[108:109]
	v_lshlrev_b32_e32 v108, 16, v178
	v_and_b32_e32 v109, 0xffff0000, v178
	v_lshlrev_b32_e32 v110, 16, v179
	v_and_b32_e32 v111, 0xffff0000, v179
	v_pk_add_f32 v[108:109], v[96:97], v[108:109]
	v_mul_f32_e32 v96, v101, v101
	v_mul_f32_e32 v97, v103, v103
	v_pk_add_f32 v[110:111], v[98:99], v[110:111]
	v_fmac_f32_e32 v96, v100, v100
	v_fmac_f32_e32 v97, v102, v102
	v_add_f32_e32 v96, v96, v97
	v_mul_f32_e32 v97, v109, v109
	v_mul_f32_e32 v98, v111, v111
	v_fmac_f32_e32 v97, v108, v108
	v_fmac_f32_e32 v98, v110, v110
	v_add_f32_e32 v97, v97, v98
	v_add_f32_e32 v96, v96, v97
	v_add_f32_e32 v96, v126, v96
	ds_bpermute_b32 v97, v222, v96
	s_waitcnt lgkmcnt(0)
	v_lshl_add_u64 v[124:125], s[6:7], 0, v[218:219]
	v_lshl_add_u64 v[124:125], v[204:205], 1, v[124:125]
	v_cvt_pk_bf16_f32 v106, v106, v107
	v_cvt_pk_bf16_f32 v107, v132, v133
	v_add_f32_e32 v96, v96, v97
	ds_bpermute_b32 v97, v223, v96
	global_store_dwordx4 v[124:125], v[104:107], off
	v_cvt_pk_bf16_f32 v98, v100, v101
	v_cvt_pk_bf16_f32 v99, v102, v103
	v_cvt_pk_bf16_f32 v100, v108, v109
	v_cvt_pk_bf16_f32 v101, v110, v111
	global_store_dwordx4 v[124:125], v[98:101], off offset:256
	s_and_saveexec_b64 s[16:17], s[0:1]
	s_cbranch_execz .LBB0_689
	s_waitcnt lgkmcnt(0)
	v_add_f32_e32 v96, v96, v97
	ds_write_b32 v224, v96 offset:64
.LBB0_689:
	s_or_b64 exec, exec, s[16:17]
	v_lshlrev_b32_e32 v98, 16, v172
	v_and_b32_e32 v99, 0xffff0000, v172
	v_lshlrev_b32_e32 v100, 16, v173
	v_and_b32_e32 v101, 0xffff0000, v173
	v_pk_add_f32 v[94:95], v[94:95], v[100:101]
	v_pk_add_f32 v[92:93], v[92:93], v[98:99]
	v_lshlrev_b32_e32 v98, 16, v174
	v_and_b32_e32 v99, 0xffff0000, v174
	v_lshlrev_b32_e32 v100, 16, v175
	v_and_b32_e32 v101, 0xffff0000, v175
	v_pk_add_f32 v[100:101], v[90:91], v[100:101]
	v_pk_add_f32 v[90:91], v[88:89], v[98:99]
	v_cvt_pk_bf16_f32 v88, v92, v93
	v_mul_f32_e32 v93, v93, v93
	v_fmac_f32_e32 v93, v92, v92
	v_mul_f32_e32 v92, v95, v95
	v_fmac_f32_e32 v92, v94, v94
	v_cvt_pk_bf16_f32 v89, v94, v95
	v_add_f32_e32 v92, v93, v92
	v_mul_f32_e32 v93, v91, v91
	v_mul_f32_e32 v94, v101, v101
	v_fmac_f32_e32 v93, v90, v90
	v_fmac_f32_e32 v94, v100, v100
	v_add_f32_e32 v93, v93, v94
	v_add_f32_e32 v98, v92, v93
	v_lshlrev_b32_e32 v92, 16, v168
	v_and_b32_e32 v93, 0xffff0000, v168
	v_lshlrev_b32_e32 v94, 16, v169
	v_and_b32_e32 v95, 0xffff0000, v169
	v_pk_add_f32 v[86:87], v[86:87], v[94:95]
	v_pk_add_f32 v[84:85], v[84:85], v[92:93]
	v_lshlrev_b32_e32 v92, 16, v170
	v_and_b32_e32 v93, 0xffff0000, v170
	v_lshlrev_b32_e32 v94, 16, v171
	v_and_b32_e32 v95, 0xffff0000, v171
	v_pk_add_f32 v[92:93], v[80:81], v[92:93]
	v_mul_f32_e32 v80, v85, v85
	v_mul_f32_e32 v81, v87, v87
	v_pk_add_f32 v[94:95], v[82:83], v[94:95]
	v_fmac_f32_e32 v80, v84, v84
	v_fmac_f32_e32 v81, v86, v86
	v_add_f32_e32 v80, v80, v81
	v_mul_f32_e32 v81, v93, v93
	v_mul_f32_e32 v82, v95, v95
	v_fmac_f32_e32 v81, v92, v92
	v_fmac_f32_e32 v82, v94, v94
	v_add_f32_e32 v81, v81, v82
	v_add_f32_e32 v80, v80, v81
	v_add_f32_e32 v80, v98, v80
	ds_bpermute_b32 v81, v222, v80
	s_waitcnt lgkmcnt(0)
	v_lshl_add_u64 v[96:97], s[6:7], 0, v[216:217]
	v_lshl_add_u64 v[96:97], v[204:205], 1, v[96:97]
	v_cvt_pk_bf16_f32 v90, v90, v91
	v_cvt_pk_bf16_f32 v91, v100, v101
	v_add_f32_e32 v80, v80, v81
	ds_bpermute_b32 v81, v223, v80
	global_store_dwordx4 v[96:97], v[88:91], off
	v_cvt_pk_bf16_f32 v82, v84, v85
	v_cvt_pk_bf16_f32 v83, v86, v87
	v_cvt_pk_bf16_f32 v84, v92, v93
	v_cvt_pk_bf16_f32 v85, v94, v95
	global_store_dwordx4 v[96:97], v[82:85], off offset:256
	s_and_saveexec_b64 s[16:17], s[0:1]
	s_cbranch_execz .LBB0_691
	s_waitcnt lgkmcnt(0)
	v_add_f32_e32 v80, v80, v81
	ds_write_b32 v224, v80 offset:128
; __device__ __forceinline__ unsigned cvt_pk_bf16(float lo, float hi) { unsigned r; asm("v_cvt_pk_bf16_f32 %0, %1, %2" : "=v"(r) : "v"(lo), "v"(hi)); return r; }
; __device__ __forceinline__ float bflo(unsigned w) { return __uint_as_float(w << 16); }
; __device__ __forceinline__ float bfhi(unsigned w) { return __uint_as_float(w & 0xffff0000u); }
; __device__ __forceinline__ float shx(float v, int off, int lane) { return __int_as_float(__builtin_amdgcn_ds_bpermute((lane ^ off) << 2, __float_as_int(v))); }
;     __device__ __forceinline__ void operator()(const f32x4 (&acc)[2][2][4][2], const RU& u, int wr, int wc, int fr, int fq) const {
;     ...
;         for (int ai = 0; ai < 2; ++ai)
; #pragma unroll
;             for (int m = 0; m < 4; ++m) {
;                 const int row = u.pm * 256 + ai * 128 + wr * 64 + m * 16 + fr; float sq = 0.f;
;                 bf16_t* rp = hb + (size_t)row * D_ + col0;
; #pragma unroll
;                 for (int bj = 0; bj < 2; ++bj) {
;                     const u32x4 b = bb[ai][m][bj];
;                     const f32x4 v0 = acc[ai][bj][m][0] + (f32x4){bflo(b.x), bfhi(b.x), bflo(b.y), bfhi(b.y)};
;                     const f32x4 v1 = acc[ai][bj][m][1] + (f32x4){bflo(b.z), bfhi(b.z), bflo(b.w), bfhi(b.w)};
;                     u32x4 w; w.x = cvt_pk_bf16(v0[0], v0[1]); w.y = cvt_pk_bf16(v0[2], v0[3]); w.z = cvt_pk_bf16(v1[0], v1[1]); w.w = cvt_pk_bf16(v1[2], v1[3]);
;                     *(u32x4*)(rp + bj * 128) = w;
;                     sq += ((v0[0] * v0[0] + v0[1] * v0[1]) + (v0[2] * v0[2] + v0[3] * v0[3])) + ((v1[0] * v1[0] + v1[1] * v1[1]) + (v1[2] * v1[2] + v1[3] * v1[3]));
;                 }
;                 sq += shx(sq, 16, ln_); sq += shx(sq, 32, ln_);
;                 if (fq == 0) red[wc * 256 + ai * 128 + wr * 64 + m * 16 + fr] = sq;
.LBB0_691:
	s_or_b64 exec, exec, s[16:17]
	v_lshlrev_b32_e32 v82, 16, v164
	v_and_b32_e32 v83, 0xffff0000, v164
	v_lshlrev_b32_e32 v84, 16, v165
	v_and_b32_e32 v85, 0xffff0000, v165
	v_pk_add_f32 v[78:79], v[78:79], v[84:85]
	v_pk_add_f32 v[76:77], v[76:77], v[82:83]
	v_lshlrev_b32_e32 v82, 16, v166
	v_and_b32_e32 v83, 0xffff0000, v166
	v_lshlrev_b32_e32 v84, 16, v167
	v_and_b32_e32 v85, 0xffff0000, v167
	v_pk_add_f32 v[84:85], v[74:75], v[84:85]
	v_pk_add_f32 v[74:75], v[72:73], v[82:83]
	v_cvt_pk_bf16_f32 v72, v76, v77
	v_mul_f32_e32 v77, v77, v77
	v_fmac_f32_e32 v77, v76, v76
	v_mul_f32_e32 v76, v79, v79
	v_fmac_f32_e32 v76, v78, v78
	v_cvt_pk_bf16_f32 v73, v78, v79
	v_add_f32_e32 v76, v77, v76
	v_mul_f32_e32 v77, v75, v75
	v_mul_f32_e32 v78, v85, v85
	v_fmac_f32_e32 v77, v74, v74
	v_fmac_f32_e32 v78, v84, v84
	v_add_f32_e32 v77, v77, v78
	v_add_f32_e32 v82, v76, v77
	v_lshlrev_b32_e32 v76, 16, v160
	v_and_b32_e32 v77, 0xffff0000, v160
	v_lshlrev_b32_e32 v78, 16, v161
	v_and_b32_e32 v79, 0xffff0000, v161
	v_pk_add_f32 v[70:71], v[70:71], v[78:79]
	v_pk_add_f32 v[68:69], v[68:69], v[76:77]
	v_lshlrev_b32_e32 v76, 16, v162
	v_and_b32_e32 v77, 0xffff0000, v162
	v_lshlrev_b32_e32 v78, 16, v163
	v_and_b32_e32 v79, 0xffff0000, v163
	v_pk_add_f32 v[76:77], v[64:65], v[76:77]
	v_mul_f32_e32 v64, v69, v69
	v_mul_f32_e32 v65, v71, v71
	v_pk_add_f32 v[78:79], v[66:67], v[78:79]
	v_fmac_f32_e32 v64, v68, v68
	v_fmac_f32_e32 v65, v70, v70
	v_add_f32_e32 v64, v64, v65
	v_mul_f32_e32 v65, v77, v77
	v_mul_f32_e32 v66, v79, v79
	v_fmac_f32_e32 v65, v76, v76
	v_fmac_f32_e32 v66, v78, v78
	v_add_f32_e32 v65, v65, v66
	v_add_f32_e32 v64, v64, v65
	v_add_f32_e32 v64, v82, v64
	ds_bpermute_b32 v65, v222, v64
	s_waitcnt lgkmcnt(0)
	v_lshl_add_u64 v[80:81], s[6:7], 0, v[214:215]
	v_lshl_add_u64 v[80:81], v[204:205], 1, v[80:81]
	v_cvt_pk_bf16_f32 v74, v74, v75
	v_cvt_pk_bf16_f32 v75, v84, v85
	v_add_f32_e32 v64, v64, v65
	ds_bpermute_b32 v65, v223, v64
	global_store_dwordx4 v[80:81], v[72:75], off
	v_cvt_pk_bf16_f32 v66, v68, v69
	v_cvt_pk_bf16_f32 v67, v70, v71
	v_cvt_pk_bf16_f32 v68, v76, v77
	v_cvt_pk_bf16_f32 v69, v78, v79
	global_store_dwordx4 v[80:81], v[66:69], off offset:256
	s_and_saveexec_b64 s[16:17], s[0:1]
	s_cbranch_execz .LBB0_693
	s_waitcnt lgkmcnt(0)
	v_add_f32_e32 v64, v64, v65
	ds_write_b32 v224, v64 offset:192
.LBB0_693:
	s_or_b64 exec, exec, s[16:17]
	v_lshlrev_b32_e32 v66, 16, v156
	v_and_b32_e32 v67, 0xffff0000, v156
	v_lshlrev_b32_e32 v68, 16, v157
	v_and_b32_e32 v69, 0xffff0000, v157
	v_pk_add_f32 v[62:63], v[62:63], v[68:69]
	v_pk_add_f32 v[60:61], v[60:61], v[66:67]
	v_lshlrev_b32_e32 v66, 16, v158
	v_and_b32_e32 v67, 0xffff0000, v158
	v_lshlrev_b32_e32 v68, 16, v159
	v_and_b32_e32 v69, 0xffff0000, v159
	v_pk_add_f32 v[68:69], v[58:59], v[68:69]
	v_pk_add_f32 v[58:59], v[56:57], v[66:67]
	v_cvt_pk_bf16_f32 v56, v60, v61
	v_mul_f32_e32 v61, v61, v61
	v_fmac_f32_e32 v61, v60, v60
	v_mul_f32_e32 v60, v63, v63
	v_fmac_f32_e32 v60, v62, v62
	v_cvt_pk_bf16_f32 v57, v62, v63
	v_add_f32_e32 v60, v61, v60
	v_mul_f32_e32 v61, v59, v59
	v_mul_f32_e32 v62, v69, v69
	v_fmac_f32_e32 v61, v58, v58
	v_fmac_f32_e32 v62, v68, v68
	v_add_f32_e32 v61, v61, v62
	v_add_f32_e32 v66, v60, v61
	v_lshlrev_b32_e32 v60, 16, v144
	v_and_b32_e32 v61, 0xffff0000, v144
	v_lshlrev_b32_e32 v62, 16, v145
	v_and_b32_e32 v63, 0xffff0000, v145
	v_pk_add_f32 v[54:55], v[54:55], v[62:63]
	v_pk_add_f32 v[52:53], v[52:53], v[60:61]
	v_lshlrev_b32_e32 v60, 16, v146
	v_and_b32_e32 v61, 0xffff0000, v146
	v_lshlrev_b32_e32 v62, 16, v147
	v_and_b32_e32 v63, 0xffff0000, v147
	v_pk_add_f32 v[60:61], v[48:49], v[60:61]
	v_mul_f32_e32 v48, v53, v53
	v_mul_f32_e32 v49, v55, v55
	v_pk_add_f32 v[62:63], v[50:51], v[62:63]
	v_fmac_f32_e32 v48, v52, v52
	v_fmac_f32_e32 v49, v54, v54
	v_add_f32_e32 v48, v48, v49
	v_mul_f32_e32 v49, v61, v61
	v_mul_f32_e32 v50, v63, v63
	v_fmac_f32_e32 v49, v60, v60
	v_fmac_f32_e32 v50, v62, v62
	v_add_f32_e32 v49, v49, v50
	v_add_f32_e32 v48, v48, v49
	v_add_f32_e32 v48, v66, v48
	ds_bpermute_b32 v49, v222, v48
	s_waitcnt lgkmcnt(0)
	v_lshl_add_u64 v[64:65], s[6:7], 0, v[212:213]
	v_lshl_add_u64 v[64:65], v[204:205], 1, v[64:65]
	v_cvt_pk_bf16_f32 v58, v58, v59
	v_cvt_pk_bf16_f32 v59, v68, v69
	v_add_f32_e32 v48, v48, v49
	ds_bpermute_b32 v49, v223, v48
	global_store_dwordx4 v[64:65], v[56:59], off
	v_cvt_pk_bf16_f32 v50, v52, v53
	v_cvt_pk_bf16_f32 v51, v54, v55
	v_cvt_pk_bf16_f32 v52, v60, v61
	v_cvt_pk_bf16_f32 v53, v62, v63
	global_store_dwordx4 v[64:65], v[50:53], off offset:256
	s_and_saveexec_b64 s[16:17], s[0:1]
	s_cbranch_execz .LBB0_695
	s_waitcnt lgkmcnt(0)
	v_add_f32_e32 v48, v48, v49
	ds_write_b32 v224, v48 offset:512
; __device__ __forceinline__ unsigned cvt_pk_bf16(float lo, float hi) { unsigned r; asm("v_cvt_pk_bf16_f32 %0, %1, %2" : "=v"(r) : "v"(lo), "v"(hi)); return r; }
; __device__ __forceinline__ float bflo(unsigned w) { return __uint_as_float(w << 16); }
; __device__ __forceinline__ float bfhi(unsigned w) { return __uint_as_float(w & 0xffff0000u); }
; __device__ __forceinline__ float shx(float v, int off, int lane) { return __int_as_float(__builtin_amdgcn_ds_bpermute((lane ^ off) << 2, __float_as_int(v))); }
;     __device__ __forceinline__ void operator()(const f32x4 (&acc)[2][2][4][2], const RU& u, int wr, int wc, int fr, int fq) const {
;     ...
;         for (int ai = 0; ai < 2; ++ai)
; #pragma unroll
;             for (int m = 0; m < 4; ++m) {
;                 const int row = u.pm * 256 + ai * 128 + wr * 64 + m * 16 + fr; float sq = 0.f;
;                 bf16_t* rp = hb + (size_t)row * D_ + col0;
; #pragma unroll
;                 for (int bj = 0; bj < 2; ++bj) {
;                     const u32x4 b = bb[ai][m][bj];
;                     const f32x4 v0 = acc[ai][bj][m][0] + (f32x4){bflo(b.x), bfhi(b.x), bflo(b.y), bfhi(b.y)};
;                     const f32x4 v1 = acc[ai][bj][m][1] + (f32x4){bflo(b.z), bfhi(b.z), bflo(b.w), bfhi(b.w)};
;                     u32x4 w; w.x = cvt_pk_bf16(v0[0], v0[1]); w.y = cvt_pk_bf16(v0[2], v0[3]); w.z = cvt_pk_bf16(v1[0], v1[1]); w.w = cvt_pk_bf16(v1[2], v1[3]);
;                     *(u32x4*)(rp + bj * 128) = w;
;                     sq += ((v0[0] * v0[0] + v0[1] * v0[1]) + (v0[2] * v0[2] + v0[3] * v0[3])) + ((v1[0] * v1[0] + v1[1] * v1[1]) + (v1[2] * v1[2] + v1[3] * v1[3]));
;                 }
;                 sq += shx(sq, 16, ln_); sq += shx(sq, 32, ln_);
;                 if (fq == 0) red[wc * 256 + ai * 128 + wr * 64 + m * 16 + fr] = sq;
.LBB0_695:
	s_or_b64 exec, exec, s[16:17]
	v_lshlrev_b32_e32 v50, 16, v140
	v_and_b32_e32 v51, 0xffff0000, v140
	v_lshlrev_b32_e32 v52, 16, v141
	v_and_b32_e32 v53, 0xffff0000, v141
	v_pk_add_f32 v[46:47], v[46:47], v[52:53]
	v_pk_add_f32 v[44:45], v[44:45], v[50:51]
	v_lshlrev_b32_e32 v50, 16, v142
	v_and_b32_e32 v51, 0xffff0000, v142
	v_lshlrev_b32_e32 v52, 16, v143
	v_and_b32_e32 v53, 0xffff0000, v143
	v_pk_add_f32 v[52:53], v[42:43], v[52:53]
	v_pk_add_f32 v[42:43], v[40:41], v[50:51]
	v_cvt_pk_bf16_f32 v40, v44, v45
	v_mul_f32_e32 v45, v45, v45
	v_fmac_f32_e32 v45, v44, v44
	v_mul_f32_e32 v44, v47, v47
	v_fmac_f32_e32 v44, v46, v46
	v_cvt_pk_bf16_f32 v41, v46, v47
	v_add_f32_e32 v44, v45, v44
	v_mul_f32_e32 v45, v43, v43
	v_mul_f32_e32 v46, v53, v53
	v_fmac_f32_e32 v45, v42, v42
	v_fmac_f32_e32 v46, v52, v52
	v_add_f32_e32 v45, v45, v46
	v_add_f32_e32 v50, v44, v45
	v_lshlrev_b32_e32 v44, 16, v136
	v_and_b32_e32 v45, 0xffff0000, v136
	v_lshlrev_b32_e32 v46, 16, v137
	v_and_b32_e32 v47, 0xffff0000, v137
	v_pk_add_f32 v[38:39], v[38:39], v[46:47]
	v_pk_add_f32 v[36:37], v[36:37], v[44:45]
	v_lshlrev_b32_e32 v44, 16, v138
	v_and_b32_e32 v45, 0xffff0000, v138
	v_lshlrev_b32_e32 v46, 16, v139
	v_and_b32_e32 v47, 0xffff0000, v139
	v_pk_add_f32 v[44:45], v[32:33], v[44:45]
	v_mul_f32_e32 v32, v37, v37
	v_mul_f32_e32 v33, v39, v39
	v_pk_add_f32 v[46:47], v[34:35], v[46:47]
	v_fmac_f32_e32 v32, v36, v36
	v_fmac_f32_e32 v33, v38, v38
	v_add_f32_e32 v32, v32, v33
	v_mul_f32_e32 v33, v45, v45
	v_mul_f32_e32 v34, v47, v47
	v_fmac_f32_e32 v33, v44, v44
	v_fmac_f32_e32 v34, v46, v46
	v_add_f32_e32 v33, v33, v34
	v_add_f32_e32 v32, v32, v33
	v_add_f32_e32 v32, v50, v32
	ds_bpermute_b32 v33, v222, v32
	s_waitcnt lgkmcnt(0)
	v_lshl_add_u64 v[48:49], s[6:7], 0, v[210:211]
	v_lshl_add_u64 v[48:49], v[204:205], 1, v[48:49]
	v_cvt_pk_bf16_f32 v42, v42, v43
	v_cvt_pk_bf16_f32 v43, v52, v53
	v_add_f32_e32 v32, v32, v33
	ds_bpermute_b32 v33, v223, v32
	global_store_dwordx4 v[48:49], v[40:43], off
	v_cvt_pk_bf16_f32 v34, v36, v37
	v_cvt_pk_bf16_f32 v35, v38, v39
	v_cvt_pk_bf16_f32 v36, v44, v45
	v_cvt_pk_bf16_f32 v37, v46, v47
	global_store_dwordx4 v[48:49], v[34:37], off offset:256
	s_and_saveexec_b64 s[16:17], s[0:1]
	s_cbranch_execz .LBB0_697
	s_waitcnt lgkmcnt(0)
	v_add_f32_e32 v32, v32, v33
	ds_write_b32 v224, v32 offset:576
.LBB0_697:
	s_or_b64 exec, exec, s[16:17]
	v_lshlrev_b32_e32 v34, 16, v128
	v_and_b32_e32 v35, 0xffff0000, v128
	v_lshlrev_b32_e32 v36, 16, v129
	v_and_b32_e32 v37, 0xffff0000, v129
	v_pk_add_f32 v[30:31], v[30:31], v[36:37]
	v_pk_add_f32 v[28:29], v[28:29], v[34:35]
	v_lshlrev_b32_e32 v34, 16, v130
	v_and_b32_e32 v35, 0xffff0000, v130
	v_lshlrev_b32_e32 v36, 16, v131
	v_and_b32_e32 v37, 0xffff0000, v131
	v_pk_add_f32 v[36:37], v[26:27], v[36:37]
	v_pk_add_f32 v[26:27], v[24:25], v[34:35]
	v_cvt_pk_bf16_f32 v24, v28, v29
	v_mul_f32_e32 v29, v29, v29
	v_fmac_f32_e32 v29, v28, v28
	v_mul_f32_e32 v28, v31, v31
	v_fmac_f32_e32 v28, v30, v30
	v_cvt_pk_bf16_f32 v25, v30, v31
	v_add_f32_e32 v28, v29, v28
	v_mul_f32_e32 v29, v27, v27
	v_mul_f32_e32 v30, v37, v37
	v_fmac_f32_e32 v29, v26, v26
	v_fmac_f32_e32 v30, v36, v36
	v_add_f32_e32 v29, v29, v30
	v_add_f32_e32 v34, v28, v29
	v_lshlrev_b32_e32 v28, 16, v116
	v_and_b32_e32 v29, 0xffff0000, v116
	v_lshlrev_b32_e32 v30, 16, v117
	v_and_b32_e32 v31, 0xffff0000, v117
	v_pk_add_f32 v[22:23], v[22:23], v[30:31]
	v_pk_add_f32 v[20:21], v[20:21], v[28:29]
	v_lshlrev_b32_e32 v28, 16, v118
	v_and_b32_e32 v29, 0xffff0000, v118
	v_lshlrev_b32_e32 v30, 16, v119
	v_and_b32_e32 v31, 0xffff0000, v119
	v_pk_add_f32 v[28:29], v[16:17], v[28:29]
	v_mul_f32_e32 v16, v21, v21
	v_mul_f32_e32 v17, v23, v23
	v_pk_add_f32 v[30:31], v[18:19], v[30:31]
	v_fmac_f32_e32 v16, v20, v20
	v_fmac_f32_e32 v17, v22, v22
	v_add_f32_e32 v16, v16, v17
	v_mul_f32_e32 v17, v29, v29
	v_mul_f32_e32 v18, v31, v31
	v_fmac_f32_e32 v17, v28, v28
	v_fmac_f32_e32 v18, v30, v30
	v_add_f32_e32 v17, v17, v18
	v_add_f32_e32 v16, v16, v17
	v_add_f32_e32 v16, v34, v16
	ds_bpermute_b32 v17, v222, v16
	s_waitcnt lgkmcnt(0)
	v_lshl_add_u64 v[32:33], s[6:7], 0, v[208:209]
	v_lshl_add_u64 v[32:33], v[204:205], 1, v[32:33]
	v_cvt_pk_bf16_f32 v26, v26, v27
	v_cvt_pk_bf16_f32 v27, v36, v37
	v_add_f32_e32 v16, v16, v17
	ds_bpermute_b32 v17, v223, v16
	global_store_dwordx4 v[32:33], v[24:27], off
	v_cvt_pk_bf16_f32 v18, v20, v21
	v_cvt_pk_bf16_f32 v19, v22, v23
	v_cvt_pk_bf16_f32 v20, v28, v29
	v_cvt_pk_bf16_f32 v21, v30, v31
	global_store_dwordx4 v[32:33], v[18:21], off offset:256
	s_and_saveexec_b64 s[16:17], s[0:1]
	s_cbranch_execz .LBB0_699
	s_waitcnt lgkmcnt(0)
	v_add_f32_e32 v16, v16, v17
	ds_write_b32 v224, v16 offset:640
; __device__ __forceinline__ unsigned cvt_pk_bf16(float lo, float hi) { unsigned r; asm("v_cvt_pk_bf16_f32 %0, %1, %2" : "=v"(r) : "v"(lo), "v"(hi)); return r; }
; __device__ __forceinline__ float bflo(unsigned w) { return __uint_as_float(w << 16); }
; __device__ __forceinline__ float bfhi(unsigned w) { return __uint_as_float(w & 0xffff0000u); }
; __device__ __forceinline__ float shx(float v, int off, int lane) { return __int_as_float(__builtin_amdgcn_ds_bpermute((lane ^ off) << 2, __float_as_int(v))); }
;     __device__ __forceinline__ void operator()(const f32x4 (&acc)[2][2][4][2], const RU& u, int wr, int wc, int fr, int fq) const {
;     ...
;         for (int ai = 0; ai < 2; ++ai)
; #pragma unroll
;             for (int m = 0; m < 4; ++m) {
;                 const int row = u.pm * 256 + ai * 128 + wr * 64 + m * 16 + fr; float sq = 0.f;
;                 bf16_t* rp = hb + (size_t)row * D_ + col0;
; #pragma unroll
;                 for (int bj = 0; bj < 2; ++bj) {
;                     const u32x4 b = bb[ai][m][bj];
;                     const f32x4 v0 = acc[ai][bj][m][0] + (f32x4){bflo(b.x), bfhi(b.x), bflo(b.y), bfhi(b.y)};
;                     const f32x4 v1 = acc[ai][bj][m][1] + (f32x4){bflo(b.z), bfhi(b.z), bflo(b.w), bfhi(b.w)};
;                     u32x4 w; w.x = cvt_pk_bf16(v0[0], v0[1]); w.y = cvt_pk_bf16(v0[2], v0[3]); w.z = cvt_pk_bf16(v1[0], v1[1]); w.w = cvt_pk_bf16(v1[2], v1[3]);
;                     *(u32x4*)(rp + bj * 128) = w;
;                     sq += ((v0[0] * v0[0] + v0[1] * v0[1]) + (v0[2] * v0[2] + v0[3] * v0[3])) + ((v1[0] * v1[0] + v1[1] * v1[1]) + (v1[2] * v1[2] + v1[3] * v1[3]));
;                 }
;                 sq += shx(sq, 16, ln_); sq += shx(sq, 32, ln_);
;                 if (fq == 0) red[wc * 256 + ai * 128 + wr * 64 + m * 16 + fr] = sq;
;             }
;         asm volatile("s_waitcnt lgkmcnt(0)" ::: "memory"); __builtin_amdgcn_s_barrier(); asm volatile("" ::: "memory");
;         { const int t_ = (wr * 4 + wc) * 64 + ln_;
;           if (t_ < 256) atomicAdd(ssq + u.pm * 256 + t_, (u64)__float2ull_rn(((red[t_] + red[256 + t_]) + (red[512 + t_] + red[768 + t_])) * SSQ_SCALE)); }
.LBB0_699:
	s_or_b64 exec, exec, s[16:17]
	v_lshlrev_b32_e32 v18, 16, v120
	v_and_b32_e32 v19, 0xffff0000, v120
	v_lshlrev_b32_e32 v20, 16, v121
	v_and_b32_e32 v21, 0xffff0000, v121
	v_pk_add_f32 v[14:15], v[14:15], v[20:21]
	v_pk_add_f32 v[12:13], v[12:13], v[18:19]
	v_lshlrev_b32_e32 v18, 16, v122
	v_and_b32_e32 v19, 0xffff0000, v122
	v_lshlrev_b32_e32 v20, 16, v123
	v_and_b32_e32 v21, 0xffff0000, v123
	v_pk_add_f32 v[20:21], v[10:11], v[20:21]
	v_pk_add_f32 v[10:11], v[8:9], v[18:19]
	v_cvt_pk_bf16_f32 v8, v12, v13
	v_mul_f32_e32 v13, v13, v13
	v_fmac_f32_e32 v13, v12, v12
	v_mul_f32_e32 v12, v15, v15
	v_fmac_f32_e32 v12, v14, v14
	v_cvt_pk_bf16_f32 v9, v14, v15
	v_add_f32_e32 v12, v13, v12
	v_mul_f32_e32 v13, v11, v11
	v_mul_f32_e32 v14, v21, v21
	v_fmac_f32_e32 v13, v10, v10
	v_fmac_f32_e32 v14, v20, v20
	v_add_f32_e32 v13, v13, v14
	v_add_f32_e32 v18, v12, v13
	v_lshlrev_b32_e32 v12, 16, v112
	v_and_b32_e32 v13, 0xffff0000, v112
	v_lshlrev_b32_e32 v14, 16, v113
	v_and_b32_e32 v15, 0xffff0000, v113
	v_pk_add_f32 v[6:7], v[6:7], v[14:15]
	v_pk_add_f32 v[4:5], v[4:5], v[12:13]
	v_lshlrev_b32_e32 v12, 16, v114
	v_and_b32_e32 v13, 0xffff0000, v114
	v_lshlrev_b32_e32 v14, 16, v115
	v_and_b32_e32 v15, 0xffff0000, v115
	v_pk_add_f32 v[12:13], v[0:1], v[12:13]
	v_mul_f32_e32 v0, v5, v5
	v_mul_f32_e32 v1, v7, v7
	v_pk_add_f32 v[14:15], v[2:3], v[14:15]
	v_fmac_f32_e32 v0, v4, v4
	v_fmac_f32_e32 v1, v6, v6
	v_add_f32_e32 v0, v0, v1
	v_mul_f32_e32 v1, v13, v13
	v_mul_f32_e32 v2, v15, v15
	v_fmac_f32_e32 v1, v12, v12
	v_fmac_f32_e32 v2, v14, v14
	v_add_f32_e32 v1, v1, v2
	v_add_f32_e32 v0, v0, v1
	v_add_f32_e32 v0, v18, v0
	ds_bpermute_b32 v1, v222, v0
	s_waitcnt lgkmcnt(0)
	v_lshl_add_u64 v[16:17], s[6:7], 0, v[206:207]
	v_lshl_add_u64 v[16:17], v[204:205], 1, v[16:17]
	v_cvt_pk_bf16_f32 v10, v10, v11
	v_cvt_pk_bf16_f32 v11, v20, v21
	v_add_f32_e32 v0, v0, v1
	ds_bpermute_b32 v1, v223, v0
	global_store_dwordx4 v[16:17], v[8:11], off
	v_cvt_pk_bf16_f32 v2, v4, v5
	v_cvt_pk_bf16_f32 v3, v6, v7
	v_cvt_pk_bf16_f32 v4, v12, v13
	v_cvt_pk_bf16_f32 v5, v14, v15
	global_store_dwordx4 v[16:17], v[2:5], off offset:256
	s_and_saveexec_b64 s[16:17], s[0:1]
	s_cbranch_execz .LBB0_701
	s_waitcnt lgkmcnt(0)
	v_add_f32_e32 v0, v0, v1
	ds_write_b32 v224, v0 offset:704
.LBB0_701:
	s_or_b64 exec, exec, s[16:17]
	s_waitcnt lgkmcnt(0)
	s_barrier
	s_and_saveexec_b64 s[16:17], s[4:5]
	s_cbranch_execz .LBB0_703
	ds_read2st64_b32 v[2:3], v225 offset1:4
	s_lshl_b32 s72, s18, 3
	s_waitcnt lgkmcnt(0)
	v_lshl_add_u64 v[0:1], v[194:195], 0, s[72:73]
	v_add_f32_e32 v4, v2, v3
	ds_read2st64_b32 v[2:3], v225 offset0:8 offset1:12
	s_waitcnt lgkmcnt(0)
	v_add_f32_e32 v2, v2, v3
	v_add_f32_e32 v2, v4, v2
	v_mul_f32_e32 v2, 0x4b800000, v2
	v_rndne_f32_e32 v2, v2
	v_mul_f32_e32 v3, 0x2f800000, v2
	v_floor_f32_e32 v3, v3
	v_fmac_f32_e32 v2, 0xcf800000, v3
	v_cvt_u32_f32_e32 v2, v2
	v_cvt_u32_f32_e32 v3, v3
	global_atomic_add_x2 v[0:1], v[2:3], off

; __device__ __forceinline__ unsigned cvt_pk_bf16(float lo, float hi) { unsigned r; asm("v_cvt_pk_bf16_f32 %0, %1, %2" : "=v"(r) : "v"(lo), "v"(hi)); return r; }
; __device__ __forceinline__ float u64f(u64 q) { return (float)(unsigned)(q >> 32) * 4294967296.f + (float)(unsigned)q; }
;     __device__ __forceinline__ void operator()(const f32x4 (&acc)[2][2][4][2], const GU& u, int wr, int wc, int fr, int fq) const {
;     ...
;         if ((u.mode & 3) == 1) { u64 q_[2][4];
; #pragma unroll
;             for (int ai = 0; ai < 2; ++ai)
; #pragma unroll
;                 for (int m = 0; m < 4; ++m) q_[ai][m] = u.sc[r0 + ai * 128 + m * 16];
; #pragma unroll
;             for (int ai = 0; ai < 2; ++ai)
; #pragma unroll
;                 for (int m = 0; m < 4; ++m) rsv[ai][m] = rsqrtf(u64f(q_[ai][m]) * SSQ_INV + EPS);
;         } else {
; #pragma unroll
;             for (int ai = 0; ai < 2; ++ai)
; #pragma unroll
;                 for (int m = 0; m < 4; ++m) rsv[ai][m] = 1.f;
;         }
; #pragma unroll
;         for (int ai = 0; ai < 2; ++ai)
; #pragma unroll
;             for (int m = 0; m < 4; ++m) {
;                 const int row = r0 + ai * 128 + m * 16;
;                 const float rs = rsv[ai][m];
;                 bf16_t* rowp = u.out + (size_t)row * u.ldc + c0;
; #pragma unroll
;                 for (int bj = 0; bj < 2; ++bj) {
;                     if (bj == 1 && (u.mode & 8)) continue;
;                     f32x4 v0 = acc[ai][bj][m][0] * cs[bj][0] * rs, v1 = acc[ai][bj][m][1] * cs[bj][1] * rs;
;                     u32x4 w; w.x = cvt_pk_bf16(v0[0], v0[1]); w.y = cvt_pk_bf16(v0[2], v0[3]); w.z = cvt_pk_bf16(v1[0], v1[1]); w.w = cvt_pk_bf16(v1[2], v1[3]);
.Lp6_epi:
	s_mul_i32 s18, s72, s26
	s_add_i32 s18, s18, s24
	s_and_b32 s20, s18, 31
	s_lshl_b32 s19, s20, 18
	s_add_u32 s21, s14, s19
	s_addc_u32 s22, s15, 0
	s_lshl_b32 s18, s18, 2
	s_and_b32 s18, s18, 0xffffff80
	s_ashr_i32 s19, s18, 31
	s_lshl_b64 s[18:19], s[18:19], 1
	s_add_u32 s18, s21, s18
	s_addc_u32 s19, s22, s19
	s_lshl_b32 s72, s20, 11
	v_lshl_add_u64 v[96:97], v[88:89], 0, s[72:73]
	global_load_dwordx2 v[104:105], v[96:97], off
	global_load_dwordx2 v[112:113], v[96:97], off offset:128
	global_load_dwordx2 v[114:115], v[96:97], off offset:256
	global_load_dwordx2 v[106:107], v[96:97], off offset:384
	global_load_dwordx2 v[108:109], v[96:97], off offset:1024
	global_load_dwordx2 v[110:111], v[96:97], off offset:1152
	global_load_dwordx2 v[102:103], v[96:97], off offset:1280
	s_nop 0
	global_load_dwordx2 v[96:97], v[96:97], off offset:1408
	s_min_u32 s20, s91, 32
	s_sub_i32 s21, 32, s20
	s_waitcnt vmcnt(0) lgkmcnt(0)
	v_mov_b32_e32 v200, v105
	v_lshlrev_b64 v[116:117], s20, v[200:201]
	v_min_u32_e32 v95, 1, v116
	v_or_b32_e32 v95, v117, v95
	v_cvt_f32_u32_e32 v95, v95
	v_cvt_f32_u32_e32 v98, v104
	v_mov_b32_e32 v200, v113
	v_lshlrev_b64 v[104:105], s20, v[200:201]
	v_ldexp_f32 v95, v95, s21
	v_fmac_f32_e32 v98, 0x4f800000, v95
	v_fmamk_f32 v95, v98, 0x2e000000, v240
	v_cmp_gt_f32_e32 vcc, s85, v95
	v_mul_f32_e32 v98, 0x4b800000, v95
	v_cvt_f32_u32_e32 v100, v112
	v_cndmask_b32_e32 v95, v95, v98, vcc
	v_rsq_f32_e32 v95, v95
	v_mov_b32_e32 v200, v115
	v_cvt_f32_u32_e32 v102, v102
	v_cvt_f32_u32_e32 v96, v96
	v_mul_f32_e32 v98, 0x45800000, v95
	v_cndmask_b32_e32 v98, v95, v98, vcc
	v_min_u32_e32 v95, 1, v104
	v_or_b32_e32 v95, v105, v95
	v_cvt_f32_u32_e32 v95, v95
	v_lshlrev_b64 v[104:105], s20, v[200:201]
	v_mov_b32_e32 v200, v107
	v_lshlrev_b64 v[112:113], s20, v[200:201]
	v_ldexp_f32 v95, v95, s21
	v_fmac_f32_e32 v100, 0x4f800000, v95
	v_fmamk_f32 v95, v100, 0x2e000000, v240
	v_cmp_gt_f32_e32 vcc, s85, v95
	v_mul_f32_e32 v100, 0x4b800000, v95
	v_mov_b32_e32 v200, v109
	v_cndmask_b32_e32 v95, v95, v100, vcc
	v_rsq_f32_e32 v95, v95
	v_pk_mul_f32 v[62:63], v[62:63], v[98:99] op_sel_hi:[1,0]
	v_pk_mul_f32 v[60:61], v[60:61], v[98:99] op_sel_hi:[1,0]
	v_mul_f32_e32 v100, 0x45800000, v95
	v_cndmask_b32_e32 v100, v95, v100, vcc
	v_min_u32_e32 v95, 1, v104
	v_or_b32_e32 v95, v105, v95
	v_cvt_f32_u32_e32 v95, v95
	v_cvt_f32_u32_e32 v104, v114
	v_cvt_f32_u32_e32 v105, v106
	v_pk_mul_f32 v[114:115], v[58:59], v[98:99] op_sel_hi:[1,0]
	v_ldexp_f32 v95, v95, s21
	v_fmac_f32_e32 v104, 0x4f800000, v95
	v_fmamk_f32 v95, v104, 0x2e000000, v240
	v_cmp_gt_f32_e32 vcc, s85, v95
	v_mul_f32_e32 v104, 0x4b800000, v95
	v_pk_mul_f32 v[58:59], v[56:57], v[98:99] op_sel_hi:[1,0]
	v_cndmask_b32_e32 v95, v95, v104, vcc
	v_rsq_f32_e32 v95, v95
	v_cvt_pk_bf16_f32 v56, v60, v61
	v_cvt_pk_bf16_f32 v57, v62, v63
	v_cvt_pk_bf16_f32 v58, v58, v59
	v_cvt_pk_bf16_f32 v59, v114, v115
	v_pk_mul_f32 v[54:55], v[54:55], v[100:101] op_sel_hi:[1,0]
	v_mul_f32_e32 v104, 0x45800000, v95
	v_cndmask_b32_e32 v104, v95, v104, vcc
	v_min_u32_e32 v95, 1, v112
	v_or_b32_e32 v95, v113, v95
	v_cvt_f32_u32_e32 v95, v95
	v_lshlrev_b64 v[112:113], s20, v[200:201]
	v_mov_b32_e32 v200, v111
	v_pk_mul_f32 v[52:53], v[52:53], v[100:101] op_sel_hi:[1,0]
	v_ldexp_f32 v95, v95, s21
	v_fmac_f32_e32 v105, 0x4f800000, v95
	v_fmamk_f32 v95, v105, 0x2e000000, v240
	v_cmp_gt_f32_e32 vcc, s85, v95
	v_mul_f32_e32 v105, 0x4b800000, v95
	s_nop 0
	v_cndmask_b32_e32 v95, v95, v105, vcc
	v_rsq_f32_e32 v95, v95
	s_nop 0
	v_mul_f32_e32 v105, 0x45800000, v95
	v_cndmask_b32_e32 v106, v95, v105, vcc
	v_min_u32_e32 v95, 1, v112
	v_or_b32_e32 v95, v113, v95
	v_cvt_f32_u32_e32 v95, v95
	v_cvt_f32_u32_e32 v105, v108
	v_lshlrev_b64 v[112:113], s20, v[200:201]
	v_mov_b32_e32 v200, v103
	v_ldexp_f32 v95, v95, s21
	v_fmac_f32_e32 v105, 0x4f800000, v95
	v_fmamk_f32 v95, v105, 0x2e000000, v240
	v_cmp_gt_f32_e32 vcc, s85, v95
	v_mul_f32_e32 v105, 0x4b800000, v95
	v_pk_mul_f32 v[38:39], v[38:39], v[106:107] op_sel_hi:[1,0]
	v_cndmask_b32_e32 v95, v95, v105, vcc
	v_rsq_f32_e32 v95, v95
	v_pk_mul_f32 v[36:37], v[36:37], v[106:107] op_sel_hi:[1,0]
	v_mul_f32_e32 v105, 0x45800000, v95
	v_cndmask_b32_e32 v108, v95, v105, vcc
	v_min_u32_e32 v95, 1, v112
	v_or_b32_e32 v95, v113, v95
	v_cvt_f32_u32_e32 v95, v95
	v_cvt_f32_u32_e32 v105, v110
	v_lshlrev_b64 v[112:113], s20, v[200:201]
	v_mov_b32_e32 v200, v97
	v_ldexp_f32 v95, v95, s21
	v_fmac_f32_e32 v105, 0x4f800000, v95
	v_fmamk_f32 v95, v105, 0x2e000000, v240
	v_cmp_gt_f32_e32 vcc, s85, v95
	v_mul_f32_e32 v105, 0x4b800000, v95
	v_pk_mul_f32 v[30:31], v[30:31], v[108:109] op_sel_hi:[1,0]
	v_cndmask_b32_e32 v95, v95, v105, vcc
	v_rsq_f32_e32 v95, v95
	v_pk_mul_f32 v[28:29], v[28:29], v[108:109] op_sel_hi:[1,0]
	v_mul_f32_e32 v105, 0x45800000, v95
	v_cndmask_b32_e32 v110, v95, v105, vcc
	v_min_u32_e32 v95, 1, v112
	v_or_b32_e32 v95, v113, v95
	v_cvt_f32_u32_e32 v95, v95
	v_lshlrev_b64 v[112:113], s20, v[200:201]
	v_pk_mul_f32 v[46:47], v[46:47], v[104:105] op_sel_hi:[1,0]
	v_pk_mul_f32 v[44:45], v[44:45], v[104:105] op_sel_hi:[1,0]
	v_ldexp_f32 v95, v95, s21
	v_fmac_f32_e32 v102, 0x4f800000, v95
	v_fmamk_f32 v95, v102, 0x2e000000, v240
	v_cmp_gt_f32_e32 vcc, s85, v95
	v_mul_f32_e32 v102, 0x4b800000, v95
	v_pk_mul_f32 v[22:23], v[22:23], v[110:111] op_sel_hi:[1,0]
	v_cndmask_b32_e32 v95, v95, v102, vcc
	v_rsq_f32_e32 v95, v95
	v_pk_mul_f32 v[20:21], v[20:21], v[110:111] op_sel_hi:[1,0]
	v_mul_f32_e32 v102, 0x45800000, v95
	v_cndmask_b32_e32 v102, v95, v102, vcc
	v_min_u32_e32 v95, 1, v112
	v_or_b32_e32 v95, v113, v95
	v_cvt_f32_u32_e32 v95, v95
	v_lshl_add_u64 v[112:113], s[18:19], 0, v[72:73]
; __device__ __forceinline__ unsigned cvt_pk_bf16(float lo, float hi) { unsigned r; asm("v_cvt_pk_bf16_f32 %0, %1, %2" : "=v"(r) : "v"(lo), "v"(hi)); return r; }
;     __device__ __forceinline__ void operator()(const f32x4 (&acc)[2][2][4][2], const GU& u, int wr, int wc, int fr, int fq) const {
;     ...
;                 const int row = r0 + ai * 128 + m * 16;
;                 const float rs = rsv[ai][m];
;                 bf16_t* rowp = u.out + (size_t)row * u.ldc + c0;
; #pragma unroll
;                 for (int bj = 0; bj < 2; ++bj) {
;                     if (bj == 1 && (u.mode & 8)) continue;
;                     f32x4 v0 = acc[ai][bj][m][0] * cs[bj][0] * rs, v1 = acc[ai][bj][m][1] * cs[bj][1] * rs;
;                     u32x4 w; w.x = cvt_pk_bf16(v0[0], v0[1]); w.y = cvt_pk_bf16(v0[2], v0[3]); w.z = cvt_pk_bf16(v1[0], v1[1]); w.w = cvt_pk_bf16(v1[2], v1[3]);
;                     *(u32x4*)(rowp + bj * 128) = w;
;                     if (bj == 0 && u.gates != nullptr && wc == 0) { float* gp = u.gates + (size_t)row * 32 + 8 * fq; *(f32x4*)gp = v0; *(f32x4*)(gp + 4) = v1; }
; __global__ void __launch_bounds__(512, 2) hybrid_fwd(Params p) {
;     ...
;             if (c < 128) {
;                 asm volatile("s_waitcnt vmcnt(0)" ::: "memory"); __syncthreads();
;                 const int hd = c >> 5, qb = c & 31, tq0 = 256 * qb + 32 * wave, t_row = tq0 + (lane & 31);
;                 attn_unit<2>(lds, tid, QX + (size_t)t_row * 512 + hd * 128, KX + (size_t)l * 256 * 512 + hd * 128, 512, VXT + (size_t)l * 512 * 256 + (size_t)hd * 128 * 256, 256,
	v_pk_mul_f32 v[14:15], v[14:15], v[102:103] op_sel_hi:[1,0]
	v_pk_mul_f32 v[12:13], v[12:13], v[102:103] op_sel_hi:[1,0]
	v_ldexp_f32 v95, v95, s21
	v_fmac_f32_e32 v96, 0x4f800000, v95
	v_fmamk_f32 v95, v96, 0x2e000000, v240
	v_cmp_gt_f32_e32 vcc, s85, v95
	v_mul_f32_e32 v96, 0x4b800000, v95
	s_nop 0
	v_cndmask_b32_e32 v95, v95, v96, vcc
	v_rsq_f32_e32 v95, v95
	s_nop 0
	v_mul_f32_e32 v96, 0x45800000, v95
	v_cndmask_b32_e32 v96, v95, v96, vcc
	v_mov_b32_e32 v95, v201
	v_lshl_add_u64 v[112:113], v[112:113], 0, v[94:95]
	global_store_dwordx4 v[112:113], v[56:59], off
	s_andn2_b64 vcc, exec, s[16:17]
	v_pk_mul_f32 v[6:7], v[6:7], v[96:97] op_sel_hi:[1,0]
	v_lshl_add_u64 v[56:57], s[18:19], 0, v[74:75]
	v_lshl_add_u64 v[56:57], v[56:57], 0, v[94:95]
	v_pk_mul_f32 v[58:59], v[50:51], v[100:101] op_sel_hi:[1,0]
	v_pk_mul_f32 v[50:51], v[48:49], v[100:101] op_sel_hi:[1,0]
	v_cvt_pk_bf16_f32 v48, v52, v53
	v_cvt_pk_bf16_f32 v49, v54, v55
	v_pk_mul_f32 v[4:5], v[4:5], v[96:97] op_sel_hi:[1,0]
	v_cvt_pk_bf16_f32 v50, v50, v51
	v_cvt_pk_bf16_f32 v51, v58, v59
	global_store_dwordx4 v[56:57], v[48:51], off
	s_nop 1
	v_lshl_add_u64 v[48:49], s[18:19], 0, v[76:77]
	v_lshl_add_u64 v[48:49], v[48:49], 0, v[94:95]
	v_pk_mul_f32 v[50:51], v[42:43], v[104:105] op_sel_hi:[1,0]
	v_pk_mul_f32 v[42:43], v[40:41], v[104:105] op_sel_hi:[1,0]
	v_cvt_pk_bf16_f32 v40, v44, v45
	v_cvt_pk_bf16_f32 v41, v46, v47
	s_nop 0
	v_cvt_pk_bf16_f32 v42, v42, v43
	v_cvt_pk_bf16_f32 v43, v50, v51
	global_store_dwordx4 v[48:49], v[40:43], off
	s_nop 1
	v_lshl_add_u64 v[40:41], s[18:19], 0, v[78:79]
	v_lshl_add_u64 v[40:41], v[40:41], 0, v[94:95]
	v_pk_mul_f32 v[42:43], v[34:35], v[106:107] op_sel_hi:[1,0]
	v_pk_mul_f32 v[34:35], v[32:33], v[106:107] op_sel_hi:[1,0]
	v_cvt_pk_bf16_f32 v32, v36, v37
	v_cvt_pk_bf16_f32 v33, v38, v39
	s_nop 0
	v_cvt_pk_bf16_f32 v34, v34, v35
	v_cvt_pk_bf16_f32 v35, v42, v43
	global_store_dwordx4 v[40:41], v[32:35], off
	s_nop 1
	v_lshl_add_u64 v[32:33], s[18:19], 0, v[80:81]
	v_lshl_add_u64 v[32:33], v[32:33], 0, v[94:95]
	v_pk_mul_f32 v[34:35], v[26:27], v[108:109] op_sel_hi:[1,0]
	v_pk_mul_f32 v[26:27], v[24:25], v[108:109] op_sel_hi:[1,0]
	v_cvt_pk_bf16_f32 v24, v28, v29
	v_cvt_pk_bf16_f32 v25, v30, v31
	s_nop 0
	v_cvt_pk_bf16_f32 v26, v26, v27
	v_cvt_pk_bf16_f32 v27, v34, v35
	global_store_dwordx4 v[32:33], v[24:27], off
	s_nop 1
	v_lshl_add_u64 v[24:25], s[18:19], 0, v[82:83]
	v_lshl_add_u64 v[24:25], v[24:25], 0, v[94:95]
	v_pk_mul_f32 v[26:27], v[18:19], v[110:111] op_sel_hi:[1,0]
	v_pk_mul_f32 v[18:19], v[16:17], v[110:111] op_sel_hi:[1,0]
	v_cvt_pk_bf16_f32 v16, v20, v21
	v_cvt_pk_bf16_f32 v17, v22, v23
	s_nop 0
	v_cvt_pk_bf16_f32 v18, v18, v19
	v_cvt_pk_bf16_f32 v19, v26, v27
	global_store_dwordx4 v[24:25], v[16:19], off
	s_nop 1
	v_lshl_add_u64 v[16:17], s[18:19], 0, v[84:85]
	v_lshl_add_u64 v[16:17], v[16:17], 0, v[94:95]
	v_pk_mul_f32 v[18:19], v[10:11], v[102:103] op_sel_hi:[1,0]
	v_pk_mul_f32 v[10:11], v[8:9], v[102:103] op_sel_hi:[1,0]
	v_cvt_pk_bf16_f32 v8, v12, v13
	v_cvt_pk_bf16_f32 v9, v14, v15
	s_nop 0
	v_cvt_pk_bf16_f32 v10, v10, v11
	v_cvt_pk_bf16_f32 v11, v18, v19
	global_store_dwordx4 v[16:17], v[8:11], off
	s_nop 1
	v_lshl_add_u64 v[8:9], s[18:19], 0, v[86:87]
	v_lshl_add_u64 v[8:9], v[8:9], 0, v[94:95]
	v_pk_mul_f32 v[10:11], v[2:3], v[96:97] op_sel_hi:[1,0]
	v_pk_mul_f32 v[2:3], v[0:1], v[96:97] op_sel_hi:[1,0]
	s_mov_b64 s[18:19], -1
	v_cvt_pk_bf16_f32 v0, v4, v5
	v_cvt_pk_bf16_f32 v1, v6, v7
	v_cvt_pk_bf16_f32 v2, v2, v3
	v_cvt_pk_bf16_f32 v3, v10, v11
	global_store_dwordx4 v[8:9], v[0:3], off
	s_cbranch_vccnz .LBB0_764
	s_andn2_b64 vcc, exec, s[10:11]
	s_cbranch_vccnz .LBB0_763
	s_barrier
	s_branch .LBB0_763
.LBB0_772:
	v_readlane_b32 s6, v255, 42
	v_readlane_b32 s7, v255, 43
	s_lshl_b64 s[10:11], s[6:7], 18
	s_and_b32 s12, s24, 31
	s_ashr_i32 s7, s25, 1
	s_lshl_b32 s6, s12, 8
	s_andn2_b32 s7, s7, 31
	s_add_i32 s7, s7, s6
	s_lshl_b32 s6, s4, 7
	v_and_or_b32 v0, v147, 31, s7
	s_ashr_i32 s7, s6, 31
	v_ashrrev_i32_e32 v1, 31, v0
	s_lshl_b64 s[8:9], s[6:7], 1
	v_lshlrev_b64 v[144:145], 9, v[0:1]
	v_lshlrev_b64 v[0:1], 10, v[0:1]
	s_add_u32 s13, s2, s10
	v_mov_b32_e32 v3, v147
	s_waitcnt vmcnt(0)
	s_barrier
	s_waitcnt vmcnt(0)
	s_waitcnt lgkmcnt(0)
	s_barrier
; #define LAS __attribute__((address_space(3)))
; __device__ __forceinline__ float bflo(unsigned w) { return __uint_as_float(w << 16); }
; __device__ __forceinline__ float bfhi(unsigned w) { return __uint_as_float(w & 0xffff0000u); }
; __device__ __forceinline__ float xsum(float v) { const auto r = __builtin_amdgcn_permlane32_swap(__float_as_uint(v), __float_as_uint(v), false, false); return __uint_as_float(r[0]) + __uint_as_float(r[1]); }
;     ...
;     bf16x8 qf[8];
; #pragma unroll
;     for (int ks = 0; ks < 8; ++ks) qf[ks] = *(const bf16x8*)(Qrow + 16 * ks + 8 * hh);
;     f32x16 o[4];
; #pragma unroll
;     for (int db = 0; db < 4; ++db)
; #pragma unroll
;         for (int i = 0; i < 16; ++i) o[db][i] = 0.f;
;     float m = m_init, l = (hh == 0) ? l_init : 0.f;
;     const int pr = (r & ~12) | ((r & 4) << 1) | ((r & 8) >> 1);
;     const unsigned koff = pr * AT_KROW + 16 * hh, voff = AT_KBUF + r * AT_VROW + 16 * hh;
;     const int kkey0 = tid >> 4, kc16 = tid & 15, vd0 = tid >> 3, vc8 = tid & 7;
;     u32x4 kreg[2], vreg[2]; float creg = 0.f;
;     ...
;     float qn = 0.f; bool wdone = false;
;     LAS unsigned* flg = (LAS unsigned*)(lds + 2 * AT_BUF);
;     if (MODE == 0) {
; #pragma unroll
;         for (int ks = 0; ks < 8; ++ks) { const u32x4 qq = __builtin_bit_cast(u32x4, qf[ks]);
;             qn += bflo(qq.x) * bflo(qq.x) + bfhi(qq.x) * bfhi(qq.x) + bflo(qq.y) * bflo(qq.y) + bfhi(qq.y) * bfhi(qq.y) + bflo(qq.z) * bflo(qq.z) + bfhi(qq.z) * bfhi(qq.z) + bflo(qq.w) * bflo(qq.w) + bfhi(qq.w) * bfhi(qq.w); }
;         qn = xsum(qn); qn = sqrtf(qn) * kn * SC * 1.0001f + 1e-3f;
;     }
;     AT_LOAD(kt1 - 1); AT_WRITE(0); __syncthreads();
; #pragma unroll 1
;     ...
;         const int cur = (kt1 - 1 - kt) & 1, k0 = kt * 64;
;         if (kt > kt0) AT_LOAD(kt - 1);
	v_lshl_add_u64 v[0:1], s[14:15], 0, v[0:1]
	s_addc_u32 s14, s3, s11
	v_lshl_add_u64 v[0:1], v[0:1], 0, s[8:9]
	v_bfe_u32 v2, v3, 5, 1
	s_add_u32 s10, s13, s8
	v_lshlrev_b32_e32 v200, 4, v2
	s_addc_u32 s11, s14, s9
	s_lshl_b64 s[4:5], s[4:5], 16
	v_lshlrev_b32_e32 v146, 3, v2
	v_lshl_add_u64 v[0:1], v[0:1], 0, v[200:201]
	v_lshlrev_b32_e32 v2, 1, v3
	v_lshrrev_b32_e32 v4, 1, v3
	s_add_u32 s4, s13, s4
	global_load_dwordx4 v[96:99], v[0:1], off
	global_load_dwordx4 v[100:103], v[0:1], off offset:32
	global_load_dwordx4 v[104:107], v[0:1], off offset:64
	global_load_dwordx4 v[108:111], v[0:1], off offset:96
	global_load_dwordx4 v[112:115], v[0:1], off offset:128
	global_load_dwordx4 v[116:119], v[0:1], off offset:160
	global_load_dwordx4 v[120:123], v[0:1], off offset:192
	global_load_dwordx4 v[124:127], v[0:1], off offset:224
	v_and_b32_e32 v0, 31, v3
	v_and_b32_e32 v1, 19, v3
	v_and_b32_e32 v2, 8, v2
	v_and_b32_e32 v4, 4, v4
	s_addc_u32 s5, s14, s5
	v_or3_b32 v1, v1, v2, v4
	s_movk_i32 s14, 0x110
	v_mul_u32_u24_e32 v159, 0x90, v0
	v_ashrrev_i32_e32 v0, 4, v3
	v_mad_u32_u24 v158, v1, s14, v200
	v_ashrrev_i32_e32 v1, 31, v0
	v_lshlrev_b64 v[4:5], 10, v[0:1]
	v_lshlrev_b32_e32 v1, 4, v3
	v_lshl_add_u64 v[6:7], s[10:11], 0, v[4:5]
	v_and_b32_e32 v148, 0xf0, v1
	v_mov_b32_e32 v149, v201
	v_lshl_add_u64 v[6:7], v[6:7], 0, v[148:149]
	s_mov_b32 s10, 0x27330000
	v_add_co_u32_e32 v8, vcc, s10, v6
	s_mov_b32 s10, 0x27338000
	s_nop 0
	v_addc_co_u32_e32 v9, vcc, 0, v7, vcc
	v_ashrrev_i32_e32 v2, 3, v3
	v_add_co_u32_e32 v6, vcc, s10, v6
	v_ashrrev_i32_e32 v3, 31, v2
	s_nop 0
	v_addc_co_u32_e32 v7, vcc, 0, v7, vcc
	global_load_dwordx4 v[128:131], v[8:9], off
	global_load_dwordx4 v[132:135], v[6:7], off
	v_lshlrev_b64 v[6:7], 9, v[2:3]
	v_lshl_add_u64 v[6:7], s[4:5], 0, v[6:7]
	v_and_b32_e32 v150, 0x70, v1
	v_mov_b32_e32 v151, v201
	v_lshl_add_u64 v[6:7], v[6:7], 0, v[150:151]
	s_mov_b64 s[4:5], 0x27400000
	v_lshl_add_u64 v[152:153], v[6:7], 0, s[4:5]
	s_mov_b64 s[4:5], 0x27408000
	v_lshl_add_u64 v[154:155], v[6:7], 0, s[4:5]
	global_load_dwordx4 v[136:139], v[152:153], off offset:384
	global_load_dwordx4 v[140:143], v[154:155], off offset:384
	v_mul_lo_u32 v151, v0, s14
	v_add3_u32 v0, 0, v151, v148
	v_mul_lo_u32 v160, v2, s83
	v_readlane_b32 s4, v255, 32
	v_readlane_b32 s5, v255, 33
	s_mov_b32 s13, 3
	v_add_u32_e32 v161, 0x2400, v160
	v_mov_b32_e32 v163, 0xf149f2ca
	s_movk_i32 s72, 0x80
	v_mov_b32_e32 v48, 0
	v_mov_b32_e32 v32, 0
	v_mov_b32_e32 v16, 0
	v_readlane_b32 s22, v255, 1
	s_waitcnt vmcnt(0) lgkmcnt(0)
	ds_write_b128 v0, v[128:131]
	ds_write_b128 v0, v[132:135] offset:8704
	v_add3_u32 v0, 0, v160, v150
	ds_write_b128 v0, v[136:139] offset:17408
	ds_write_b128 v0, v[140:143] offset:26624
	v_lshl_add_u64 v[0:1], s[4:5], 0, v[4:5]
	s_add_u32 s4, s2, s8
	v_lshl_add_u64 v[0:1], v[0:1], 0, v[148:149]
	s_addc_u32 s5, s3, s9
	v_mov_b32_e32 v149, 0
	v_lshl_add_u64 v[156:157], s[4:5], 0, v[0:1]
	v_mov_b32_e32 v49, v149
	v_mov_b32_e32 v50, v149
	v_mov_b32_e32 v51, v149
	v_mov_b32_e32 v52, v149
	v_mov_b32_e32 v53, v149
	v_mov_b32_e32 v54, v149
	v_mov_b32_e32 v55, v149
	v_mov_b32_e32 v56, v149
	v_mov_b32_e32 v57, v149
	v_mov_b32_e32 v58, v149
	v_mov_b32_e32 v59, v149
	v_mov_b32_e32 v60, v149
	v_mov_b32_e32 v61, v149
	v_mov_b32_e32 v62, v149
	v_mov_b32_e32 v63, v149
	v_mov_b32_e32 v33, v149
	v_mov_b32_e32 v34, v149
	v_mov_b32_e32 v35, v149
	v_mov_b32_e32 v36, v149
	v_mov_b32_e32 v37, v149
	v_mov_b32_e32 v38, v149
	v_mov_b32_e32 v39, v149
	v_mov_b32_e32 v40, v149
	v_mov_b32_e32 v41, v149
	v_mov_b32_e32 v42, v149
	v_mov_b32_e32 v43, v149
	v_mov_b32_e32 v44, v149
	v_mov_b32_e32 v45, v149
	v_mov_b32_e32 v46, v149
	v_mov_b32_e32 v47, v149
	v_mov_b32_e32 v17, v149
	v_mov_b32_e32 v18, v149
	v_mov_b32_e32 v19, v149
	v_mov_b32_e32 v20, v149
	v_mov_b32_e32 v21, v149
	v_mov_b32_e32 v22, v149
	v_mov_b32_e32 v23, v149
	v_mov_b32_e32 v24, v149
	v_mov_b32_e32 v25, v149
	v_mov_b32_e32 v26, v149
	v_mov_b32_e32 v27, v149
	v_mov_b32_e32 v28, v149
	v_mov_b32_e32 v29, v149
	v_mov_b32_e32 v30, v149
	v_mov_b32_e32 v31, v149
	v_mov_b32_e32 v0, 0
	v_mov_b32_e32 v1, v149
	v_mov_b32_e32 v2, v149
	v_mov_b32_e32 v3, v149
	v_mov_b32_e32 v4, v149
	v_mov_b32_e32 v5, v149
	v_mov_b32_e32 v6, v149
	v_mov_b32_e32 v7, v149
	v_mov_b32_e32 v8, v149
	v_mov_b32_e32 v9, v149
	v_mov_b32_e32 v10, v149
	v_mov_b32_e32 v11, v149
	v_mov_b32_e32 v12, v149
	v_mov_b32_e32 v13, v149
	v_mov_b32_e32 v14, v149
	v_mov_b32_e32 v15, v149
	s_waitcnt lgkmcnt(0)
	s_barrier
	s_cmpk_lg_i32 s72, 0xffc0
	s_cselect_b64 s[4:5], -1, 0
	s_cmpk_eq_i32 s72, 0xffc0
	s_cbranch_scc1 .LBB0_774
.LBB0_773:
	v_add_co_u32_e32 v64, vcc, 0x27320000, v156
	s_lshl_b64 s[8:9], s[72:73], 1
	s_nop 0
	v_addc_co_u32_e32 v65, vcc, 0, v157, vcc
	v_add_co_u32_e32 v66, vcc, 0x27328000, v156
	s_nop 1
	v_addc_co_u32_e32 v67, vcc, 0, v157, vcc
	s_waitcnt vmcnt(0)
	global_load_dwordx4 v[128:131], v[64:65], off
	global_load_dwordx4 v[132:135], v[66:67], off
	v_lshl_add_u64 v[64:65], v[152:153], 0, s[8:9]
	v_lshl_add_u64 v[66:67], v[154:155], 0, s[8:9]
	global_load_dwordx4 v[136:139], v[64:65], off
	global_load_dwordx4 v[140:143], v[66:67], off
; #define LAS __attribute__((address_space(3)))
;     ...
;             const LAS unsigned char* base = lds + cur * AT_BUF;
;             f32x16 s0, s1;
; #pragma unroll
;             for (int i = 0; i < 16; ++i) { s0[i] = 0.f; s1[i] = 0.f; }
;             {
;                 bf16x8 ka[8];
; #pragma unroll
;                 for (int ks = 0; ks < 8; ++ks) ka[ks] = *(const LAS bf16x8*)(base + koff + ks * 32);
;                 __builtin_amdgcn_sched_barrier(0);
; #pragma unroll
;                 for (int ks = 0; ks < 8; ++ks) s0 = MFMA32(ka[ks], qf[ks], s0);
;                 __builtin_amdgcn_sched_barrier(0);
; #pragma unroll
;                 for (int ks = 0; ks < 8; ++ks) ka[ks] = *(const LAS bf16x8*)(base + 32 * AT_KROW + koff + ks * 32);
;                 __builtin_amdgcn_sched_barrier(0);
; #pragma unroll
;                 for (int ks = 0; ks < 8; ++ks) s1 = MFMA32(ka[ks], qf[ks], s1);
;             }
;             float x[32];
;             const LAS float* cbl = (const LAS float*)(base + AT_KBUF + AT_VBUF);
;             const bool need_mask = (MODE == 0) ? (k0 + 63 > tq0) : true;
;             float mx = NEG;
;             if (MODE == 1) {
; #pragma unroll
;                 for (int i = 0; i < 32; ++i) { const int ii = i & 15, kl = 32 * (i >> 4) + (ii & 7) + 8 * hh + 16 * (ii >> 3); x[i] = t5[(t_row - (k0 + kl)) & 127]; }
;                 __builtin_amdgcn_sched_barrier(0);
;             }
; #pragma unroll
;             for (int i = 0; i < 32; ++i) {
;                 const int blk = i >> 4, ii = i & 15, kl = 32 * blk + (ii & 7) + 8 * hh + 16 * (ii >> 3);
;                 float v = (blk ? s1[ii] : s0[ii]) * SC;
;                 if (MODE == 0) v += cbl[kl];
;                 if (MODE == 1) { const int rel = t_row - (k0 + kl); v = ((unsigned)rel < 128u) ? v + x[i] : NEG; }
;                 x[i] = v;
;             }
;             if (MODE == 0 && need_mask) {
; #pragma unroll
;                 for (int i = 0; i < 32; ++i) { const int ii = i & 15, kl = 32 * (i >> 4) + (ii & 7) + 8 * hh + 16 * (ii >> 3); if (k0 + kl > t_row) x[i] = NEG; }
;             }
; #pragma unroll
;             for (int i = 0; i < 32; ++i) mx = fmaxf(mx, x[i]);
;             mx = xmax(mx);
;             const float mn = fmaxf(m, mx), alpha = ex2(m - mn); m = mn;
;             float rs = 0.f;
; #pragma unroll
;             for (int i = 0; i < 32; ++i) { x[i] = ex2(x[i] - mn); rs += x[i]; }
.LBB0_774:
	s_and_b32 s8, s13, 1
	s_xor_b32 s9, s8, 1
	s_mul_i32 s9, s9, 0x8d00
	s_add_i32 s9, s9, 0
	v_add_u32_e32 v162, s9, v158
	ds_read_b128 v[64:67], v162
	ds_read_b128 v[68:71], v162 offset:32
	ds_read_b128 v[72:75], v162 offset:64
	ds_read_b128 v[76:79], v162 offset:96
	ds_read_b128 v[164:167], v162 offset:128
	ds_read_b128 v[168:171], v162 offset:160
	ds_read_b128 v[172:175], v162 offset:192
	ds_read_b128 v[176:179], v162 offset:224
	s_waitcnt lgkmcnt(7)
	v_mfma_f32_32x32x16_bf16 v[80:95], v[64:67], v[96:99], 0
	s_waitcnt lgkmcnt(6)
	v_mfma_f32_32x32x16_bf16 v[80:95], v[68:71], v[100:103], v[80:95]
	s_waitcnt lgkmcnt(5)
	v_mfma_f32_32x32x16_bf16 v[80:95], v[72:75], v[104:107], v[80:95]
	s_waitcnt lgkmcnt(4)
	v_mfma_f32_32x32x16_bf16 v[80:95], v[76:79], v[108:111], v[80:95]
	s_waitcnt lgkmcnt(3)
	v_mfma_f32_32x32x16_bf16 v[80:95], v[164:167], v[112:115], v[80:95]
	s_waitcnt lgkmcnt(2)
	v_mfma_f32_32x32x16_bf16 v[80:95], v[168:171], v[116:119], v[80:95]
	s_waitcnt lgkmcnt(1)
	v_mfma_f32_32x32x16_bf16 v[80:95], v[172:175], v[120:123], v[80:95]
	s_waitcnt lgkmcnt(0)
	v_mfma_f32_32x32x16_bf16 v[80:95], v[176:179], v[124:127], v[80:95]
	ds_read_b128 v[64:67], v162 offset:8704
	ds_read_b128 v[164:167], v162 offset:8736
	ds_read_b128 v[168:171], v162 offset:8768
	ds_read_b128 v[172:175], v162 offset:8800
	ds_read_b128 v[176:179], v162 offset:8832
	ds_read_b128 v[180:183], v162 offset:8864
	ds_read_b128 v[184:187], v162 offset:8896
	ds_read_b128 v[188:191], v162 offset:8928
	s_waitcnt lgkmcnt(7)
	v_mfma_f32_32x32x16_bf16 v[64:79], v[64:67], v[96:99], 0
	s_nop 1
	v_mul_f32_e32 v162, 0x3e0293ee, v80
	v_add3_u32 v202, s9, v159, v200
	s_waitcnt lgkmcnt(6)
	v_mfma_f32_32x32x16_bf16 v[64:79], v[164:167], v[100:103], v[64:79]
	v_mul_f32_e32 v164, 0x3e0293ee, v81
	v_mul_f32_e32 v165, 0x3e0293ee, v82
	v_mul_f32_e32 v166, 0x3e0293ee, v83
	v_max3_f32 v162, v162, s36, v164
	v_mul_f32_e32 v167, 0x3e0293ee, v84
	v_max3_f32 v162, v162, v165, v166
	s_waitcnt lgkmcnt(5)
	v_mfma_f32_32x32x16_bf16 v[64:79], v[168:171], v[104:107], v[64:79]
	v_mul_f32_e32 v168, 0x3e0293ee, v85
	v_mul_f32_e32 v169, 0x3e0293ee, v86
	v_mul_f32_e32 v170, 0x3e0293ee, v87
	v_max3_f32 v162, v162, v167, v168
	v_mul_f32_e32 v171, 0x3e0293ee, v88
	v_max3_f32 v162, v162, v169, v170
	s_waitcnt lgkmcnt(4)
	v_mfma_f32_32x32x16_bf16 v[64:79], v[172:175], v[108:111], v[64:79]
	v_mul_f32_e32 v172, 0x3e0293ee, v89
	v_mul_f32_e32 v173, 0x3e0293ee, v90
	v_mul_f32_e32 v174, 0x3e0293ee, v91
	v_max3_f32 v162, v162, v171, v172
	v_mul_f32_e32 v175, 0x3e0293ee, v92
	v_max3_f32 v162, v162, v173, v174
	s_waitcnt lgkmcnt(3)
	v_mfma_f32_32x32x16_bf16 v[64:79], v[176:179], v[112:115], v[64:79]
	v_mul_f32_e32 v176, 0x3e0293ee, v93
	v_mul_f32_e32 v177, 0x3e0293ee, v94
	v_mul_f32_e32 v178, 0x3e0293ee, v95
	v_max3_f32 v162, v162, v175, v176
	v_max3_f32 v162, v162, v177, v178
	s_waitcnt lgkmcnt(2)
	v_mfma_f32_32x32x16_bf16 v[64:79], v[180:183], v[116:119], v[64:79]
	s_waitcnt lgkmcnt(1)
	v_mfma_f32_32x32x16_bf16 v[64:79], v[184:187], v[120:123], v[64:79]
	s_waitcnt lgkmcnt(0)
	v_mfma_f32_32x32x16_bf16 v[64:79], v[188:191], v[124:127], v[64:79]
	s_nop 11
	v_mul_f32_e32 v164, 0x3e0293ee, v64
	v_mul_f32_e32 v165, 0x3e0293ee, v65
	v_mul_f32_e32 v166, 0x3e0293ee, v66
	v_mul_f32_e32 v167, 0x3e0293ee, v67
	v_max3_f32 v162, v162, v164, v165
	v_mul_f32_e32 v168, 0x3e0293ee, v68
	v_mul_f32_e32 v169, 0x3e0293ee, v69
	v_max3_f32 v162, v162, v166, v167
	v_mul_f32_e32 v170, 0x3e0293ee, v70
	v_mul_f32_e32 v171, 0x3e0293ee, v71
	v_max3_f32 v162, v162, v168, v169
	v_mul_f32_e32 v172, 0x3e0293ee, v72
	v_mul_f32_e32 v173, 0x3e0293ee, v73
	v_max3_f32 v162, v162, v170, v171
	v_mul_f32_e32 v174, 0x3e0293ee, v74
	v_mul_f32_e32 v175, 0x3e0293ee, v75
	v_max3_f32 v162, v162, v172, v173
	v_mul_f32_e32 v176, 0x3e0293ee, v76
	v_mul_f32_e32 v177, 0x3e0293ee, v77
	v_max3_f32 v162, v162, v174, v175
	v_mul_f32_e32 v178, 0x3e0293ee, v78
	v_mul_f32_e32 v179, 0x3e0293ee, v79
	v_max3_f32 v162, v162, v176, v177
	v_max3_f32 v162, v162, v178, v179
	v_mov_b32_e32 v164, v162
	s_nop 1
	v_permlane32_swap_b32_e32 v162, v164
	v_max3_f32 v162, v163, v162, v164
	v_fma_f32 v64, v64, s94, -v162
	v_sub_f32_e32 v164, v163, v162
	v_exp_f32_e32 v163, v64
	v_fma_f32 v64, v65, s94, -v162
	v_exp_f32_e32 v65, v64
	v_fma_f32 v64, v66, s94, -v162
	v_exp_f32_e32 v66, v64
	v_fma_f32 v64, v67, s94, -v162
	v_exp_f32_e32 v67, v64
	v_fma_f32 v64, v68, s94, -v162
	v_exp_f32_e32 v68, v64
	v_fma_f32 v64, v69, s94, -v162
	v_exp_f32_e32 v69, v64
	v_fma_f32 v64, v70, s94, -v162
	v_exp_f32_e32 v70, v64
	v_fma_f32 v64, v71, s94, -v162
	v_exp_f32_e32 v71, v64
	v_fma_f32 v64, v72, s94, -v162
	ds_read_b128 v[176:179], v202 offset:17408
	ds_read_b128 v[180:183], v202 offset:17440
	ds_read_b128 v[184:187], v202 offset:22016
	ds_read_b128 v[188:191], v202 offset:22048
	ds_read_b128 v[192:195], v202 offset:26624
	ds_read_b128 v[196:199], v202 offset:26656
	ds_read_b128 v[204:207], v202 offset:31232
	ds_read_b128 v[208:211], v202 offset:31264
	v_exp_f32_e32 v72, v64
	v_fma_f32 v64, v73, s94, -v162
	v_exp_f32_e32 v73, v64
	v_fma_f32 v64, v74, s94, -v162
	v_exp_f32_e32 v74, v64
	v_fma_f32 v64, v75, s94, -v162
	v_exp_f32_e32 v75, v64
	v_fma_f32 v64, v76, s94, -v162
	v_exp_f32_e32 v76, v64
	v_fma_f32 v64, v77, s94, -v162
	v_fma_f32 v80, v80, s94, -v162
	v_fma_f32 v81, v81, s94, -v162
	v_fma_f32 v82, v82, s94, -v162
; #define LAS __attribute__((address_space(3)))
; __device__ __forceinline__ float ex2(float x) { return __builtin_amdgcn_exp2f(x); }
; #define MFMA32(a, b, c) __builtin_amdgcn_mfma_f32_32x32x16_bf16((a), (b), (c), 0, 0, 0)
;     ...
;             const float mn = fmaxf(m, mx), alpha = ex2(m - mn); m = mn;
;             float rs = 0.f;
; #pragma unroll
;             for (int i = 0; i < 32; ++i) { x[i] = ex2(x[i] - mn); rs += x[i]; }
;             l = l * alpha + rs;
; #pragma unroll
;             for (int db = 0; db < 4; ++db)
; #pragma unroll
;                 for (int i = 0; i < 16; ++i) o[db][i] *= alpha;
;             bf16x8 pf[4];
; #pragma unroll
;             for (int j = 0; j < 4; ++j) pf[j] = pack8(x[8 * j], x[8 * j + 1], x[8 * j + 2], x[8 * j + 3], x[8 * j + 4], x[8 * j + 5], x[8 * j + 6], x[8 * j + 7]);
; #pragma unroll
;             for (int jh = 0; jh < 2; ++jh) {
;                 bf16x8 va[2][4];
; #pragma unroll
;                 for (int j = 0; j < 2; ++j)
; #pragma unroll
;                     for (int db = 0; db < 4; ++db) va[j][db] = *(const LAS bf16x8*)(base + voff + db * 32 * AT_VROW + (2 * jh + j) * 32);
;                 __builtin_amdgcn_sched_barrier(0);
; #pragma unroll
;                 for (int j = 0; j < 2; ++j)
; #pragma unroll
;                     for (int db = 0; db < 4; ++db) o[db] = MFMA32(va[j][db], pf[2 * jh + j], o[db]);
;                 __builtin_amdgcn_sched_barrier(0);
;             }
;             if (MODE == 0 && kt > kt0 && k0 <= tq0) {
;                 const float ub = qn + cbl[0];
;                 wdone = __all(ub < m - 30.f);
;             }
;         }
;         if (kt > kt0) AT_WRITE(cur ^ 1);
	v_fma_f32 v83, v83, s94, -v162
	v_fma_f32 v84, v84, s94, -v162
	v_fma_f32 v85, v85, s94, -v162
	v_fma_f32 v86, v86, s94, -v162
	v_fma_f32 v87, v87, s94, -v162
	v_fma_f32 v88, v88, s94, -v162
	v_fma_f32 v89, v89, s94, -v162
	v_fma_f32 v90, v90, s94, -v162
	v_fma_f32 v91, v91, s94, -v162
	v_fma_f32 v92, v92, s94, -v162
	v_fma_f32 v93, v93, s94, -v162
	v_fma_f32 v94, v94, s94, -v162
	v_fma_f32 v95, v95, s94, -v162
	v_exp_f32_e32 v77, v64
	v_fma_f32 v78, v78, s94, -v162
	v_exp_f32_e32 v64, v164
	v_fma_f32 v79, v79, s94, -v162
	v_exp_f32_e32 v80, v80
	v_exp_f32_e32 v81, v81
	v_exp_f32_e32 v82, v82
	v_exp_f32_e32 v83, v83
	v_exp_f32_e32 v84, v84
	v_exp_f32_e32 v85, v85
	v_exp_f32_e32 v86, v86
	v_exp_f32_e32 v87, v87
	v_exp_f32_e32 v88, v88
	v_exp_f32_e32 v89, v89
	v_exp_f32_e32 v90, v90
	v_exp_f32_e32 v91, v91
	v_exp_f32_e32 v92, v92
	v_exp_f32_e32 v93, v93
	v_exp_f32_e32 v94, v94
	v_exp_f32_e32 v95, v95
	v_exp_f32_e32 v78, v78
	v_exp_f32_e32 v79, v79
	v_pk_mul_f32 v[62:63], v[62:63], v[64:65] op_sel_hi:[1,0]
	v_pk_mul_f32 v[60:61], v[60:61], v[64:65] op_sel_hi:[1,0]
	v_pk_mul_f32 v[58:59], v[58:59], v[64:65] op_sel_hi:[1,0]
	v_pk_mul_f32 v[56:57], v[56:57], v[64:65] op_sel_hi:[1,0]
	v_pk_mul_f32 v[54:55], v[54:55], v[64:65] op_sel_hi:[1,0]
	v_pk_mul_f32 v[52:53], v[52:53], v[64:65] op_sel_hi:[1,0]
	v_pk_mul_f32 v[50:51], v[50:51], v[64:65] op_sel_hi:[1,0]
	v_pk_mul_f32 v[48:49], v[48:49], v[64:65] op_sel_hi:[1,0]
	v_pk_mul_f32 v[46:47], v[46:47], v[64:65] op_sel_hi:[1,0]
	v_pk_mul_f32 v[44:45], v[44:45], v[64:65] op_sel_hi:[1,0]
	v_pk_mul_f32 v[42:43], v[42:43], v[64:65] op_sel_hi:[1,0]
	v_pk_mul_f32 v[40:41], v[40:41], v[64:65] op_sel_hi:[1,0]
	v_pk_mul_f32 v[38:39], v[38:39], v[64:65] op_sel_hi:[1,0]
	v_pk_mul_f32 v[36:37], v[36:37], v[64:65] op_sel_hi:[1,0]
	v_pk_mul_f32 v[34:35], v[34:35], v[64:65] op_sel_hi:[1,0]
	v_pk_mul_f32 v[32:33], v[32:33], v[64:65] op_sel_hi:[1,0]
	v_pk_mul_f32 v[30:31], v[30:31], v[64:65] op_sel_hi:[1,0]
	v_pk_mul_f32 v[28:29], v[28:29], v[64:65] op_sel_hi:[1,0]
	v_pk_mul_f32 v[26:27], v[26:27], v[64:65] op_sel_hi:[1,0]
	v_pk_mul_f32 v[24:25], v[24:25], v[64:65] op_sel_hi:[1,0]
	v_pk_mul_f32 v[22:23], v[22:23], v[64:65] op_sel_hi:[1,0]
	v_pk_mul_f32 v[20:21], v[20:21], v[64:65] op_sel_hi:[1,0]
	v_pk_mul_f32 v[18:19], v[18:19], v[64:65] op_sel_hi:[1,0]
	v_pk_mul_f32 v[16:17], v[16:17], v[64:65] op_sel_hi:[1,0]
	v_pk_mul_f32 v[14:15], v[14:15], v[64:65] op_sel_hi:[1,0]
	v_pk_mul_f32 v[12:13], v[12:13], v[64:65] op_sel_hi:[1,0]
	v_pk_mul_f32 v[10:11], v[10:11], v[64:65] op_sel_hi:[1,0]
	v_pk_mul_f32 v[8:9], v[8:9], v[64:65] op_sel_hi:[1,0]
	v_pk_mul_f32 v[6:7], v[6:7], v[64:65] op_sel_hi:[1,0]
	v_pk_mul_f32 v[4:5], v[4:5], v[64:65] op_sel_hi:[1,0]
	v_pk_mul_f32 v[2:3], v[2:3], v[64:65] op_sel_hi:[1,0]
	v_pk_mul_f32 v[0:1], v[0:1], v[64:65] op_sel_hi:[1,0]
	v_cvt_pk_bf16_f32 v164, v80, v81
	v_cvt_pk_bf16_f32 v165, v82, v83
	v_cvt_pk_bf16_f32 v166, v84, v85
	v_cvt_pk_bf16_f32 v167, v86, v87
	v_cvt_pk_bf16_f32 v168, v88, v89
	v_cvt_pk_bf16_f32 v169, v90, v91
	v_cvt_pk_bf16_f32 v170, v92, v93
	v_cvt_pk_bf16_f32 v171, v94, v95
	v_cvt_pk_bf16_f32 v172, v163, v65
	v_cvt_pk_bf16_f32 v173, v66, v67
	v_cvt_pk_bf16_f32 v174, v68, v69
	v_cvt_pk_bf16_f32 v175, v70, v71
	v_cvt_pk_bf16_f32 v212, v72, v73
	v_cvt_pk_bf16_f32 v213, v74, v75
	v_cvt_pk_bf16_f32 v214, v76, v77
	v_cvt_pk_bf16_f32 v215, v78, v79
	s_waitcnt lgkmcnt(0)
	v_mfma_f32_32x32x16_bf16 v[48:63], v[176:179], v[164:167], v[48:63]
	v_mfma_f32_32x32x16_bf16 v[32:47], v[184:187], v[164:167], v[32:47]
	v_mfma_f32_32x32x16_bf16 v[16:31], v[192:195], v[164:167], v[16:31]
	v_mfma_f32_32x32x16_bf16 v[0:15], v[204:207], v[164:167], v[0:15]
	v_mfma_f32_32x32x16_bf16 v[48:63], v[180:183], v[168:171], v[48:63]
	v_mfma_f32_32x32x16_bf16 v[32:47], v[188:191], v[168:171], v[32:47]
	v_mfma_f32_32x32x16_bf16 v[16:31], v[196:199], v[168:171], v[16:31]
	v_mfma_f32_32x32x16_bf16 v[0:15], v[208:211], v[168:171], v[0:15]
	ds_read_b128 v[164:167], v202 offset:17472
	ds_read_b128 v[168:171], v202 offset:17504
	ds_read_b128 v[176:179], v202 offset:22080
	ds_read_b128 v[180:183], v202 offset:22112
	ds_read_b128 v[184:187], v202 offset:26688
	ds_read_b128 v[188:191], v202 offset:26720
	ds_read_b128 v[192:195], v202 offset:31296
	ds_read_b128 v[196:199], v202 offset:31328
	s_waitcnt lgkmcnt(7)
	v_mfma_f32_32x32x16_bf16 v[48:63], v[164:167], v[172:175], v[48:63]
	s_waitcnt lgkmcnt(5)
	v_mfma_f32_32x32x16_bf16 v[32:47], v[176:179], v[172:175], v[32:47]
	s_waitcnt lgkmcnt(3)
	v_mfma_f32_32x32x16_bf16 v[16:31], v[184:187], v[172:175], v[16:31]
	s_waitcnt lgkmcnt(1)
	v_mfma_f32_32x32x16_bf16 v[0:15], v[192:195], v[172:175], v[0:15]
	v_mfma_f32_32x32x16_bf16 v[48:63], v[168:171], v[212:215], v[48:63]
	v_mfma_f32_32x32x16_bf16 v[32:47], v[180:183], v[212:215], v[32:47]
	v_mfma_f32_32x32x16_bf16 v[16:31], v[188:191], v[212:215], v[16:31]
	s_waitcnt lgkmcnt(0)
	v_mfma_f32_32x32x16_bf16 v[0:15], v[196:199], v[212:215], v[0:15]
	s_andn2_b64 vcc, exec, s[4:5]
	s_cbranch_vccnz .LBB0_776
	s_mul_i32 s8, s8, 0x8d00
	s_add_i32 s4, s8, 0
	v_add3_u32 v164, s4, v151, v148
	v_add3_u32 v165, s4, v160, v150
	v_add3_u32 v166, s4, v161, v150
	s_waitcnt vmcnt(0)
	ds_write_b128 v164, v[128:131]
	ds_write_b128 v164, v[132:135] offset:8704
	ds_write_b128 v165, v[136:139] offset:17408
	ds_write_b128 v166, v[140:143] offset:17408

; __device__ __forceinline__ unsigned cvt_pk_bf16(float lo, float hi) { unsigned r; asm("v_cvt_pk_bf16_f32 %0, %1, %2" : "=v"(r) : "v"(lo), "v"(hi)); return r; }
; __device__ __forceinline__ float xsum(float v) { const auto r = __builtin_amdgcn_permlane32_swap(__float_as_uint(v), __float_as_uint(v), false, false); return __uint_as_float(r[0]) + __uint_as_float(r[1]); }
; __device__ __forceinline__ void st16_wt(void* p, u32x4 v) { asm volatile("global_store_dwordx4 %0, %1, off sc1\n\ts_nop 1" :: "v"(p), "v"(v) : "memory"); }
;     ...
;     l = xsum(l);
;     const float inv = 1.f / l;
; #pragma unroll
;     for (int db = 0; db < 4; ++db)
; #pragma unroll
;         for (int g = 0; g < 4; g += 2) {
;             unsigned ax = cvt_pk_bf16(o[db][4 * g] * inv, o[db][4 * g + 1] * inv), ay = cvt_pk_bf16(o[db][4 * g + 2] * inv, o[db][4 * g + 3] * inv);
;             unsigned bx = cvt_pk_bf16(o[db][4 * g + 4] * inv, o[db][4 * g + 5] * inv), by = cvt_pk_bf16(o[db][4 * g + 6] * inv, o[db][4 * g + 7] * inv);
;             const auto rx = __builtin_amdgcn_permlane32_swap(ax, bx, false, false), ry = __builtin_amdgcn_permlane32_swap(ay, by, false, false);
;             u32x4 w; w.x = rx[0]; w.y = ry[0]; w.z = rx[1]; w.w = ry[1];
;             if (MODE == 2) st16_wt(Orow + 32 * db + 8 * g + 8 * hh, w); else *(u32x4*)(Orow + 32 * db + 8 * g + 8 * hh) = w;
;         }
; __global__ void __launch_bounds__(512, 2) hybrid_fwd(Params p) {
;     ...
;                 asm volatile("s_waitcnt vmcnt(0)" ::: "memory"); __syncthreads();
;                 if (tid == 0) (void)__hip_atomic_fetch_add((unsigned*)ws + 3840 + 32 * l + qb, 1u, __ATOMIC_RELAXED, __HIP_MEMORY_SCOPE_AGENT);
.LBB0_778:
	v_mov_b32_e32 v64, v65
	s_nop 1
	v_permlane32_swap_b32_e32 v65, v64
	v_add_f32_e32 v64, v65, v64
	v_div_scale_f32 v65, s[4:5], v64, v64, 1.0
	v_rcp_f32_e32 v68, v65
	v_lshl_add_u64 v[66:67], v[144:145], 1, s[2:3]
	v_lshl_add_u64 v[66:67], s[6:7], 1, v[66:67]
	v_lshlrev_b32_e32 v200, 1, v146
	v_fma_f32 v69, -v65, v68, 1.0
	v_fmac_f32_e32 v68, v69, v68
	v_div_scale_f32 v69, vcc, 1.0, v64, 1.0
	v_mul_f32_e32 v70, v69, v68
	v_fma_f32 v71, -v65, v70, v69
	v_fmac_f32_e32 v70, v71, v68
	v_fma_f32 v65, -v65, v70, v69
	v_div_fmas_f32 v65, v65, v68, v70
	v_div_fixup_f32 v68, v65, v64, 1.0
	v_mul_f32_e32 v48, v48, v68
	v_mul_f32_e32 v49, v49, v68
	v_cvt_pk_bf16_f32 v48, v48, v49
	v_mul_f32_e32 v49, v50, v68
	v_mul_f32_e32 v50, v51, v68
	v_cvt_pk_bf16_f32 v49, v49, v50
	v_mul_f32_e32 v50, v52, v68
	v_mul_f32_e32 v51, v53, v68
	v_cvt_pk_bf16_f32 v50, v50, v51
	v_mul_f32_e32 v51, v54, v68
	v_mul_f32_e32 v52, v55, v68
	v_cvt_pk_bf16_f32 v51, v51, v52
	v_lshl_add_u64 v[64:65], v[66:67], 0, v[200:201]
	s_mov_b64 s[4:5], 0x26b00000
	v_permlane32_swap_b32_e32 v48, v50
	v_permlane32_swap_b32_e32 v49, v51
	v_lshl_add_u64 v[66:67], v[64:65], 0, s[4:5]
	global_store_dwordx4 v[66:67], v[48:51], off sc1
	s_nop 1
	v_mul_f32_e32 v48, v56, v68
	v_mul_f32_e32 v49, v57, v68
	v_mul_f32_e32 v32, v32, v68
	v_mul_f32_e32 v33, v33, v68
	v_cvt_pk_bf16_f32 v48, v48, v49
	v_mul_f32_e32 v49, v58, v68
	v_mul_f32_e32 v50, v59, v68
	v_cvt_pk_bf16_f32 v32, v32, v33
	v_mul_f32_e32 v33, v34, v68
	v_mul_f32_e32 v34, v35, v68
	v_cvt_pk_bf16_f32 v49, v49, v50
	v_mul_f32_e32 v50, v60, v68
	v_mul_f32_e32 v51, v61, v68
	v_cvt_pk_bf16_f32 v33, v33, v34
	v_mul_f32_e32 v34, v36, v68
	v_mul_f32_e32 v35, v37, v68
	v_cvt_pk_bf16_f32 v50, v50, v51
	v_mul_f32_e32 v51, v62, v68
	v_cvt_pk_bf16_f32 v34, v34, v35
	v_mul_f32_e32 v35, v38, v68
	v_mul_f32_e32 v52, v63, v68
	v_cvt_pk_bf16_f32 v51, v51, v52
	s_mov_b64 s[4:5], 0x26b00020
	v_mul_f32_e32 v36, v39, v68
	v_cvt_pk_bf16_f32 v35, v35, v36
	v_permlane32_swap_b32_e32 v48, v50
	v_permlane32_swap_b32_e32 v49, v51
	v_lshl_add_u64 v[52:53], v[64:65], 0, s[4:5]
	global_store_dwordx4 v[52:53], v[48:51], off sc1
	s_nop 1
	s_mov_b64 s[4:5], 0x26b00040
	v_permlane32_swap_b32_e32 v32, v34
	v_permlane32_swap_b32_e32 v33, v35
	v_lshl_add_u64 v[48:49], v[64:65], 0, s[4:5]
	global_store_dwordx4 v[48:49], v[32:35], off sc1
	s_nop 1
	v_mul_f32_e32 v32, v40, v68
	v_mul_f32_e32 v33, v41, v68
	v_mul_f32_e32 v16, v16, v68
	v_mul_f32_e32 v17, v17, v68
	v_cvt_pk_bf16_f32 v32, v32, v33
	v_mul_f32_e32 v33, v42, v68
	v_mul_f32_e32 v34, v43, v68
	v_cvt_pk_bf16_f32 v16, v16, v17
	v_mul_f32_e32 v17, v18, v68
	v_mul_f32_e32 v18, v19, v68
	v_cvt_pk_bf16_f32 v33, v33, v34
	v_mul_f32_e32 v34, v44, v68
	v_mul_f32_e32 v35, v45, v68
	v_cvt_pk_bf16_f32 v17, v17, v18
	v_mul_f32_e32 v18, v20, v68
	v_mul_f32_e32 v19, v21, v68
	v_cvt_pk_bf16_f32 v34, v34, v35
	v_mul_f32_e32 v35, v46, v68
	v_cvt_pk_bf16_f32 v18, v18, v19
	v_mul_f32_e32 v19, v22, v68
	v_mul_f32_e32 v36, v47, v68
	v_cvt_pk_bf16_f32 v35, v35, v36
	s_mov_b64 s[4:5], 0x26b00060
	v_mul_f32_e32 v20, v23, v68
	v_cvt_pk_bf16_f32 v19, v19, v20
	v_permlane32_swap_b32_e32 v32, v34
	v_permlane32_swap_b32_e32 v33, v35
	v_lshl_add_u64 v[36:37], v[64:65], 0, s[4:5]
	global_store_dwordx4 v[36:37], v[32:35], off sc1
	s_nop 1
	s_mov_b64 s[4:5], 0x26b00080
	v_permlane32_swap_b32_e32 v16, v18
	v_permlane32_swap_b32_e32 v17, v19
	v_lshl_add_u64 v[32:33], v[64:65], 0, s[4:5]
	global_store_dwordx4 v[32:33], v[16:19], off sc1
	s_nop 1
	v_mul_f32_e32 v16, v24, v68
	v_mul_f32_e32 v17, v25, v68
	v_mul_f32_e32 v0, v0, v68
	v_mul_f32_e32 v1, v1, v68
	v_cvt_pk_bf16_f32 v16, v16, v17
	v_mul_f32_e32 v17, v26, v68
	v_mul_f32_e32 v18, v27, v68
	v_cvt_pk_bf16_f32 v0, v0, v1
	v_mul_f32_e32 v1, v2, v68
	v_mul_f32_e32 v2, v3, v68
	v_cvt_pk_bf16_f32 v17, v17, v18
	v_mul_f32_e32 v18, v28, v68
	v_mul_f32_e32 v19, v29, v68
	v_cvt_pk_bf16_f32 v1, v1, v2
	v_mul_f32_e32 v2, v4, v68
	v_mul_f32_e32 v3, v5, v68
	v_cvt_pk_bf16_f32 v18, v18, v19
	v_mul_f32_e32 v19, v30, v68
	v_cvt_pk_bf16_f32 v2, v2, v3
	v_mul_f32_e32 v3, v6, v68
	v_mul_f32_e32 v20, v31, v68
	v_cvt_pk_bf16_f32 v19, v19, v20
	s_mov_b64 s[4:5], 0x26b000a0
	v_mul_f32_e32 v4, v7, v68
	v_cvt_pk_bf16_f32 v3, v3, v4
	v_permlane32_swap_b32_e32 v16, v18
	v_permlane32_swap_b32_e32 v17, v19
	v_lshl_add_u64 v[20:21], v[64:65], 0, s[4:5]
	global_store_dwordx4 v[20:21], v[16:19], off sc1
	s_nop 1
	s_mov_b64 s[4:5], 0x26b000c0
	v_permlane32_swap_b32_e32 v0, v2
	v_permlane32_swap_b32_e32 v1, v3
	v_lshl_add_u64 v[16:17], v[64:65], 0, s[4:5]
	global_store_dwordx4 v[16:17], v[0:3], off sc1
	s_nop 1
	v_mul_f32_e32 v0, v8, v68
	v_mul_f32_e32 v1, v9, v68
	v_cvt_pk_bf16_f32 v0, v0, v1
	v_mul_f32_e32 v1, v10, v68
	v_mul_f32_e32 v2, v11, v68
	v_cvt_pk_bf16_f32 v1, v1, v2
	v_mul_f32_e32 v2, v12, v68
	v_mul_f32_e32 v3, v13, v68
	v_cvt_pk_bf16_f32 v2, v2, v3
	v_mul_f32_e32 v3, v14, v68
	v_mul_f32_e32 v4, v15, v68
	v_cvt_pk_bf16_f32 v3, v3, v4
	s_mov_b64 s[4:5], 0x26b000e0
	v_permlane32_swap_b32_e32 v0, v2
	v_permlane32_swap_b32_e32 v1, v3
	v_lshl_add_u64 v[4:5], v[64:65], 0, s[4:5]
	global_store_dwordx4 v[4:5], v[0:3], off sc1
	s_nop 1
	s_waitcnt vmcnt(0)
	v_cmp_eq_u32_e32 vcc, 0, v147
	s_barrier
	s_and_saveexec_b64 s[4:5], vcc
	s_cbranch_execz .LBB0_780
	s_lshl_b64 s[6:7], s[0:1], 2
	s_add_u32 s2, s2, s6
	s_addc_u32 s3, s3, s7
	s_lshl_b32 s6, s12, 2
	s_add_u32 s2, s2, s6
	s_addc_u32 s3, s3, 0
	v_mov_b32_e32 v0, s2
	v_add_co_u32_e32 v0, vcc, 0x3000, v0
	v_mov_b32_e32 v1, s3
	s_nop 0
	v_addc_co_u32_e32 v1, vcc, 0, v1, vcc
	global_atomic_add v[0:1], v238, off offset:3072

; __global__ void __launch_bounds__(512, 2) hybrid_fwd(Params p) {
;     ...
;             if (tid == 0) { unsigned* cw_ = (unsigned*)ws + 3840 + 32 * l + (c & 31); unsigned sp_ = 0;
;                 while (__hip_atomic_load(cw_, __ATOMIC_RELAXED, __HIP_MEMORY_SCOPE_AGENT) < 4u) { __builtin_amdgcn_s_sleep(2); if (++sp_ > (1u << 22)) break; }
;                 __builtin_amdgcn_fence(__ATOMIC_ACQUIRE, "agent"); asm volatile("s_waitcnt vmcnt(0)" ::: "memory"); }
.LBB0_788:
	v_mov_b64_e32 v[0:1], s[0:1]
	global_load_dword v0, v[0:1], off sc1
	s_or_b64 s[8:9], s[8:9], exec
	s_waitcnt vmcnt(0) lgkmcnt(0)
	v_cmp_gt_u32_e32 vcc, 4, v0
	s_and_saveexec_b64 s[10:11], vcc
	s_cbranch_execz .LBB0_787
	v_mov_b64_e32 v[0:1], s[0:1]
	s_sleep 2
	global_load_dword v0, v[0:1], off sc1
	s_mov_b64 s[14:15], -1
	s_waitcnt vmcnt(0) lgkmcnt(0)
	v_cmp_gt_u32_e32 vcc, 4, v0
	s_and_saveexec_b64 s[12:13], vcc
	s_cbranch_execz .LBB0_786
	v_mov_b64_e32 v[0:1], s[0:1]
	s_sleep 2
	global_load_dword v0, v[0:1], off sc1
	s_mov_b64 s[16:17], -1
	s_waitcnt vmcnt(0) lgkmcnt(0)
	v_cmp_gt_u32_e32 vcc, 4, v0
	s_and_saveexec_b64 s[14:15], vcc
	s_cbranch_execz .LBB0_785
	v_mov_b64_e32 v[0:1], s[0:1]
	s_sleep 2
	global_load_dword v0, v[0:1], off sc1
	s_mov_b64 s[18:19], -1
	s_waitcnt vmcnt(0) lgkmcnt(0)
	v_cmp_gt_u32_e32 vcc, 4, v0
	s_and_saveexec_b64 s[16:17], vcc
	s_cbranch_execz .LBB0_784
	v_mov_b64_e32 v[0:1], s[0:1]
	s_sleep 2
	global_load_dword v0, v[0:1], off sc1
	s_waitcnt vmcnt(0) lgkmcnt(0)
	v_cmp_gt_u32_e32 vcc, 4, v0
	s_and_saveexec_b64 s[20:21], vcc
	s_cbranch_execz .LBB0_783
	s_add_i32 s24, s24, -5
	s_cmp_eq_u32 s24, 0
	s_cselect_b64 s[18:19], -1, 0
	s_orn2_b64 s[18:19], s[18:19], exec
	s_sleep 2
	s_branch .LBB0_783

; __device__ __forceinline__ unsigned cvt_pk_bf16(float lo, float hi) { unsigned r; asm("v_cvt_pk_bf16_f32 %0, %1, %2" : "=v"(r) : "v"(lo), "v"(hi)); return r; }
; __device__ __forceinline__ float bflo(unsigned w) { return __uint_as_float(w << 16); }
; __device__ __forceinline__ float bfhi(unsigned w) { return __uint_as_float(w & 0xffff0000u); }
; __device__ __forceinline__ float shx(float v, int off, int lane) { return __int_as_float(__builtin_amdgcn_ds_bpermute((lane ^ off) << 2, __float_as_int(v))); }
;     __device__ __forceinline__ void operator()(const f32x4 (&acc)[2][2][4][2], const RU& u, int wr, int wc, int fr, int fq) const {
;         const int col0 = u.pn * 256 + wc * 32 + 8 * fq, ln_ = fq * 16 + fr;
;         u32x4 bb[2][4][2];
; #pragma unroll
;         for (int ai = 0; ai < 2; ++ai)
; #pragma unroll
;             for (int m = 0; m < 4; ++m) { const bf16_t* rp = hb + (size_t)(u.pm * 256 + ai * 128 + wr * 64 + m * 16 + fr) * D_ + col0; bb[ai][m][0] = *(const u32x4*)rp; bb[ai][m][1] = *(const u32x4*)(rp + 128); }
; #pragma unroll
;         for (int ai = 0; ai < 2; ++ai)
; #pragma unroll
;             for (int m = 0; m < 4; ++m) {
;                 const int row = u.pm * 256 + ai * 128 + wr * 64 + m * 16 + fr; float sq = 0.f;
;                 bf16_t* rp = hb + (size_t)row * D_ + col0;
; #pragma unroll
;                 for (int bj = 0; bj < 2; ++bj) {
;                     const u32x4 b = bb[ai][m][bj];
;                     const f32x4 v0 = acc[ai][bj][m][0] + (f32x4){bflo(b.x), bfhi(b.x), bflo(b.y), bfhi(b.y)};
;                     const f32x4 v1 = acc[ai][bj][m][1] + (f32x4){bflo(b.z), bfhi(b.z), bflo(b.w), bfhi(b.w)};
;                     u32x4 w; w.x = cvt_pk_bf16(v0[0], v0[1]); w.y = cvt_pk_bf16(v0[2], v0[3]); w.z = cvt_pk_bf16(v1[0], v1[1]); w.w = cvt_pk_bf16(v1[2], v1[3]);
;                     *(u32x4*)(rp + bj * 128) = w;
;                     sq += ((v0[0] * v0[0] + v0[1] * v0[1]) + (v0[2] * v0[2] + v0[3] * v0[3])) + ((v1[0] * v1[0] + v1[1] * v1[1]) + (v1[2] * v1[2] + v1[3] * v1[3]));
;                 }
;                 sq += shx(sq, 16, ln_); sq += shx(sq, 32, ln_);
;                 if (fq == 0) red[wc * 256 + ai * 128 + wr * 64 + m * 16 + fr] = sq;
.LBB0_809:
	s_mul_i32 s16, s44, s22
	s_add_i32 s16, s16, s23
	s_lshl_b32 s17, s16, 3
	s_and_b32 s17, s17, 0xffffff00
	s_lshl_b32 s16, s16, 8
	v_or_b32_e32 v204, s17, v221
	s_and_b32 s18, s16, 0x1f00
	v_add_u32_e32 v112, s18, v202
	v_ashrrev_i32_e32 v205, 31, v204
	v_lshlrev_b64 v[232:233], 1, v[204:205]
	v_ashrrev_i32_e32 v113, 31, v112
	v_lshl_add_u64 v[114:115], s[6:7], 0, v[232:233]
	v_lshlrev_b64 v[236:237], 12, v[112:113]
	v_lshl_add_u64 v[116:117], v[114:115], 0, v[236:237]
	global_load_dwordx4 v[228:231], v[116:117], off
	global_load_dwordx4 v[184:187], v[116:117], off offset:256
	v_or_b32_e32 v116, 16, v112
	v_ashrrev_i32_e32 v117, 31, v116
	v_lshlrev_b64 v[218:219], 12, v[116:117]
	v_lshl_add_u64 v[116:117], v[114:115], 0, v[218:219]
	global_load_dwordx4 v[180:183], v[116:117], off
	global_load_dwordx4 v[176:179], v[116:117], off offset:256
	v_or_b32_e32 v116, 32, v112
	v_or_b32_e32 v112, 48, v112
	v_ashrrev_i32_e32 v117, 31, v116
	v_ashrrev_i32_e32 v113, 31, v112
	v_lshlrev_b64 v[216:217], 12, v[116:117]
	v_lshlrev_b64 v[214:215], 12, v[112:113]
	s_mov_b64 s[16:17], 0x80000
	v_lshl_add_u64 v[116:117], v[114:115], 0, v[216:217]
	v_lshl_add_u64 v[112:113], v[114:115], 0, v[214:215]
	v_lshl_add_u64 v[212:213], v[236:237], 0, s[16:17]
	s_mov_b64 s[16:17], 0x90000
	global_load_dwordx4 v[172:175], v[116:117], off
	global_load_dwordx4 v[168:171], v[116:117], off offset:256
	global_load_dwordx4 v[164:167], v[112:113], off
	global_load_dwordx4 v[160:163], v[112:113], off offset:256
	v_lshl_add_u64 v[112:113], v[114:115], 0, v[212:213]
	v_lshl_add_u64 v[210:211], v[236:237], 0, s[16:17]
	s_mov_b64 s[16:17], 0xa0000
	global_load_dwordx4 v[156:159], v[112:113], off
	global_load_dwordx4 v[144:147], v[112:113], off offset:256
	v_lshl_add_u64 v[112:113], v[114:115], 0, v[210:211]
	v_lshl_add_u64 v[208:209], v[236:237], 0, s[16:17]
	s_mov_b64 s[16:17], 0xb0000
	global_load_dwordx4 v[140:143], v[112:113], off
	global_load_dwordx4 v[136:139], v[112:113], off offset:256
	v_lshl_add_u64 v[112:113], v[114:115], 0, v[208:209]
	v_lshl_add_u64 v[206:207], v[236:237], 0, s[16:17]
	global_load_dwordx4 v[128:131], v[112:113], off
	global_load_dwordx4 v[116:119], v[112:113], off offset:256
	v_lshl_add_u64 v[112:113], v[114:115], 0, v[206:207]
	global_load_dwordx4 v[120:123], v[112:113], off
	s_nop 0
	global_load_dwordx4 v[112:115], v[112:113], off offset:256
	v_lshl_add_u64 v[236:237], s[6:7], 0, v[236:237]
	v_lshl_add_u64 v[232:233], v[236:237], 0, v[232:233]
	s_waitcnt vmcnt(0) lgkmcnt(0)
	v_lshlrev_b32_e32 v236, 16, v228
	v_and_b32_e32 v237, 0xffff0000, v228
	v_lshlrev_b32_e32 v228, 16, v229
	v_and_b32_e32 v229, 0xffff0000, v229
	v_pk_add_f32 v[154:155], v[154:155], v[228:229]
	v_lshlrev_b32_e32 v228, 16, v230
	v_and_b32_e32 v229, 0xffff0000, v230
	v_pk_add_f32 v[152:153], v[152:153], v[236:237]
	v_lshlrev_b32_e32 v230, 16, v231
	v_and_b32_e32 v231, 0xffff0000, v231
	v_pk_add_f32 v[228:229], v[148:149], v[228:229]
	v_cvt_pk_bf16_f32 v148, v152, v153
	v_cvt_pk_bf16_f32 v149, v154, v155
	v_pk_add_f32 v[230:231], v[150:151], v[230:231]
	v_cvt_pk_bf16_f32 v150, v228, v229
	s_nop 0
	v_cvt_pk_bf16_f32 v151, v230, v231
	global_store_dwordx4 v[232:233], v[148:151], off
	s_nop 1
	v_mul_f32_e32 v148, v153, v153
	v_mul_f32_e32 v149, v155, v155
	v_fmac_f32_e32 v148, v152, v152
	v_fmac_f32_e32 v149, v154, v154
	v_add_f32_e32 v148, v148, v149
	v_mul_f32_e32 v149, v229, v229
	v_mul_f32_e32 v150, v231, v231
	v_fmac_f32_e32 v149, v228, v228
	v_fmac_f32_e32 v150, v230, v230
	v_add_f32_e32 v149, v149, v150
	v_add_f32_e32 v152, v148, v149
	v_lshlrev_b32_e32 v148, 16, v184
	v_and_b32_e32 v149, 0xffff0000, v184
	v_lshlrev_b32_e32 v150, 16, v185
	v_and_b32_e32 v151, 0xffff0000, v185
	v_pk_add_f32 v[132:133], v[132:133], v[148:149]
	v_lshlrev_b32_e32 v148, 16, v186
	v_and_b32_e32 v149, 0xffff0000, v186
	v_pk_add_f32 v[134:135], v[134:135], v[150:151]
	v_lshlrev_b32_e32 v150, 16, v187
	v_and_b32_e32 v151, 0xffff0000, v187
	v_pk_add_f32 v[148:149], v[124:125], v[148:149]
	v_cvt_pk_bf16_f32 v124, v132, v133
	v_cvt_pk_bf16_f32 v125, v134, v135
	v_pk_add_f32 v[150:151], v[126:127], v[150:151]
	v_cvt_pk_bf16_f32 v126, v148, v149
	s_nop 0
	v_cvt_pk_bf16_f32 v127, v150, v151
	global_store_dwordx4 v[232:233], v[124:127], off offset:256
	s_nop 1
	v_mul_f32_e32 v124, v133, v133
	v_mul_f32_e32 v125, v135, v135
	v_fmac_f32_e32 v124, v132, v132
	v_fmac_f32_e32 v125, v134, v134
	v_add_f32_e32 v124, v124, v125
	v_mul_f32_e32 v125, v149, v149
	v_mul_f32_e32 v126, v151, v151
	v_fmac_f32_e32 v125, v148, v148
	v_fmac_f32_e32 v126, v150, v150
	v_add_f32_e32 v125, v125, v126
	v_add_f32_e32 v124, v124, v125
	v_add_f32_e32 v124, v152, v124
	ds_bpermute_b32 v125, v222, v124
	s_waitcnt lgkmcnt(0)
	v_add_f32_e32 v124, v124, v125
	ds_bpermute_b32 v125, v223, v124
	s_and_saveexec_b64 s[16:17], s[0:1]
	s_cbranch_execz .LBB0_811
	s_waitcnt lgkmcnt(0)
	v_add_f32_e32 v124, v124, v125
	ds_write_b32 v224, v124

; __device__ __forceinline__ unsigned cvt_pk_bf16(float lo, float hi) { unsigned r; asm("v_cvt_pk_bf16_f32 %0, %1, %2" : "=v"(r) : "v"(lo), "v"(hi)); return r; }
; __device__ __forceinline__ float bflo(unsigned w) { return __uint_as_float(w << 16); }
; __device__ __forceinline__ float bfhi(unsigned w) { return __uint_as_float(w & 0xffff0000u); }
; __device__ __forceinline__ float shx(float v, int off, int lane) { return __int_as_float(__builtin_amdgcn_ds_bpermute((lane ^ off) << 2, __float_as_int(v))); }
;     __device__ __forceinline__ void operator()(const f32x4 (&acc)[2][2][4][2], const RU& u, int wr, int wc, int fr, int fq) const {
;         const int col0 = u.pn * 256 + wc * 32 + 8 * fq, ln_ = fq * 16 + fr;
;         u32x4 bb[2][4][2];
; #pragma unroll
;         for (int ai = 0; ai < 2; ++ai)
; #pragma unroll
;             for (int m = 0; m < 4; ++m) { const bf16_t* rp = hb + (size_t)(u.pm * 256 + ai * 128 + wr * 64 + m * 16 + fr) * D_ + col0; bb[ai][m][0] = *(const u32x4*)rp; bb[ai][m][1] = *(const u32x4*)(rp + 128); }
; #pragma unroll
;         for (int ai = 0; ai < 2; ++ai)
; #pragma unroll
;             for (int m = 0; m < 4; ++m) {
;                 const int row = u.pm * 256 + ai * 128 + wr * 64 + m * 16 + fr; float sq = 0.f;
;                 bf16_t* rp = hb + (size_t)row * D_ + col0;
; #pragma unroll
;                 for (int bj = 0; bj < 2; ++bj) {
;                     const u32x4 b = bb[ai][m][bj];
;                     const f32x4 v0 = acc[ai][bj][m][0] + (f32x4){bflo(b.x), bfhi(b.x), bflo(b.y), bfhi(b.y)};
;                     const f32x4 v1 = acc[ai][bj][m][1] + (f32x4){bflo(b.z), bfhi(b.z), bflo(b.w), bfhi(b.w)};
;                     u32x4 w; w.x = cvt_pk_bf16(v0[0], v0[1]); w.y = cvt_pk_bf16(v0[2], v0[3]); w.z = cvt_pk_bf16(v1[0], v1[1]); w.w = cvt_pk_bf16(v1[2], v1[3]);
;                     *(u32x4*)(rp + bj * 128) = w;
;                     sq += ((v0[0] * v0[0] + v0[1] * v0[1]) + (v0[2] * v0[2] + v0[3] * v0[3])) + ((v1[0] * v1[0] + v1[1] * v1[1]) + (v1[2] * v1[2] + v1[3] * v1[3]));
;                 }
;                 sq += shx(sq, 16, ln_); sq += shx(sq, 32, ln_);
;                 if (fq == 0) red[wc * 256 + ai * 128 + wr * 64 + m * 16 + fr] = sq;
.LBB0_1036:
	s_mul_i32 s16, s52, s25
	s_add_i32 s16, s16, s24
	s_lshl_b32 s17, s16, 3
	s_and_b32 s17, s17, 0xffffff00
	s_lshl_b32 s16, s16, 8
	v_or_b32_e32 v204, s17, v221
	s_and_b32 s18, s16, 0x1f00
	v_add_u32_e32 v112, s18, v202
	v_ashrrev_i32_e32 v205, 31, v204
	v_lshlrev_b64 v[232:233], 1, v[204:205]
	v_ashrrev_i32_e32 v113, 31, v112
	v_lshl_add_u64 v[114:115], s[6:7], 0, v[232:233]
	v_lshlrev_b64 v[236:237], 12, v[112:113]
	v_lshl_add_u64 v[116:117], v[114:115], 0, v[236:237]
	global_load_dwordx4 v[228:231], v[116:117], off
	global_load_dwordx4 v[184:187], v[116:117], off offset:256
	v_or_b32_e32 v116, 16, v112
	v_ashrrev_i32_e32 v117, 31, v116
	v_lshlrev_b64 v[218:219], 12, v[116:117]
	v_lshl_add_u64 v[116:117], v[114:115], 0, v[218:219]
	global_load_dwordx4 v[180:183], v[116:117], off
	global_load_dwordx4 v[176:179], v[116:117], off offset:256
	v_or_b32_e32 v116, 32, v112
	v_or_b32_e32 v112, 48, v112
	v_ashrrev_i32_e32 v117, 31, v116
	v_ashrrev_i32_e32 v113, 31, v112
	v_lshlrev_b64 v[216:217], 12, v[116:117]
	v_lshlrev_b64 v[214:215], 12, v[112:113]
	s_mov_b64 s[16:17], 0x80000
	v_lshl_add_u64 v[116:117], v[114:115], 0, v[216:217]
	v_lshl_add_u64 v[112:113], v[114:115], 0, v[214:215]
	v_lshl_add_u64 v[212:213], v[236:237], 0, s[16:17]
	s_mov_b64 s[16:17], 0x90000
	global_load_dwordx4 v[172:175], v[116:117], off
	global_load_dwordx4 v[168:171], v[116:117], off offset:256
	global_load_dwordx4 v[164:167], v[112:113], off
	global_load_dwordx4 v[160:163], v[112:113], off offset:256
	v_lshl_add_u64 v[112:113], v[114:115], 0, v[212:213]
	v_lshl_add_u64 v[210:211], v[236:237], 0, s[16:17]
	s_mov_b64 s[16:17], 0xa0000
	global_load_dwordx4 v[156:159], v[112:113], off
	global_load_dwordx4 v[144:147], v[112:113], off offset:256
	v_lshl_add_u64 v[112:113], v[114:115], 0, v[210:211]
	v_lshl_add_u64 v[208:209], v[236:237], 0, s[16:17]
	s_mov_b64 s[16:17], 0xb0000
	global_load_dwordx4 v[140:143], v[112:113], off
	global_load_dwordx4 v[136:139], v[112:113], off offset:256
	v_lshl_add_u64 v[112:113], v[114:115], 0, v[208:209]
	v_lshl_add_u64 v[206:207], v[236:237], 0, s[16:17]
	global_load_dwordx4 v[128:131], v[112:113], off
	global_load_dwordx4 v[116:119], v[112:113], off offset:256
	v_lshl_add_u64 v[112:113], v[114:115], 0, v[206:207]
	global_load_dwordx4 v[120:123], v[112:113], off
	s_nop 0
	global_load_dwordx4 v[112:115], v[112:113], off offset:256
	v_lshl_add_u64 v[236:237], s[6:7], 0, v[236:237]
	v_lshl_add_u64 v[232:233], v[236:237], 0, v[232:233]
	s_waitcnt vmcnt(0) lgkmcnt(0)
	v_lshlrev_b32_e32 v236, 16, v228
	v_and_b32_e32 v237, 0xffff0000, v228
	v_lshlrev_b32_e32 v228, 16, v229
	v_and_b32_e32 v229, 0xffff0000, v229
	v_pk_add_f32 v[154:155], v[154:155], v[228:229]
	v_lshlrev_b32_e32 v228, 16, v230
	v_and_b32_e32 v229, 0xffff0000, v230
	v_pk_add_f32 v[152:153], v[152:153], v[236:237]
	v_lshlrev_b32_e32 v230, 16, v231
	v_and_b32_e32 v231, 0xffff0000, v231
	v_pk_add_f32 v[228:229], v[148:149], v[228:229]
	v_cvt_pk_bf16_f32 v148, v152, v153
	v_cvt_pk_bf16_f32 v149, v154, v155
	v_pk_add_f32 v[230:231], v[150:151], v[230:231]
	v_cvt_pk_bf16_f32 v150, v228, v229
	s_nop 0
	v_cvt_pk_bf16_f32 v151, v230, v231
	global_store_dwordx4 v[232:233], v[148:151], off
	s_nop 1
	v_mul_f32_e32 v148, v153, v153
	v_mul_f32_e32 v149, v155, v155
	v_fmac_f32_e32 v148, v152, v152
	v_fmac_f32_e32 v149, v154, v154
	v_add_f32_e32 v148, v148, v149
	v_mul_f32_e32 v149, v229, v229
	v_mul_f32_e32 v150, v231, v231
	v_fmac_f32_e32 v149, v228, v228
	v_fmac_f32_e32 v150, v230, v230
	v_add_f32_e32 v149, v149, v150
	v_add_f32_e32 v152, v148, v149
	v_lshlrev_b32_e32 v148, 16, v184
	v_and_b32_e32 v149, 0xffff0000, v184
	v_lshlrev_b32_e32 v150, 16, v185
	v_and_b32_e32 v151, 0xffff0000, v185
	v_pk_add_f32 v[132:133], v[132:133], v[148:149]
	v_lshlrev_b32_e32 v148, 16, v186
	v_and_b32_e32 v149, 0xffff0000, v186
	v_pk_add_f32 v[134:135], v[134:135], v[150:151]
	v_lshlrev_b32_e32 v150, 16, v187
	v_and_b32_e32 v151, 0xffff0000, v187
	v_pk_add_f32 v[148:149], v[124:125], v[148:149]
	v_cvt_pk_bf16_f32 v124, v132, v133
	v_cvt_pk_bf16_f32 v125, v134, v135
	v_pk_add_f32 v[150:151], v[126:127], v[150:151]
	v_cvt_pk_bf16_f32 v126, v148, v149
	s_nop 0
	v_cvt_pk_bf16_f32 v127, v150, v151
	global_store_dwordx4 v[232:233], v[124:127], off offset:256
	s_nop 1
	v_mul_f32_e32 v124, v133, v133
	v_mul_f32_e32 v125, v135, v135
	v_fmac_f32_e32 v124, v132, v132
	v_fmac_f32_e32 v125, v134, v134
	v_add_f32_e32 v124, v124, v125
	v_mul_f32_e32 v125, v149, v149
	v_mul_f32_e32 v126, v151, v151
	v_fmac_f32_e32 v125, v148, v148
	v_fmac_f32_e32 v126, v150, v150
	v_add_f32_e32 v125, v125, v126
	v_add_f32_e32 v124, v124, v125
	v_add_f32_e32 v124, v152, v124
	ds_bpermute_b32 v125, v222, v124
	s_waitcnt lgkmcnt(0)
	v_add_f32_e32 v124, v124, v125
	ds_bpermute_b32 v125, v223, v124
	s_and_saveexec_b64 s[16:17], s[0:1]
	s_cbranch_execz .LBB0_1038
	s_waitcnt lgkmcnt(0)
	v_add_f32_e32 v124, v124, v125
	ds_write_b32 v224, v124

; __device__ __forceinline__ float bflo(unsigned w) { return __uint_as_float(w << 16); }
; __device__ __forceinline__ float bfhi(unsigned w) { return __uint_as_float(w & 0xffff0000u); }
; __device__ __forceinline__ float u64f(u64 q) { return (float)(unsigned)(q >> 32) * 4294967296.f + (float)(unsigned)q; }
; __global__ void __launch_bounds__(512, 2) hybrid_fwd(Params p) {
;     ...
;         for (int row = c * 8 + wave; row < T_; row += G * 8) {
;             const float rs = rsqrtf(u64f(sq[row]) * SSQ_INV + EPS);
; #pragma unroll
;             for (int j = 0; j < 8; ++j) { const u32x2 hv = *(const u32x2*)(HB + (size_t)row * D_ + 256 * j + 4 * lane); const f32x4 g = *(const f32x4*)(p.final_norm + 256 * j + 4 * lane);
;                 *(f32x4*)(p.out + (size_t)row * D_ + 256 * j + 4 * lane) = (f32x4){bflo(hv.x), bfhi(hv.x), bflo(hv.y), bfhi(hv.y)} * rs * g; }
.LBB0_1111:
	s_add_u32 s14, s50, s10
	v_lshl_add_u64 v[18:19], s[50:51], 0, v[14:15]
	s_addc_u32 s15, s51, s11
	v_add_co_u32_e32 v22, vcc, s13, v18
	v_mov_b64_e32 v[24:25], s[14:15]
	s_nop 0
	v_addc_co_u32_e32 v23, vcc, 0, v19, vcc
	global_load_dwordx2 v[26:27], v[24:25], off
	global_load_dwordx2 v[28:29], v[22:23], off
	global_load_dwordx4 v[18:21], v[2:3], off
	s_add_i32 s0, s0, s2
	s_add_u32 s10, s10, s6
	s_addc_u32 s11, s11, s7
	v_lshl_add_u64 v[14:15], v[14:15], 0, s[8:9]
	s_cmpk_gt_i32 s0, 0x1fff
	s_waitcnt vmcnt(0) lgkmcnt(0)
	v_mov_b32_e32 v0, v27
	v_cvt_f32_u32_e32 v17, v26
	v_lshlrev_b32_e32 v24, 16, v28
	v_and_b32_e32 v25, 0xffff0000, v28
	v_lshlrev_b32_e32 v26, 16, v29
	v_and_b32_e32 v27, 0xffff0000, v29
	v_lshlrev_b64 v[28:29], s1, v[0:1]
	v_min_u32_e32 v0, 1, v28
	v_or_b32_e32 v0, v29, v0
	v_cvt_f32_u32_e32 v0, v0
	v_ldexp_f32 v0, v0, s3
	v_fmac_f32_e32 v17, 0x4f800000, v0
	v_fmamk_f32 v0, v17, 0x2e000000, v16
	v_mul_f32_e32 v17, 0x4b800000, v0
	v_cmp_gt_f32_e32 vcc, s12, v0
	s_nop 1
	v_cndmask_b32_e32 v0, v0, v17, vcc
	v_rsq_f32_e32 v0, v0
	s_nop 0
	v_mul_f32_e32 v17, 0x45800000, v0
	v_cndmask_b32_e32 v0, v0, v17, vcc
	v_pk_mul_f32 v[24:25], v[0:1], v[24:25] op_sel_hi:[0,1]
	v_pk_mul_f32 v[26:27], v[0:1], v[26:27] op_sel_hi:[0,1]
	v_pk_mul_f32 v[20:21], v[20:21], v[26:27]
	v_pk_mul_f32 v[18:19], v[18:19], v[24:25]
	global_store_dwordx4 v[12:13], v[18:21], off offset:-4096
	global_load_dwordx2 v[24:25], v[22:23], off offset:512
	s_nop 0
	global_load_dwordx4 v[18:21], v[2:3], off offset:1024
	s_waitcnt vmcnt(0) lgkmcnt(0)
	v_lshlrev_b32_e32 v26, 16, v24
	v_and_b32_e32 v27, 0xffff0000, v24
	v_lshlrev_b32_e32 v24, 16, v25
	v_and_b32_e32 v25, 0xffff0000, v25
	v_pk_mul_f32 v[26:27], v[0:1], v[26:27] op_sel_hi:[0,1]
	v_pk_mul_f32 v[24:25], v[0:1], v[24:25] op_sel_hi:[0,1]
	v_pk_mul_f32 v[20:21], v[20:21], v[24:25]
	v_pk_mul_f32 v[18:19], v[18:19], v[26:27]
	global_store_dwordx4 v[12:13], v[18:21], off offset:-3072
	global_load_dwordx2 v[24:25], v[22:23], off offset:1024
	s_nop 0
	global_load_dwordx4 v[18:21], v[2:3], off offset:2048
	s_waitcnt vmcnt(0) lgkmcnt(0)
	v_lshlrev_b32_e32 v26, 16, v24
	v_and_b32_e32 v27, 0xffff0000, v24
	v_lshlrev_b32_e32 v24, 16, v25
	v_and_b32_e32 v25, 0xffff0000, v25
	v_pk_mul_f32 v[26:27], v[0:1], v[26:27] op_sel_hi:[0,1]
	v_pk_mul_f32 v[24:25], v[0:1], v[24:25] op_sel_hi:[0,1]
	v_pk_mul_f32 v[20:21], v[20:21], v[24:25]
	v_pk_mul_f32 v[18:19], v[18:19], v[26:27]
	global_store_dwordx4 v[12:13], v[18:21], off offset:-2048
	global_load_dwordx2 v[24:25], v[22:23], off offset:1536
	s_nop 0
	global_load_dwordx4 v[18:21], v[2:3], off offset:3072
	s_waitcnt vmcnt(0) lgkmcnt(0)
	v_lshlrev_b32_e32 v26, 16, v24
	v_and_b32_e32 v27, 0xffff0000, v24
	v_lshlrev_b32_e32 v24, 16, v25
	v_and_b32_e32 v25, 0xffff0000, v25
	v_pk_mul_f32 v[26:27], v[0:1], v[26:27] op_sel_hi:[0,1]
	v_pk_mul_f32 v[24:25], v[0:1], v[24:25] op_sel_hi:[0,1]
	v_pk_mul_f32 v[20:21], v[20:21], v[24:25]
	v_pk_mul_f32 v[18:19], v[18:19], v[26:27]
	global_store_dwordx4 v[12:13], v[18:21], off offset:-1024
	global_load_dwordx2 v[24:25], v[22:23], off offset:2048
	s_nop 0
	global_load_dwordx4 v[18:21], v[4:5], off
	s_waitcnt vmcnt(0) lgkmcnt(0)
	v_lshlrev_b32_e32 v26, 16, v24
	v_and_b32_e32 v27, 0xffff0000, v24
	v_lshlrev_b32_e32 v24, 16, v25
	v_and_b32_e32 v25, 0xffff0000, v25
	v_pk_mul_f32 v[26:27], v[0:1], v[26:27] op_sel_hi:[0,1]
	v_pk_mul_f32 v[24:25], v[0:1], v[24:25] op_sel_hi:[0,1]
	v_pk_mul_f32 v[20:21], v[20:21], v[24:25]
	v_pk_mul_f32 v[18:19], v[18:19], v[26:27]
	global_store_dwordx4 v[12:13], v[18:21], off
	global_load_dwordx2 v[24:25], v[22:23], off offset:2560
	s_nop 0
	global_load_dwordx4 v[18:21], v[6:7], off
	s_waitcnt vmcnt(0) lgkmcnt(0)
	v_lshlrev_b32_e32 v26, 16, v24
	v_and_b32_e32 v27, 0xffff0000, v24
	v_lshlrev_b32_e32 v24, 16, v25
	v_and_b32_e32 v25, 0xffff0000, v25
	v_pk_mul_f32 v[26:27], v[0:1], v[26:27] op_sel_hi:[0,1]
	v_pk_mul_f32 v[24:25], v[0:1], v[24:25] op_sel_hi:[0,1]
	v_pk_mul_f32 v[20:21], v[20:21], v[24:25]
	v_pk_mul_f32 v[18:19], v[18:19], v[26:27]
	global_store_dwordx4 v[12:13], v[18:21], off offset:1024
	global_load_dwordx2 v[24:25], v[22:23], off offset:3072
	s_nop 0
	global_load_dwordx4 v[18:21], v[8:9], off
	s_waitcnt vmcnt(0) lgkmcnt(0)
	v_lshlrev_b32_e32 v26, 16, v24
	v_and_b32_e32 v27, 0xffff0000, v24
	v_lshlrev_b32_e32 v24, 16, v25
	v_and_b32_e32 v25, 0xffff0000, v25
	v_pk_mul_f32 v[26:27], v[0:1], v[26:27] op_sel_hi:[0,1]
	v_pk_mul_f32 v[24:25], v[0:1], v[24:25] op_sel_hi:[0,1]
	v_pk_mul_f32 v[20:21], v[20:21], v[24:25]
	v_pk_mul_f32 v[18:19], v[18:19], v[26:27]
	global_store_dwordx4 v[12:13], v[18:21], off offset:2048
	global_load_dwordx2 v[24:25], v[22:23], off offset:3584
	s_nop 0
	global_load_dwordx4 v[18:21], v[10:11], off
	s_waitcnt vmcnt(0) lgkmcnt(0)
	v_lshlrev_b32_e32 v22, 16, v24
	v_and_b32_e32 v23, 0xffff0000, v24
	v_lshlrev_b32_e32 v24, 16, v25
	v_and_b32_e32 v25, 0xffff0000, v25
	v_pk_mul_f32 v[22:23], v[0:1], v[22:23] op_sel_hi:[0,1]
	v_pk_mul_f32 v[24:25], v[0:1], v[24:25] op_sel_hi:[0,1]
	v_pk_mul_f32 v[20:21], v[20:21], v[24:25]
	v_pk_mul_f32 v[18:19], v[18:19], v[22:23]
	global_store_dwordx4 v[12:13], v[18:21], off offset:3072
	v_lshl_add_u64 v[12:13], v[12:13], 0, s[4:5]
	s_cbranch_scc0 .LBB0_1111
